# K-loop MFMA blocks cleaned everywhere, accumulator zero-init with 64-bit moves, m0 write hoisted over the address add so the DMA groups need no s_nop
# speedup vs baseline: 1.0247x; 1.0116x over previous
; #define PG8_STAGE(bufoff, gbase, voff, p64) do { _Pragma("unroll") for (int _i = 0; _i < 2; ++_i) { \
;         const char* _gb = (const char*)(gbase) + (size_t)_i * (p64); const unsigned _la = ldsbase + (unsigned)(bufoff) + (unsigned)_i * 8192u; \
;         asm volatile("s_mov_b32 m0, %0\n\ts_nop 0\n\tglobal_load_lds_dwordx4 %1, %2" :: "s"(_la), "v"(voff), "s"(_gb) : "memory"); } } while (0)
; #define PG8_LDA(dst, b, h) do { _Pragma("unroll") for (int m = 0; m < 4; ++m) _Pragma("unroll") for (int k = 0; k < 2; ++k) dst[m][k] = *(const LAS bf16x8*)(lds + PG8_SA(b, h) + aoff + m * 2048 + k * 1024); } while (0)
; #define PG8_LDB(dst, b, h) do { _Pragma("unroll") for (int n = 0; n < 2; ++n) _Pragma("unroll") for (int k = 0; k < 2; ++k) dst[n][k] = *(const LAS bf16x8*)(lds + PG8_SB(b, h) + boff + n * 2048 + k * 1024); } while (0)
; #define PG8_MMA(ai, bj, At, Bt) do { __builtin_amdgcn_s_setprio(1); _Pragma("unroll") for (int m = 0; m < 4; ++m) _Pragma("unroll") for (int n = 0; n < 2; ++n) _Pragma("unroll") for (int k = 0; k < 2; ++k) \
;         acc[ai][bj][m][n] = __builtin_amdgcn_mfma_f32_16x16x32_bf16(Bt[n][k], At[m][k], acc[ai][bj][m][n], 0, 0, 0); __builtin_amdgcn_s_setprio(0); } while (0)
; #define PG8_BAR __builtin_amdgcn_s_barrier()
; template <class Epi, class Sched>
; __device__ __forceinline__ void gemm_phase(LAS unsigned char* lds, const Sched& S, const Epi& E) {
;     ...
;     f32x4 acc[2][2][4][2];
; #pragma unroll
;     for (int a = 0; a < 2; ++a)
; #pragma unroll
;         for (int b = 0; b < 2; ++b)
; #pragma unroll
;             for (int m = 0; m < 4; ++m)
; #pragma unroll
;                 for (int n = 0; n < 2; ++n) acc[a][b][m][n] = (f32x4){0.f, 0.f, 0.f, 0.f};
;     ...
;         for (int t = 0; t < nt; t += 2) {
;             const bool last = (t == nt - 2);
;             const char* a1 = cA + (size_t)(t + 1) * kstep;
;             const char* a2 = last ? nA : cA + (size_t)(t + 2) * kstep; const char* b2 = last ? nB : cB + (size_t)(t + 2) * kstep;
;             const char* a3 = a2 + kstep; const char* b3 = b2 + kstep;
;             const unsigned vA2 = voffA, vB2 = voffB, hA2 = hA, hB2 = hB;
;             PG8_LDB(B0, 0, 0); PG8_LDB(B1, 0, 1); PG8_SCHED; PG8_LDA(At, 0, 0); PG8_STAGE(PG8_SA(1, 1), a1 + hA, voffA, hA / 2);
;             PG8_WAIT_V(8); PG8_WAIT_L(0); PG8_BAR; PG8_MMA(0, 0, At, B0); PG8_MMA(0, 1, At, B1); PG8_BAR; PG8_SCHED;
.LBB0_303:
	s_add_u32 s38, s38, 0x40080
	s_addc_u32 s39, s39, 0
	s_add_u32 s62, s40, 0x100
	s_addc_u32 s63, s41, 0
	s_mov_b32 s64, -2
	v_mov_b64_e32 v[0:1], 0
	v_mov_b64_e32 v[2:3], 0
	v_mov_b64_e32 v[4:5], 0
	v_mov_b64_e32 v[6:7], 0
	v_mov_b64_e32 v[16:17], 0
	v_mov_b64_e32 v[18:19], 0
	v_mov_b64_e32 v[20:21], 0
	v_mov_b64_e32 v[22:23], 0
	v_mov_b64_e32 v[32:33], 0
	v_mov_b64_e32 v[34:35], 0
	v_mov_b64_e32 v[36:37], 0
	v_mov_b64_e32 v[38:39], 0
	v_mov_b64_e32 v[48:49], 0
	v_mov_b64_e32 v[50:51], 0
	v_mov_b64_e32 v[52:53], 0
	v_mov_b64_e32 v[54:55], 0
	v_mov_b64_e32 v[8:9], 0
	v_mov_b64_e32 v[10:11], 0
	v_mov_b64_e32 v[12:13], 0
	v_mov_b64_e32 v[14:15], 0
	v_mov_b64_e32 v[24:25], 0
	v_mov_b64_e32 v[26:27], 0
	v_mov_b64_e32 v[28:29], 0
	v_mov_b64_e32 v[30:31], 0
	v_mov_b64_e32 v[40:41], 0
	v_mov_b64_e32 v[42:43], 0
	v_mov_b64_e32 v[44:45], 0
	v_mov_b64_e32 v[46:47], 0
	v_mov_b64_e32 v[56:57], 0
	v_mov_b64_e32 v[58:59], 0
	v_mov_b64_e32 v[60:61], 0
	v_mov_b64_e32 v[62:63], 0
	v_mov_b64_e32 v[64:65], 0
	v_mov_b64_e32 v[66:67], 0
	v_mov_b64_e32 v[68:69], 0
	v_mov_b64_e32 v[70:71], 0
	v_mov_b64_e32 v[80:81], 0
	v_mov_b64_e32 v[82:83], 0
	v_mov_b64_e32 v[84:85], 0
	v_mov_b64_e32 v[86:87], 0
	v_mov_b64_e32 v[96:97], 0
	v_mov_b64_e32 v[98:99], 0
	v_mov_b64_e32 v[100:101], 0
	v_mov_b64_e32 v[102:103], 0
	v_mov_b64_e32 v[112:113], 0
	v_mov_b64_e32 v[114:115], 0
	v_mov_b64_e32 v[116:117], 0
	v_mov_b64_e32 v[118:119], 0
	v_mov_b64_e32 v[72:73], 0
	v_mov_b64_e32 v[74:75], 0
	v_mov_b64_e32 v[76:77], 0
	v_mov_b64_e32 v[78:79], 0
	v_mov_b64_e32 v[88:89], 0
	v_mov_b64_e32 v[90:91], 0
	v_mov_b64_e32 v[92:93], 0
	v_mov_b64_e32 v[94:95], 0
	v_mov_b64_e32 v[104:105], 0
	v_mov_b64_e32 v[106:107], 0
	v_mov_b64_e32 v[108:109], 0
	v_mov_b64_e32 v[110:111], 0
	v_mov_b64_e32 v[120:121], 0
	v_mov_b64_e32 v[122:123], 0
	v_mov_b64_e32 v[124:125], 0
	v_mov_b64_e32 v[126:127], 0
.LBB0_304:
	ds_read_b128 v[144:147], v138
	ds_read_b128 v[148:151], v138 offset:1024
	ds_read_b128 v[152:155], v138 offset:2048
	ds_read_b128 v[156:159], v138 offset:3072
	ds_read_b128 v[160:163], v139
	ds_read_b128 v[164:167], v139 offset:1024
	ds_read_b128 v[168:171], v139 offset:2048
	ds_read_b128 v[172:175], v139 offset:3072
	s_add_u32 s30, s38, 0xfffc0080
	s_addc_u32 s31, s39, -1
	s_cmp_eq_u32 s64, 12
	s_cselect_b32 s40, s24, s30
	s_cselect_b32 s41, s25, s31
	s_cselect_b32 s44, s26, s62
	s_cselect_b32 s45, s27, s63
	s_add_u32 s42, s40, 0x80
	s_addc_u32 s43, s41, 0
	ds_read_b128 v[178:181], v140
	ds_read_b128 v[182:185], v140 offset:1024
	ds_read_b128 v[186:189], v140 offset:2048
	ds_read_b128 v[190:193], v140 offset:3072
	ds_read_b128 v[194:197], v140 offset:4096
	ds_read_b128 v[198:201], v140 offset:5120
	ds_read_b128 v[202:205], v140 offset:6144
	ds_read_b128 v[206:209], v140 offset:7168
	s_mov_b32 m0, s55
	s_nop 0
	global_load_lds_dwordx4 v134, s[38:39]
	s_add_u32 s66, s38, 0x20000
	s_mov_b32 m0, s56
	s_addc_u32 s67, s39, 0
	global_load_lds_dwordx4 v134, s[66:67]
	s_waitcnt vmcnt(8)
	s_waitcnt lgkmcnt(0)
	s_barrier
	s_setprio 1
	v_mfma_f32_16x16x32_bf16 v[124:127], v[144:147], v[178:181], v[124:127]
	v_mfma_f32_16x16x32_bf16 v[120:123], v[152:155], v[178:181], v[120:123]
	v_mfma_f32_16x16x32_bf16 v[108:111], v[144:147], v[186:189], v[108:111]
	v_mfma_f32_16x16x32_bf16 v[104:107], v[152:155], v[186:189], v[104:107]
	v_mfma_f32_16x16x32_bf16 v[92:95], v[144:147], v[194:197], v[92:95]
	v_mfma_f32_16x16x32_bf16 v[88:91], v[152:155], v[194:197], v[88:91]
	v_mfma_f32_16x16x32_bf16 v[76:79], v[144:147], v[202:205], v[76:79]
	v_mfma_f32_16x16x32_bf16 v[72:75], v[152:155], v[202:205], v[72:75]
	v_mfma_f32_16x16x32_bf16 v[124:127], v[148:151], v[182:185], v[124:127]
	v_mfma_f32_16x16x32_bf16 v[120:123], v[156:159], v[182:185], v[120:123]
	v_mfma_f32_16x16x32_bf16 v[108:111], v[148:151], v[190:193], v[108:111]
	v_mfma_f32_16x16x32_bf16 v[104:107], v[156:159], v[190:193], v[104:107]
	v_mfma_f32_16x16x32_bf16 v[92:95], v[148:151], v[198:201], v[92:95]
	v_mfma_f32_16x16x32_bf16 v[88:91], v[156:159], v[198:201], v[88:91]
	v_mfma_f32_16x16x32_bf16 v[76:79], v[148:151], v[206:209], v[76:79]
	v_mfma_f32_16x16x32_bf16 v[72:75], v[156:159], v[206:209], v[72:75]
	v_mfma_f32_16x16x32_bf16 v[116:119], v[160:163], v[178:181], v[116:119]
	v_mfma_f32_16x16x32_bf16 v[112:115], v[168:171], v[178:181], v[112:115]
	v_mfma_f32_16x16x32_bf16 v[100:103], v[160:163], v[186:189], v[100:103]
	v_mfma_f32_16x16x32_bf16 v[96:99], v[168:171], v[186:189], v[96:99]
	v_mfma_f32_16x16x32_bf16 v[84:87], v[160:163], v[194:197], v[84:87]
	v_mfma_f32_16x16x32_bf16 v[80:83], v[168:171], v[194:197], v[80:83]
	v_mfma_f32_16x16x32_bf16 v[68:71], v[160:163], v[202:205], v[68:71]
	v_mfma_f32_16x16x32_bf16 v[64:67], v[168:171], v[202:205], v[64:67]
	v_mfma_f32_16x16x32_bf16 v[116:119], v[164:167], v[182:185], v[116:119]
	v_mfma_f32_16x16x32_bf16 v[112:115], v[172:175], v[182:185], v[112:115]
	v_mfma_f32_16x16x32_bf16 v[100:103], v[164:167], v[190:193], v[100:103]
	v_mfma_f32_16x16x32_bf16 v[96:99], v[172:175], v[190:193], v[96:99]
	v_mfma_f32_16x16x32_bf16 v[84:87], v[164:167], v[198:201], v[84:87]
	v_mfma_f32_16x16x32_bf16 v[80:83], v[172:175], v[198:201], v[80:83]
	v_mfma_f32_16x16x32_bf16 v[68:71], v[164:167], v[206:209], v[68:71]
	v_mfma_f32_16x16x32_bf16 v[64:67], v[172:175], v[206:209], v[64:67]
	s_setprio 0
	s_barrier
; #define PG8_STAGE(bufoff, gbase, voff, p64) do { _Pragma("unroll") for (int _i = 0; _i < 2; ++_i) { \
;         const char* _gb = (const char*)(gbase) + (size_t)_i * (p64); const unsigned _la = ldsbase + (unsigned)(bufoff) + (unsigned)_i * 8192u; \
;         asm volatile("s_mov_b32 m0, %0\n\ts_nop 0\n\tglobal_load_lds_dwordx4 %1, %2" :: "s"(_la), "v"(voff), "s"(_gb) : "memory"); } } while (0)
; #define PG8_LDA(dst, b, h) do { _Pragma("unroll") for (int m = 0; m < 4; ++m) _Pragma("unroll") for (int k = 0; k < 2; ++k) dst[m][k] = *(const LAS bf16x8*)(lds + PG8_SA(b, h) + aoff + m * 2048 + k * 1024); } while (0)
; #define PG8_LDB(dst, b, h) do { _Pragma("unroll") for (int n = 0; n < 2; ++n) _Pragma("unroll") for (int k = 0; k < 2; ++k) dst[n][k] = *(const LAS bf16x8*)(lds + PG8_SB(b, h) + boff + n * 2048 + k * 1024); } while (0)
; #define PG8_MMA(ai, bj, At, Bt) do { __builtin_amdgcn_s_setprio(1); _Pragma("unroll") for (int m = 0; m < 4; ++m) _Pragma("unroll") for (int n = 0; n < 2; ++n) _Pragma("unroll") for (int k = 0; k < 2; ++k) \
;         acc[ai][bj][m][n] = __builtin_amdgcn_mfma_f32_16x16x32_bf16(Bt[n][k], At[m][k], acc[ai][bj][m][n], 0, 0, 0); __builtin_amdgcn_s_setprio(0); } while (0)
; #define PG8_WAIT_V(n) asm volatile("s_waitcnt vmcnt(" #n ")" ::: "memory")
; #define PG8_WAIT_L(n) asm volatile("s_waitcnt lgkmcnt(" #n ")" ::: "memory")
; #define PG8_BAR __builtin_amdgcn_s_barrier()
; #define PG8_SCHED __builtin_amdgcn_sched_barrier(0)
; template <class Epi, class Sched>
; __device__ __forceinline__ void gemm_phase(LAS unsigned char* lds, const Sched& S, const Epi& E) {
;     ...
;             PG8_LDA(At, 0, 1); PG8_STAGE(PG8_SB(0, 0), b2, vB2, hB2 / 2); PG8_STAGE(PG8_SB(0, 1), b2 + hB2, vB2, hB2 / 2); PG8_STAGE(PG8_SA(0, 0), a2, vA2, hA2 / 2);
;             PG8_WAIT_V(8); PG8_WAIT_L(0); PG8_BAR; PG8_MMA(1, 0, At, B0); PG8_MMA(1, 1, At, B1); PG8_BAR; PG8_SCHED;
;             PG8_LDB(B0, 1, 0); PG8_LDB(B1, 1, 1); PG8_SCHED; PG8_LDA(At, 1, 0); PG8_STAGE(PG8_SA(0, 1), a2 + hA2, vA2, hA2 / 2);
;             PG8_WAIT_V(8); PG8_WAIT_L(0); PG8_BAR; PG8_MMA(0, 0, At, B0); PG8_MMA(0, 1, At, B1); PG8_BAR; PG8_SCHED;
	s_add_u32 s66, s44, 0x20000
	ds_read_b128 v[178:181], v140 offset:16384
	ds_read_b128 v[182:185], v140 offset:17408
	ds_read_b128 v[186:189], v140 offset:18432
	ds_read_b128 v[190:193], v140 offset:19456
	ds_read_b128 v[194:197], v140 offset:20480
	ds_read_b128 v[198:201], v140 offset:21504
	ds_read_b128 v[202:205], v140 offset:22528
	ds_read_b128 v[206:209], v140 offset:23552
	s_mov_b32 m0, s33
	s_nop 0
	global_load_lds_dwordx4 v135, s[44:45]
	s_mov_b32 m0, s34
	s_addc_u32 s67, s45, 0
	global_load_lds_dwordx4 v135, s[66:67]
	s_add_u32 s66, s44, 0x40000
	s_mov_b32 m0, s35
	s_addc_u32 s67, s45, 0
	global_load_lds_dwordx4 v135, s[66:67]
	s_add_u32 s66, s44, 0x60000
	s_mov_b32 m0, s36
	s_addc_u32 s67, s45, 0
	global_load_lds_dwordx4 v135, s[66:67]
	s_mov_b32 m0, s12
	s_nop 0
	global_load_lds_dwordx4 v134, s[40:41]
	s_add_u32 s66, s40, 0x20000
	s_mov_b32 m0, s37
	s_addc_u32 s67, s41, 0
	global_load_lds_dwordx4 v134, s[66:67]
	s_waitcnt vmcnt(8)
	s_waitcnt lgkmcnt(0)
	s_barrier
	s_setprio 1
	v_mfma_f32_16x16x32_bf16 v[60:63], v[144:147], v[178:181], v[60:63]
	v_mfma_f32_16x16x32_bf16 v[56:59], v[152:155], v[178:181], v[56:59]
	v_mfma_f32_16x16x32_bf16 v[44:47], v[144:147], v[186:189], v[44:47]
	v_mfma_f32_16x16x32_bf16 v[40:43], v[152:155], v[186:189], v[40:43]
	v_mfma_f32_16x16x32_bf16 v[28:31], v[144:147], v[194:197], v[28:31]
	v_mfma_f32_16x16x32_bf16 v[24:27], v[152:155], v[194:197], v[24:27]
	v_mfma_f32_16x16x32_bf16 v[12:15], v[144:147], v[202:205], v[12:15]
	v_mfma_f32_16x16x32_bf16 v[8:11], v[152:155], v[202:205], v[8:11]
	v_mfma_f32_16x16x32_bf16 v[60:63], v[148:151], v[182:185], v[60:63]
	v_mfma_f32_16x16x32_bf16 v[56:59], v[156:159], v[182:185], v[56:59]
	v_mfma_f32_16x16x32_bf16 v[44:47], v[148:151], v[190:193], v[44:47]
	v_mfma_f32_16x16x32_bf16 v[40:43], v[156:159], v[190:193], v[40:43]
	v_mfma_f32_16x16x32_bf16 v[28:31], v[148:151], v[198:201], v[28:31]
	v_mfma_f32_16x16x32_bf16 v[24:27], v[156:159], v[198:201], v[24:27]
	v_mfma_f32_16x16x32_bf16 v[12:15], v[148:151], v[206:209], v[12:15]
	v_mfma_f32_16x16x32_bf16 v[8:11], v[156:159], v[206:209], v[8:11]
	v_mfma_f32_16x16x32_bf16 v[52:55], v[160:163], v[178:181], v[52:55]
	v_mfma_f32_16x16x32_bf16 v[48:51], v[168:171], v[178:181], v[48:51]
	v_mfma_f32_16x16x32_bf16 v[36:39], v[160:163], v[186:189], v[36:39]
	v_mfma_f32_16x16x32_bf16 v[32:35], v[168:171], v[186:189], v[32:35]
	v_mfma_f32_16x16x32_bf16 v[20:23], v[160:163], v[194:197], v[20:23]
	v_mfma_f32_16x16x32_bf16 v[16:19], v[168:171], v[194:197], v[16:19]
	v_mfma_f32_16x16x32_bf16 v[4:7], v[160:163], v[202:205], v[4:7]
	v_mfma_f32_16x16x32_bf16 v[0:3], v[168:171], v[202:205], v[0:3]
	v_mfma_f32_16x16x32_bf16 v[52:55], v[164:167], v[182:185], v[52:55]
	v_mfma_f32_16x16x32_bf16 v[48:51], v[172:175], v[182:185], v[48:51]
	v_mfma_f32_16x16x32_bf16 v[36:39], v[164:167], v[190:193], v[36:39]
	v_mfma_f32_16x16x32_bf16 v[32:35], v[172:175], v[190:193], v[32:35]
	v_mfma_f32_16x16x32_bf16 v[20:23], v[164:167], v[198:201], v[20:23]
	v_mfma_f32_16x16x32_bf16 v[16:19], v[172:175], v[198:201], v[16:19]
	v_mfma_f32_16x16x32_bf16 v[4:7], v[164:167], v[206:209], v[4:7]
	v_mfma_f32_16x16x32_bf16 v[0:3], v[172:175], v[206:209], v[0:3]
	s_setprio 0
	s_barrier
	ds_read_b128 v[144:147], v141
	ds_read_b128 v[148:151], v141 offset:1024
	ds_read_b128 v[152:155], v141 offset:2048
	ds_read_b128 v[156:159], v141 offset:3072
	ds_read_b128 v[160:163], v142
	ds_read_b128 v[164:167], v142 offset:1024
	ds_read_b128 v[168:171], v142 offset:2048
	ds_read_b128 v[172:175], v142 offset:3072
	ds_read_b128 v[178:181], v140 offset:32768
	ds_read_b128 v[182:185], v140 offset:33792
	ds_read_b128 v[186:189], v140 offset:34816
	ds_read_b128 v[190:193], v140 offset:35840
	ds_read_b128 v[194:197], v140 offset:36864
	ds_read_b128 v[198:201], v140 offset:37888
	ds_read_b128 v[202:205], v140 offset:38912
	ds_read_b128 v[206:209], v140 offset:39936
	s_add_u32 s66, s40, 0x40000
	s_mov_b32 m0, s46
	s_addc_u32 s67, s41, 0
	global_load_lds_dwordx4 v134, s[66:67]
	s_add_u32 s66, s40, 0x60000
	s_mov_b32 m0, s47
	s_addc_u32 s67, s41, 0
	global_load_lds_dwordx4 v134, s[66:67]
	s_waitcnt vmcnt(8)
	s_waitcnt lgkmcnt(0)
	s_barrier
; #define PG8_STAGE(bufoff, gbase, voff, p64) do { _Pragma("unroll") for (int _i = 0; _i < 2; ++_i) { \
;         const char* _gb = (const char*)(gbase) + (size_t)_i * (p64); const unsigned _la = ldsbase + (unsigned)(bufoff) + (unsigned)_i * 8192u; \
;         asm volatile("s_mov_b32 m0, %0\n\ts_nop 0\n\tglobal_load_lds_dwordx4 %1, %2" :: "s"(_la), "v"(voff), "s"(_gb) : "memory"); } } while (0)
; #define PG8_LDA(dst, b, h) do { _Pragma("unroll") for (int m = 0; m < 4; ++m) _Pragma("unroll") for (int k = 0; k < 2; ++k) dst[m][k] = *(const LAS bf16x8*)(lds + PG8_SA(b, h) + aoff + m * 2048 + k * 1024); } while (0)
; #define PG8_MMA(ai, bj, At, Bt) do { __builtin_amdgcn_s_setprio(1); _Pragma("unroll") for (int m = 0; m < 4; ++m) _Pragma("unroll") for (int n = 0; n < 2; ++n) _Pragma("unroll") for (int k = 0; k < 2; ++k) \
;         acc[ai][bj][m][n] = __builtin_amdgcn_mfma_f32_16x16x32_bf16(Bt[n][k], At[m][k], acc[ai][bj][m][n], 0, 0, 0); __builtin_amdgcn_s_setprio(0); } while (0)
; #define PG8_WAIT_V(n) asm volatile("s_waitcnt vmcnt(" #n ")" ::: "memory")
; #define PG8_WAIT_L(n) asm volatile("s_waitcnt lgkmcnt(" #n ")" ::: "memory")
; #define PG8_BAR __builtin_amdgcn_s_barrier()
; #define PG8_SCHED __builtin_amdgcn_sched_barrier(0)
; template <class Epi, class Sched>
; __device__ __forceinline__ void gemm_phase(LAS unsigned char* lds, const Sched& S, const Epi& E) {
;     ...
;             PG8_WAIT_V(8); PG8_WAIT_L(0); PG8_BAR; PG8_MMA(0, 0, At, B0); PG8_MMA(0, 1, At, B1); PG8_BAR; PG8_SCHED;
;             PG8_LDA(At, 1, 1); PG8_STAGE(PG8_SB(1, 0), b3, vB2, hB2 / 2); PG8_STAGE(PG8_SB(1, 1), b3 + hB2, vB2, hB2 / 2); PG8_STAGE(PG8_SA(1, 0), a3, vA2, hA2 / 2);
;             PG8_WAIT_V(8); PG8_WAIT_L(0); PG8_BAR; PG8_MMA(1, 0, At, B0); PG8_MMA(1, 1, At, B1); PG8_BAR; PG8_SCHED;
;         }
;         if (wr == 0) PG8_BAR;
	s_setprio 1
	v_mfma_f32_16x16x32_bf16 v[124:127], v[144:147], v[178:181], v[124:127]
	v_mfma_f32_16x16x32_bf16 v[120:123], v[152:155], v[178:181], v[120:123]
	v_mfma_f32_16x16x32_bf16 v[108:111], v[144:147], v[186:189], v[108:111]
	v_mfma_f32_16x16x32_bf16 v[104:107], v[152:155], v[186:189], v[104:107]
	v_mfma_f32_16x16x32_bf16 v[92:95], v[144:147], v[194:197], v[92:95]
	v_mfma_f32_16x16x32_bf16 v[88:91], v[152:155], v[194:197], v[88:91]
	v_mfma_f32_16x16x32_bf16 v[76:79], v[144:147], v[202:205], v[76:79]
	v_mfma_f32_16x16x32_bf16 v[72:75], v[152:155], v[202:205], v[72:75]
	v_mfma_f32_16x16x32_bf16 v[124:127], v[148:151], v[182:185], v[124:127]
	v_mfma_f32_16x16x32_bf16 v[120:123], v[156:159], v[182:185], v[120:123]
	v_mfma_f32_16x16x32_bf16 v[108:111], v[148:151], v[190:193], v[108:111]
	v_mfma_f32_16x16x32_bf16 v[104:107], v[156:159], v[190:193], v[104:107]
	v_mfma_f32_16x16x32_bf16 v[92:95], v[148:151], v[198:201], v[92:95]
	v_mfma_f32_16x16x32_bf16 v[88:91], v[156:159], v[198:201], v[88:91]
	v_mfma_f32_16x16x32_bf16 v[76:79], v[148:151], v[206:209], v[76:79]
	v_mfma_f32_16x16x32_bf16 v[72:75], v[156:159], v[206:209], v[72:75]
	v_mfma_f32_16x16x32_bf16 v[116:119], v[160:163], v[178:181], v[116:119]
	v_mfma_f32_16x16x32_bf16 v[112:115], v[168:171], v[178:181], v[112:115]
	v_mfma_f32_16x16x32_bf16 v[100:103], v[160:163], v[186:189], v[100:103]
	v_mfma_f32_16x16x32_bf16 v[96:99], v[168:171], v[186:189], v[96:99]
	v_mfma_f32_16x16x32_bf16 v[84:87], v[160:163], v[194:197], v[84:87]
	v_mfma_f32_16x16x32_bf16 v[80:83], v[168:171], v[194:197], v[80:83]
	v_mfma_f32_16x16x32_bf16 v[68:71], v[160:163], v[202:205], v[68:71]
	v_mfma_f32_16x16x32_bf16 v[64:67], v[168:171], v[202:205], v[64:67]
	v_mfma_f32_16x16x32_bf16 v[116:119], v[164:167], v[182:185], v[116:119]
	v_mfma_f32_16x16x32_bf16 v[112:115], v[172:175], v[182:185], v[112:115]
	v_mfma_f32_16x16x32_bf16 v[100:103], v[164:167], v[190:193], v[100:103]
	v_mfma_f32_16x16x32_bf16 v[96:99], v[172:175], v[190:193], v[96:99]
	v_mfma_f32_16x16x32_bf16 v[84:87], v[164:167], v[198:201], v[84:87]
	v_mfma_f32_16x16x32_bf16 v[80:83], v[172:175], v[198:201], v[80:83]
	v_mfma_f32_16x16x32_bf16 v[68:71], v[164:167], v[206:209], v[68:71]
	v_mfma_f32_16x16x32_bf16 v[64:67], v[172:175], v[206:209], v[64:67]
	s_setprio 0
	s_barrier
	s_add_u32 s66, s44, 0x80
	s_addc_u32 s67, s45, 0
	ds_read_b128 v[178:181], v140 offset:49152
	ds_read_b128 v[182:185], v140 offset:50176
	ds_read_b128 v[186:189], v140 offset:51200
	ds_read_b128 v[190:193], v140 offset:52224
	ds_read_b128 v[194:197], v140 offset:53248
	ds_read_b128 v[198:201], v140 offset:54272
	ds_read_b128 v[202:205], v140 offset:55296
	ds_read_b128 v[206:209], v140 offset:56320
	s_mov_b32 m0, s49
	s_nop 0
	global_load_lds_dwordx4 v135, s[66:67]
	s_add_u32 s66, s44, 0x20080
	s_mov_b32 m0, s50
	s_addc_u32 s67, s45, 0
	global_load_lds_dwordx4 v135, s[66:67]
	s_add_u32 s66, s44, 0x40080
	s_mov_b32 m0, s53
	s_addc_u32 s67, s45, 0
	global_load_lds_dwordx4 v135, s[66:67]
	s_add_u32 s44, s44, 0x60080
	s_mov_b32 m0, s54
	s_addc_u32 s45, s45, 0
	global_load_lds_dwordx4 v135, s[44:45]
	s_mov_b32 m0, s51
	s_nop 0
	global_load_lds_dwordx4 v134, s[42:43]
	s_add_u32 s40, s40, 0x20080
	s_mov_b32 m0, s52
	s_addc_u32 s41, s41, 0
	global_load_lds_dwordx4 v134, s[40:41]
	s_waitcnt vmcnt(8)
	s_waitcnt lgkmcnt(0)
	s_barrier
	s_setprio 1
	v_mfma_f32_16x16x32_bf16 v[60:63], v[144:147], v[178:181], v[60:63]
	v_mfma_f32_16x16x32_bf16 v[56:59], v[152:155], v[178:181], v[56:59]
	v_mfma_f32_16x16x32_bf16 v[44:47], v[144:147], v[186:189], v[44:47]
	v_mfma_f32_16x16x32_bf16 v[40:43], v[152:155], v[186:189], v[40:43]
	v_mfma_f32_16x16x32_bf16 v[28:31], v[144:147], v[194:197], v[28:31]
	v_mfma_f32_16x16x32_bf16 v[24:27], v[152:155], v[194:197], v[24:27]
	v_mfma_f32_16x16x32_bf16 v[12:15], v[144:147], v[202:205], v[12:15]
	v_mfma_f32_16x16x32_bf16 v[8:11], v[152:155], v[202:205], v[8:11]
	v_mfma_f32_16x16x32_bf16 v[60:63], v[148:151], v[182:185], v[60:63]
	v_mfma_f32_16x16x32_bf16 v[56:59], v[156:159], v[182:185], v[56:59]
	v_mfma_f32_16x16x32_bf16 v[44:47], v[148:151], v[190:193], v[44:47]
	v_mfma_f32_16x16x32_bf16 v[40:43], v[156:159], v[190:193], v[40:43]
	v_mfma_f32_16x16x32_bf16 v[28:31], v[148:151], v[198:201], v[28:31]
	v_mfma_f32_16x16x32_bf16 v[24:27], v[156:159], v[198:201], v[24:27]
	v_mfma_f32_16x16x32_bf16 v[12:15], v[148:151], v[206:209], v[12:15]
	v_mfma_f32_16x16x32_bf16 v[8:11], v[156:159], v[206:209], v[8:11]
	v_mfma_f32_16x16x32_bf16 v[52:55], v[160:163], v[178:181], v[52:55]
	v_mfma_f32_16x16x32_bf16 v[48:51], v[168:171], v[178:181], v[48:51]
	v_mfma_f32_16x16x32_bf16 v[36:39], v[160:163], v[186:189], v[36:39]
	v_mfma_f32_16x16x32_bf16 v[32:35], v[168:171], v[186:189], v[32:35]
	v_mfma_f32_16x16x32_bf16 v[20:23], v[160:163], v[194:197], v[20:23]
	v_mfma_f32_16x16x32_bf16 v[16:19], v[168:171], v[194:197], v[16:19]
	v_mfma_f32_16x16x32_bf16 v[4:7], v[160:163], v[202:205], v[4:7]
	v_mfma_f32_16x16x32_bf16 v[0:3], v[168:171], v[202:205], v[0:3]
	v_mfma_f32_16x16x32_bf16 v[52:55], v[164:167], v[182:185], v[52:55]
	v_mfma_f32_16x16x32_bf16 v[48:51], v[172:175], v[182:185], v[48:51]
	v_mfma_f32_16x16x32_bf16 v[36:39], v[164:167], v[190:193], v[36:39]
	v_mfma_f32_16x16x32_bf16 v[32:35], v[172:175], v[190:193], v[32:35]
	v_mfma_f32_16x16x32_bf16 v[20:23], v[164:167], v[198:201], v[20:23]
	v_mfma_f32_16x16x32_bf16 v[16:19], v[172:175], v[198:201], v[16:19]
	v_mfma_f32_16x16x32_bf16 v[4:7], v[164:167], v[206:209], v[4:7]
	v_mfma_f32_16x16x32_bf16 v[0:3], v[172:175], v[206:209], v[0:3]
	s_setprio 0
	s_barrier
	s_add_i32 s64, s64, 2
	s_add_u32 s38, s38, 0x100
	s_addc_u32 s39, s39, 0
	s_add_u32 s62, s62, 0x100
	s_addc_u32 s63, s63, 0
	s_cmp_gt_u32 s64, 13
	s_cbranch_scc0 .LBB0_304
	s_and_b64 vcc, exec, s[18:19]
	s_cbranch_vccz .LBB0_307
	s_barrier

; #define PG8_STAGE(bufoff, gbase, voff, p64) do { _Pragma("unroll") for (int _i = 0; _i < 2; ++_i) { \
;         const char* _gb = (const char*)(gbase) + (size_t)_i * (p64); const unsigned _la = ldsbase + (unsigned)(bufoff) + (unsigned)_i * 8192u; \
;         asm volatile("s_mov_b32 m0, %0\n\ts_nop 0\n\tglobal_load_lds_dwordx4 %1, %2" :: "s"(_la), "v"(voff), "s"(_gb) : "memory"); } } while (0)
; #define PG8_BAR __builtin_amdgcn_s_barrier()
; template <class Epi, class Sched>
; __device__ __forceinline__ void gemm_phase(LAS unsigned char* lds, const Sched& S, const Epi& E) {
;     ...
;     const unsigned ldsbase = (unsigned)(size_t)lds + (unsigned)wid * 1024u;
;     const int aoff = lds_byte(wr * 64 + fr, fq * 8), boff = lds_byte(wc * 32 + fr, fq * 8);
;     ...
;     int ui = 0;
;     const char* cA; const char* cB; unsigned hA, hB; int nt; unsigned voffA, voffB;
;     { Unit u0; if (!S.next(0, u0)) return;
;       cA = u0.A; cB = u0.B; hA = (unsigned)HALF * u0.lda2; hB = (unsigned)HALF * u0.ldb2; nt = u0.nt;
;       voffA = (unsigned)(sR * u0.lda2 + sC2); voffB = (unsigned)(sRb * u0.ldb2 + sC2); }
;     f32x4 acc[2][2][4][2];
; #pragma unroll
;     for (int a = 0; a < 2; ++a)
; #pragma unroll
;         for (int b = 0; b < 2; ++b)
; #pragma unroll
;             for (int m = 0; m < 4; ++m)
; #pragma unroll
;                 for (int n = 0; n < 2; ++n) acc[a][b][m][n] = (f32x4){0.f, 0.f, 0.f, 0.f};
;     bf16x8 At[4][2], B0[2][2], B1[2][2];
;     PG8_STAGE(PG8_SB(0, 0), cB, voffB, hB / 2); PG8_STAGE(PG8_SB(0, 1), cB + hB, voffB, hB / 2); PG8_STAGE(PG8_SA(0, 0), cA, voffA, hA / 2); PG8_STAGE(PG8_SA(0, 1), cA + hA, voffA, hA / 2);
;     if (wr == 1) PG8_BAR;
.LBB0_381:
.LBB0_382:
	v_writelane_b32 v254, s68, 6
	s_and_b64 vcc, exec, s[6:7]
	s_nop 0
	v_writelane_b32 v254, s69, 7
	v_writelane_b32 v254, s70, 8
	s_nop 1
	v_writelane_b32 v254, s71, 9
	s_cbranch_vccnz .LBB0_422
	s_ashr_i32 s6, s20, 6
	s_lshl_b32 s14, s6, 10
	s_add_i32 s14, s14, 0
	s_ashr_i32 s18, s20, 8
	s_add_i32 s15, s14, 0x10000
	s_mov_b32 m0, s15
	s_add_u32 s16, s40, 0x58000
	global_load_lds_dwordx4 v129, s[40:41]
	s_addc_u32 s17, s41, 0
	s_add_i32 s33, s14, 0x12000
	s_mov_b32 m0, s33
	s_nop 0
	global_load_lds_dwordx4 v129, s[16:17]
	s_add_u32 s16, s40, 0xb0000
	s_addc_u32 s17, s41, 0
	s_add_i32 s34, s14, 0x14000
	s_mov_b32 m0, s34
	s_nop 0
	global_load_lds_dwordx4 v129, s[16:17]
	s_add_u32 s16, s40, 0x108000
	s_addc_u32 s17, s41, 0
	s_add_i32 s35, s14, 0x16000
	s_mov_b32 m0, s35
	s_nop 0
	global_load_lds_dwordx4 v129, s[16:17]
	s_mov_b32 m0, s14
	s_add_u32 s16, s38, 0x58000
	global_load_lds_dwordx4 v128, s[38:39]
	s_addc_u32 s17, s39, 0
	s_add_i32 s36, s14, 0x2000
	s_mov_b32 m0, s36
	s_nop 0
	global_load_lds_dwordx4 v128, s[16:17]
	s_add_u32 s16, s38, 0xb0000
	s_addc_u32 s17, s39, 0
	s_add_i32 s37, s14, 0x4000
	s_mov_b32 m0, s37
	s_nop 0
	global_load_lds_dwordx4 v128, s[16:17]
	s_add_u32 s22, s38, 0x108000
	s_addc_u32 s23, s39, 0
	s_add_i32 s46, s14, 0x6000
	s_mov_b32 m0, s46
	s_nop 0
	global_load_lds_dwordx4 v128, s[22:23]
	s_cmp_eq_u32 s18, 1
	s_mov_b32 s7, 0
	s_cselect_b64 s[16:17], -1, 0
	s_cmp_lg_u32 s18, 1
	s_cbranch_scc1 .LBB0_385
	s_barrier

; #define PG8_STAGE(bufoff, gbase, voff, p64) do { _Pragma("unroll") for (int _i = 0; _i < 2; ++_i) { \
;         const char* _gb = (const char*)(gbase) + (size_t)_i * (p64); const unsigned _la = ldsbase + (unsigned)(bufoff) + (unsigned)_i * 8192u; \
;         asm volatile("s_mov_b32 m0, %0\n\ts_nop 0\n\tglobal_load_lds_dwordx4 %1, %2" :: "s"(_la), "v"(voff), "s"(_gb) : "memory"); } } while (0)
; #define PG8_LDA(dst, b, h) do { _Pragma("unroll") for (int m = 0; m < 4; ++m) _Pragma("unroll") for (int k = 0; k < 2; ++k) dst[m][k] = *(const LAS bf16x8*)(lds + PG8_SA(b, h) + aoff + m * 2048 + k * 1024); } while (0)
; #define PG8_LDB(dst, b, h) do { _Pragma("unroll") for (int n = 0; n < 2; ++n) _Pragma("unroll") for (int k = 0; k < 2; ++k) dst[n][k] = *(const LAS bf16x8*)(lds + PG8_SB(b, h) + boff + n * 2048 + k * 1024); } while (0)
; #define PG8_MMA(ai, bj, At, Bt) do { __builtin_amdgcn_s_setprio(1); _Pragma("unroll") for (int m = 0; m < 4; ++m) _Pragma("unroll") for (int n = 0; n < 2; ++n) _Pragma("unroll") for (int k = 0; k < 2; ++k) \
;         acc[ai][bj][m][n] = __builtin_amdgcn_mfma_f32_16x16x32_bf16(Bt[n][k], At[m][k], acc[ai][bj][m][n], 0, 0, 0); __builtin_amdgcn_s_setprio(0); } while (0)
; #define PG8_BAR __builtin_amdgcn_s_barrier()
; template <class Epi, class Sched>
; __device__ __forceinline__ void gemm_phase(LAS unsigned char* lds, const Sched& S, const Epi& E) {
;     ...
;     f32x4 acc[2][2][4][2];
; #pragma unroll
;     for (int a = 0; a < 2; ++a)
; #pragma unroll
;         for (int b = 0; b < 2; ++b)
; #pragma unroll
;             for (int m = 0; m < 4; ++m)
; #pragma unroll
;                 for (int n = 0; n < 2; ++n) acc[a][b][m][n] = (f32x4){0.f, 0.f, 0.f, 0.f};
;     ...
;         for (int t = 0; t < nt; t += 2) {
;             const bool last = (t == nt - 2);
;             const char* a1 = cA + (size_t)(t + 1) * kstep;
;             const char* a2 = last ? nA : cA + (size_t)(t + 2) * kstep; const char* b2 = last ? nB : cB + (size_t)(t + 2) * kstep;
;             const char* a3 = a2 + kstep; const char* b3 = b2 + kstep;
;             const unsigned vA2 = voffA, vB2 = voffB, hA2 = hA, hB2 = hB;
;             PG8_LDB(B0, 0, 0); PG8_LDB(B1, 0, 1); PG8_SCHED; PG8_LDA(At, 0, 0); PG8_STAGE(PG8_SA(1, 1), a1 + hA, voffA, hA / 2);
;             PG8_WAIT_V(8); PG8_WAIT_L(0); PG8_BAR; PG8_MMA(0, 0, At, B0); PG8_MMA(0, 1, At, B1); PG8_BAR; PG8_SCHED;
.LBB0_397:
	s_and_b64 s[42:43], s[26:27], exec
	s_cselect_b32 s44, s25, s41
	s_cselect_b32 s45, s24, s40
	s_cselect_b32 s66, s23, s39
	s_cselect_b32 s67, s22, s38
	s_add_i32 s68, s21, -2
	s_add_u32 s69, s38, 0x100
	s_addc_u32 s70, s39, 0
	s_add_u32 s71, s40, 0x100
	s_addc_u32 s72, s41, 0
	s_mov_b32 s38, 0
	v_mov_b64_e32 v[0:1], 0
	v_mov_b64_e32 v[2:3], 0
	v_mov_b64_e32 v[4:5], 0
	v_mov_b64_e32 v[6:7], 0
	v_mov_b64_e32 v[8:9], 0
	v_mov_b64_e32 v[10:11], 0
	v_mov_b64_e32 v[12:13], 0
	v_mov_b64_e32 v[14:15], 0
	v_mov_b64_e32 v[16:17], 0
	v_mov_b64_e32 v[18:19], 0
	v_mov_b64_e32 v[20:21], 0
	v_mov_b64_e32 v[22:23], 0
	v_mov_b64_e32 v[24:25], 0
	v_mov_b64_e32 v[26:27], 0
	v_mov_b64_e32 v[28:29], 0
	v_mov_b64_e32 v[30:31], 0
	v_mov_b64_e32 v[64:65], 0
	v_mov_b64_e32 v[66:67], 0
	v_mov_b64_e32 v[68:69], 0
	v_mov_b64_e32 v[70:71], 0
	v_mov_b64_e32 v[72:73], 0
	v_mov_b64_e32 v[74:75], 0
	v_mov_b64_e32 v[76:77], 0
	v_mov_b64_e32 v[78:79], 0
	v_mov_b64_e32 v[80:81], 0
	v_mov_b64_e32 v[82:83], 0
	v_mov_b64_e32 v[84:85], 0
	v_mov_b64_e32 v[86:87], 0
	v_mov_b64_e32 v[88:89], 0
	v_mov_b64_e32 v[90:91], 0
	v_mov_b64_e32 v[92:93], 0
	v_mov_b64_e32 v[94:95], 0
	v_mov_b64_e32 v[32:33], 0
	v_mov_b64_e32 v[34:35], 0
	v_mov_b64_e32 v[36:37], 0
	v_mov_b64_e32 v[38:39], 0
	v_mov_b64_e32 v[40:41], 0
	v_mov_b64_e32 v[42:43], 0
	v_mov_b64_e32 v[44:45], 0
	v_mov_b64_e32 v[46:47], 0
	v_mov_b64_e32 v[48:49], 0
	v_mov_b64_e32 v[50:51], 0
	v_mov_b64_e32 v[52:53], 0
	v_mov_b64_e32 v[54:55], 0
	v_mov_b64_e32 v[56:57], 0
	v_mov_b64_e32 v[58:59], 0
	v_mov_b64_e32 v[60:61], 0
	v_mov_b64_e32 v[62:63], 0
	v_mov_b64_e32 v[96:97], 0
	v_mov_b64_e32 v[98:99], 0
	v_mov_b64_e32 v[100:101], 0
	v_mov_b64_e32 v[102:103], 0
	v_mov_b64_e32 v[104:105], 0
	v_mov_b64_e32 v[106:107], 0
	v_mov_b64_e32 v[108:109], 0
	v_mov_b64_e32 v[110:111], 0
	v_mov_b64_e32 v[112:113], 0
	v_mov_b64_e32 v[114:115], 0
	v_mov_b64_e32 v[116:117], 0
	v_mov_b64_e32 v[118:119], 0
	v_mov_b64_e32 v[120:121], 0
	v_mov_b64_e32 v[122:123], 0
	v_mov_b64_e32 v[124:125], 0
	v_mov_b64_e32 v[126:127], 0
.LBB0_398:
	ds_read_b128 v[130:133], v164
	ds_read_b128 v[134:137], v164 offset:1024
	ds_read_b128 v[138:141], v164 offset:2048
	ds_read_b128 v[142:145], v164 offset:3072
	ds_read_b128 v[146:149], v165
	ds_read_b128 v[150:153], v165 offset:1024
	ds_read_b128 v[154:157], v165 offset:2048
	ds_read_b128 v[158:161], v165 offset:3072
	s_add_i32 s73, s38, 2
	s_cmp_eq_u32 s68, s38
	s_cselect_b32 s38, s67, s69
	s_cselect_b32 s39, s66, s70
	s_cselect_b32 s42, s45, s71
	s_cselect_b32 s43, s44, s72
	s_add_u32 s40, s38, 0x80
	s_addc_u32 s41, s39, 0
	ds_read_b128 v[170:173], v166
	ds_read_b128 v[178:181], v166 offset:1024
	ds_read_b128 v[182:185], v166 offset:2048
	ds_read_b128 v[186:189], v166 offset:3072
	ds_read_b128 v[190:193], v166 offset:4096
	ds_read_b128 v[194:197], v166 offset:5120
	ds_read_b128 v[198:201], v166 offset:6144
	ds_read_b128 v[202:205], v166 offset:7168
	s_add_u32 s74, s69, 0xaff80
	s_mov_b32 m0, s59
	s_addc_u32 s75, s70, 0
	global_load_lds_dwordx4 v128, s[74:75]
	s_add_u32 s74, s69, 0x107f80
	s_mov_b32 m0, s60
	s_addc_u32 s75, s70, 0
	global_load_lds_dwordx4 v128, s[74:75]
	s_waitcnt vmcnt(8)
	s_waitcnt lgkmcnt(0)
	s_barrier
	s_setprio 1
	v_mfma_f32_16x16x32_bf16 v[124:127], v[130:133], v[170:173], v[124:127]
	v_mfma_f32_16x16x32_bf16 v[120:123], v[138:141], v[170:173], v[120:123]
	v_mfma_f32_16x16x32_bf16 v[116:119], v[130:133], v[182:185], v[116:119]
	v_mfma_f32_16x16x32_bf16 v[112:115], v[138:141], v[182:185], v[112:115]
	v_mfma_f32_16x16x32_bf16 v[108:111], v[130:133], v[190:193], v[108:111]
	v_mfma_f32_16x16x32_bf16 v[104:107], v[138:141], v[190:193], v[104:107]
	v_mfma_f32_16x16x32_bf16 v[100:103], v[130:133], v[198:201], v[100:103]
	v_mfma_f32_16x16x32_bf16 v[96:99], v[138:141], v[198:201], v[96:99]
	v_mfma_f32_16x16x32_bf16 v[124:127], v[134:137], v[178:181], v[124:127]
	v_mfma_f32_16x16x32_bf16 v[120:123], v[142:145], v[178:181], v[120:123]
	v_mfma_f32_16x16x32_bf16 v[116:119], v[134:137], v[186:189], v[116:119]
	v_mfma_f32_16x16x32_bf16 v[112:115], v[142:145], v[186:189], v[112:115]
	v_mfma_f32_16x16x32_bf16 v[108:111], v[134:137], v[194:197], v[108:111]
	v_mfma_f32_16x16x32_bf16 v[104:107], v[142:145], v[194:197], v[104:107]
	v_mfma_f32_16x16x32_bf16 v[100:103], v[134:137], v[202:205], v[100:103]
	v_mfma_f32_16x16x32_bf16 v[96:99], v[142:145], v[202:205], v[96:99]
	v_mfma_f32_16x16x32_bf16 v[60:63], v[146:149], v[170:173], v[60:63]
	v_mfma_f32_16x16x32_bf16 v[56:59], v[154:157], v[170:173], v[56:59]
	v_mfma_f32_16x16x32_bf16 v[52:55], v[146:149], v[182:185], v[52:55]
	v_mfma_f32_16x16x32_bf16 v[48:51], v[154:157], v[182:185], v[48:51]
	v_mfma_f32_16x16x32_bf16 v[44:47], v[146:149], v[190:193], v[44:47]
	v_mfma_f32_16x16x32_bf16 v[40:43], v[154:157], v[190:193], v[40:43]
	v_mfma_f32_16x16x32_bf16 v[36:39], v[146:149], v[198:201], v[36:39]
	v_mfma_f32_16x16x32_bf16 v[32:35], v[154:157], v[198:201], v[32:35]
	v_mfma_f32_16x16x32_bf16 v[60:63], v[150:153], v[178:181], v[60:63]
	v_mfma_f32_16x16x32_bf16 v[56:59], v[158:161], v[178:181], v[56:59]
	v_mfma_f32_16x16x32_bf16 v[52:55], v[150:153], v[186:189], v[52:55]
	v_mfma_f32_16x16x32_bf16 v[48:51], v[158:161], v[186:189], v[48:51]
	v_mfma_f32_16x16x32_bf16 v[44:47], v[150:153], v[194:197], v[44:47]
	v_mfma_f32_16x16x32_bf16 v[40:43], v[158:161], v[194:197], v[40:43]
	v_mfma_f32_16x16x32_bf16 v[36:39], v[150:153], v[202:205], v[36:39]
	v_mfma_f32_16x16x32_bf16 v[32:35], v[158:161], v[202:205], v[32:35]
	s_setprio 0
	s_barrier
; #define PG8_STAGE(bufoff, gbase, voff, p64) do { _Pragma("unroll") for (int _i = 0; _i < 2; ++_i) { \
;         const char* _gb = (const char*)(gbase) + (size_t)_i * (p64); const unsigned _la = ldsbase + (unsigned)(bufoff) + (unsigned)_i * 8192u; \
;         asm volatile("s_mov_b32 m0, %0\n\ts_nop 0\n\tglobal_load_lds_dwordx4 %1, %2" :: "s"(_la), "v"(voff), "s"(_gb) : "memory"); } } while (0)
; #define PG8_LDA(dst, b, h) do { _Pragma("unroll") for (int m = 0; m < 4; ++m) _Pragma("unroll") for (int k = 0; k < 2; ++k) dst[m][k] = *(const LAS bf16x8*)(lds + PG8_SA(b, h) + aoff + m * 2048 + k * 1024); } while (0)
; #define PG8_LDB(dst, b, h) do { _Pragma("unroll") for (int n = 0; n < 2; ++n) _Pragma("unroll") for (int k = 0; k < 2; ++k) dst[n][k] = *(const LAS bf16x8*)(lds + PG8_SB(b, h) + boff + n * 2048 + k * 1024); } while (0)
; #define PG8_MMA(ai, bj, At, Bt) do { __builtin_amdgcn_s_setprio(1); _Pragma("unroll") for (int m = 0; m < 4; ++m) _Pragma("unroll") for (int n = 0; n < 2; ++n) _Pragma("unroll") for (int k = 0; k < 2; ++k) \
;         acc[ai][bj][m][n] = __builtin_amdgcn_mfma_f32_16x16x32_bf16(Bt[n][k], At[m][k], acc[ai][bj][m][n], 0, 0, 0); __builtin_amdgcn_s_setprio(0); } while (0)
; #define PG8_WAIT_V(n) asm volatile("s_waitcnt vmcnt(" #n ")" ::: "memory")
; #define PG8_WAIT_L(n) asm volatile("s_waitcnt lgkmcnt(" #n ")" ::: "memory")
; #define PG8_BAR __builtin_amdgcn_s_barrier()
; #define PG8_SCHED __builtin_amdgcn_sched_barrier(0)
; template <class Epi, class Sched>
; __device__ __forceinline__ void gemm_phase(LAS unsigned char* lds, const Sched& S, const Epi& E) {
;     ...
;             PG8_LDA(At, 0, 1); PG8_STAGE(PG8_SB(0, 0), b2, vB2, hB2 / 2); PG8_STAGE(PG8_SB(0, 1), b2 + hB2, vB2, hB2 / 2); PG8_STAGE(PG8_SA(0, 0), a2, vA2, hA2 / 2);
;             PG8_WAIT_V(8); PG8_WAIT_L(0); PG8_BAR; PG8_MMA(1, 0, At, B0); PG8_MMA(1, 1, At, B1); PG8_BAR; PG8_SCHED;
;             PG8_LDB(B0, 1, 0); PG8_LDB(B1, 1, 1); PG8_SCHED; PG8_LDA(At, 1, 0); PG8_STAGE(PG8_SA(0, 1), a2 + hA2, vA2, hA2 / 2);
;             PG8_WAIT_V(8); PG8_WAIT_L(0); PG8_BAR; PG8_MMA(0, 0, At, B0); PG8_MMA(0, 1, At, B1); PG8_BAR; PG8_SCHED;
	s_add_u32 s74, s42, 0x58000
	ds_read_b128 v[170:173], v166 offset:16384
	ds_read_b128 v[178:181], v166 offset:17408
	ds_read_b128 v[182:185], v166 offset:18432
	ds_read_b128 v[186:189], v166 offset:19456
	ds_read_b128 v[190:193], v166 offset:20480
	ds_read_b128 v[194:197], v166 offset:21504
	ds_read_b128 v[198:201], v166 offset:22528
	ds_read_b128 v[202:205], v166 offset:23552
	s_mov_b32 m0, s15
	s_nop 0
	global_load_lds_dwordx4 v129, s[42:43]
	s_mov_b32 m0, s33
	s_addc_u32 s75, s43, 0
	global_load_lds_dwordx4 v129, s[74:75]
	s_add_u32 s74, s42, 0xb0000
	s_mov_b32 m0, s34
	s_addc_u32 s75, s43, 0
	global_load_lds_dwordx4 v129, s[74:75]
	s_add_u32 s74, s42, 0x108000
	s_mov_b32 m0, s35
	s_addc_u32 s75, s43, 0
	global_load_lds_dwordx4 v129, s[74:75]
	s_mov_b32 m0, s14
	s_nop 0
	global_load_lds_dwordx4 v128, s[38:39]
	s_add_u32 s74, s38, 0x58000
	s_mov_b32 m0, s36
	s_addc_u32 s75, s39, 0
	global_load_lds_dwordx4 v128, s[74:75]
	s_waitcnt vmcnt(8)
	s_waitcnt lgkmcnt(0)
	s_barrier
	s_setprio 1
	v_mfma_f32_16x16x32_bf16 v[92:95], v[130:133], v[170:173], v[92:95]
	v_mfma_f32_16x16x32_bf16 v[88:91], v[138:141], v[170:173], v[88:91]
	v_mfma_f32_16x16x32_bf16 v[84:87], v[130:133], v[182:185], v[84:87]
	v_mfma_f32_16x16x32_bf16 v[80:83], v[138:141], v[182:185], v[80:83]
	v_mfma_f32_16x16x32_bf16 v[76:79], v[130:133], v[190:193], v[76:79]
	v_mfma_f32_16x16x32_bf16 v[72:75], v[138:141], v[190:193], v[72:75]
	v_mfma_f32_16x16x32_bf16 v[68:71], v[130:133], v[198:201], v[68:71]
	v_mfma_f32_16x16x32_bf16 v[64:67], v[138:141], v[198:201], v[64:67]
	v_mfma_f32_16x16x32_bf16 v[92:95], v[134:137], v[178:181], v[92:95]
	v_mfma_f32_16x16x32_bf16 v[88:91], v[142:145], v[178:181], v[88:91]
	v_mfma_f32_16x16x32_bf16 v[84:87], v[134:137], v[186:189], v[84:87]
	v_mfma_f32_16x16x32_bf16 v[80:83], v[142:145], v[186:189], v[80:83]
	v_mfma_f32_16x16x32_bf16 v[76:79], v[134:137], v[194:197], v[76:79]
	v_mfma_f32_16x16x32_bf16 v[72:75], v[142:145], v[194:197], v[72:75]
	v_mfma_f32_16x16x32_bf16 v[68:71], v[134:137], v[202:205], v[68:71]
	v_mfma_f32_16x16x32_bf16 v[64:67], v[142:145], v[202:205], v[64:67]
	v_mfma_f32_16x16x32_bf16 v[28:31], v[146:149], v[170:173], v[28:31]
	v_mfma_f32_16x16x32_bf16 v[24:27], v[154:157], v[170:173], v[24:27]
	v_mfma_f32_16x16x32_bf16 v[20:23], v[146:149], v[182:185], v[20:23]
	v_mfma_f32_16x16x32_bf16 v[16:19], v[154:157], v[182:185], v[16:19]
	v_mfma_f32_16x16x32_bf16 v[12:15], v[146:149], v[190:193], v[12:15]
	v_mfma_f32_16x16x32_bf16 v[8:11], v[154:157], v[190:193], v[8:11]
	v_mfma_f32_16x16x32_bf16 v[4:7], v[146:149], v[198:201], v[4:7]
	v_mfma_f32_16x16x32_bf16 v[0:3], v[154:157], v[198:201], v[0:3]
	v_mfma_f32_16x16x32_bf16 v[28:31], v[150:153], v[178:181], v[28:31]
	v_mfma_f32_16x16x32_bf16 v[24:27], v[158:161], v[178:181], v[24:27]
	v_mfma_f32_16x16x32_bf16 v[20:23], v[150:153], v[186:189], v[20:23]
	v_mfma_f32_16x16x32_bf16 v[16:19], v[158:161], v[186:189], v[16:19]
	v_mfma_f32_16x16x32_bf16 v[12:15], v[150:153], v[194:197], v[12:15]
	v_mfma_f32_16x16x32_bf16 v[8:11], v[158:161], v[194:197], v[8:11]
	v_mfma_f32_16x16x32_bf16 v[4:7], v[150:153], v[202:205], v[4:7]
	v_mfma_f32_16x16x32_bf16 v[0:3], v[158:161], v[202:205], v[0:3]
	s_setprio 0
	s_barrier
	ds_read_b128 v[130:133], v167
	ds_read_b128 v[134:137], v167 offset:1024
	ds_read_b128 v[138:141], v167 offset:2048
	ds_read_b128 v[142:145], v167 offset:3072
	ds_read_b128 v[146:149], v168
	ds_read_b128 v[150:153], v168 offset:1024
	ds_read_b128 v[154:157], v168 offset:2048
	ds_read_b128 v[158:161], v168 offset:3072
	ds_read_b128 v[170:173], v166 offset:32768
	ds_read_b128 v[178:181], v166 offset:33792
	ds_read_b128 v[182:185], v166 offset:34816
	ds_read_b128 v[186:189], v166 offset:35840
	ds_read_b128 v[190:193], v166 offset:36864
	ds_read_b128 v[194:197], v166 offset:37888
	ds_read_b128 v[198:201], v166 offset:38912
	ds_read_b128 v[202:205], v166 offset:39936
	s_add_u32 s74, s38, 0xb0000
	s_mov_b32 m0, s37
	s_addc_u32 s75, s39, 0
	global_load_lds_dwordx4 v128, s[74:75]
	s_add_u32 s74, s38, 0x108000
	s_mov_b32 m0, s46
	s_addc_u32 s75, s39, 0
	global_load_lds_dwordx4 v128, s[74:75]
	s_waitcnt vmcnt(8)
	s_waitcnt lgkmcnt(0)
	s_barrier
; #define PG8_STAGE(bufoff, gbase, voff, p64) do { _Pragma("unroll") for (int _i = 0; _i < 2; ++_i) { \
;         const char* _gb = (const char*)(gbase) + (size_t)_i * (p64); const unsigned _la = ldsbase + (unsigned)(bufoff) + (unsigned)_i * 8192u; \
;         asm volatile("s_mov_b32 m0, %0\n\ts_nop 0\n\tglobal_load_lds_dwordx4 %1, %2" :: "s"(_la), "v"(voff), "s"(_gb) : "memory"); } } while (0)
; #define PG8_LDA(dst, b, h) do { _Pragma("unroll") for (int m = 0; m < 4; ++m) _Pragma("unroll") for (int k = 0; k < 2; ++k) dst[m][k] = *(const LAS bf16x8*)(lds + PG8_SA(b, h) + aoff + m * 2048 + k * 1024); } while (0)
; #define PG8_MMA(ai, bj, At, Bt) do { __builtin_amdgcn_s_setprio(1); _Pragma("unroll") for (int m = 0; m < 4; ++m) _Pragma("unroll") for (int n = 0; n < 2; ++n) _Pragma("unroll") for (int k = 0; k < 2; ++k) \
;         acc[ai][bj][m][n] = __builtin_amdgcn_mfma_f32_16x16x32_bf16(Bt[n][k], At[m][k], acc[ai][bj][m][n], 0, 0, 0); __builtin_amdgcn_s_setprio(0); } while (0)
; #define PG8_WAIT_V(n) asm volatile("s_waitcnt vmcnt(" #n ")" ::: "memory")
; #define PG8_WAIT_L(n) asm volatile("s_waitcnt lgkmcnt(" #n ")" ::: "memory")
; #define PG8_BAR __builtin_amdgcn_s_barrier()
; #define PG8_SCHED __builtin_amdgcn_sched_barrier(0)
; template <class Epi, class Sched>
; __device__ __forceinline__ void gemm_phase(LAS unsigned char* lds, const Sched& S, const Epi& E) {
;     ...
;             PG8_WAIT_V(8); PG8_WAIT_L(0); PG8_BAR; PG8_MMA(0, 0, At, B0); PG8_MMA(0, 1, At, B1); PG8_BAR; PG8_SCHED;
;             PG8_LDA(At, 1, 1); PG8_STAGE(PG8_SB(1, 0), b3, vB2, hB2 / 2); PG8_STAGE(PG8_SB(1, 1), b3 + hB2, vB2, hB2 / 2); PG8_STAGE(PG8_SA(1, 0), a3, vA2, hA2 / 2);
;             PG8_WAIT_V(8); PG8_WAIT_L(0); PG8_BAR; PG8_MMA(1, 0, At, B0); PG8_MMA(1, 1, At, B1); PG8_BAR; PG8_SCHED;
;         }
;         if (wr == 0) PG8_BAR;
	s_setprio 1
	v_mfma_f32_16x16x32_bf16 v[124:127], v[130:133], v[170:173], v[124:127]
	v_mfma_f32_16x16x32_bf16 v[120:123], v[138:141], v[170:173], v[120:123]
	v_mfma_f32_16x16x32_bf16 v[116:119], v[130:133], v[182:185], v[116:119]
	v_mfma_f32_16x16x32_bf16 v[112:115], v[138:141], v[182:185], v[112:115]
	v_mfma_f32_16x16x32_bf16 v[108:111], v[130:133], v[190:193], v[108:111]
	v_mfma_f32_16x16x32_bf16 v[104:107], v[138:141], v[190:193], v[104:107]
	v_mfma_f32_16x16x32_bf16 v[100:103], v[130:133], v[198:201], v[100:103]
	v_mfma_f32_16x16x32_bf16 v[96:99], v[138:141], v[198:201], v[96:99]
	v_mfma_f32_16x16x32_bf16 v[124:127], v[134:137], v[178:181], v[124:127]
	v_mfma_f32_16x16x32_bf16 v[120:123], v[142:145], v[178:181], v[120:123]
	v_mfma_f32_16x16x32_bf16 v[116:119], v[134:137], v[186:189], v[116:119]
	v_mfma_f32_16x16x32_bf16 v[112:115], v[142:145], v[186:189], v[112:115]
	v_mfma_f32_16x16x32_bf16 v[108:111], v[134:137], v[194:197], v[108:111]
	v_mfma_f32_16x16x32_bf16 v[104:107], v[142:145], v[194:197], v[104:107]
	v_mfma_f32_16x16x32_bf16 v[100:103], v[134:137], v[202:205], v[100:103]
	v_mfma_f32_16x16x32_bf16 v[96:99], v[142:145], v[202:205], v[96:99]
	v_mfma_f32_16x16x32_bf16 v[60:63], v[146:149], v[170:173], v[60:63]
	v_mfma_f32_16x16x32_bf16 v[56:59], v[154:157], v[170:173], v[56:59]
	v_mfma_f32_16x16x32_bf16 v[52:55], v[146:149], v[182:185], v[52:55]
	v_mfma_f32_16x16x32_bf16 v[48:51], v[154:157], v[182:185], v[48:51]
	v_mfma_f32_16x16x32_bf16 v[44:47], v[146:149], v[190:193], v[44:47]
	v_mfma_f32_16x16x32_bf16 v[40:43], v[154:157], v[190:193], v[40:43]
	v_mfma_f32_16x16x32_bf16 v[36:39], v[146:149], v[198:201], v[36:39]
	v_mfma_f32_16x16x32_bf16 v[32:35], v[154:157], v[198:201], v[32:35]
	v_mfma_f32_16x16x32_bf16 v[60:63], v[150:153], v[178:181], v[60:63]
	v_mfma_f32_16x16x32_bf16 v[56:59], v[158:161], v[178:181], v[56:59]
	v_mfma_f32_16x16x32_bf16 v[52:55], v[150:153], v[186:189], v[52:55]
	v_mfma_f32_16x16x32_bf16 v[48:51], v[158:161], v[186:189], v[48:51]
	v_mfma_f32_16x16x32_bf16 v[44:47], v[150:153], v[194:197], v[44:47]
	v_mfma_f32_16x16x32_bf16 v[40:43], v[158:161], v[194:197], v[40:43]
	v_mfma_f32_16x16x32_bf16 v[36:39], v[150:153], v[202:205], v[36:39]
	v_mfma_f32_16x16x32_bf16 v[32:35], v[158:161], v[202:205], v[32:35]
	s_setprio 0
	s_barrier
	s_add_u32 s74, s42, 0x80
	s_addc_u32 s75, s43, 0
	ds_read_b128 v[170:173], v166 offset:49152
	ds_read_b128 v[178:181], v166 offset:50176
	ds_read_b128 v[182:185], v166 offset:51200
	ds_read_b128 v[186:189], v166 offset:52224
	ds_read_b128 v[190:193], v166 offset:53248
	ds_read_b128 v[194:197], v166 offset:54272
	ds_read_b128 v[198:201], v166 offset:55296
	ds_read_b128 v[202:205], v166 offset:56320
	s_mov_b32 m0, s53
	s_nop 0
	global_load_lds_dwordx4 v129, s[74:75]
	s_add_u32 s74, s42, 0x58080
	s_mov_b32 m0, s54
	s_addc_u32 s75, s43, 0
	global_load_lds_dwordx4 v129, s[74:75]
	s_add_u32 s74, s42, 0xb0080
	s_mov_b32 m0, s57
	s_addc_u32 s75, s43, 0
	global_load_lds_dwordx4 v129, s[74:75]
	s_add_u32 s42, s42, 0x108080
	s_mov_b32 m0, s58
	s_addc_u32 s43, s43, 0
	global_load_lds_dwordx4 v129, s[42:43]
	s_mov_b32 m0, s55
	s_nop 0
	global_load_lds_dwordx4 v128, s[40:41]
	s_add_u32 s38, s38, 0x58080
	s_mov_b32 m0, s56
	s_addc_u32 s39, s39, 0
	global_load_lds_dwordx4 v128, s[38:39]
	s_waitcnt vmcnt(8)
	s_waitcnt lgkmcnt(0)
	s_barrier
	s_setprio 1
	v_mfma_f32_16x16x32_bf16 v[92:95], v[130:133], v[170:173], v[92:95]
	v_mfma_f32_16x16x32_bf16 v[88:91], v[138:141], v[170:173], v[88:91]
	v_mfma_f32_16x16x32_bf16 v[84:87], v[130:133], v[182:185], v[84:87]
	v_mfma_f32_16x16x32_bf16 v[80:83], v[138:141], v[182:185], v[80:83]
	v_mfma_f32_16x16x32_bf16 v[76:79], v[130:133], v[190:193], v[76:79]
	v_mfma_f32_16x16x32_bf16 v[72:75], v[138:141], v[190:193], v[72:75]
	v_mfma_f32_16x16x32_bf16 v[68:71], v[130:133], v[198:201], v[68:71]
	v_mfma_f32_16x16x32_bf16 v[64:67], v[138:141], v[198:201], v[64:67]
	v_mfma_f32_16x16x32_bf16 v[92:95], v[134:137], v[178:181], v[92:95]
	v_mfma_f32_16x16x32_bf16 v[88:91], v[142:145], v[178:181], v[88:91]
	v_mfma_f32_16x16x32_bf16 v[84:87], v[134:137], v[186:189], v[84:87]
	v_mfma_f32_16x16x32_bf16 v[80:83], v[142:145], v[186:189], v[80:83]
	v_mfma_f32_16x16x32_bf16 v[76:79], v[134:137], v[194:197], v[76:79]
	v_mfma_f32_16x16x32_bf16 v[72:75], v[142:145], v[194:197], v[72:75]
	v_mfma_f32_16x16x32_bf16 v[68:71], v[134:137], v[202:205], v[68:71]
	v_mfma_f32_16x16x32_bf16 v[64:67], v[142:145], v[202:205], v[64:67]
	v_mfma_f32_16x16x32_bf16 v[28:31], v[146:149], v[170:173], v[28:31]
	v_mfma_f32_16x16x32_bf16 v[24:27], v[154:157], v[170:173], v[24:27]
	v_mfma_f32_16x16x32_bf16 v[20:23], v[146:149], v[182:185], v[20:23]
	v_mfma_f32_16x16x32_bf16 v[16:19], v[154:157], v[182:185], v[16:19]
	v_mfma_f32_16x16x32_bf16 v[12:15], v[146:149], v[190:193], v[12:15]
	v_mfma_f32_16x16x32_bf16 v[8:11], v[154:157], v[190:193], v[8:11]
	v_mfma_f32_16x16x32_bf16 v[4:7], v[146:149], v[198:201], v[4:7]
	v_mfma_f32_16x16x32_bf16 v[0:3], v[154:157], v[198:201], v[0:3]
	v_mfma_f32_16x16x32_bf16 v[28:31], v[150:153], v[178:181], v[28:31]
	v_mfma_f32_16x16x32_bf16 v[24:27], v[158:161], v[178:181], v[24:27]
	v_mfma_f32_16x16x32_bf16 v[20:23], v[150:153], v[186:189], v[20:23]
	v_mfma_f32_16x16x32_bf16 v[16:19], v[158:161], v[186:189], v[16:19]
	v_mfma_f32_16x16x32_bf16 v[12:15], v[150:153], v[194:197], v[12:15]
	v_mfma_f32_16x16x32_bf16 v[8:11], v[158:161], v[194:197], v[8:11]
	v_mfma_f32_16x16x32_bf16 v[4:7], v[150:153], v[202:205], v[4:7]
	v_mfma_f32_16x16x32_bf16 v[0:3], v[158:161], v[202:205], v[0:3]
	s_setprio 0
	s_barrier
	s_add_u32 s69, s69, 0x100
	s_addc_u32 s70, s70, 0
	s_add_u32 s71, s71, 0x100
	s_addc_u32 s72, s72, 0
	s_cmp_ge_i32 s73, s21
	s_mov_b32 s38, s73
	s_cbranch_scc0 .LBB0_398
	s_and_b64 vcc, exec, s[18:19]
	s_cbranch_vccz .LBB0_401
	s_barrier

; #define PG8_STAGE(bufoff, gbase, voff, p64) do { _Pragma("unroll") for (int _i = 0; _i < 2; ++_i) { \
;         const char* _gb = (const char*)(gbase) + (size_t)_i * (p64); const unsigned _la = ldsbase + (unsigned)(bufoff) + (unsigned)_i * 8192u; \
;         asm volatile("s_mov_b32 m0, %0\n\ts_nop 0\n\tglobal_load_lds_dwordx4 %1, %2" :: "s"(_la), "v"(voff), "s"(_gb) : "memory"); } } while (0)
; #define PG8_LDA(dst, b, h) do { _Pragma("unroll") for (int m = 0; m < 4; ++m) _Pragma("unroll") for (int k = 0; k < 2; ++k) dst[m][k] = *(const LAS bf16x8*)(lds + PG8_SA(b, h) + aoff + m * 2048 + k * 1024); } while (0)
; #define PG8_LDB(dst, b, h) do { _Pragma("unroll") for (int n = 0; n < 2; ++n) _Pragma("unroll") for (int k = 0; k < 2; ++k) dst[n][k] = *(const LAS bf16x8*)(lds + PG8_SB(b, h) + boff + n * 2048 + k * 1024); } while (0)
; #define PG8_MMA(ai, bj, At, Bt) do { __builtin_amdgcn_s_setprio(1); _Pragma("unroll") for (int m = 0; m < 4; ++m) _Pragma("unroll") for (int n = 0; n < 2; ++n) _Pragma("unroll") for (int k = 0; k < 2; ++k) \
;         acc[ai][bj][m][n] = __builtin_amdgcn_mfma_f32_16x16x32_bf16(Bt[n][k], At[m][k], acc[ai][bj][m][n], 0, 0, 0); __builtin_amdgcn_s_setprio(0); } while (0)
; #define PG8_BAR __builtin_amdgcn_s_barrier()
; template <class Epi, class Sched>
; __device__ __forceinline__ void gemm_phase(LAS unsigned char* lds, const Sched& S, const Epi& E) {
;     ...
;     f32x4 acc[2][2][4][2];
; #pragma unroll
;     for (int a = 0; a < 2; ++a)
; #pragma unroll
;         for (int b = 0; b < 2; ++b)
; #pragma unroll
;             for (int m = 0; m < 4; ++m)
; #pragma unroll
;                 for (int n = 0; n < 2; ++n) acc[a][b][m][n] = (f32x4){0.f, 0.f, 0.f, 0.f};
;     ...
;         for (int t = 0; t < nt; t += 2) {
;             const bool last = (t == nt - 2);
;             const char* a1 = cA + (size_t)(t + 1) * kstep;
;             const char* a2 = last ? nA : cA + (size_t)(t + 2) * kstep; const char* b2 = last ? nB : cB + (size_t)(t + 2) * kstep;
;             const char* a3 = a2 + kstep; const char* b3 = b2 + kstep;
;             const unsigned vA2 = voffA, vB2 = voffB, hA2 = hA, hB2 = hB;
;             PG8_LDB(B0, 0, 0); PG8_LDB(B1, 0, 1); PG8_SCHED; PG8_LDA(At, 0, 0); PG8_STAGE(PG8_SA(1, 1), a1 + hA, voffA, hA / 2);
;             PG8_WAIT_V(8); PG8_WAIT_L(0); PG8_BAR; PG8_MMA(0, 0, At, B0); PG8_MMA(0, 1, At, B1); PG8_BAR; PG8_SCHED;
.LBB0_552:
	s_add_u32 s74, s22, 0x40080
	s_addc_u32 s75, s23, 0
	s_add_u32 s57, s16, 0x100
	s_addc_u32 s80, s17, 0
	s_mov_b32 s81, -2
	v_mov_b64_e32 v[0:1], 0
	v_mov_b64_e32 v[2:3], 0
	v_mov_b64_e32 v[4:5], 0
	v_mov_b64_e32 v[6:7], 0
	s_waitcnt vmcnt(2)
	v_mov_b64_e32 v[12:13], 0
	v_mov_b64_e32 v[14:15], 0
	s_waitcnt vmcnt(0)
	v_mov_b64_e32 v[20:21], 0
	v_mov_b64_e32 v[22:23], 0
	v_mov_b64_e32 v[28:29], 0
	v_mov_b64_e32 v[30:31], 0
	v_mov_b64_e32 v[36:37], 0
	v_mov_b64_e32 v[38:39], 0
	v_mov_b64_e32 v[44:45], 0
	v_mov_b64_e32 v[46:47], 0
	v_mov_b64_e32 v[52:53], 0
	v_mov_b64_e32 v[54:55], 0
	v_mov_b64_e32 v[8:9], 0
	v_mov_b64_e32 v[10:11], 0
	v_mov_b64_e32 v[16:17], 0
	v_mov_b64_e32 v[18:19], 0
	v_mov_b64_e32 v[24:25], 0
	v_mov_b64_e32 v[26:27], 0
	v_mov_b64_e32 v[32:33], 0
	v_mov_b64_e32 v[34:35], 0
	v_mov_b64_e32 v[40:41], 0
	v_mov_b64_e32 v[42:43], 0
	v_mov_b64_e32 v[48:49], 0
	v_mov_b64_e32 v[50:51], 0
	v_mov_b64_e32 v[56:57], 0
	v_mov_b64_e32 v[58:59], 0
	v_mov_b64_e32 v[60:61], 0
	v_mov_b64_e32 v[62:63], 0
	v_mov_b64_e32 v[64:65], 0
	v_mov_b64_e32 v[66:67], 0
	v_mov_b64_e32 v[68:69], 0
	v_mov_b64_e32 v[70:71], 0
	v_mov_b64_e32 v[76:77], 0
	v_mov_b64_e32 v[78:79], 0
	v_mov_b64_e32 v[84:85], 0
	v_mov_b64_e32 v[86:87], 0
	v_mov_b64_e32 v[92:93], 0
	v_mov_b64_e32 v[94:95], 0
	v_mov_b64_e32 v[100:101], 0
	v_mov_b64_e32 v[102:103], 0
	v_mov_b64_e32 v[108:109], 0
	v_mov_b64_e32 v[110:111], 0
	v_mov_b64_e32 v[116:117], 0
	v_mov_b64_e32 v[118:119], 0
	v_mov_b64_e32 v[72:73], 0
	v_mov_b64_e32 v[74:75], 0
	v_mov_b64_e32 v[80:81], 0
	v_mov_b64_e32 v[82:83], 0
	v_mov_b64_e32 v[88:89], 0
	v_mov_b64_e32 v[90:91], 0
	v_mov_b64_e32 v[96:97], 0
	v_mov_b64_e32 v[98:99], 0
	v_mov_b64_e32 v[104:105], 0
	v_mov_b64_e32 v[106:107], 0
	v_mov_b64_e32 v[112:113], 0
	v_mov_b64_e32 v[114:115], 0
	v_mov_b64_e32 v[120:121], 0
	v_mov_b64_e32 v[122:123], 0
	v_mov_b64_e32 v[124:125], 0
	v_mov_b64_e32 v[126:127], 0
.LBB0_553:
	v_add_u32_e32 v128, 0x10000, v154
	ds_read_b128 v[138:141], v128
	ds_read_b128 v[142:145], v128 offset:1024
	ds_read_b128 v[146:149], v128 offset:2048
	ds_read_b128 v[172:175], v128 offset:3072
	v_add_u32_e32 v128, 0x14000, v154
	ds_read_b128 v[178:181], v128
	ds_read_b128 v[182:185], v128 offset:1024
	ds_read_b128 v[186:189], v128 offset:2048
	ds_read_b128 v[190:193], v128 offset:3072
	s_add_u32 s16, s74, 0xfffc0080
	s_addc_u32 s17, s75, -1
	s_cmp_eq_u32 s81, 12
	s_cselect_b32 s16, s58, s16
	s_cselect_b32 s17, s59, s17
	s_cselect_b32 s76, s62, s57
	s_cselect_b32 s77, s63, s80
	s_add_u32 s22, s16, 0x80
	s_addc_u32 s23, s17, 0
	ds_read_b128 v[194:197], v155
	ds_read_b128 v[198:201], v155 offset:1024
	ds_read_b128 v[202:205], v155 offset:2048
	ds_read_b128 v[206:209], v155 offset:3072
	ds_read_b128 v[210:213], v155 offset:4096
	ds_read_b128 v[214:217], v155 offset:5120
	ds_read_b128 v[218:221], v155 offset:6144
	ds_read_b128 v[222:225], v155 offset:7168
	s_mov_b32 m0, s67
	s_nop 0
	global_load_lds_dwordx4 v150, s[74:75]
	s_add_u32 s82, s74, 0x20000
	s_mov_b32 m0, s69
	s_addc_u32 s83, s75, 0
	global_load_lds_dwordx4 v150, s[82:83]
	s_waitcnt vmcnt(8)
	s_waitcnt lgkmcnt(0)
	s_barrier
	s_setprio 1
	v_mfma_f32_16x16x32_bf16 v[124:127], v[138:141], v[194:197], v[124:127]
	v_mfma_f32_16x16x32_bf16 v[120:123], v[146:149], v[194:197], v[120:123]
	v_mfma_f32_16x16x32_bf16 v[112:115], v[138:141], v[202:205], v[112:115]
	v_mfma_f32_16x16x32_bf16 v[104:107], v[146:149], v[202:205], v[104:107]
	v_mfma_f32_16x16x32_bf16 v[96:99], v[138:141], v[210:213], v[96:99]
	v_mfma_f32_16x16x32_bf16 v[88:91], v[146:149], v[210:213], v[88:91]
	v_mfma_f32_16x16x32_bf16 v[80:83], v[138:141], v[218:221], v[80:83]
	v_mfma_f32_16x16x32_bf16 v[72:75], v[146:149], v[218:221], v[72:75]
	v_mfma_f32_16x16x32_bf16 v[124:127], v[142:145], v[198:201], v[124:127]
	v_mfma_f32_16x16x32_bf16 v[120:123], v[172:175], v[198:201], v[120:123]
	v_mfma_f32_16x16x32_bf16 v[112:115], v[142:145], v[206:209], v[112:115]
	v_mfma_f32_16x16x32_bf16 v[104:107], v[172:175], v[206:209], v[104:107]
	v_mfma_f32_16x16x32_bf16 v[96:99], v[142:145], v[214:217], v[96:99]
	v_mfma_f32_16x16x32_bf16 v[88:91], v[172:175], v[214:217], v[88:91]
	v_mfma_f32_16x16x32_bf16 v[80:83], v[142:145], v[222:225], v[80:83]
	v_mfma_f32_16x16x32_bf16 v[72:75], v[172:175], v[222:225], v[72:75]
	v_mfma_f32_16x16x32_bf16 v[116:119], v[178:181], v[194:197], v[116:119]
	v_mfma_f32_16x16x32_bf16 v[108:111], v[186:189], v[194:197], v[108:111]
	v_mfma_f32_16x16x32_bf16 v[100:103], v[178:181], v[202:205], v[100:103]
	v_mfma_f32_16x16x32_bf16 v[92:95], v[186:189], v[202:205], v[92:95]
	v_mfma_f32_16x16x32_bf16 v[84:87], v[178:181], v[210:213], v[84:87]
	v_mfma_f32_16x16x32_bf16 v[76:79], v[186:189], v[210:213], v[76:79]
	v_mfma_f32_16x16x32_bf16 v[68:71], v[178:181], v[218:221], v[68:71]
	v_mfma_f32_16x16x32_bf16 v[64:67], v[186:189], v[218:221], v[64:67]
	v_mfma_f32_16x16x32_bf16 v[116:119], v[182:185], v[198:201], v[116:119]
	v_mfma_f32_16x16x32_bf16 v[108:111], v[190:193], v[198:201], v[108:111]
	v_mfma_f32_16x16x32_bf16 v[100:103], v[182:185], v[206:209], v[100:103]
	v_mfma_f32_16x16x32_bf16 v[92:95], v[190:193], v[206:209], v[92:95]
	v_mfma_f32_16x16x32_bf16 v[84:87], v[182:185], v[214:217], v[84:87]
	v_mfma_f32_16x16x32_bf16 v[76:79], v[190:193], v[214:217], v[76:79]
	v_mfma_f32_16x16x32_bf16 v[68:71], v[182:185], v[222:225], v[68:71]
	v_mfma_f32_16x16x32_bf16 v[64:67], v[190:193], v[222:225], v[64:67]
	s_setprio 0
	s_barrier
; #define PG8_STAGE(bufoff, gbase, voff, p64) do { _Pragma("unroll") for (int _i = 0; _i < 2; ++_i) { \
;         const char* _gb = (const char*)(gbase) + (size_t)_i * (p64); const unsigned _la = ldsbase + (unsigned)(bufoff) + (unsigned)_i * 8192u; \
;         asm volatile("s_mov_b32 m0, %0\n\ts_nop 0\n\tglobal_load_lds_dwordx4 %1, %2" :: "s"(_la), "v"(voff), "s"(_gb) : "memory"); } } while (0)
; #define PG8_LDA(dst, b, h) do { _Pragma("unroll") for (int m = 0; m < 4; ++m) _Pragma("unroll") for (int k = 0; k < 2; ++k) dst[m][k] = *(const LAS bf16x8*)(lds + PG8_SA(b, h) + aoff + m * 2048 + k * 1024); } while (0)
; #define PG8_LDB(dst, b, h) do { _Pragma("unroll") for (int n = 0; n < 2; ++n) _Pragma("unroll") for (int k = 0; k < 2; ++k) dst[n][k] = *(const LAS bf16x8*)(lds + PG8_SB(b, h) + boff + n * 2048 + k * 1024); } while (0)
; #define PG8_MMA(ai, bj, At, Bt) do { __builtin_amdgcn_s_setprio(1); _Pragma("unroll") for (int m = 0; m < 4; ++m) _Pragma("unroll") for (int n = 0; n < 2; ++n) _Pragma("unroll") for (int k = 0; k < 2; ++k) \
;         acc[ai][bj][m][n] = __builtin_amdgcn_mfma_f32_16x16x32_bf16(Bt[n][k], At[m][k], acc[ai][bj][m][n], 0, 0, 0); __builtin_amdgcn_s_setprio(0); } while (0)
; #define PG8_WAIT_V(n) asm volatile("s_waitcnt vmcnt(" #n ")" ::: "memory")
; #define PG8_WAIT_L(n) asm volatile("s_waitcnt lgkmcnt(" #n ")" ::: "memory")
; #define PG8_BAR __builtin_amdgcn_s_barrier()
; #define PG8_SCHED __builtin_amdgcn_sched_barrier(0)
; template <class Epi, class Sched>
; __device__ __forceinline__ void gemm_phase(LAS unsigned char* lds, const Sched& S, const Epi& E) {
;     ...
;             PG8_LDA(At, 0, 1); PG8_STAGE(PG8_SB(0, 0), b2, vB2, hB2 / 2); PG8_STAGE(PG8_SB(0, 1), b2 + hB2, vB2, hB2 / 2); PG8_STAGE(PG8_SA(0, 0), a2, vA2, hA2 / 2);
;             PG8_WAIT_V(8); PG8_WAIT_L(0); PG8_BAR; PG8_MMA(1, 0, At, B0); PG8_MMA(1, 1, At, B1); PG8_BAR; PG8_SCHED;
;             PG8_LDB(B0, 1, 0); PG8_LDB(B1, 1, 1); PG8_SCHED; PG8_LDA(At, 1, 0); PG8_STAGE(PG8_SA(0, 1), a2 + hA2, vA2, hA2 / 2);
;             PG8_WAIT_V(8); PG8_WAIT_L(0); PG8_BAR; PG8_MMA(0, 0, At, B0); PG8_MMA(0, 1, At, B1); PG8_BAR; PG8_SCHED;
	s_add_u32 s82, s76, 0x20000
	ds_read_b128 v[194:197], v155 offset:16384
	ds_read_b128 v[198:201], v155 offset:17408
	ds_read_b128 v[202:205], v155 offset:18432
	ds_read_b128 v[206:209], v155 offset:19456
	ds_read_b128 v[210:213], v155 offset:20480
	ds_read_b128 v[214:217], v155 offset:21504
	ds_read_b128 v[218:221], v155 offset:22528
	ds_read_b128 v[222:225], v155 offset:23552
	s_mov_b32 m0, s24
	s_nop 0
	global_load_lds_dwordx4 v151, s[76:77]
	s_mov_b32 m0, s33
	s_addc_u32 s83, s77, 0
	global_load_lds_dwordx4 v151, s[82:83]
	s_add_u32 s82, s76, 0x40000
	s_mov_b32 m0, s34
	s_addc_u32 s83, s77, 0
	global_load_lds_dwordx4 v151, s[82:83]
	s_add_u32 s82, s76, 0x60000
	s_mov_b32 m0, s35
	s_addc_u32 s83, s77, 0
	global_load_lds_dwordx4 v151, s[82:83]
	s_mov_b32 m0, s15
	s_nop 0
	global_load_lds_dwordx4 v150, s[16:17]
	s_add_u32 s82, s16, 0x20000
	s_mov_b32 m0, s36
	s_addc_u32 s83, s17, 0
	global_load_lds_dwordx4 v150, s[82:83]
	s_waitcnt vmcnt(8)
	s_waitcnt lgkmcnt(0)
	s_barrier
	s_setprio 1
	v_mfma_f32_16x16x32_bf16 v[60:63], v[138:141], v[194:197], v[60:63]
	v_mfma_f32_16x16x32_bf16 v[56:59], v[146:149], v[194:197], v[56:59]
	v_mfma_f32_16x16x32_bf16 v[48:51], v[138:141], v[202:205], v[48:51]
	v_mfma_f32_16x16x32_bf16 v[40:43], v[146:149], v[202:205], v[40:43]
	v_mfma_f32_16x16x32_bf16 v[32:35], v[138:141], v[210:213], v[32:35]
	v_mfma_f32_16x16x32_bf16 v[24:27], v[146:149], v[210:213], v[24:27]
	v_mfma_f32_16x16x32_bf16 v[16:19], v[138:141], v[218:221], v[16:19]
	v_mfma_f32_16x16x32_bf16 v[8:11], v[146:149], v[218:221], v[8:11]
	v_mfma_f32_16x16x32_bf16 v[60:63], v[142:145], v[198:201], v[60:63]
	v_mfma_f32_16x16x32_bf16 v[56:59], v[172:175], v[198:201], v[56:59]
	v_mfma_f32_16x16x32_bf16 v[48:51], v[142:145], v[206:209], v[48:51]
	v_mfma_f32_16x16x32_bf16 v[40:43], v[172:175], v[206:209], v[40:43]
	v_mfma_f32_16x16x32_bf16 v[32:35], v[142:145], v[214:217], v[32:35]
	v_mfma_f32_16x16x32_bf16 v[24:27], v[172:175], v[214:217], v[24:27]
	v_mfma_f32_16x16x32_bf16 v[16:19], v[142:145], v[222:225], v[16:19]
	v_mfma_f32_16x16x32_bf16 v[8:11], v[172:175], v[222:225], v[8:11]
	v_mfma_f32_16x16x32_bf16 v[52:55], v[178:181], v[194:197], v[52:55]
	v_mfma_f32_16x16x32_bf16 v[44:47], v[186:189], v[194:197], v[44:47]
	v_mfma_f32_16x16x32_bf16 v[36:39], v[178:181], v[202:205], v[36:39]
	v_mfma_f32_16x16x32_bf16 v[28:31], v[186:189], v[202:205], v[28:31]
	v_mfma_f32_16x16x32_bf16 v[20:23], v[178:181], v[210:213], v[20:23]
	v_mfma_f32_16x16x32_bf16 v[12:15], v[186:189], v[210:213], v[12:15]
	v_mfma_f32_16x16x32_bf16 v[4:7], v[178:181], v[218:221], v[4:7]
	v_mfma_f32_16x16x32_bf16 v[0:3], v[186:189], v[218:221], v[0:3]
	v_mfma_f32_16x16x32_bf16 v[52:55], v[182:185], v[198:201], v[52:55]
	v_mfma_f32_16x16x32_bf16 v[44:47], v[190:193], v[198:201], v[44:47]
	v_mfma_f32_16x16x32_bf16 v[36:39], v[182:185], v[206:209], v[36:39]
	v_mfma_f32_16x16x32_bf16 v[28:31], v[190:193], v[206:209], v[28:31]
	v_mfma_f32_16x16x32_bf16 v[20:23], v[182:185], v[214:217], v[20:23]
	v_mfma_f32_16x16x32_bf16 v[12:15], v[190:193], v[214:217], v[12:15]
	v_mfma_f32_16x16x32_bf16 v[4:7], v[182:185], v[222:225], v[4:7]
	v_mfma_f32_16x16x32_bf16 v[0:3], v[190:193], v[222:225], v[0:3]
	s_setprio 0
	s_barrier
	v_add_u32_e32 v128, 0x18000, v154
	ds_read_b128 v[138:141], v128
	ds_read_b128 v[142:145], v128 offset:1024
	ds_read_b128 v[146:149], v128 offset:2048
	ds_read_b128 v[172:175], v128 offset:3072
	v_add_u32_e32 v128, 0x1c000, v154
	ds_read_b128 v[178:181], v128
	ds_read_b128 v[182:185], v128 offset:1024
	ds_read_b128 v[186:189], v128 offset:2048
	ds_read_b128 v[190:193], v128 offset:3072
	ds_read_b128 v[194:197], v155 offset:32768
	ds_read_b128 v[198:201], v155 offset:33792
	ds_read_b128 v[202:205], v155 offset:34816
	ds_read_b128 v[206:209], v155 offset:35840
	ds_read_b128 v[210:213], v155 offset:36864
	ds_read_b128 v[214:217], v155 offset:37888
	ds_read_b128 v[218:221], v155 offset:38912
	ds_read_b128 v[222:225], v155 offset:39936
	s_add_u32 s82, s16, 0x40000
	s_mov_b32 m0, s37
	s_addc_u32 s83, s17, 0
	global_load_lds_dwordx4 v150, s[82:83]
	s_add_u32 s82, s16, 0x60000
	s_mov_b32 m0, s42
	s_addc_u32 s83, s17, 0
	global_load_lds_dwordx4 v150, s[82:83]
	s_waitcnt vmcnt(8)
	s_waitcnt lgkmcnt(0)
	s_barrier
; #define PG8_STAGE(bufoff, gbase, voff, p64) do { _Pragma("unroll") for (int _i = 0; _i < 2; ++_i) { \
;         const char* _gb = (const char*)(gbase) + (size_t)_i * (p64); const unsigned _la = ldsbase + (unsigned)(bufoff) + (unsigned)_i * 8192u; \
;         asm volatile("s_mov_b32 m0, %0\n\ts_nop 0\n\tglobal_load_lds_dwordx4 %1, %2" :: "s"(_la), "v"(voff), "s"(_gb) : "memory"); } } while (0)
; #define PG8_LDA(dst, b, h) do { _Pragma("unroll") for (int m = 0; m < 4; ++m) _Pragma("unroll") for (int k = 0; k < 2; ++k) dst[m][k] = *(const LAS bf16x8*)(lds + PG8_SA(b, h) + aoff + m * 2048 + k * 1024); } while (0)
; #define PG8_MMA(ai, bj, At, Bt) do { __builtin_amdgcn_s_setprio(1); _Pragma("unroll") for (int m = 0; m < 4; ++m) _Pragma("unroll") for (int n = 0; n < 2; ++n) _Pragma("unroll") for (int k = 0; k < 2; ++k) \
;         acc[ai][bj][m][n] = __builtin_amdgcn_mfma_f32_16x16x32_bf16(Bt[n][k], At[m][k], acc[ai][bj][m][n], 0, 0, 0); __builtin_amdgcn_s_setprio(0); } while (0)
; #define PG8_WAIT_V(n) asm volatile("s_waitcnt vmcnt(" #n ")" ::: "memory")
; #define PG8_WAIT_L(n) asm volatile("s_waitcnt lgkmcnt(" #n ")" ::: "memory")
; #define PG8_BAR __builtin_amdgcn_s_barrier()
; #define PG8_SCHED __builtin_amdgcn_sched_barrier(0)
; template <class Epi, class Sched>
; __device__ __forceinline__ void gemm_phase(LAS unsigned char* lds, const Sched& S, const Epi& E) {
;     ...
;             PG8_WAIT_V(8); PG8_WAIT_L(0); PG8_BAR; PG8_MMA(0, 0, At, B0); PG8_MMA(0, 1, At, B1); PG8_BAR; PG8_SCHED;
;             PG8_LDA(At, 1, 1); PG8_STAGE(PG8_SB(1, 0), b3, vB2, hB2 / 2); PG8_STAGE(PG8_SB(1, 1), b3 + hB2, vB2, hB2 / 2); PG8_STAGE(PG8_SA(1, 0), a3, vA2, hA2 / 2);
;             PG8_WAIT_V(8); PG8_WAIT_L(0); PG8_BAR; PG8_MMA(1, 0, At, B0); PG8_MMA(1, 1, At, B1); PG8_BAR; PG8_SCHED;
;         }
;         if (wr == 0) PG8_BAR;
	s_setprio 1
	v_mfma_f32_16x16x32_bf16 v[124:127], v[138:141], v[194:197], v[124:127]
	v_mfma_f32_16x16x32_bf16 v[120:123], v[146:149], v[194:197], v[120:123]
	v_mfma_f32_16x16x32_bf16 v[112:115], v[138:141], v[202:205], v[112:115]
	v_mfma_f32_16x16x32_bf16 v[104:107], v[146:149], v[202:205], v[104:107]
	v_mfma_f32_16x16x32_bf16 v[96:99], v[138:141], v[210:213], v[96:99]
	v_mfma_f32_16x16x32_bf16 v[88:91], v[146:149], v[210:213], v[88:91]
	v_mfma_f32_16x16x32_bf16 v[80:83], v[138:141], v[218:221], v[80:83]
	v_mfma_f32_16x16x32_bf16 v[72:75], v[146:149], v[218:221], v[72:75]
	v_mfma_f32_16x16x32_bf16 v[124:127], v[142:145], v[198:201], v[124:127]
	v_mfma_f32_16x16x32_bf16 v[120:123], v[172:175], v[198:201], v[120:123]
	v_mfma_f32_16x16x32_bf16 v[112:115], v[142:145], v[206:209], v[112:115]
	v_mfma_f32_16x16x32_bf16 v[104:107], v[172:175], v[206:209], v[104:107]
	v_mfma_f32_16x16x32_bf16 v[96:99], v[142:145], v[214:217], v[96:99]
	v_mfma_f32_16x16x32_bf16 v[88:91], v[172:175], v[214:217], v[88:91]
	v_mfma_f32_16x16x32_bf16 v[80:83], v[142:145], v[222:225], v[80:83]
	v_mfma_f32_16x16x32_bf16 v[72:75], v[172:175], v[222:225], v[72:75]
	v_mfma_f32_16x16x32_bf16 v[116:119], v[178:181], v[194:197], v[116:119]
	v_mfma_f32_16x16x32_bf16 v[108:111], v[186:189], v[194:197], v[108:111]
	v_mfma_f32_16x16x32_bf16 v[100:103], v[178:181], v[202:205], v[100:103]
	v_mfma_f32_16x16x32_bf16 v[92:95], v[186:189], v[202:205], v[92:95]
	v_mfma_f32_16x16x32_bf16 v[84:87], v[178:181], v[210:213], v[84:87]
	v_mfma_f32_16x16x32_bf16 v[76:79], v[186:189], v[210:213], v[76:79]
	v_mfma_f32_16x16x32_bf16 v[68:71], v[178:181], v[218:221], v[68:71]
	v_mfma_f32_16x16x32_bf16 v[64:67], v[186:189], v[218:221], v[64:67]
	v_mfma_f32_16x16x32_bf16 v[116:119], v[182:185], v[198:201], v[116:119]
	v_mfma_f32_16x16x32_bf16 v[108:111], v[190:193], v[198:201], v[108:111]
	v_mfma_f32_16x16x32_bf16 v[100:103], v[182:185], v[206:209], v[100:103]
	v_mfma_f32_16x16x32_bf16 v[92:95], v[190:193], v[206:209], v[92:95]
	v_mfma_f32_16x16x32_bf16 v[84:87], v[182:185], v[214:217], v[84:87]
	v_mfma_f32_16x16x32_bf16 v[76:79], v[190:193], v[214:217], v[76:79]
	v_mfma_f32_16x16x32_bf16 v[68:71], v[182:185], v[222:225], v[68:71]
	v_mfma_f32_16x16x32_bf16 v[64:67], v[190:193], v[222:225], v[64:67]
	s_setprio 0
	s_barrier
	s_add_u32 s82, s76, 0x80
	s_addc_u32 s83, s77, 0
	ds_read_b128 v[194:197], v155 offset:49152
	ds_read_b128 v[198:201], v155 offset:50176
	ds_read_b128 v[202:205], v155 offset:51200
	ds_read_b128 v[206:209], v155 offset:52224
	ds_read_b128 v[210:213], v155 offset:53248
	ds_read_b128 v[214:217], v155 offset:54272
	ds_read_b128 v[218:221], v155 offset:55296
	ds_read_b128 v[222:225], v155 offset:56320
	s_mov_b32 m0, s50
	s_nop 0
	global_load_lds_dwordx4 v151, s[82:83]
	s_add_u32 s82, s76, 0x20080
	s_mov_b32 m0, s51
	s_addc_u32 s83, s77, 0
	global_load_lds_dwordx4 v151, s[82:83]
	s_add_u32 s82, s76, 0x40080
	s_mov_b32 m0, s65
	s_addc_u32 s83, s77, 0
	global_load_lds_dwordx4 v151, s[82:83]
	s_add_u32 s76, s76, 0x60080
	s_mov_b32 m0, s66
	s_addc_u32 s77, s77, 0
	global_load_lds_dwordx4 v151, s[76:77]
	s_mov_b32 m0, s61
	s_nop 0
	global_load_lds_dwordx4 v150, s[22:23]
	s_add_u32 s16, s16, 0x20080
	s_mov_b32 m0, s64
	s_addc_u32 s17, s17, 0
	global_load_lds_dwordx4 v150, s[16:17]
	s_waitcnt vmcnt(8)
	s_waitcnt lgkmcnt(0)
	s_barrier
	s_setprio 1
	v_mfma_f32_16x16x32_bf16 v[60:63], v[138:141], v[194:197], v[60:63]
	v_mfma_f32_16x16x32_bf16 v[56:59], v[146:149], v[194:197], v[56:59]
	v_mfma_f32_16x16x32_bf16 v[48:51], v[138:141], v[202:205], v[48:51]
	v_mfma_f32_16x16x32_bf16 v[40:43], v[146:149], v[202:205], v[40:43]
	v_mfma_f32_16x16x32_bf16 v[32:35], v[138:141], v[210:213], v[32:35]
	v_mfma_f32_16x16x32_bf16 v[24:27], v[146:149], v[210:213], v[24:27]
	v_mfma_f32_16x16x32_bf16 v[16:19], v[138:141], v[218:221], v[16:19]
	v_mfma_f32_16x16x32_bf16 v[8:11], v[146:149], v[218:221], v[8:11]
	v_mfma_f32_16x16x32_bf16 v[60:63], v[142:145], v[198:201], v[60:63]
	v_mfma_f32_16x16x32_bf16 v[56:59], v[172:175], v[198:201], v[56:59]
	v_mfma_f32_16x16x32_bf16 v[48:51], v[142:145], v[206:209], v[48:51]
	v_mfma_f32_16x16x32_bf16 v[40:43], v[172:175], v[206:209], v[40:43]
	v_mfma_f32_16x16x32_bf16 v[32:35], v[142:145], v[214:217], v[32:35]
	v_mfma_f32_16x16x32_bf16 v[24:27], v[172:175], v[214:217], v[24:27]
	v_mfma_f32_16x16x32_bf16 v[16:19], v[142:145], v[222:225], v[16:19]
	v_mfma_f32_16x16x32_bf16 v[8:11], v[172:175], v[222:225], v[8:11]
	v_mfma_f32_16x16x32_bf16 v[52:55], v[178:181], v[194:197], v[52:55]
	v_mfma_f32_16x16x32_bf16 v[44:47], v[186:189], v[194:197], v[44:47]
	v_mfma_f32_16x16x32_bf16 v[36:39], v[178:181], v[202:205], v[36:39]
	v_mfma_f32_16x16x32_bf16 v[28:31], v[186:189], v[202:205], v[28:31]
	v_mfma_f32_16x16x32_bf16 v[20:23], v[178:181], v[210:213], v[20:23]
	v_mfma_f32_16x16x32_bf16 v[12:15], v[186:189], v[210:213], v[12:15]
	v_mfma_f32_16x16x32_bf16 v[4:7], v[178:181], v[218:221], v[4:7]
	v_mfma_f32_16x16x32_bf16 v[0:3], v[186:189], v[218:221], v[0:3]
	v_mfma_f32_16x16x32_bf16 v[52:55], v[182:185], v[198:201], v[52:55]
	v_mfma_f32_16x16x32_bf16 v[44:47], v[190:193], v[198:201], v[44:47]
	v_mfma_f32_16x16x32_bf16 v[36:39], v[182:185], v[206:209], v[36:39]
	v_mfma_f32_16x16x32_bf16 v[28:31], v[190:193], v[206:209], v[28:31]
	v_mfma_f32_16x16x32_bf16 v[20:23], v[182:185], v[214:217], v[20:23]
	v_mfma_f32_16x16x32_bf16 v[12:15], v[190:193], v[214:217], v[12:15]
	v_mfma_f32_16x16x32_bf16 v[4:7], v[182:185], v[222:225], v[4:7]
	v_mfma_f32_16x16x32_bf16 v[0:3], v[190:193], v[222:225], v[0:3]
	s_setprio 0
	s_barrier
	s_add_i32 s81, s81, 2
	s_add_u32 s74, s74, 0x100
	s_addc_u32 s75, s75, 0
	s_add_u32 s57, s57, 0x100
	s_addc_u32 s80, s80, 0
	s_cmp_gt_u32 s81, 13
	s_cbranch_scc0 .LBB0_553
	s_and_b64 vcc, exec, s[6:7]
	s_cbranch_vccz .LBB0_556
	s_barrier

; #define PG8_STAGE(bufoff, gbase, voff, p64) do { _Pragma("unroll") for (int _i = 0; _i < 2; ++_i) { \
;         const char* _gb = (const char*)(gbase) + (size_t)_i * (p64); const unsigned _la = ldsbase + (unsigned)(bufoff) + (unsigned)_i * 8192u; \
;         asm volatile("s_mov_b32 m0, %0\n\ts_nop 0\n\tglobal_load_lds_dwordx4 %1, %2" :: "s"(_la), "v"(voff), "s"(_gb) : "memory"); } } while (0)
; #define PG8_LDA(dst, b, h) do { _Pragma("unroll") for (int m = 0; m < 4; ++m) _Pragma("unroll") for (int k = 0; k < 2; ++k) dst[m][k] = *(const LAS bf16x8*)(lds + PG8_SA(b, h) + aoff + m * 2048 + k * 1024); } while (0)
; #define PG8_LDB(dst, b, h) do { _Pragma("unroll") for (int n = 0; n < 2; ++n) _Pragma("unroll") for (int k = 0; k < 2; ++k) dst[n][k] = *(const LAS bf16x8*)(lds + PG8_SB(b, h) + boff + n * 2048 + k * 1024); } while (0)
; #define PG8_MMA(ai, bj, At, Bt) do { __builtin_amdgcn_s_setprio(1); _Pragma("unroll") for (int m = 0; m < 4; ++m) _Pragma("unroll") for (int n = 0; n < 2; ++n) _Pragma("unroll") for (int k = 0; k < 2; ++k) \
;         acc[ai][bj][m][n] = __builtin_amdgcn_mfma_f32_16x16x32_bf16(Bt[n][k], At[m][k], acc[ai][bj][m][n], 0, 0, 0); __builtin_amdgcn_s_setprio(0); } while (0)
; #define PG8_BAR __builtin_amdgcn_s_barrier()
; template <class Epi, class Sched>
; __device__ __forceinline__ void gemm_phase(LAS unsigned char* lds, const Sched& S, const Epi& E) {
;     ...
;     f32x4 acc[2][2][4][2];
; #pragma unroll
;     for (int a = 0; a < 2; ++a)
; #pragma unroll
;         for (int b = 0; b < 2; ++b)
; #pragma unroll
;             for (int m = 0; m < 4; ++m)
; #pragma unroll
;                 for (int n = 0; n < 2; ++n) acc[a][b][m][n] = (f32x4){0.f, 0.f, 0.f, 0.f};
;     ...
;         for (int t = 0; t < nt; t += 2) {
;             const bool last = (t == nt - 2);
;             const char* a1 = cA + (size_t)(t + 1) * kstep;
;             const char* a2 = last ? nA : cA + (size_t)(t + 2) * kstep; const char* b2 = last ? nB : cB + (size_t)(t + 2) * kstep;
;             const char* a3 = a2 + kstep; const char* b3 = b2 + kstep;
;             const unsigned vA2 = voffA, vB2 = voffB, hA2 = hA, hB2 = hB;
;             PG8_LDB(B0, 0, 0); PG8_LDB(B1, 0, 1); PG8_SCHED; PG8_LDA(At, 0, 0); PG8_STAGE(PG8_SA(1, 1), a1 + hA, voffA, hA / 2);
;             PG8_WAIT_V(8); PG8_WAIT_L(0); PG8_BAR; PG8_MMA(0, 0, At, B0); PG8_MMA(0, 1, At, B1); PG8_BAR; PG8_SCHED;
.LBB0_581:
	s_add_u32 s62, s16, 0x40080
	s_addc_u32 s63, s17, 0
	s_add_u32 s55, s22, 0x100
	s_addc_u32 s74, s23, 0
	s_mov_b32 s75, -2
	v_mov_b64_e32 v[0:1], 0
	v_mov_b64_e32 v[2:3], 0
	v_mov_b64_e32 v[4:5], 0
	v_mov_b64_e32 v[6:7], 0
	v_mov_b64_e32 v[8:9], 0
	v_mov_b64_e32 v[10:11], 0
	s_waitcnt vmcnt(1)
	v_mov_b64_e32 v[16:17], 0
	v_mov_b64_e32 v[18:19], 0
	v_mov_b64_e32 v[24:25], 0
	v_mov_b64_e32 v[26:27], 0
	v_mov_b64_e32 v[32:33], 0
	v_mov_b64_e32 v[34:35], 0
	v_mov_b64_e32 v[40:41], 0
	v_mov_b64_e32 v[42:43], 0
	v_mov_b64_e32 v[48:49], 0
	v_mov_b64_e32 v[50:51], 0
	v_mov_b64_e32 v[12:13], 0
	v_mov_b64_e32 v[14:15], 0
	s_waitcnt vmcnt(0)
	v_mov_b64_e32 v[20:21], 0
	v_mov_b64_e32 v[22:23], 0
	v_mov_b64_e32 v[28:29], 0
	v_mov_b64_e32 v[30:31], 0
	v_mov_b64_e32 v[36:37], 0
	v_mov_b64_e32 v[38:39], 0
	v_mov_b64_e32 v[44:45], 0
	v_mov_b64_e32 v[46:47], 0
	v_mov_b64_e32 v[52:53], 0
	v_mov_b64_e32 v[54:55], 0
	v_mov_b64_e32 v[56:57], 0
	v_mov_b64_e32 v[58:59], 0
	v_mov_b64_e32 v[60:61], 0
	v_mov_b64_e32 v[62:63], 0
	v_mov_b64_e32 v[64:65], 0
	v_mov_b64_e32 v[66:67], 0
	v_mov_b64_e32 v[68:69], 0
	v_mov_b64_e32 v[70:71], 0
	v_mov_b64_e32 v[72:73], 0
	v_mov_b64_e32 v[74:75], 0
	v_mov_b64_e32 v[80:81], 0
	v_mov_b64_e32 v[82:83], 0
	v_mov_b64_e32 v[88:89], 0
	v_mov_b64_e32 v[90:91], 0
	v_mov_b64_e32 v[96:97], 0
	v_mov_b64_e32 v[98:99], 0
	v_mov_b64_e32 v[104:105], 0
	v_mov_b64_e32 v[106:107], 0
	v_mov_b64_e32 v[112:113], 0
	v_mov_b64_e32 v[114:115], 0
	v_mov_b64_e32 v[76:77], 0
	v_mov_b64_e32 v[78:79], 0
	v_mov_b64_e32 v[84:85], 0
	v_mov_b64_e32 v[86:87], 0
	v_mov_b64_e32 v[92:93], 0
	v_mov_b64_e32 v[94:95], 0
	v_mov_b64_e32 v[100:101], 0
	v_mov_b64_e32 v[102:103], 0
	v_mov_b64_e32 v[108:109], 0
	v_mov_b64_e32 v[110:111], 0
	v_mov_b64_e32 v[116:117], 0
	v_mov_b64_e32 v[118:119], 0
	v_mov_b64_e32 v[120:121], 0
	v_mov_b64_e32 v[122:123], 0
	v_mov_b64_e32 v[124:125], 0
	v_mov_b64_e32 v[126:127], 0
.LBB0_582:
	v_add_u32_e32 v130, 0x10000, v153
	ds_read_b128 v[138:141], v130
	ds_read_b128 v[142:145], v130 offset:1024
	ds_read_b128 v[146:149], v130 offset:2048
	ds_read_b128 v[172:175], v130 offset:3072
	v_add_u32_e32 v130, 0x14000, v153
	ds_read_b128 v[178:181], v130
	ds_read_b128 v[182:185], v130 offset:1024
	ds_read_b128 v[186:189], v130 offset:2048
	ds_read_b128 v[190:193], v130 offset:3072
	s_add_u32 s16, s62, 0xfffc0080
	s_addc_u32 s17, s63, -1
	s_cmp_eq_u32 s75, 12
	s_cselect_b32 s16, s56, s16
	s_cselect_b32 s17, s57, s17
	s_cselect_b32 s72, s58, s55
	s_cselect_b32 s73, s59, s74
	s_add_u32 s22, s16, 0x80
	s_addc_u32 s23, s17, 0
	ds_read_b128 v[194:197], v154
	ds_read_b128 v[198:201], v154 offset:1024
	ds_read_b128 v[202:205], v154 offset:2048
	ds_read_b128 v[206:209], v154 offset:3072
	ds_read_b128 v[210:213], v154 offset:4096
	ds_read_b128 v[214:217], v154 offset:5120
	ds_read_b128 v[218:221], v154 offset:6144
	ds_read_b128 v[222:225], v154 offset:7168
	s_mov_b32 m0, s78
	s_nop 0
	global_load_lds_dwordx4 v128, s[62:63]
	s_add_u32 s82, s62, 0x20000
	s_mov_b32 m0, s80
	s_addc_u32 s83, s63, 0
	global_load_lds_dwordx4 v128, s[82:83]
	s_waitcnt vmcnt(8)
	s_waitcnt lgkmcnt(0)
	s_barrier
	s_setprio 1
	v_mfma_f32_16x16x32_bf16 v[124:127], v[138:141], v[194:197], v[124:127]
	v_mfma_f32_16x16x32_bf16 v[120:123], v[146:149], v[194:197], v[120:123]
	v_mfma_f32_16x16x32_bf16 v[116:119], v[138:141], v[202:205], v[116:119]
	v_mfma_f32_16x16x32_bf16 v[108:111], v[146:149], v[202:205], v[108:111]
	v_mfma_f32_16x16x32_bf16 v[100:103], v[138:141], v[210:213], v[100:103]
	v_mfma_f32_16x16x32_bf16 v[92:95], v[146:149], v[210:213], v[92:95]
	v_mfma_f32_16x16x32_bf16 v[84:87], v[138:141], v[218:221], v[84:87]
	v_mfma_f32_16x16x32_bf16 v[76:79], v[146:149], v[218:221], v[76:79]
	v_mfma_f32_16x16x32_bf16 v[124:127], v[142:145], v[198:201], v[124:127]
	v_mfma_f32_16x16x32_bf16 v[120:123], v[172:175], v[198:201], v[120:123]
	v_mfma_f32_16x16x32_bf16 v[116:119], v[142:145], v[206:209], v[116:119]
	v_mfma_f32_16x16x32_bf16 v[108:111], v[172:175], v[206:209], v[108:111]
	v_mfma_f32_16x16x32_bf16 v[100:103], v[142:145], v[214:217], v[100:103]
	v_mfma_f32_16x16x32_bf16 v[92:95], v[172:175], v[214:217], v[92:95]
	v_mfma_f32_16x16x32_bf16 v[84:87], v[142:145], v[222:225], v[84:87]
	v_mfma_f32_16x16x32_bf16 v[76:79], v[172:175], v[222:225], v[76:79]
	v_mfma_f32_16x16x32_bf16 v[112:115], v[178:181], v[194:197], v[112:115]
	v_mfma_f32_16x16x32_bf16 v[104:107], v[186:189], v[194:197], v[104:107]
	v_mfma_f32_16x16x32_bf16 v[96:99], v[178:181], v[202:205], v[96:99]
	v_mfma_f32_16x16x32_bf16 v[88:91], v[186:189], v[202:205], v[88:91]
	v_mfma_f32_16x16x32_bf16 v[80:83], v[178:181], v[210:213], v[80:83]
	v_mfma_f32_16x16x32_bf16 v[72:75], v[186:189], v[210:213], v[72:75]
	v_mfma_f32_16x16x32_bf16 v[68:71], v[178:181], v[218:221], v[68:71]
	v_mfma_f32_16x16x32_bf16 v[64:67], v[186:189], v[218:221], v[64:67]
	v_mfma_f32_16x16x32_bf16 v[112:115], v[182:185], v[198:201], v[112:115]
	v_mfma_f32_16x16x32_bf16 v[104:107], v[190:193], v[198:201], v[104:107]
	v_mfma_f32_16x16x32_bf16 v[96:99], v[182:185], v[206:209], v[96:99]
	v_mfma_f32_16x16x32_bf16 v[88:91], v[190:193], v[206:209], v[88:91]
	v_mfma_f32_16x16x32_bf16 v[80:83], v[182:185], v[214:217], v[80:83]
	v_mfma_f32_16x16x32_bf16 v[72:75], v[190:193], v[214:217], v[72:75]
	v_mfma_f32_16x16x32_bf16 v[68:71], v[182:185], v[222:225], v[68:71]
	v_mfma_f32_16x16x32_bf16 v[64:67], v[190:193], v[222:225], v[64:67]
	s_setprio 0
	s_barrier
; #define PG8_STAGE(bufoff, gbase, voff, p64) do { _Pragma("unroll") for (int _i = 0; _i < 2; ++_i) { \
;         const char* _gb = (const char*)(gbase) + (size_t)_i * (p64); const unsigned _la = ldsbase + (unsigned)(bufoff) + (unsigned)_i * 8192u; \
;         asm volatile("s_mov_b32 m0, %0\n\ts_nop 0\n\tglobal_load_lds_dwordx4 %1, %2" :: "s"(_la), "v"(voff), "s"(_gb) : "memory"); } } while (0)
; #define PG8_LDA(dst, b, h) do { _Pragma("unroll") for (int m = 0; m < 4; ++m) _Pragma("unroll") for (int k = 0; k < 2; ++k) dst[m][k] = *(const LAS bf16x8*)(lds + PG8_SA(b, h) + aoff + m * 2048 + k * 1024); } while (0)
; #define PG8_LDB(dst, b, h) do { _Pragma("unroll") for (int n = 0; n < 2; ++n) _Pragma("unroll") for (int k = 0; k < 2; ++k) dst[n][k] = *(const LAS bf16x8*)(lds + PG8_SB(b, h) + boff + n * 2048 + k * 1024); } while (0)
; #define PG8_MMA(ai, bj, At, Bt) do { __builtin_amdgcn_s_setprio(1); _Pragma("unroll") for (int m = 0; m < 4; ++m) _Pragma("unroll") for (int n = 0; n < 2; ++n) _Pragma("unroll") for (int k = 0; k < 2; ++k) \
;         acc[ai][bj][m][n] = __builtin_amdgcn_mfma_f32_16x16x32_bf16(Bt[n][k], At[m][k], acc[ai][bj][m][n], 0, 0, 0); __builtin_amdgcn_s_setprio(0); } while (0)
; #define PG8_WAIT_V(n) asm volatile("s_waitcnt vmcnt(" #n ")" ::: "memory")
; #define PG8_WAIT_L(n) asm volatile("s_waitcnt lgkmcnt(" #n ")" ::: "memory")
; #define PG8_BAR __builtin_amdgcn_s_barrier()
; #define PG8_SCHED __builtin_amdgcn_sched_barrier(0)
; template <class Epi, class Sched>
; __device__ __forceinline__ void gemm_phase(LAS unsigned char* lds, const Sched& S, const Epi& E) {
;     ...
;             PG8_LDA(At, 0, 1); PG8_STAGE(PG8_SB(0, 0), b2, vB2, hB2 / 2); PG8_STAGE(PG8_SB(0, 1), b2 + hB2, vB2, hB2 / 2); PG8_STAGE(PG8_SA(0, 0), a2, vA2, hA2 / 2);
;             PG8_WAIT_V(8); PG8_WAIT_L(0); PG8_BAR; PG8_MMA(1, 0, At, B0); PG8_MMA(1, 1, At, B1); PG8_BAR; PG8_SCHED;
;             PG8_LDB(B0, 1, 0); PG8_LDB(B1, 1, 1); PG8_SCHED; PG8_LDA(At, 1, 0); PG8_STAGE(PG8_SA(0, 1), a2 + hA2, vA2, hA2 / 2);
;             PG8_WAIT_V(8); PG8_WAIT_L(0); PG8_BAR; PG8_MMA(0, 0, At, B0); PG8_MMA(0, 1, At, B1); PG8_BAR; PG8_SCHED;
	s_add_u32 s82, s72, 0x20000
	ds_read_b128 v[194:197], v154 offset:16384
	ds_read_b128 v[198:201], v154 offset:17408
	ds_read_b128 v[202:205], v154 offset:18432
	ds_read_b128 v[206:209], v154 offset:19456
	ds_read_b128 v[210:213], v154 offset:20480
	ds_read_b128 v[214:217], v154 offset:21504
	ds_read_b128 v[218:221], v154 offset:22528
	ds_read_b128 v[222:225], v154 offset:23552
	s_mov_b32 m0, s20
	s_nop 0
	global_load_lds_dwordx4 v150, s[72:73]
	s_mov_b32 m0, s24
	s_addc_u32 s83, s73, 0
	global_load_lds_dwordx4 v150, s[82:83]
	s_add_u32 s82, s72, 0x40000
	s_mov_b32 m0, s33
	s_addc_u32 s83, s73, 0
	global_load_lds_dwordx4 v150, s[82:83]
	s_add_u32 s82, s72, 0x60000
	s_mov_b32 m0, s34
	s_addc_u32 s83, s73, 0
	global_load_lds_dwordx4 v150, s[82:83]
	s_mov_b32 m0, s15
	s_nop 0
	global_load_lds_dwordx4 v128, s[16:17]
	s_add_u32 s82, s16, 0x20000
	s_mov_b32 m0, s35
	s_addc_u32 s83, s17, 0
	global_load_lds_dwordx4 v128, s[82:83]
	s_waitcnt vmcnt(8)
	s_waitcnt lgkmcnt(0)
	s_barrier
	s_setprio 1
	v_mfma_f32_16x16x32_bf16 v[60:63], v[138:141], v[194:197], v[60:63]
	v_mfma_f32_16x16x32_bf16 v[56:59], v[146:149], v[194:197], v[56:59]
	v_mfma_f32_16x16x32_bf16 v[52:55], v[138:141], v[202:205], v[52:55]
	v_mfma_f32_16x16x32_bf16 v[44:47], v[146:149], v[202:205], v[44:47]
	v_mfma_f32_16x16x32_bf16 v[36:39], v[138:141], v[210:213], v[36:39]
	v_mfma_f32_16x16x32_bf16 v[28:31], v[146:149], v[210:213], v[28:31]
	v_mfma_f32_16x16x32_bf16 v[20:23], v[138:141], v[218:221], v[20:23]
	v_mfma_f32_16x16x32_bf16 v[12:15], v[146:149], v[218:221], v[12:15]
	v_mfma_f32_16x16x32_bf16 v[60:63], v[142:145], v[198:201], v[60:63]
	v_mfma_f32_16x16x32_bf16 v[56:59], v[172:175], v[198:201], v[56:59]
	v_mfma_f32_16x16x32_bf16 v[52:55], v[142:145], v[206:209], v[52:55]
	v_mfma_f32_16x16x32_bf16 v[44:47], v[172:175], v[206:209], v[44:47]
	v_mfma_f32_16x16x32_bf16 v[36:39], v[142:145], v[214:217], v[36:39]
	v_mfma_f32_16x16x32_bf16 v[28:31], v[172:175], v[214:217], v[28:31]
	v_mfma_f32_16x16x32_bf16 v[20:23], v[142:145], v[222:225], v[20:23]
	v_mfma_f32_16x16x32_bf16 v[12:15], v[172:175], v[222:225], v[12:15]
	v_mfma_f32_16x16x32_bf16 v[48:51], v[178:181], v[194:197], v[48:51]
	v_mfma_f32_16x16x32_bf16 v[40:43], v[186:189], v[194:197], v[40:43]
	v_mfma_f32_16x16x32_bf16 v[32:35], v[178:181], v[202:205], v[32:35]
	v_mfma_f32_16x16x32_bf16 v[24:27], v[186:189], v[202:205], v[24:27]
	v_mfma_f32_16x16x32_bf16 v[16:19], v[178:181], v[210:213], v[16:19]
	v_mfma_f32_16x16x32_bf16 v[8:11], v[186:189], v[210:213], v[8:11]
	v_mfma_f32_16x16x32_bf16 v[4:7], v[178:181], v[218:221], v[4:7]
	v_mfma_f32_16x16x32_bf16 v[0:3], v[186:189], v[218:221], v[0:3]
	v_mfma_f32_16x16x32_bf16 v[48:51], v[182:185], v[198:201], v[48:51]
	v_mfma_f32_16x16x32_bf16 v[40:43], v[190:193], v[198:201], v[40:43]
	v_mfma_f32_16x16x32_bf16 v[32:35], v[182:185], v[206:209], v[32:35]
	v_mfma_f32_16x16x32_bf16 v[24:27], v[190:193], v[206:209], v[24:27]
	v_mfma_f32_16x16x32_bf16 v[16:19], v[182:185], v[214:217], v[16:19]
	v_mfma_f32_16x16x32_bf16 v[8:11], v[190:193], v[214:217], v[8:11]
	v_mfma_f32_16x16x32_bf16 v[4:7], v[182:185], v[222:225], v[4:7]
	v_mfma_f32_16x16x32_bf16 v[0:3], v[190:193], v[222:225], v[0:3]
	s_setprio 0
	s_barrier
	v_add_u32_e32 v130, 0x18000, v153
	ds_read_b128 v[138:141], v130
	ds_read_b128 v[142:145], v130 offset:1024
	ds_read_b128 v[146:149], v130 offset:2048
	ds_read_b128 v[172:175], v130 offset:3072
	v_add_u32_e32 v130, 0x1c000, v153
	ds_read_b128 v[178:181], v130
	ds_read_b128 v[182:185], v130 offset:1024
	ds_read_b128 v[186:189], v130 offset:2048
	ds_read_b128 v[190:193], v130 offset:3072
	ds_read_b128 v[194:197], v154 offset:32768
	ds_read_b128 v[198:201], v154 offset:33792
	ds_read_b128 v[202:205], v154 offset:34816
	ds_read_b128 v[206:209], v154 offset:35840
	ds_read_b128 v[210:213], v154 offset:36864
	ds_read_b128 v[214:217], v154 offset:37888
	ds_read_b128 v[218:221], v154 offset:38912
	ds_read_b128 v[222:225], v154 offset:39936
	s_add_u32 s82, s16, 0x40000
	s_mov_b32 m0, s36
	s_addc_u32 s83, s17, 0
	global_load_lds_dwordx4 v128, s[82:83]
	s_add_u32 s82, s16, 0x60000
	s_mov_b32 m0, s37
	s_addc_u32 s83, s17, 0
	global_load_lds_dwordx4 v128, s[82:83]
	s_waitcnt vmcnt(8)
	s_waitcnt lgkmcnt(0)
	s_barrier
; #define PG8_STAGE(bufoff, gbase, voff, p64) do { _Pragma("unroll") for (int _i = 0; _i < 2; ++_i) { \
;         const char* _gb = (const char*)(gbase) + (size_t)_i * (p64); const unsigned _la = ldsbase + (unsigned)(bufoff) + (unsigned)_i * 8192u; \
;         asm volatile("s_mov_b32 m0, %0\n\ts_nop 0\n\tglobal_load_lds_dwordx4 %1, %2" :: "s"(_la), "v"(voff), "s"(_gb) : "memory"); } } while (0)
; #define PG8_LDA(dst, b, h) do { _Pragma("unroll") for (int m = 0; m < 4; ++m) _Pragma("unroll") for (int k = 0; k < 2; ++k) dst[m][k] = *(const LAS bf16x8*)(lds + PG8_SA(b, h) + aoff + m * 2048 + k * 1024); } while (0)
; #define PG8_MMA(ai, bj, At, Bt) do { __builtin_amdgcn_s_setprio(1); _Pragma("unroll") for (int m = 0; m < 4; ++m) _Pragma("unroll") for (int n = 0; n < 2; ++n) _Pragma("unroll") for (int k = 0; k < 2; ++k) \
;         acc[ai][bj][m][n] = __builtin_amdgcn_mfma_f32_16x16x32_bf16(Bt[n][k], At[m][k], acc[ai][bj][m][n], 0, 0, 0); __builtin_amdgcn_s_setprio(0); } while (0)
; #define PG8_WAIT_V(n) asm volatile("s_waitcnt vmcnt(" #n ")" ::: "memory")
; #define PG8_WAIT_L(n) asm volatile("s_waitcnt lgkmcnt(" #n ")" ::: "memory")
; #define PG8_BAR __builtin_amdgcn_s_barrier()
; #define PG8_SCHED __builtin_amdgcn_sched_barrier(0)
; template <class Epi, class Sched>
; __device__ __forceinline__ void gemm_phase(LAS unsigned char* lds, const Sched& S, const Epi& E) {
;     ...
;             PG8_WAIT_V(8); PG8_WAIT_L(0); PG8_BAR; PG8_MMA(0, 0, At, B0); PG8_MMA(0, 1, At, B1); PG8_BAR; PG8_SCHED;
;             PG8_LDA(At, 1, 1); PG8_STAGE(PG8_SB(1, 0), b3, vB2, hB2 / 2); PG8_STAGE(PG8_SB(1, 1), b3 + hB2, vB2, hB2 / 2); PG8_STAGE(PG8_SA(1, 0), a3, vA2, hA2 / 2);
;             PG8_WAIT_V(8); PG8_WAIT_L(0); PG8_BAR; PG8_MMA(1, 0, At, B0); PG8_MMA(1, 1, At, B1); PG8_BAR; PG8_SCHED;
;         }
;         if (wr == 0) PG8_BAR;
	s_setprio 1
	v_mfma_f32_16x16x32_bf16 v[124:127], v[138:141], v[194:197], v[124:127]
	v_mfma_f32_16x16x32_bf16 v[120:123], v[146:149], v[194:197], v[120:123]
	v_mfma_f32_16x16x32_bf16 v[116:119], v[138:141], v[202:205], v[116:119]
	v_mfma_f32_16x16x32_bf16 v[108:111], v[146:149], v[202:205], v[108:111]
	v_mfma_f32_16x16x32_bf16 v[100:103], v[138:141], v[210:213], v[100:103]
	v_mfma_f32_16x16x32_bf16 v[92:95], v[146:149], v[210:213], v[92:95]
	v_mfma_f32_16x16x32_bf16 v[84:87], v[138:141], v[218:221], v[84:87]
	v_mfma_f32_16x16x32_bf16 v[76:79], v[146:149], v[218:221], v[76:79]
	v_mfma_f32_16x16x32_bf16 v[124:127], v[142:145], v[198:201], v[124:127]
	v_mfma_f32_16x16x32_bf16 v[120:123], v[172:175], v[198:201], v[120:123]
	v_mfma_f32_16x16x32_bf16 v[116:119], v[142:145], v[206:209], v[116:119]
	v_mfma_f32_16x16x32_bf16 v[108:111], v[172:175], v[206:209], v[108:111]
	v_mfma_f32_16x16x32_bf16 v[100:103], v[142:145], v[214:217], v[100:103]
	v_mfma_f32_16x16x32_bf16 v[92:95], v[172:175], v[214:217], v[92:95]
	v_mfma_f32_16x16x32_bf16 v[84:87], v[142:145], v[222:225], v[84:87]
	v_mfma_f32_16x16x32_bf16 v[76:79], v[172:175], v[222:225], v[76:79]
	v_mfma_f32_16x16x32_bf16 v[112:115], v[178:181], v[194:197], v[112:115]
	v_mfma_f32_16x16x32_bf16 v[104:107], v[186:189], v[194:197], v[104:107]
	v_mfma_f32_16x16x32_bf16 v[96:99], v[178:181], v[202:205], v[96:99]
	v_mfma_f32_16x16x32_bf16 v[88:91], v[186:189], v[202:205], v[88:91]
	v_mfma_f32_16x16x32_bf16 v[80:83], v[178:181], v[210:213], v[80:83]
	v_mfma_f32_16x16x32_bf16 v[72:75], v[186:189], v[210:213], v[72:75]
	v_mfma_f32_16x16x32_bf16 v[68:71], v[178:181], v[218:221], v[68:71]
	v_mfma_f32_16x16x32_bf16 v[64:67], v[186:189], v[218:221], v[64:67]
	v_mfma_f32_16x16x32_bf16 v[112:115], v[182:185], v[198:201], v[112:115]
	v_mfma_f32_16x16x32_bf16 v[104:107], v[190:193], v[198:201], v[104:107]
	v_mfma_f32_16x16x32_bf16 v[96:99], v[182:185], v[206:209], v[96:99]
	v_mfma_f32_16x16x32_bf16 v[88:91], v[190:193], v[206:209], v[88:91]
	v_mfma_f32_16x16x32_bf16 v[80:83], v[182:185], v[214:217], v[80:83]
	v_mfma_f32_16x16x32_bf16 v[72:75], v[190:193], v[214:217], v[72:75]
	v_mfma_f32_16x16x32_bf16 v[68:71], v[182:185], v[222:225], v[68:71]
	v_mfma_f32_16x16x32_bf16 v[64:67], v[190:193], v[222:225], v[64:67]
	s_setprio 0
	s_barrier
	s_add_u32 s82, s72, 0x80
	s_addc_u32 s83, s73, 0
	ds_read_b128 v[194:197], v154 offset:49152
	ds_read_b128 v[198:201], v154 offset:50176
	ds_read_b128 v[202:205], v154 offset:51200
	ds_read_b128 v[206:209], v154 offset:52224
	ds_read_b128 v[210:213], v154 offset:53248
	ds_read_b128 v[214:217], v154 offset:54272
	ds_read_b128 v[218:221], v154 offset:55296
	ds_read_b128 v[222:225], v154 offset:56320
	s_mov_b32 m0, s66
	s_nop 0
	global_load_lds_dwordx4 v150, s[82:83]
	s_add_u32 s82, s72, 0x20080
	s_mov_b32 m0, s67
	s_addc_u32 s83, s73, 0
	global_load_lds_dwordx4 v150, s[82:83]
	s_add_u32 s82, s72, 0x40080
	s_mov_b32 m0, s76
	s_addc_u32 s83, s73, 0
	global_load_lds_dwordx4 v150, s[82:83]
	s_add_u32 s72, s72, 0x60080
	s_mov_b32 m0, s77
	s_addc_u32 s73, s73, 0
	global_load_lds_dwordx4 v150, s[72:73]
	s_mov_b32 m0, s68
	s_nop 0
	global_load_lds_dwordx4 v128, s[22:23]
	s_add_u32 s16, s16, 0x20080
	s_mov_b32 m0, s69
	s_addc_u32 s17, s17, 0
	global_load_lds_dwordx4 v128, s[16:17]
	s_waitcnt vmcnt(8)
	s_waitcnt lgkmcnt(0)
	s_barrier
	s_setprio 1
	v_mfma_f32_16x16x32_bf16 v[60:63], v[138:141], v[194:197], v[60:63]
	v_mfma_f32_16x16x32_bf16 v[56:59], v[146:149], v[194:197], v[56:59]
	v_mfma_f32_16x16x32_bf16 v[52:55], v[138:141], v[202:205], v[52:55]
	v_mfma_f32_16x16x32_bf16 v[44:47], v[146:149], v[202:205], v[44:47]
	v_mfma_f32_16x16x32_bf16 v[36:39], v[138:141], v[210:213], v[36:39]
	v_mfma_f32_16x16x32_bf16 v[28:31], v[146:149], v[210:213], v[28:31]
	v_mfma_f32_16x16x32_bf16 v[20:23], v[138:141], v[218:221], v[20:23]
	v_mfma_f32_16x16x32_bf16 v[12:15], v[146:149], v[218:221], v[12:15]
	v_mfma_f32_16x16x32_bf16 v[60:63], v[142:145], v[198:201], v[60:63]
	v_mfma_f32_16x16x32_bf16 v[56:59], v[172:175], v[198:201], v[56:59]
	v_mfma_f32_16x16x32_bf16 v[52:55], v[142:145], v[206:209], v[52:55]
	v_mfma_f32_16x16x32_bf16 v[44:47], v[172:175], v[206:209], v[44:47]
	v_mfma_f32_16x16x32_bf16 v[36:39], v[142:145], v[214:217], v[36:39]
	v_mfma_f32_16x16x32_bf16 v[28:31], v[172:175], v[214:217], v[28:31]
	v_mfma_f32_16x16x32_bf16 v[20:23], v[142:145], v[222:225], v[20:23]
	v_mfma_f32_16x16x32_bf16 v[12:15], v[172:175], v[222:225], v[12:15]
	v_mfma_f32_16x16x32_bf16 v[48:51], v[178:181], v[194:197], v[48:51]
	v_mfma_f32_16x16x32_bf16 v[40:43], v[186:189], v[194:197], v[40:43]
	v_mfma_f32_16x16x32_bf16 v[32:35], v[178:181], v[202:205], v[32:35]
	v_mfma_f32_16x16x32_bf16 v[24:27], v[186:189], v[202:205], v[24:27]
	v_mfma_f32_16x16x32_bf16 v[16:19], v[178:181], v[210:213], v[16:19]
	v_mfma_f32_16x16x32_bf16 v[8:11], v[186:189], v[210:213], v[8:11]
	v_mfma_f32_16x16x32_bf16 v[4:7], v[178:181], v[218:221], v[4:7]
	v_mfma_f32_16x16x32_bf16 v[0:3], v[186:189], v[218:221], v[0:3]
	v_mfma_f32_16x16x32_bf16 v[48:51], v[182:185], v[198:201], v[48:51]
	v_mfma_f32_16x16x32_bf16 v[40:43], v[190:193], v[198:201], v[40:43]
	v_mfma_f32_16x16x32_bf16 v[32:35], v[182:185], v[206:209], v[32:35]
	v_mfma_f32_16x16x32_bf16 v[24:27], v[190:193], v[206:209], v[24:27]
	v_mfma_f32_16x16x32_bf16 v[16:19], v[182:185], v[214:217], v[16:19]
	v_mfma_f32_16x16x32_bf16 v[8:11], v[190:193], v[214:217], v[8:11]
	v_mfma_f32_16x16x32_bf16 v[4:7], v[182:185], v[222:225], v[4:7]
	v_mfma_f32_16x16x32_bf16 v[0:3], v[190:193], v[222:225], v[0:3]
	s_setprio 0
	s_barrier
	s_add_i32 s75, s75, 2
	s_add_u32 s62, s62, 0x100
	s_addc_u32 s63, s63, 0
	s_add_u32 s55, s55, 0x100
	s_addc_u32 s74, s74, 0
	s_cmp_gt_u32 s75, 13
	s_cbranch_scc0 .LBB0_582
	s_and_b64 vcc, exec, s[26:27]
	s_cbranch_vccz .LBB0_585
	s_barrier

; #define PG8_STAGE(bufoff, gbase, voff, p64) do { _Pragma("unroll") for (int _i = 0; _i < 2; ++_i) { \
;         const char* _gb = (const char*)(gbase) + (size_t)_i * (p64); const unsigned _la = ldsbase + (unsigned)(bufoff) + (unsigned)_i * 8192u; \
;         asm volatile("s_mov_b32 m0, %0\n\ts_nop 0\n\tglobal_load_lds_dwordx4 %1, %2" :: "s"(_la), "v"(voff), "s"(_gb) : "memory"); } } while (0)
; #define PG8_LDA(dst, b, h) do { _Pragma("unroll") for (int m = 0; m < 4; ++m) _Pragma("unroll") for (int k = 0; k < 2; ++k) dst[m][k] = *(const LAS bf16x8*)(lds + PG8_SA(b, h) + aoff + m * 2048 + k * 1024); } while (0)
; #define PG8_LDB(dst, b, h) do { _Pragma("unroll") for (int n = 0; n < 2; ++n) _Pragma("unroll") for (int k = 0; k < 2; ++k) dst[n][k] = *(const LAS bf16x8*)(lds + PG8_SB(b, h) + boff + n * 2048 + k * 1024); } while (0)
; #define PG8_MMA(ai, bj, At, Bt) do { __builtin_amdgcn_s_setprio(1); _Pragma("unroll") for (int m = 0; m < 4; ++m) _Pragma("unroll") for (int n = 0; n < 2; ++n) _Pragma("unroll") for (int k = 0; k < 2; ++k) \
;         acc[ai][bj][m][n] = __builtin_amdgcn_mfma_f32_16x16x32_bf16(Bt[n][k], At[m][k], acc[ai][bj][m][n], 0, 0, 0); __builtin_amdgcn_s_setprio(0); } while (0)
; #define PG8_BAR __builtin_amdgcn_s_barrier()
; template <class Epi, class Sched>
; __device__ __forceinline__ void gemm_phase(LAS unsigned char* lds, const Sched& S, const Epi& E) {
;     ...
;         for (int t = 0; t < nt; t += 2) {
;             const bool last = (t == nt - 2);
;             const char* a1 = cA + (size_t)(t + 1) * kstep;
;             const char* a2 = last ? nA : cA + (size_t)(t + 2) * kstep; const char* b2 = last ? nB : cB + (size_t)(t + 2) * kstep;
;             const char* a3 = a2 + kstep; const char* b3 = b2 + kstep;
;             const unsigned vA2 = voffA, vB2 = voffB, hA2 = hA, hB2 = hB;
;             PG8_LDB(B0, 0, 0); PG8_LDB(B1, 0, 1); PG8_SCHED; PG8_LDA(At, 0, 0); PG8_STAGE(PG8_SA(1, 1), a1 + hA, voffA, hA / 2);
;             PG8_WAIT_V(8); PG8_WAIT_L(0); PG8_BAR; PG8_MMA(0, 0, At, B0); PG8_MMA(0, 1, At, B1); PG8_BAR; PG8_SCHED;
;     ...
; #pragma unroll
;             for (int a = 0; a < 2; ++a)
; #pragma unroll
;                 for (int b = 0; b < 2; ++b)
; #pragma unroll
;                     for (int m = 0; m < 4; ++m)
; #pragma unroll
;                         for (int n = 0; n < 2; ++n) acc[a][b][m][n] = (f32x4){0.f, 0.f, 0.f, 0.f};
.LBB0_659:
	s_add_u32 s78, s16, 0x100
	s_addc_u32 s79, s17, 0
	s_mov_b32 s80, -2
	v_mov_b64_e32 v[0:1], 0
	v_mov_b64_e32 v[2:3], 0
	v_mov_b64_e32 v[4:5], 0
	v_mov_b64_e32 v[6:7], 0
	v_mov_b64_e32 v[8:9], 0
	v_mov_b64_e32 v[10:11], 0
	v_mov_b64_e32 v[16:17], 0
	v_mov_b64_e32 v[18:19], 0
	v_mov_b64_e32 v[24:25], 0
	v_mov_b64_e32 v[26:27], 0
	v_mov_b64_e32 v[32:33], 0
	v_mov_b64_e32 v[34:35], 0
	v_mov_b64_e32 v[40:41], 0
	v_mov_b64_e32 v[42:43], 0
	v_mov_b64_e32 v[48:49], 0
	v_mov_b64_e32 v[50:51], 0
	v_mov_b64_e32 v[12:13], 0
	v_mov_b64_e32 v[14:15], 0
	v_mov_b64_e32 v[20:21], 0
	v_mov_b64_e32 v[22:23], 0
	v_mov_b64_e32 v[28:29], 0
	v_mov_b64_e32 v[30:31], 0
	v_mov_b64_e32 v[36:37], 0
	v_mov_b64_e32 v[38:39], 0
	v_mov_b64_e32 v[44:45], 0
	v_mov_b64_e32 v[46:47], 0
	v_mov_b64_e32 v[52:53], 0
	v_mov_b64_e32 v[54:55], 0
	v_mov_b64_e32 v[56:57], 0
	v_mov_b64_e32 v[58:59], 0
	v_mov_b64_e32 v[60:61], 0
	v_mov_b64_e32 v[62:63], 0
	v_mov_b64_e32 v[64:65], 0
	v_mov_b64_e32 v[66:67], 0
	v_mov_b64_e32 v[68:69], 0
	v_mov_b64_e32 v[70:71], 0
	v_mov_b64_e32 v[72:73], 0
	v_mov_b64_e32 v[74:75], 0
	v_mov_b64_e32 v[80:81], 0
	v_mov_b64_e32 v[82:83], 0
	v_mov_b64_e32 v[88:89], 0
	v_mov_b64_e32 v[90:91], 0
	v_mov_b64_e32 v[96:97], 0
	v_mov_b64_e32 v[98:99], 0
	v_mov_b64_e32 v[104:105], 0
	v_mov_b64_e32 v[106:107], 0
	v_mov_b64_e32 v[112:113], 0
	v_mov_b64_e32 v[114:115], 0
	v_mov_b64_e32 v[76:77], 0
	v_mov_b64_e32 v[78:79], 0
	v_mov_b64_e32 v[84:85], 0
	v_mov_b64_e32 v[86:87], 0
	v_mov_b64_e32 v[92:93], 0
	v_mov_b64_e32 v[94:95], 0
	v_mov_b64_e32 v[100:101], 0
	v_mov_b64_e32 v[102:103], 0
	v_mov_b64_e32 v[108:109], 0
	v_mov_b64_e32 v[110:111], 0
	v_mov_b64_e32 v[116:117], 0
	v_mov_b64_e32 v[118:119], 0
	v_mov_b64_e32 v[120:121], 0
	v_mov_b64_e32 v[122:123], 0
	v_mov_b64_e32 v[124:125], 0
	v_mov_b64_e32 v[126:127], 0
.LBB0_660:
	v_add_u32_e32 v130, 0x10000, v143
	ds_read_b128 v[146:149], v130
	ds_read_b128 v[150:153], v130 offset:1024
	ds_read_b128 v[172:175], v130 offset:2048
	ds_read_b128 v[178:181], v130 offset:3072
	v_add_u32_e32 v130, 0x14000, v143
	ds_read_b128 v[182:185], v130
	ds_read_b128 v[186:189], v130 offset:1024
	ds_read_b128 v[190:193], v130 offset:2048
	ds_read_b128 v[194:197], v130 offset:3072
	s_add_u32 s16, s58, 0x100
	s_addc_u32 s17, s59, 0
	s_cmp_eq_u32 s80, 4
	s_cselect_b32 s22, s40, s16
	s_cselect_b32 s23, s41, s17
	s_cselect_b32 s72, s54, s78
	s_cselect_b32 s73, s55, s79
	s_add_u32 s62, s22, 0x80
	s_addc_u32 s63, s23, 0
	ds_read_b128 v[198:201], v144
	ds_read_b128 v[202:205], v144 offset:1024
	ds_read_b128 v[206:209], v144 offset:2048
	ds_read_b128 v[210:213], v144 offset:3072
	ds_read_b128 v[214:217], v144 offset:4096
	ds_read_b128 v[218:221], v144 offset:5120
	ds_read_b128 v[222:225], v144 offset:6144
	ds_read_b128 v[226:229], v144 offset:7168
	s_add_u32 s82, s58, 0x20080
	s_mov_b32 m0, s66
	s_addc_u32 s83, s59, 0
	global_load_lds_dwordx4 v128, s[82:83]
	s_add_u32 s58, s58, 0x30080
	s_mov_b32 m0, s67
	s_addc_u32 s59, s59, 0
	global_load_lds_dwordx4 v128, s[58:59]
	s_waitcnt vmcnt(8)
	s_waitcnt lgkmcnt(0)
	s_barrier
	s_setprio 1
	v_mfma_f32_16x16x32_bf16 v[124:127], v[146:149], v[198:201], v[124:127]
	v_mfma_f32_16x16x32_bf16 v[120:123], v[172:175], v[198:201], v[120:123]
	v_mfma_f32_16x16x32_bf16 v[116:119], v[146:149], v[206:209], v[116:119]
	v_mfma_f32_16x16x32_bf16 v[108:111], v[172:175], v[206:209], v[108:111]
	v_mfma_f32_16x16x32_bf16 v[100:103], v[146:149], v[214:217], v[100:103]
	v_mfma_f32_16x16x32_bf16 v[92:95], v[172:175], v[214:217], v[92:95]
	v_mfma_f32_16x16x32_bf16 v[84:87], v[146:149], v[222:225], v[84:87]
	v_mfma_f32_16x16x32_bf16 v[76:79], v[172:175], v[222:225], v[76:79]
	v_mfma_f32_16x16x32_bf16 v[124:127], v[150:153], v[202:205], v[124:127]
	v_mfma_f32_16x16x32_bf16 v[120:123], v[178:181], v[202:205], v[120:123]
	v_mfma_f32_16x16x32_bf16 v[116:119], v[150:153], v[210:213], v[116:119]
	v_mfma_f32_16x16x32_bf16 v[108:111], v[178:181], v[210:213], v[108:111]
	v_mfma_f32_16x16x32_bf16 v[100:103], v[150:153], v[218:221], v[100:103]
	v_mfma_f32_16x16x32_bf16 v[92:95], v[178:181], v[218:221], v[92:95]
	v_mfma_f32_16x16x32_bf16 v[84:87], v[150:153], v[226:229], v[84:87]
	v_mfma_f32_16x16x32_bf16 v[76:79], v[178:181], v[226:229], v[76:79]
	v_mfma_f32_16x16x32_bf16 v[112:115], v[182:185], v[198:201], v[112:115]
	v_mfma_f32_16x16x32_bf16 v[104:107], v[190:193], v[198:201], v[104:107]
	v_mfma_f32_16x16x32_bf16 v[96:99], v[182:185], v[206:209], v[96:99]
	v_mfma_f32_16x16x32_bf16 v[88:91], v[190:193], v[206:209], v[88:91]
	v_mfma_f32_16x16x32_bf16 v[80:83], v[182:185], v[214:217], v[80:83]
	v_mfma_f32_16x16x32_bf16 v[72:75], v[190:193], v[214:217], v[72:75]
	v_mfma_f32_16x16x32_bf16 v[68:71], v[182:185], v[222:225], v[68:71]
	v_mfma_f32_16x16x32_bf16 v[64:67], v[190:193], v[222:225], v[64:67]
	v_mfma_f32_16x16x32_bf16 v[112:115], v[186:189], v[202:205], v[112:115]
	v_mfma_f32_16x16x32_bf16 v[104:107], v[194:197], v[202:205], v[104:107]
	v_mfma_f32_16x16x32_bf16 v[96:99], v[186:189], v[210:213], v[96:99]
	v_mfma_f32_16x16x32_bf16 v[88:91], v[194:197], v[210:213], v[88:91]
	v_mfma_f32_16x16x32_bf16 v[80:83], v[186:189], v[218:221], v[80:83]
	v_mfma_f32_16x16x32_bf16 v[72:75], v[194:197], v[218:221], v[72:75]
	v_mfma_f32_16x16x32_bf16 v[68:71], v[186:189], v[226:229], v[68:71]
	v_mfma_f32_16x16x32_bf16 v[64:67], v[194:197], v[226:229], v[64:67]
	s_setprio 0
	s_barrier
; #define PG8_STAGE(bufoff, gbase, voff, p64) do { _Pragma("unroll") for (int _i = 0; _i < 2; ++_i) { \
;         const char* _gb = (const char*)(gbase) + (size_t)_i * (p64); const unsigned _la = ldsbase + (unsigned)(bufoff) + (unsigned)_i * 8192u; \
;         asm volatile("s_mov_b32 m0, %0\n\ts_nop 0\n\tglobal_load_lds_dwordx4 %1, %2" :: "s"(_la), "v"(voff), "s"(_gb) : "memory"); } } while (0)
; #define PG8_LDA(dst, b, h) do { _Pragma("unroll") for (int m = 0; m < 4; ++m) _Pragma("unroll") for (int k = 0; k < 2; ++k) dst[m][k] = *(const LAS bf16x8*)(lds + PG8_SA(b, h) + aoff + m * 2048 + k * 1024); } while (0)
; #define PG8_LDB(dst, b, h) do { _Pragma("unroll") for (int n = 0; n < 2; ++n) _Pragma("unroll") for (int k = 0; k < 2; ++k) dst[n][k] = *(const LAS bf16x8*)(lds + PG8_SB(b, h) + boff + n * 2048 + k * 1024); } while (0)
; #define PG8_MMA(ai, bj, At, Bt) do { __builtin_amdgcn_s_setprio(1); _Pragma("unroll") for (int m = 0; m < 4; ++m) _Pragma("unroll") for (int n = 0; n < 2; ++n) _Pragma("unroll") for (int k = 0; k < 2; ++k) \
;         acc[ai][bj][m][n] = __builtin_amdgcn_mfma_f32_16x16x32_bf16(Bt[n][k], At[m][k], acc[ai][bj][m][n], 0, 0, 0); __builtin_amdgcn_s_setprio(0); } while (0)
; #define PG8_WAIT_V(n) asm volatile("s_waitcnt vmcnt(" #n ")" ::: "memory")
; #define PG8_WAIT_L(n) asm volatile("s_waitcnt lgkmcnt(" #n ")" ::: "memory")
; #define PG8_BAR __builtin_amdgcn_s_barrier()
; #define PG8_SCHED __builtin_amdgcn_sched_barrier(0)
; template <class Epi, class Sched>
; __device__ __forceinline__ void gemm_phase(LAS unsigned char* lds, const Sched& S, const Epi& E) {
;     ...
;             PG8_LDA(At, 0, 1); PG8_STAGE(PG8_SB(0, 0), b2, vB2, hB2 / 2); PG8_STAGE(PG8_SB(0, 1), b2 + hB2, vB2, hB2 / 2); PG8_STAGE(PG8_SA(0, 0), a2, vA2, hA2 / 2);
;             PG8_WAIT_V(8); PG8_WAIT_L(0); PG8_BAR; PG8_MMA(1, 0, At, B0); PG8_MMA(1, 1, At, B1); PG8_BAR; PG8_SCHED;
;             PG8_LDB(B0, 1, 0); PG8_LDB(B1, 1, 1); PG8_SCHED; PG8_LDA(At, 1, 0); PG8_STAGE(PG8_SA(0, 1), a2 + hA2, vA2, hA2 / 2);
;             PG8_WAIT_V(8); PG8_WAIT_L(0); PG8_BAR; PG8_MMA(0, 0, At, B0); PG8_MMA(0, 1, At, B1); PG8_BAR; PG8_SCHED;
	s_add_u32 s58, s72, 0x10000
	ds_read_b128 v[198:201], v144 offset:16384
	ds_read_b128 v[202:205], v144 offset:17408
	ds_read_b128 v[206:209], v144 offset:18432
	ds_read_b128 v[210:213], v144 offset:19456
	ds_read_b128 v[214:217], v144 offset:20480
	ds_read_b128 v[218:221], v144 offset:21504
	ds_read_b128 v[222:225], v144 offset:22528
	ds_read_b128 v[226:229], v144 offset:23552
	s_mov_b32 m0, s33
	s_nop 0
	global_load_lds_dwordx4 v140, s[72:73]
	s_mov_b32 m0, s34
	s_addc_u32 s59, s73, 0
	global_load_lds_dwordx4 v140, s[58:59]
	s_add_u32 s58, s72, 0x20000
	s_mov_b32 m0, s35
	s_addc_u32 s59, s73, 0
	global_load_lds_dwordx4 v140, s[58:59]
	s_add_u32 s58, s72, 0x30000
	s_mov_b32 m0, s36
	s_addc_u32 s59, s73, 0
	global_load_lds_dwordx4 v140, s[58:59]
	s_mov_b32 m0, s24
	s_nop 0
	global_load_lds_dwordx4 v128, s[22:23]
	s_add_u32 s58, s22, 0x10000
	s_mov_b32 m0, s37
	s_addc_u32 s59, s23, 0
	global_load_lds_dwordx4 v128, s[58:59]
	s_waitcnt vmcnt(8)
	s_waitcnt lgkmcnt(0)
	s_barrier
	s_setprio 1
	v_mfma_f32_16x16x32_bf16 v[60:63], v[146:149], v[198:201], v[60:63]
	v_mfma_f32_16x16x32_bf16 v[56:59], v[172:175], v[198:201], v[56:59]
	v_mfma_f32_16x16x32_bf16 v[52:55], v[146:149], v[206:209], v[52:55]
	v_mfma_f32_16x16x32_bf16 v[44:47], v[172:175], v[206:209], v[44:47]
	v_mfma_f32_16x16x32_bf16 v[36:39], v[146:149], v[214:217], v[36:39]
	v_mfma_f32_16x16x32_bf16 v[28:31], v[172:175], v[214:217], v[28:31]
	v_mfma_f32_16x16x32_bf16 v[20:23], v[146:149], v[222:225], v[20:23]
	v_mfma_f32_16x16x32_bf16 v[12:15], v[172:175], v[222:225], v[12:15]
	v_mfma_f32_16x16x32_bf16 v[60:63], v[150:153], v[202:205], v[60:63]
	v_mfma_f32_16x16x32_bf16 v[56:59], v[178:181], v[202:205], v[56:59]
	v_mfma_f32_16x16x32_bf16 v[52:55], v[150:153], v[210:213], v[52:55]
	v_mfma_f32_16x16x32_bf16 v[44:47], v[178:181], v[210:213], v[44:47]
	v_mfma_f32_16x16x32_bf16 v[36:39], v[150:153], v[218:221], v[36:39]
	v_mfma_f32_16x16x32_bf16 v[28:31], v[178:181], v[218:221], v[28:31]
	v_mfma_f32_16x16x32_bf16 v[20:23], v[150:153], v[226:229], v[20:23]
	v_mfma_f32_16x16x32_bf16 v[12:15], v[178:181], v[226:229], v[12:15]
	v_mfma_f32_16x16x32_bf16 v[48:51], v[182:185], v[198:201], v[48:51]
	v_mfma_f32_16x16x32_bf16 v[40:43], v[190:193], v[198:201], v[40:43]
	v_mfma_f32_16x16x32_bf16 v[32:35], v[182:185], v[206:209], v[32:35]
	v_mfma_f32_16x16x32_bf16 v[24:27], v[190:193], v[206:209], v[24:27]
	v_mfma_f32_16x16x32_bf16 v[16:19], v[182:185], v[214:217], v[16:19]
	v_mfma_f32_16x16x32_bf16 v[8:11], v[190:193], v[214:217], v[8:11]
	v_mfma_f32_16x16x32_bf16 v[4:7], v[182:185], v[222:225], v[4:7]
	v_mfma_f32_16x16x32_bf16 v[0:3], v[190:193], v[222:225], v[0:3]
	v_mfma_f32_16x16x32_bf16 v[48:51], v[186:189], v[202:205], v[48:51]
	v_mfma_f32_16x16x32_bf16 v[40:43], v[194:197], v[202:205], v[40:43]
	v_mfma_f32_16x16x32_bf16 v[32:35], v[186:189], v[210:213], v[32:35]
	v_mfma_f32_16x16x32_bf16 v[24:27], v[194:197], v[210:213], v[24:27]
	v_mfma_f32_16x16x32_bf16 v[16:19], v[186:189], v[218:221], v[16:19]
	v_mfma_f32_16x16x32_bf16 v[8:11], v[194:197], v[218:221], v[8:11]
	v_mfma_f32_16x16x32_bf16 v[4:7], v[186:189], v[226:229], v[4:7]
	v_mfma_f32_16x16x32_bf16 v[0:3], v[194:197], v[226:229], v[0:3]
	s_setprio 0
	s_barrier
	v_add_u32_e32 v130, 0x18000, v143
	ds_read_b128 v[146:149], v130
	ds_read_b128 v[150:153], v130 offset:1024
	ds_read_b128 v[172:175], v130 offset:2048
	ds_read_b128 v[178:181], v130 offset:3072
	v_add_u32_e32 v130, 0x1c000, v143
	ds_read_b128 v[182:185], v130
	ds_read_b128 v[186:189], v130 offset:1024
	ds_read_b128 v[190:193], v130 offset:2048
	ds_read_b128 v[194:197], v130 offset:3072
	ds_read_b128 v[198:201], v144 offset:32768
	ds_read_b128 v[202:205], v144 offset:33792
	ds_read_b128 v[206:209], v144 offset:34816
	ds_read_b128 v[210:213], v144 offset:35840
	ds_read_b128 v[214:217], v144 offset:36864
	ds_read_b128 v[218:221], v144 offset:37888
	ds_read_b128 v[222:225], v144 offset:38912
	ds_read_b128 v[226:229], v144 offset:39936
	s_add_u32 s58, s22, 0x20000
	s_mov_b32 m0, s42
	s_addc_u32 s59, s23, 0
	global_load_lds_dwordx4 v128, s[58:59]
	s_add_u32 s58, s22, 0x30000
	s_mov_b32 m0, s44
	s_addc_u32 s59, s23, 0
	global_load_lds_dwordx4 v128, s[58:59]
	s_waitcnt vmcnt(8)
	s_waitcnt lgkmcnt(0)
	s_barrier
; #define PG8_STAGE(bufoff, gbase, voff, p64) do { _Pragma("unroll") for (int _i = 0; _i < 2; ++_i) { \
;         const char* _gb = (const char*)(gbase) + (size_t)_i * (p64); const unsigned _la = ldsbase + (unsigned)(bufoff) + (unsigned)_i * 8192u; \
;         asm volatile("s_mov_b32 m0, %0\n\ts_nop 0\n\tglobal_load_lds_dwordx4 %1, %2" :: "s"(_la), "v"(voff), "s"(_gb) : "memory"); } } while (0)
; #define PG8_LDA(dst, b, h) do { _Pragma("unroll") for (int m = 0; m < 4; ++m) _Pragma("unroll") for (int k = 0; k < 2; ++k) dst[m][k] = *(const LAS bf16x8*)(lds + PG8_SA(b, h) + aoff + m * 2048 + k * 1024); } while (0)
; #define PG8_MMA(ai, bj, At, Bt) do { __builtin_amdgcn_s_setprio(1); _Pragma("unroll") for (int m = 0; m < 4; ++m) _Pragma("unroll") for (int n = 0; n < 2; ++n) _Pragma("unroll") for (int k = 0; k < 2; ++k) \
;         acc[ai][bj][m][n] = __builtin_amdgcn_mfma_f32_16x16x32_bf16(Bt[n][k], At[m][k], acc[ai][bj][m][n], 0, 0, 0); __builtin_amdgcn_s_setprio(0); } while (0)
; #define PG8_WAIT_V(n) asm volatile("s_waitcnt vmcnt(" #n ")" ::: "memory")
; #define PG8_WAIT_L(n) asm volatile("s_waitcnt lgkmcnt(" #n ")" ::: "memory")
; #define PG8_BAR __builtin_amdgcn_s_barrier()
; #define PG8_SCHED __builtin_amdgcn_sched_barrier(0)
; template <class Epi, class Sched>
; __device__ __forceinline__ void gemm_phase(LAS unsigned char* lds, const Sched& S, const Epi& E) {
;     ...
;             PG8_WAIT_V(8); PG8_WAIT_L(0); PG8_BAR; PG8_MMA(0, 0, At, B0); PG8_MMA(0, 1, At, B1); PG8_BAR; PG8_SCHED;
;             PG8_LDA(At, 1, 1); PG8_STAGE(PG8_SB(1, 0), b3, vB2, hB2 / 2); PG8_STAGE(PG8_SB(1, 1), b3 + hB2, vB2, hB2 / 2); PG8_STAGE(PG8_SA(1, 0), a3, vA2, hA2 / 2);
;             PG8_WAIT_V(8); PG8_WAIT_L(0); PG8_BAR; PG8_MMA(1, 0, At, B0); PG8_MMA(1, 1, At, B1); PG8_BAR; PG8_SCHED;
;         }
;         if (wr == 0) PG8_BAR;
	s_setprio 1
	v_mfma_f32_16x16x32_bf16 v[124:127], v[146:149], v[198:201], v[124:127]
	v_mfma_f32_16x16x32_bf16 v[120:123], v[172:175], v[198:201], v[120:123]
	v_mfma_f32_16x16x32_bf16 v[116:119], v[146:149], v[206:209], v[116:119]
	v_mfma_f32_16x16x32_bf16 v[108:111], v[172:175], v[206:209], v[108:111]
	v_mfma_f32_16x16x32_bf16 v[100:103], v[146:149], v[214:217], v[100:103]
	v_mfma_f32_16x16x32_bf16 v[92:95], v[172:175], v[214:217], v[92:95]
	v_mfma_f32_16x16x32_bf16 v[84:87], v[146:149], v[222:225], v[84:87]
	v_mfma_f32_16x16x32_bf16 v[76:79], v[172:175], v[222:225], v[76:79]
	v_mfma_f32_16x16x32_bf16 v[124:127], v[150:153], v[202:205], v[124:127]
	v_mfma_f32_16x16x32_bf16 v[120:123], v[178:181], v[202:205], v[120:123]
	v_mfma_f32_16x16x32_bf16 v[116:119], v[150:153], v[210:213], v[116:119]
	v_mfma_f32_16x16x32_bf16 v[108:111], v[178:181], v[210:213], v[108:111]
	v_mfma_f32_16x16x32_bf16 v[100:103], v[150:153], v[218:221], v[100:103]
	v_mfma_f32_16x16x32_bf16 v[92:95], v[178:181], v[218:221], v[92:95]
	v_mfma_f32_16x16x32_bf16 v[84:87], v[150:153], v[226:229], v[84:87]
	v_mfma_f32_16x16x32_bf16 v[76:79], v[178:181], v[226:229], v[76:79]
	v_mfma_f32_16x16x32_bf16 v[112:115], v[182:185], v[198:201], v[112:115]
	v_mfma_f32_16x16x32_bf16 v[104:107], v[190:193], v[198:201], v[104:107]
	v_mfma_f32_16x16x32_bf16 v[96:99], v[182:185], v[206:209], v[96:99]
	v_mfma_f32_16x16x32_bf16 v[88:91], v[190:193], v[206:209], v[88:91]
	v_mfma_f32_16x16x32_bf16 v[80:83], v[182:185], v[214:217], v[80:83]
	v_mfma_f32_16x16x32_bf16 v[72:75], v[190:193], v[214:217], v[72:75]
	v_mfma_f32_16x16x32_bf16 v[68:71], v[182:185], v[222:225], v[68:71]
	v_mfma_f32_16x16x32_bf16 v[64:67], v[190:193], v[222:225], v[64:67]
	v_mfma_f32_16x16x32_bf16 v[112:115], v[186:189], v[202:205], v[112:115]
	v_mfma_f32_16x16x32_bf16 v[104:107], v[194:197], v[202:205], v[104:107]
	v_mfma_f32_16x16x32_bf16 v[96:99], v[186:189], v[210:213], v[96:99]
	v_mfma_f32_16x16x32_bf16 v[88:91], v[194:197], v[210:213], v[88:91]
	v_mfma_f32_16x16x32_bf16 v[80:83], v[186:189], v[218:221], v[80:83]
	v_mfma_f32_16x16x32_bf16 v[72:75], v[194:197], v[218:221], v[72:75]
	v_mfma_f32_16x16x32_bf16 v[68:71], v[186:189], v[226:229], v[68:71]
	v_mfma_f32_16x16x32_bf16 v[64:67], v[194:197], v[226:229], v[64:67]
	s_setprio 0
	s_barrier
	s_add_u32 s58, s72, 0x80
	s_addc_u32 s59, s73, 0
	ds_read_b128 v[198:201], v144 offset:49152
	ds_read_b128 v[202:205], v144 offset:50176
	ds_read_b128 v[206:209], v144 offset:51200
	ds_read_b128 v[210:213], v144 offset:52224
	ds_read_b128 v[214:217], v144 offset:53248
	ds_read_b128 v[218:221], v144 offset:54272
	ds_read_b128 v[222:225], v144 offset:55296
	ds_read_b128 v[226:229], v144 offset:56320
	s_mov_b32 m0, s48
	s_nop 0
	global_load_lds_dwordx4 v140, s[58:59]
	s_add_u32 s58, s72, 0x10080
	s_mov_b32 m0, s50
	s_addc_u32 s59, s73, 0
	global_load_lds_dwordx4 v140, s[58:59]
	s_add_u32 s58, s72, 0x20080
	s_mov_b32 m0, s64
	s_addc_u32 s59, s73, 0
	global_load_lds_dwordx4 v140, s[58:59]
	s_add_u32 s58, s72, 0x30080
	s_mov_b32 m0, s65
	s_addc_u32 s59, s73, 0
	global_load_lds_dwordx4 v140, s[58:59]
	s_mov_b32 m0, s51
	s_nop 0
	global_load_lds_dwordx4 v128, s[62:63]
	s_add_u32 s22, s22, 0x10080
	s_mov_b32 m0, s61
	s_addc_u32 s23, s23, 0
	global_load_lds_dwordx4 v128, s[22:23]
	s_waitcnt vmcnt(8)
	s_waitcnt lgkmcnt(0)
	s_barrier
	s_setprio 1
	v_mfma_f32_16x16x32_bf16 v[60:63], v[146:149], v[198:201], v[60:63]
	v_mfma_f32_16x16x32_bf16 v[56:59], v[172:175], v[198:201], v[56:59]
	v_mfma_f32_16x16x32_bf16 v[52:55], v[146:149], v[206:209], v[52:55]
	v_mfma_f32_16x16x32_bf16 v[44:47], v[172:175], v[206:209], v[44:47]
	v_mfma_f32_16x16x32_bf16 v[36:39], v[146:149], v[214:217], v[36:39]
	v_mfma_f32_16x16x32_bf16 v[28:31], v[172:175], v[214:217], v[28:31]
	v_mfma_f32_16x16x32_bf16 v[20:23], v[146:149], v[222:225], v[20:23]
	v_mfma_f32_16x16x32_bf16 v[12:15], v[172:175], v[222:225], v[12:15]
	v_mfma_f32_16x16x32_bf16 v[60:63], v[150:153], v[202:205], v[60:63]
	v_mfma_f32_16x16x32_bf16 v[56:59], v[178:181], v[202:205], v[56:59]
	v_mfma_f32_16x16x32_bf16 v[52:55], v[150:153], v[210:213], v[52:55]
	v_mfma_f32_16x16x32_bf16 v[44:47], v[178:181], v[210:213], v[44:47]
	v_mfma_f32_16x16x32_bf16 v[36:39], v[150:153], v[218:221], v[36:39]
	v_mfma_f32_16x16x32_bf16 v[28:31], v[178:181], v[218:221], v[28:31]
	v_mfma_f32_16x16x32_bf16 v[20:23], v[150:153], v[226:229], v[20:23]
	v_mfma_f32_16x16x32_bf16 v[12:15], v[178:181], v[226:229], v[12:15]
	v_mfma_f32_16x16x32_bf16 v[48:51], v[182:185], v[198:201], v[48:51]
	v_mfma_f32_16x16x32_bf16 v[40:43], v[190:193], v[198:201], v[40:43]
	v_mfma_f32_16x16x32_bf16 v[32:35], v[182:185], v[206:209], v[32:35]
	v_mfma_f32_16x16x32_bf16 v[24:27], v[190:193], v[206:209], v[24:27]
	v_mfma_f32_16x16x32_bf16 v[16:19], v[182:185], v[214:217], v[16:19]
	v_mfma_f32_16x16x32_bf16 v[8:11], v[190:193], v[214:217], v[8:11]
	v_mfma_f32_16x16x32_bf16 v[4:7], v[182:185], v[222:225], v[4:7]
	v_mfma_f32_16x16x32_bf16 v[0:3], v[190:193], v[222:225], v[0:3]
	v_mfma_f32_16x16x32_bf16 v[48:51], v[186:189], v[202:205], v[48:51]
	v_mfma_f32_16x16x32_bf16 v[40:43], v[194:197], v[202:205], v[40:43]
	v_mfma_f32_16x16x32_bf16 v[32:35], v[186:189], v[210:213], v[32:35]
	v_mfma_f32_16x16x32_bf16 v[24:27], v[194:197], v[210:213], v[24:27]
	v_mfma_f32_16x16x32_bf16 v[16:19], v[186:189], v[218:221], v[16:19]
	v_mfma_f32_16x16x32_bf16 v[8:11], v[194:197], v[218:221], v[8:11]
	v_mfma_f32_16x16x32_bf16 v[4:7], v[186:189], v[226:229], v[4:7]
	v_mfma_f32_16x16x32_bf16 v[0:3], v[194:197], v[226:229], v[0:3]
	s_setprio 0
	s_barrier
	s_add_i32 s80, s80, 2
	s_add_u32 s78, s78, 0x100
	s_addc_u32 s79, s79, 0
	s_cmp_gt_u32 s80, 5
	s_mov_b64 s[58:59], s[16:17]
	s_cbranch_scc0 .LBB0_660
	s_and_b64 vcc, exec, s[38:39]
	s_cbranch_vccz .LBB0_663
	s_barrier

; #define PG8_STAGE(bufoff, gbase, voff, p64) do { _Pragma("unroll") for (int _i = 0; _i < 2; ++_i) { \
;         const char* _gb = (const char*)(gbase) + (size_t)_i * (p64); const unsigned _la = ldsbase + (unsigned)(bufoff) + (unsigned)_i * 8192u; \
;         asm volatile("s_mov_b32 m0, %0\n\ts_nop 0\n\tglobal_load_lds_dwordx4 %1, %2" :: "s"(_la), "v"(voff), "s"(_gb) : "memory"); } } while (0)
; #define PG8_LDA(dst, b, h) do { _Pragma("unroll") for (int m = 0; m < 4; ++m) _Pragma("unroll") for (int k = 0; k < 2; ++k) dst[m][k] = *(const LAS bf16x8*)(lds + PG8_SA(b, h) + aoff + m * 2048 + k * 1024); } while (0)
; #define PG8_LDB(dst, b, h) do { _Pragma("unroll") for (int n = 0; n < 2; ++n) _Pragma("unroll") for (int k = 0; k < 2; ++k) dst[n][k] = *(const LAS bf16x8*)(lds + PG8_SB(b, h) + boff + n * 2048 + k * 1024); } while (0)
; #define PG8_MMA(ai, bj, At, Bt) do { __builtin_amdgcn_s_setprio(1); _Pragma("unroll") for (int m = 0; m < 4; ++m) _Pragma("unroll") for (int n = 0; n < 2; ++n) _Pragma("unroll") for (int k = 0; k < 2; ++k) \
;         acc[ai][bj][m][n] = __builtin_amdgcn_mfma_f32_16x16x32_bf16(Bt[n][k], At[m][k], acc[ai][bj][m][n], 0, 0, 0); __builtin_amdgcn_s_setprio(0); } while (0)
; #define PG8_WAIT_V(n) asm volatile("s_waitcnt vmcnt(" #n ")" ::: "memory")
; template <class Epi, class Sched>
; __device__ __forceinline__ void gemm_phase(LAS unsigned char* lds, const Sched& S, const Epi& E) {
;     ...
;         for (int t = 0; t < nt; t += 2) {
;             const bool last = (t == nt - 2);
;             const char* a1 = cA + (size_t)(t + 1) * kstep;
;             const char* a2 = last ? nA : cA + (size_t)(t + 2) * kstep; const char* b2 = last ? nB : cB + (size_t)(t + 2) * kstep;
;             const char* a3 = a2 + kstep; const char* b3 = b2 + kstep;
;             const unsigned vA2 = voffA, vB2 = voffB, hA2 = hA, hB2 = hB;
;             PG8_LDB(B0, 0, 0); PG8_LDB(B1, 0, 1); PG8_SCHED; PG8_LDA(At, 0, 0); PG8_STAGE(PG8_SA(1, 1), a1 + hA, voffA, hA / 2);
;             PG8_WAIT_V(8); PG8_WAIT_L(0); PG8_BAR; PG8_MMA(0, 0, At, B0); PG8_MMA(0, 1, At, B1); PG8_BAR; PG8_SCHED;
;             PG8_LDA(At, 0, 1); PG8_STAGE(PG8_SB(0, 0), b2, vB2, hB2 / 2); PG8_STAGE(PG8_SB(0, 1), b2 + hB2, vB2, hB2 / 2); PG8_STAGE(PG8_SA(0, 0), a2, vA2, hA2 / 2);
;             PG8_WAIT_V(8); PG8_WAIT_L(0); PG8_BAR; PG8_MMA(1, 0, At, B0); PG8_MMA(1, 1, At, B1); PG8_BAR; PG8_SCHED;
.LBB0_679:
	v_add_u32_e32 v130, 0x10000, v141
	v_add_u32_e32 v131, 0x14000, v141
	ds_read_b128 v[0:3], v130
	ds_read_b128 v[4:7], v130 offset:1024
	ds_read_b128 v[8:11], v130 offset:2048
	ds_read_b128 v[12:15], v130 offset:3072
	ds_read_b128 v[16:19], v131
	ds_read_b128 v[20:23], v131 offset:1024
	ds_read_b128 v[24:27], v131 offset:2048
	ds_read_b128 v[28:31], v131 offset:3072
	s_add_u32 s22, s56, 0x100
	s_addc_u32 s23, s57, 0
	s_add_u32 s76, s58, 0x100
	s_addc_u32 s77, s59, 0
	s_add_u32 s16, s56, 0x180
	s_addc_u32 s17, s57, 0
	ds_read_b128 v[32:35], v142
	ds_read_b128 v[36:39], v142 offset:1024
	ds_read_b128 v[40:43], v142 offset:2048
	ds_read_b128 v[44:47], v142 offset:3072
	ds_read_b128 v[48:51], v142 offset:4096
	ds_read_b128 v[52:55], v142 offset:5120
	ds_read_b128 v[56:59], v142 offset:6144
	ds_read_b128 v[60:63], v142 offset:7168
	s_add_u32 s78, s56, 0x10080
	s_mov_b32 m0, s66
	s_addc_u32 s79, s57, 0
	global_load_lds_dwordx4 v128, s[78:79]
	s_add_u32 s78, s56, 0x18080
	s_mov_b32 m0, s67
	s_addc_u32 s79, s57, 0
	global_load_lds_dwordx4 v128, s[78:79]
	s_waitcnt vmcnt(8)
	s_waitcnt lgkmcnt(0)
	s_barrier
	s_setprio 1
	v_mfma_f32_16x16x32_bf16 v[64:67], v[0:3], v[32:35], 0
	v_mfma_f32_16x16x32_bf16 v[68:71], v[8:11], v[32:35], 0
	v_mfma_f32_16x16x32_bf16 v[72:75], v[0:3], v[40:43], 0
	v_mfma_f32_16x16x32_bf16 v[76:79], v[8:11], v[40:43], 0
	v_mfma_f32_16x16x32_bf16 v[80:83], v[0:3], v[48:51], 0
	v_mfma_f32_16x16x32_bf16 v[84:87], v[8:11], v[48:51], 0
	v_mfma_f32_16x16x32_bf16 v[88:91], v[0:3], v[56:59], 0
	v_mfma_f32_16x16x32_bf16 v[92:95], v[8:11], v[56:59], 0
	v_mfma_f32_16x16x32_bf16 v[64:67], v[4:7], v[36:39], v[64:67]
	v_mfma_f32_16x16x32_bf16 v[68:71], v[12:15], v[36:39], v[68:71]
	v_mfma_f32_16x16x32_bf16 v[72:75], v[4:7], v[44:47], v[72:75]
	v_mfma_f32_16x16x32_bf16 v[76:79], v[12:15], v[44:47], v[76:79]
	v_mfma_f32_16x16x32_bf16 v[80:83], v[4:7], v[52:55], v[80:83]
	v_mfma_f32_16x16x32_bf16 v[84:87], v[12:15], v[52:55], v[84:87]
	v_mfma_f32_16x16x32_bf16 v[88:91], v[4:7], v[60:63], v[88:91]
	v_mfma_f32_16x16x32_bf16 v[92:95], v[12:15], v[60:63], v[92:95]
	v_mfma_f32_16x16x32_bf16 v[96:99], v[16:19], v[32:35], 0
	v_mfma_f32_16x16x32_bf16 v[32:35], v[24:27], v[32:35], 0
	v_mfma_f32_16x16x32_bf16 v[96:99], v[20:23], v[36:39], v[96:99]
	v_mfma_f32_16x16x32_bf16 v[32:35], v[28:31], v[36:39], v[32:35]
	v_mfma_f32_16x16x32_bf16 v[36:39], v[16:19], v[40:43], 0
	v_mfma_f32_16x16x32_bf16 v[40:43], v[24:27], v[40:43], 0
	v_mfma_f32_16x16x32_bf16 v[36:39], v[20:23], v[44:47], v[36:39]
	v_mfma_f32_16x16x32_bf16 v[40:43], v[28:31], v[44:47], v[40:43]
	v_mfma_f32_16x16x32_bf16 v[44:47], v[16:19], v[48:51], 0
	v_mfma_f32_16x16x32_bf16 v[48:51], v[24:27], v[48:51], 0
	v_mfma_f32_16x16x32_bf16 v[44:47], v[20:23], v[52:55], v[44:47]
	v_mfma_f32_16x16x32_bf16 v[48:51], v[28:31], v[52:55], v[48:51]
	v_mfma_f32_16x16x32_bf16 v[52:55], v[16:19], v[56:59], 0
	v_mfma_f32_16x16x32_bf16 v[56:59], v[24:27], v[56:59], 0
	v_mfma_f32_16x16x32_bf16 v[52:55], v[20:23], v[60:63], v[52:55]
	v_mfma_f32_16x16x32_bf16 v[56:59], v[28:31], v[60:63], v[56:59]
	s_setprio 0
	s_barrier
	ds_read_b128 v[60:63], v142 offset:16384
	ds_read_b128 v[100:103], v142 offset:17408
	ds_read_b128 v[104:107], v142 offset:18432
	ds_read_b128 v[108:111], v142 offset:19456
	ds_read_b128 v[112:115], v142 offset:20480
	ds_read_b128 v[116:119], v142 offset:21504
	ds_read_b128 v[120:123], v142 offset:22528
	ds_read_b128 v[124:127], v142 offset:23552
	s_mov_b32 m0, s33
	s_nop 0
	global_load_lds_dwordx4 v138, s[76:77]
	s_add_u32 s76, s58, 0x8100
	s_mov_b32 m0, s34
	s_addc_u32 s77, s59, 0
	global_load_lds_dwordx4 v138, s[76:77]
	s_add_u32 s76, s58, 0x10100
	s_mov_b32 m0, s35
	s_addc_u32 s77, s59, 0
	global_load_lds_dwordx4 v138, s[76:77]
	s_add_u32 s76, s58, 0x18100
	s_mov_b32 m0, s36
	s_addc_u32 s77, s59, 0
	global_load_lds_dwordx4 v138, s[76:77]
	s_mov_b32 m0, s24
	s_nop 0
	global_load_lds_dwordx4 v128, s[22:23]
	s_add_u32 s22, s56, 0x8100
	s_mov_b32 m0, s37
	s_addc_u32 s23, s57, 0
	global_load_lds_dwordx4 v128, s[22:23]
	s_waitcnt vmcnt(8)
	s_waitcnt lgkmcnt(0)
	s_barrier
	s_setprio 1
	v_mfma_f32_16x16x32_bf16 v[144:147], v[0:3], v[60:63], 0
	v_mfma_f32_16x16x32_bf16 v[152:155], v[0:3], v[104:107], 0
	v_mfma_f32_16x16x32_bf16 v[178:181], v[0:3], v[112:115], 0
	v_mfma_f32_16x16x32_bf16 v[0:3], v[0:3], v[120:123], 0
	v_mfma_f32_16x16x32_bf16 v[144:147], v[4:7], v[100:103], v[144:147]
	v_mfma_f32_16x16x32_bf16 v[152:155], v[4:7], v[108:111], v[152:155]
	v_mfma_f32_16x16x32_bf16 v[178:181], v[4:7], v[116:119], v[178:181]
	v_mfma_f32_16x16x32_bf16 v[0:3], v[4:7], v[124:127], v[0:3]
	v_mfma_f32_16x16x32_bf16 v[4:7], v[8:11], v[120:123], 0
	v_mfma_f32_16x16x32_bf16 v[148:151], v[8:11], v[60:63], 0
	v_mfma_f32_16x16x32_bf16 v[172:175], v[8:11], v[104:107], 0
	v_mfma_f32_16x16x32_bf16 v[182:185], v[8:11], v[112:115], 0
	v_mfma_f32_16x16x32_bf16 v[4:7], v[12:15], v[124:127], v[4:7]
	v_mfma_f32_16x16x32_bf16 v[148:151], v[12:15], v[100:103], v[148:151]
	v_mfma_f32_16x16x32_bf16 v[172:175], v[12:15], v[108:111], v[172:175]
	v_mfma_f32_16x16x32_bf16 v[182:185], v[12:15], v[116:119], v[182:185]
	v_mfma_f32_16x16x32_bf16 v[8:11], v[16:19], v[60:63], 0
	v_mfma_f32_16x16x32_bf16 v[12:15], v[24:27], v[60:63], 0
	v_mfma_f32_16x16x32_bf16 v[8:11], v[20:23], v[100:103], v[8:11]
	v_mfma_f32_16x16x32_bf16 v[12:15], v[28:31], v[100:103], v[12:15]
	v_mfma_f32_16x16x32_bf16 v[60:63], v[16:19], v[104:107], 0
	v_mfma_f32_16x16x32_bf16 v[100:103], v[24:27], v[104:107], 0
	v_mfma_f32_16x16x32_bf16 v[104:107], v[16:19], v[112:115], 0
	v_mfma_f32_16x16x32_bf16 v[16:19], v[16:19], v[120:123], 0
	v_mfma_f32_16x16x32_bf16 v[60:63], v[20:23], v[108:111], v[60:63]
	v_mfma_f32_16x16x32_bf16 v[100:103], v[28:31], v[108:111], v[100:103]
	v_mfma_f32_16x16x32_bf16 v[104:107], v[20:23], v[116:119], v[104:107]
	v_mfma_f32_16x16x32_bf16 v[108:111], v[24:27], v[112:115], 0
	v_mfma_f32_16x16x32_bf16 v[16:19], v[20:23], v[124:127], v[16:19]
	v_mfma_f32_16x16x32_bf16 v[20:23], v[24:27], v[120:123], 0
	v_mfma_f32_16x16x32_bf16 v[108:111], v[28:31], v[116:119], v[108:111]
	v_mfma_f32_16x16x32_bf16 v[20:23], v[28:31], v[124:127], v[20:23]
	s_setprio 0
	s_barrier
; #define PG8_STAGE(bufoff, gbase, voff, p64) do { _Pragma("unroll") for (int _i = 0; _i < 2; ++_i) { \
;         const char* _gb = (const char*)(gbase) + (size_t)_i * (p64); const unsigned _la = ldsbase + (unsigned)(bufoff) + (unsigned)_i * 8192u; \
;         asm volatile("s_mov_b32 m0, %0\n\ts_nop 0\n\tglobal_load_lds_dwordx4 %1, %2" :: "s"(_la), "v"(voff), "s"(_gb) : "memory"); } } while (0)
; #define PG8_LDA(dst, b, h) do { _Pragma("unroll") for (int m = 0; m < 4; ++m) _Pragma("unroll") for (int k = 0; k < 2; ++k) dst[m][k] = *(const LAS bf16x8*)(lds + PG8_SA(b, h) + aoff + m * 2048 + k * 1024); } while (0)
; #define PG8_LDB(dst, b, h) do { _Pragma("unroll") for (int n = 0; n < 2; ++n) _Pragma("unroll") for (int k = 0; k < 2; ++k) dst[n][k] = *(const LAS bf16x8*)(lds + PG8_SB(b, h) + boff + n * 2048 + k * 1024); } while (0)
; #define PG8_MMA(ai, bj, At, Bt) do { __builtin_amdgcn_s_setprio(1); _Pragma("unroll") for (int m = 0; m < 4; ++m) _Pragma("unroll") for (int n = 0; n < 2; ++n) _Pragma("unroll") for (int k = 0; k < 2; ++k) \
;         acc[ai][bj][m][n] = __builtin_amdgcn_mfma_f32_16x16x32_bf16(Bt[n][k], At[m][k], acc[ai][bj][m][n], 0, 0, 0); __builtin_amdgcn_s_setprio(0); } while (0)
; #define PG8_WAIT_V(n) asm volatile("s_waitcnt vmcnt(" #n ")" ::: "memory")
; #define PG8_WAIT_L(n) asm volatile("s_waitcnt lgkmcnt(" #n ")" ::: "memory")
; #define PG8_BAR __builtin_amdgcn_s_barrier()
; #define PG8_SCHED __builtin_amdgcn_sched_barrier(0)
; template <class Epi, class Sched>
; __device__ __forceinline__ void gemm_phase(LAS unsigned char* lds, const Sched& S, const Epi& E) {
;     ...
;             PG8_LDB(B0, 1, 0); PG8_LDB(B1, 1, 1); PG8_SCHED; PG8_LDA(At, 1, 0); PG8_STAGE(PG8_SA(0, 1), a2 + hA2, vA2, hA2 / 2);
;             PG8_WAIT_V(8); PG8_WAIT_L(0); PG8_BAR; PG8_MMA(0, 0, At, B0); PG8_MMA(0, 1, At, B1); PG8_BAR; PG8_SCHED;
;             PG8_LDA(At, 1, 1); PG8_STAGE(PG8_SB(1, 0), b3, vB2, hB2 / 2); PG8_STAGE(PG8_SB(1, 1), b3 + hB2, vB2, hB2 / 2); PG8_STAGE(PG8_SA(1, 0), a3, vA2, hA2 / 2);
;             PG8_WAIT_V(8); PG8_WAIT_L(0); PG8_BAR; PG8_MMA(1, 0, At, B0); PG8_MMA(1, 1, At, B1); PG8_BAR; PG8_SCHED;
	v_add_u32_e32 v132, 0x18000, v141
	v_add_u32_e32 v133, 0x1c000, v141
	ds_read_b128 v[24:27], v132
	ds_read_b128 v[28:31], v132 offset:1024
	ds_read_b128 v[112:115], v132 offset:2048
	ds_read_b128 v[116:119], v132 offset:3072
	ds_read_b128 v[120:123], v133
	ds_read_b128 v[124:127], v133 offset:1024
	ds_read_b128 v[186:189], v133 offset:2048
	ds_read_b128 v[190:193], v133 offset:3072
	ds_read_b128 v[194:197], v142 offset:32768
	ds_read_b128 v[198:201], v142 offset:33792
	ds_read_b128 v[202:205], v142 offset:34816
	ds_read_b128 v[206:209], v142 offset:35840
	ds_read_b128 v[210:213], v142 offset:36864
	ds_read_b128 v[214:217], v142 offset:37888
	ds_read_b128 v[218:221], v142 offset:38912
	ds_read_b128 v[222:225], v142 offset:39936
	s_add_u32 s22, s56, 0x10100
	s_mov_b32 m0, s42
	s_addc_u32 s23, s57, 0
	global_load_lds_dwordx4 v128, s[22:23]
	s_add_u32 s22, s56, 0x18100
	s_mov_b32 m0, s44
	s_addc_u32 s23, s57, 0
	global_load_lds_dwordx4 v128, s[22:23]
	s_waitcnt vmcnt(8)
	s_waitcnt lgkmcnt(0)
	s_barrier
	s_setprio 1
	v_mfma_f32_16x16x32_bf16 v[64:67], v[24:27], v[194:197], v[64:67]
	v_mfma_f32_16x16x32_bf16 v[68:71], v[112:115], v[194:197], v[68:71]
	v_mfma_f32_16x16x32_bf16 v[72:75], v[24:27], v[202:205], v[72:75]
	v_mfma_f32_16x16x32_bf16 v[76:79], v[112:115], v[202:205], v[76:79]
	v_mfma_f32_16x16x32_bf16 v[80:83], v[24:27], v[210:213], v[80:83]
	v_mfma_f32_16x16x32_bf16 v[84:87], v[112:115], v[210:213], v[84:87]
	v_mfma_f32_16x16x32_bf16 v[88:91], v[24:27], v[218:221], v[88:91]
	v_mfma_f32_16x16x32_bf16 v[92:95], v[112:115], v[218:221], v[92:95]
	v_mfma_f32_16x16x32_bf16 v[64:67], v[28:31], v[198:201], v[64:67]
	v_mfma_f32_16x16x32_bf16 v[68:71], v[116:119], v[198:201], v[68:71]
	v_mfma_f32_16x16x32_bf16 v[72:75], v[28:31], v[206:209], v[72:75]
	v_mfma_f32_16x16x32_bf16 v[76:79], v[116:119], v[206:209], v[76:79]
	v_mfma_f32_16x16x32_bf16 v[80:83], v[28:31], v[214:217], v[80:83]
	v_mfma_f32_16x16x32_bf16 v[84:87], v[116:119], v[214:217], v[84:87]
	v_mfma_f32_16x16x32_bf16 v[88:91], v[28:31], v[222:225], v[88:91]
	v_mfma_f32_16x16x32_bf16 v[92:95], v[116:119], v[222:225], v[92:95]
	v_mfma_f32_16x16x32_bf16 v[96:99], v[120:123], v[194:197], v[96:99]
	v_mfma_f32_16x16x32_bf16 v[32:35], v[186:189], v[194:197], v[32:35]
	v_mfma_f32_16x16x32_bf16 v[36:39], v[120:123], v[202:205], v[36:39]
	v_mfma_f32_16x16x32_bf16 v[40:43], v[186:189], v[202:205], v[40:43]
	v_mfma_f32_16x16x32_bf16 v[44:47], v[120:123], v[210:213], v[44:47]
	v_mfma_f32_16x16x32_bf16 v[48:51], v[186:189], v[210:213], v[48:51]
	v_mfma_f32_16x16x32_bf16 v[52:55], v[120:123], v[218:221], v[52:55]
	v_mfma_f32_16x16x32_bf16 v[56:59], v[186:189], v[218:221], v[56:59]
	v_mfma_f32_16x16x32_bf16 v[96:99], v[124:127], v[198:201], v[96:99]
	v_mfma_f32_16x16x32_bf16 v[32:35], v[190:193], v[198:201], v[32:35]
	v_mfma_f32_16x16x32_bf16 v[36:39], v[124:127], v[206:209], v[36:39]
	v_mfma_f32_16x16x32_bf16 v[40:43], v[190:193], v[206:209], v[40:43]
	v_mfma_f32_16x16x32_bf16 v[44:47], v[124:127], v[214:217], v[44:47]
	v_mfma_f32_16x16x32_bf16 v[48:51], v[190:193], v[214:217], v[48:51]
	v_mfma_f32_16x16x32_bf16 v[52:55], v[124:127], v[222:225], v[52:55]
	v_mfma_f32_16x16x32_bf16 v[56:59], v[190:193], v[222:225], v[56:59]
	s_setprio 0
	s_barrier
	s_add_u32 s22, s58, 0x180
	s_addc_u32 s23, s59, 0
	ds_read_b128 v[194:197], v142 offset:49152
	ds_read_b128 v[198:201], v142 offset:50176
	ds_read_b128 v[202:205], v142 offset:51200
	ds_read_b128 v[206:209], v142 offset:52224
	ds_read_b128 v[210:213], v142 offset:53248
	ds_read_b128 v[214:217], v142 offset:54272
	ds_read_b128 v[218:221], v142 offset:55296
	ds_read_b128 v[222:225], v142 offset:56320
	s_mov_b32 m0, s51
	s_nop 0
	global_load_lds_dwordx4 v138, s[22:23]
	s_add_u32 s22, s58, 0x8180
	s_mov_b32 m0, s61
	s_addc_u32 s23, s59, 0
	global_load_lds_dwordx4 v138, s[22:23]
	s_add_u32 s22, s58, 0x10180
	s_mov_b32 m0, s64
	s_addc_u32 s23, s59, 0
	global_load_lds_dwordx4 v138, s[22:23]
	s_add_u32 s22, s58, 0x18180
	s_mov_b32 m0, s65
	s_addc_u32 s23, s59, 0
	global_load_lds_dwordx4 v138, s[22:23]
	s_mov_b32 m0, s62
	s_nop 0
	global_load_lds_dwordx4 v128, s[16:17]
	s_add_u32 s16, s56, 0x8180
	s_mov_b32 m0, s63
	s_addc_u32 s17, s57, 0
	global_load_lds_dwordx4 v128, s[16:17]
	s_waitcnt vmcnt(8)
	s_waitcnt lgkmcnt(0)
	s_barrier
	s_setprio 1
	v_mfma_f32_16x16x32_bf16 v[0:3], v[24:27], v[218:221], v[0:3]
	v_mfma_f32_16x16x32_bf16 v[4:7], v[112:115], v[218:221], v[4:7]
	v_mfma_f32_16x16x32_bf16 v[144:147], v[24:27], v[194:197], v[144:147]
	v_mfma_f32_16x16x32_bf16 v[148:151], v[112:115], v[194:197], v[148:151]
	v_mfma_f32_16x16x32_bf16 v[152:155], v[24:27], v[202:205], v[152:155]
	v_mfma_f32_16x16x32_bf16 v[172:175], v[112:115], v[202:205], v[172:175]
	v_mfma_f32_16x16x32_bf16 v[178:181], v[24:27], v[210:213], v[178:181]
	v_mfma_f32_16x16x32_bf16 v[182:185], v[112:115], v[210:213], v[182:185]
	v_mfma_f32_16x16x32_bf16 v[0:3], v[28:31], v[222:225], v[0:3]
	v_mfma_f32_16x16x32_bf16 v[4:7], v[116:119], v[222:225], v[4:7]
	v_mfma_f32_16x16x32_bf16 v[144:147], v[28:31], v[198:201], v[144:147]
	v_mfma_f32_16x16x32_bf16 v[148:151], v[116:119], v[198:201], v[148:151]
	v_mfma_f32_16x16x32_bf16 v[152:155], v[28:31], v[206:209], v[152:155]
	v_mfma_f32_16x16x32_bf16 v[172:175], v[116:119], v[206:209], v[172:175]
	v_mfma_f32_16x16x32_bf16 v[178:181], v[28:31], v[214:217], v[178:181]
	v_mfma_f32_16x16x32_bf16 v[182:185], v[116:119], v[214:217], v[182:185]
	v_mfma_f32_16x16x32_bf16 v[8:11], v[120:123], v[194:197], v[8:11]
	v_mfma_f32_16x16x32_bf16 v[12:15], v[186:189], v[194:197], v[12:15]
	v_mfma_f32_16x16x32_bf16 v[24:27], v[120:123], v[202:205], v[60:63]
	v_mfma_f32_16x16x32_bf16 v[28:31], v[186:189], v[202:205], v[100:103]
	v_mfma_f32_16x16x32_bf16 v[60:63], v[120:123], v[210:213], v[104:107]
	v_mfma_f32_16x16x32_bf16 v[100:103], v[186:189], v[210:213], v[108:111]
	v_mfma_f32_16x16x32_bf16 v[16:19], v[120:123], v[218:221], v[16:19]
	v_mfma_f32_16x16x32_bf16 v[20:23], v[186:189], v[218:221], v[20:23]
	v_mfma_f32_16x16x32_bf16 v[8:11], v[124:127], v[198:201], v[8:11]
	v_mfma_f32_16x16x32_bf16 v[12:15], v[190:193], v[198:201], v[12:15]
	v_mfma_f32_16x16x32_bf16 v[24:27], v[124:127], v[206:209], v[24:27]
	v_mfma_f32_16x16x32_bf16 v[28:31], v[190:193], v[206:209], v[28:31]
	v_mfma_f32_16x16x32_bf16 v[60:63], v[124:127], v[214:217], v[60:63]
	v_mfma_f32_16x16x32_bf16 v[100:103], v[190:193], v[214:217], v[100:103]
	v_mfma_f32_16x16x32_bf16 v[16:19], v[124:127], v[222:225], v[16:19]
	v_mfma_f32_16x16x32_bf16 v[20:23], v[190:193], v[222:225], v[20:23]
	s_setprio 0
	s_barrier
; #define PG8_STAGE(bufoff, gbase, voff, p64) do { _Pragma("unroll") for (int _i = 0; _i < 2; ++_i) { \
;         const char* _gb = (const char*)(gbase) + (size_t)_i * (p64); const unsigned _la = ldsbase + (unsigned)(bufoff) + (unsigned)_i * 8192u; \
;         asm volatile("s_mov_b32 m0, %0\n\ts_nop 0\n\tglobal_load_lds_dwordx4 %1, %2" :: "s"(_la), "v"(voff), "s"(_gb) : "memory"); } } while (0)
; #define PG8_LDA(dst, b, h) do { _Pragma("unroll") for (int m = 0; m < 4; ++m) _Pragma("unroll") for (int k = 0; k < 2; ++k) dst[m][k] = *(const LAS bf16x8*)(lds + PG8_SA(b, h) + aoff + m * 2048 + k * 1024); } while (0)
; #define PG8_LDB(dst, b, h) do { _Pragma("unroll") for (int n = 0; n < 2; ++n) _Pragma("unroll") for (int k = 0; k < 2; ++k) dst[n][k] = *(const LAS bf16x8*)(lds + PG8_SB(b, h) + boff + n * 2048 + k * 1024); } while (0)
; #define PG8_MMA(ai, bj, At, Bt) do { __builtin_amdgcn_s_setprio(1); _Pragma("unroll") for (int m = 0; m < 4; ++m) _Pragma("unroll") for (int n = 0; n < 2; ++n) _Pragma("unroll") for (int k = 0; k < 2; ++k) \
;         acc[ai][bj][m][n] = __builtin_amdgcn_mfma_f32_16x16x32_bf16(Bt[n][k], At[m][k], acc[ai][bj][m][n], 0, 0, 0); __builtin_amdgcn_s_setprio(0); } while (0)
; #define PG8_WAIT_V(n) asm volatile("s_waitcnt vmcnt(" #n ")" ::: "memory")
; #define PG8_WAIT_L(n) asm volatile("s_waitcnt lgkmcnt(" #n ")" ::: "memory")
; #define PG8_BAR __builtin_amdgcn_s_barrier()
; #define PG8_SCHED __builtin_amdgcn_sched_barrier(0)
; template <class Epi, class Sched>
; __device__ __forceinline__ void gemm_phase(LAS unsigned char* lds, const Sched& S, const Epi& E) {
;     ...
;             PG8_LDB(B0, 0, 0); PG8_LDB(B1, 0, 1); PG8_SCHED; PG8_LDA(At, 0, 0); PG8_STAGE(PG8_SA(1, 1), a1 + hA, voffA, hA / 2);
;             PG8_WAIT_V(8); PG8_WAIT_L(0); PG8_BAR; PG8_MMA(0, 0, At, B0); PG8_MMA(0, 1, At, B1); PG8_BAR; PG8_SCHED;
;             PG8_LDA(At, 0, 1); PG8_STAGE(PG8_SB(0, 0), b2, vB2, hB2 / 2); PG8_STAGE(PG8_SB(0, 1), b2 + hB2, vB2, hB2 / 2); PG8_STAGE(PG8_SA(0, 0), a2, vA2, hA2 / 2);
;             PG8_WAIT_V(8); PG8_WAIT_L(0); PG8_BAR; PG8_MMA(1, 0, At, B0); PG8_MMA(1, 1, At, B1); PG8_BAR; PG8_SCHED;
	ds_read_b128 v[104:107], v130
	ds_read_b128 v[108:111], v130 offset:1024
	ds_read_b128 v[112:115], v130 offset:2048
	ds_read_b128 v[116:119], v130 offset:3072
	ds_read_b128 v[120:123], v131
	ds_read_b128 v[124:127], v131 offset:1024
	ds_read_b128 v[186:189], v131 offset:2048
	ds_read_b128 v[190:193], v131 offset:3072
	s_add_u32 s16, s38, 0x80
	s_addc_u32 s17, s39, 0
	ds_read_b128 v[194:197], v142
	ds_read_b128 v[198:201], v142 offset:1024
	ds_read_b128 v[202:205], v142 offset:2048
	ds_read_b128 v[206:209], v142 offset:3072
	ds_read_b128 v[210:213], v142 offset:4096
	ds_read_b128 v[214:217], v142 offset:5120
	ds_read_b128 v[218:221], v142 offset:6144
	ds_read_b128 v[222:225], v142 offset:7168
	s_add_u32 s22, s56, 0x10180
	s_mov_b32 m0, s66
	s_addc_u32 s23, s57, 0
	global_load_lds_dwordx4 v128, s[22:23]
	s_add_u32 s22, s56, 0x18180
	s_mov_b32 m0, s67
	s_addc_u32 s23, s57, 0
	global_load_lds_dwordx4 v128, s[22:23]
	s_waitcnt vmcnt(8)
	s_waitcnt lgkmcnt(0)
	s_barrier
	s_setprio 1
	v_mfma_f32_16x16x32_bf16 v[64:67], v[104:107], v[194:197], v[64:67]
	v_mfma_f32_16x16x32_bf16 v[68:71], v[112:115], v[194:197], v[68:71]
	v_mfma_f32_16x16x32_bf16 v[72:75], v[104:107], v[202:205], v[72:75]
	v_mfma_f32_16x16x32_bf16 v[76:79], v[112:115], v[202:205], v[76:79]
	v_mfma_f32_16x16x32_bf16 v[80:83], v[104:107], v[210:213], v[80:83]
	v_mfma_f32_16x16x32_bf16 v[84:87], v[112:115], v[210:213], v[84:87]
	v_mfma_f32_16x16x32_bf16 v[88:91], v[104:107], v[218:221], v[88:91]
	v_mfma_f32_16x16x32_bf16 v[92:95], v[112:115], v[218:221], v[92:95]
	v_mfma_f32_16x16x32_bf16 v[64:67], v[108:111], v[198:201], v[64:67]
	v_mfma_f32_16x16x32_bf16 v[68:71], v[116:119], v[198:201], v[68:71]
	v_mfma_f32_16x16x32_bf16 v[72:75], v[108:111], v[206:209], v[72:75]
	v_mfma_f32_16x16x32_bf16 v[76:79], v[116:119], v[206:209], v[76:79]
	v_mfma_f32_16x16x32_bf16 v[80:83], v[108:111], v[214:217], v[80:83]
	v_mfma_f32_16x16x32_bf16 v[84:87], v[116:119], v[214:217], v[84:87]
	v_mfma_f32_16x16x32_bf16 v[88:91], v[108:111], v[222:225], v[88:91]
	v_mfma_f32_16x16x32_bf16 v[92:95], v[116:119], v[222:225], v[92:95]
	v_mfma_f32_16x16x32_bf16 v[32:35], v[186:189], v[194:197], v[32:35]
	v_mfma_f32_16x16x32_bf16 v[96:99], v[120:123], v[194:197], v[96:99]
	v_mfma_f32_16x16x32_bf16 v[194:197], v[190:193], v[198:201], v[32:35]
	v_mfma_f32_16x16x32_bf16 v[32:35], v[120:123], v[202:205], v[36:39]
	v_mfma_f32_16x16x32_bf16 v[96:99], v[124:127], v[198:201], v[96:99]
	v_mfma_f32_16x16x32_bf16 v[198:201], v[124:127], v[206:209], v[32:35]
	v_mfma_f32_16x16x32_bf16 v[32:35], v[186:189], v[202:205], v[40:43]
	v_mfma_f32_16x16x32_bf16 v[40:43], v[190:193], v[206:209], v[32:35]
	v_mfma_f32_16x16x32_bf16 v[32:35], v[120:123], v[210:213], v[44:47]
	v_mfma_f32_16x16x32_bf16 v[44:47], v[124:127], v[214:217], v[32:35]
	v_mfma_f32_16x16x32_bf16 v[32:35], v[186:189], v[210:213], v[48:51]
	v_mfma_f32_16x16x32_bf16 v[202:205], v[190:193], v[214:217], v[32:35]
	v_mfma_f32_16x16x32_bf16 v[32:35], v[120:123], v[218:221], v[52:55]
	v_mfma_f32_16x16x32_bf16 v[206:209], v[124:127], v[222:225], v[32:35]
	v_mfma_f32_16x16x32_bf16 v[32:35], v[186:189], v[218:221], v[56:59]
	v_mfma_f32_16x16x32_bf16 v[210:213], v[190:193], v[222:225], v[32:35]
	s_setprio 0
	s_barrier
	s_add_u32 s22, s40, 0x8000
	s_nop 3
	ds_read_b128 v[32:35], v142 offset:16384
	ds_read_b128 v[36:39], v142 offset:17408
	ds_read_b128 v[48:51], v142 offset:18432
	ds_read_b128 v[52:55], v142 offset:19456
	ds_read_b128 v[56:59], v142 offset:20480
	ds_read_b128 v[214:217], v142 offset:21504
	ds_read_b128 v[218:221], v142 offset:22528
	ds_read_b128 v[222:225], v142 offset:23552
	s_mov_b32 m0, s33
	s_nop 0
	global_load_lds_dwordx4 v138, s[40:41]
	s_mov_b32 m0, s34
	s_addc_u32 s23, s41, 0
	global_load_lds_dwordx4 v138, s[22:23]
	s_add_u32 s22, s40, 0x10000
	s_mov_b32 m0, s35
	s_addc_u32 s23, s41, 0
	global_load_lds_dwordx4 v138, s[22:23]
	s_add_u32 s22, s40, 0x18000
	s_mov_b32 m0, s36
	s_addc_u32 s23, s41, 0
	global_load_lds_dwordx4 v138, s[22:23]
	s_mov_b32 m0, s24
	s_nop 0
	global_load_lds_dwordx4 v128, s[38:39]
	s_add_u32 s22, s38, 0x8000
	s_mov_b32 m0, s37
	s_addc_u32 s23, s39, 0
	global_load_lds_dwordx4 v128, s[22:23]
	s_waitcnt vmcnt(8)
	s_waitcnt lgkmcnt(0)
	s_barrier
	s_setprio 1
	v_mfma_f32_16x16x32_bf16 v[0:3], v[104:107], v[218:221], v[0:3]
	v_mfma_f32_16x16x32_bf16 v[144:147], v[104:107], v[32:35], v[144:147]
	v_mfma_f32_16x16x32_bf16 v[152:155], v[104:107], v[48:51], v[152:155]
	v_mfma_f32_16x16x32_bf16 v[178:181], v[104:107], v[56:59], v[178:181]
	v_mfma_f32_16x16x32_bf16 v[104:107], v[108:111], v[222:225], v[0:3]
	v_mfma_f32_16x16x32_bf16 v[0:3], v[112:115], v[218:221], v[4:7]
	v_mfma_f32_16x16x32_bf16 v[144:147], v[108:111], v[36:39], v[144:147]
	v_mfma_f32_16x16x32_bf16 v[148:151], v[112:115], v[32:35], v[148:151]
	v_mfma_f32_16x16x32_bf16 v[152:155], v[108:111], v[52:55], v[152:155]
	v_mfma_f32_16x16x32_bf16 v[172:175], v[112:115], v[48:51], v[172:175]
	v_mfma_f32_16x16x32_bf16 v[178:181], v[108:111], v[214:217], v[178:181]
	v_mfma_f32_16x16x32_bf16 v[182:185], v[112:115], v[56:59], v[182:185]
	v_mfma_f32_16x16x32_bf16 v[108:111], v[116:119], v[222:225], v[0:3]
	v_mfma_f32_16x16x32_bf16 v[148:151], v[116:119], v[36:39], v[148:151]
	v_mfma_f32_16x16x32_bf16 v[172:175], v[116:119], v[52:55], v[172:175]
	v_mfma_f32_16x16x32_bf16 v[182:185], v[116:119], v[214:217], v[182:185]
	v_mfma_f32_16x16x32_bf16 v[0:3], v[120:123], v[32:35], v[8:11]
	v_mfma_f32_16x16x32_bf16 v[112:115], v[124:127], v[36:39], v[0:3]
	v_mfma_f32_16x16x32_bf16 v[0:3], v[186:189], v[32:35], v[12:15]
	v_mfma_f32_16x16x32_bf16 v[116:119], v[190:193], v[36:39], v[0:3]
	v_mfma_f32_16x16x32_bf16 v[0:3], v[120:123], v[48:51], v[24:27]
	v_mfma_f32_16x16x32_bf16 v[226:229], v[124:127], v[52:55], v[0:3]
	v_mfma_f32_16x16x32_bf16 v[0:3], v[186:189], v[48:51], v[28:31]
	v_mfma_f32_16x16x32_bf16 v[230:233], v[190:193], v[52:55], v[0:3]
	v_mfma_f32_16x16x32_bf16 v[0:3], v[120:123], v[56:59], v[60:63]
	v_mfma_f32_16x16x32_bf16 v[234:237], v[124:127], v[214:217], v[0:3]
	v_mfma_f32_16x16x32_bf16 v[0:3], v[186:189], v[56:59], v[100:103]
	v_mfma_f32_16x16x32_bf16 v[214:217], v[190:193], v[214:217], v[0:3]
	v_mfma_f32_16x16x32_bf16 v[0:3], v[120:123], v[218:221], v[16:19]
	v_mfma_f32_16x16x32_bf16 v[238:241], v[124:127], v[222:225], v[0:3]
	v_mfma_f32_16x16x32_bf16 v[0:3], v[186:189], v[218:221], v[20:23]
	v_mfma_f32_16x16x32_bf16 v[186:189], v[190:193], v[222:225], v[0:3]
	s_setprio 0
	s_barrier
; #define PG8_STAGE(bufoff, gbase, voff, p64) do { _Pragma("unroll") for (int _i = 0; _i < 2; ++_i) { \
;         const char* _gb = (const char*)(gbase) + (size_t)_i * (p64); const unsigned _la = ldsbase + (unsigned)(bufoff) + (unsigned)_i * 8192u; \
;         asm volatile("s_mov_b32 m0, %0\n\ts_nop 0\n\tglobal_load_lds_dwordx4 %1, %2" :: "s"(_la), "v"(voff), "s"(_gb) : "memory"); } } while (0)
; #define PG8_LDA(dst, b, h) do { _Pragma("unroll") for (int m = 0; m < 4; ++m) _Pragma("unroll") for (int k = 0; k < 2; ++k) dst[m][k] = *(const LAS bf16x8*)(lds + PG8_SA(b, h) + aoff + m * 2048 + k * 1024); } while (0)
; #define PG8_LDB(dst, b, h) do { _Pragma("unroll") for (int n = 0; n < 2; ++n) _Pragma("unroll") for (int k = 0; k < 2; ++k) dst[n][k] = *(const LAS bf16x8*)(lds + PG8_SB(b, h) + boff + n * 2048 + k * 1024); } while (0)
; #define PG8_MMA(ai, bj, At, Bt) do { __builtin_amdgcn_s_setprio(1); _Pragma("unroll") for (int m = 0; m < 4; ++m) _Pragma("unroll") for (int n = 0; n < 2; ++n) _Pragma("unroll") for (int k = 0; k < 2; ++k) \
;         acc[ai][bj][m][n] = __builtin_amdgcn_mfma_f32_16x16x32_bf16(Bt[n][k], At[m][k], acc[ai][bj][m][n], 0, 0, 0); __builtin_amdgcn_s_setprio(0); } while (0)
; #define PG8_WAIT_V(n) asm volatile("s_waitcnt vmcnt(" #n ")" ::: "memory")
; #define PG8_WAIT_L(n) asm volatile("s_waitcnt lgkmcnt(" #n ")" ::: "memory")
; #define PG8_BAR __builtin_amdgcn_s_barrier()
; #define PG8_SCHED __builtin_amdgcn_sched_barrier(0)
; template <class Epi, class Sched>
; __device__ __forceinline__ void gemm_phase(LAS unsigned char* lds, const Sched& S, const Epi& E) {
;     ...
;             PG8_LDB(B0, 1, 0); PG8_LDB(B1, 1, 1); PG8_SCHED; PG8_LDA(At, 1, 0); PG8_STAGE(PG8_SA(0, 1), a2 + hA2, vA2, hA2 / 2);
;             PG8_WAIT_V(8); PG8_WAIT_L(0); PG8_BAR; PG8_MMA(0, 0, At, B0); PG8_MMA(0, 1, At, B1); PG8_BAR; PG8_SCHED;
;             PG8_LDA(At, 1, 1); PG8_STAGE(PG8_SB(1, 0), b3, vB2, hB2 / 2); PG8_STAGE(PG8_SB(1, 1), b3 + hB2, vB2, hB2 / 2); PG8_STAGE(PG8_SA(1, 0), a3, vA2, hA2 / 2);
;             PG8_WAIT_V(8); PG8_WAIT_L(0); PG8_BAR; PG8_MMA(1, 0, At, B0); PG8_MMA(1, 1, At, B1); PG8_BAR; PG8_SCHED;
;         }
;         if (wr == 0) PG8_BAR;
	ds_read_b128 v[120:123], v132
	ds_read_b128 v[124:127], v132 offset:1024
	ds_read_b128 v[190:193], v132 offset:2048
	ds_read_b128 v[218:221], v132 offset:3072
	ds_read_b128 v[222:225], v133
	ds_read_b128 v[242:245], v133 offset:1024
	ds_read_b128 v[246:249], v133 offset:2048
	ds_read_b128 v[250:253], v133 offset:3072
	ds_read_b128 v[24:27], v142 offset:32768
	ds_read_b128 v[28:31], v142 offset:33792
	ds_read_b128 v[52:55], v142 offset:34816
	ds_read_b128 v[100:103], v142 offset:35840
	ds_read_b128 v[130:133], v142 offset:36864
	ds_read_b128 v[162:165], v142 offset:37888
	ds_read_b128 v[134:137], v142 offset:38912
	ds_read_b128 v[158:161], v142 offset:39936
	s_add_u32 s22, s38, 0x10000
	s_mov_b32 m0, s42
	s_addc_u32 s23, s39, 0
	global_load_lds_dwordx4 v128, s[22:23]
	s_add_u32 s22, s38, 0x18000
	s_mov_b32 m0, s44
	s_addc_u32 s23, s39, 0
	global_load_lds_dwordx4 v128, s[22:23]
	s_waitcnt vmcnt(8)
	s_waitcnt lgkmcnt(0)
	s_barrier
	s_setprio 1
	v_mfma_f32_16x16x32_bf16 v[0:3], v[120:123], v[24:27], v[64:67]
	v_mfma_f32_16x16x32_bf16 v[32:35], v[124:127], v[28:31], v[0:3]
	v_mfma_f32_16x16x32_bf16 v[0:3], v[190:193], v[24:27], v[68:71]
	v_mfma_f32_16x16x32_bf16 v[36:39], v[218:221], v[28:31], v[0:3]
	v_mfma_f32_16x16x32_bf16 v[0:3], v[120:123], v[52:55], v[72:75]
	v_mfma_f32_16x16x32_bf16 v[16:19], v[124:127], v[100:103], v[0:3]
	v_mfma_f32_16x16x32_bf16 v[0:3], v[190:193], v[52:55], v[76:79]
	v_mfma_f32_16x16x32_bf16 v[20:23], v[218:221], v[100:103], v[0:3]
	v_mfma_f32_16x16x32_bf16 v[0:3], v[120:123], v[130:133], v[80:83]
	v_mfma_f32_16x16x32_bf16 v[8:11], v[124:127], v[162:165], v[0:3]
	v_mfma_f32_16x16x32_bf16 v[0:3], v[190:193], v[130:133], v[84:87]
	v_mfma_f32_16x16x32_bf16 v[12:15], v[218:221], v[162:165], v[0:3]
	v_mfma_f32_16x16x32_bf16 v[0:3], v[120:123], v[134:137], v[88:91]
	v_mfma_f32_16x16x32_bf16 v[4:7], v[190:193], v[134:137], v[92:95]
	v_mfma_f32_16x16x32_bf16 v[0:3], v[124:127], v[158:161], v[0:3]
	v_mfma_f32_16x16x32_bf16 v[4:7], v[218:221], v[158:161], v[4:7]
	v_mfma_f32_16x16x32_bf16 v[48:51], v[222:225], v[24:27], v[96:99]
	v_mfma_f32_16x16x32_bf16 v[24:27], v[246:249], v[24:27], v[194:197]
	v_mfma_f32_16x16x32_bf16 v[60:63], v[250:253], v[28:31], v[24:27]
	v_mfma_f32_16x16x32_bf16 v[24:27], v[222:225], v[52:55], v[198:201]
	v_mfma_f32_16x16x32_bf16 v[56:59], v[242:245], v[28:31], v[48:51]
	v_mfma_f32_16x16x32_bf16 v[48:51], v[242:245], v[100:103], v[24:27]
	v_mfma_f32_16x16x32_bf16 v[24:27], v[246:249], v[52:55], v[40:43]
	v_mfma_f32_16x16x32_bf16 v[52:55], v[250:253], v[100:103], v[24:27]
	v_mfma_f32_16x16x32_bf16 v[24:27], v[222:225], v[130:133], v[44:47]
	v_mfma_f32_16x16x32_bf16 v[40:43], v[242:245], v[162:165], v[24:27]
	v_mfma_f32_16x16x32_bf16 v[24:27], v[246:249], v[130:133], v[202:205]
	v_mfma_f32_16x16x32_bf16 v[44:47], v[250:253], v[162:165], v[24:27]
	v_mfma_f32_16x16x32_bf16 v[24:27], v[222:225], v[134:137], v[206:209]
	v_mfma_f32_16x16x32_bf16 v[28:31], v[246:249], v[134:137], v[210:213]
	v_mfma_f32_16x16x32_bf16 v[24:27], v[242:245], v[158:161], v[24:27]
	v_mfma_f32_16x16x32_bf16 v[28:31], v[250:253], v[158:161], v[28:31]
	s_setprio 0
	s_barrier
	s_add_u32 s22, s40, 0x80
	s_addc_u32 s23, s41, 0
	ds_read_b128 v[88:91], v142 offset:49152
	ds_read_b128 v[92:95], v142 offset:50176
	ds_read_b128 v[130:133], v142 offset:51200
	ds_read_b128 v[134:137], v142 offset:52224
	ds_read_b128 v[158:161], v142 offset:53248
	ds_read_b128 v[162:165], v142 offset:54272
	ds_read_b128 v[194:197], v142 offset:55296
	ds_read_b128 v[198:201], v142 offset:56320
	s_mov_b32 m0, s51
	s_nop 0
	global_load_lds_dwordx4 v138, s[22:23]
	s_add_u32 s22, s40, 0x8080
	s_mov_b32 m0, s61
	s_addc_u32 s23, s41, 0
	global_load_lds_dwordx4 v138, s[22:23]
	s_add_u32 s22, s40, 0x10080
	s_mov_b32 m0, s64
	s_addc_u32 s23, s41, 0
	global_load_lds_dwordx4 v138, s[22:23]
	s_add_u32 s22, s40, 0x18080
	s_mov_b32 m0, s65
	s_addc_u32 s23, s41, 0
	global_load_lds_dwordx4 v138, s[22:23]
	s_mov_b32 m0, s62
	s_nop 0
	global_load_lds_dwordx4 v128, s[16:17]
	s_add_u32 s16, s38, 0x8080
	s_mov_b32 m0, s63
	s_addc_u32 s17, s39, 0
	global_load_lds_dwordx4 v128, s[16:17]
	s_waitcnt vmcnt(8)
	s_waitcnt lgkmcnt(0)
	s_barrier
	s_setprio 1
	v_mfma_f32_16x16x32_bf16 v[64:67], v[120:123], v[88:91], v[144:147]
	v_mfma_f32_16x16x32_bf16 v[96:99], v[124:127], v[92:95], v[64:67]
	v_mfma_f32_16x16x32_bf16 v[64:67], v[190:193], v[88:91], v[148:151]
	v_mfma_f32_16x16x32_bf16 v[100:103], v[218:221], v[92:95], v[64:67]
	v_mfma_f32_16x16x32_bf16 v[64:67], v[120:123], v[130:133], v[152:155]
	v_mfma_f32_16x16x32_bf16 v[80:83], v[124:127], v[134:137], v[64:67]
	v_mfma_f32_16x16x32_bf16 v[64:67], v[190:193], v[130:133], v[172:175]
	v_mfma_f32_16x16x32_bf16 v[84:87], v[218:221], v[134:137], v[64:67]
	v_mfma_f32_16x16x32_bf16 v[64:67], v[120:123], v[158:161], v[178:181]
	v_mfma_f32_16x16x32_bf16 v[72:75], v[124:127], v[162:165], v[64:67]
	v_mfma_f32_16x16x32_bf16 v[64:67], v[190:193], v[158:161], v[182:185]
	v_mfma_f32_16x16x32_bf16 v[76:79], v[218:221], v[162:165], v[64:67]
	v_mfma_f32_16x16x32_bf16 v[64:67], v[120:123], v[194:197], v[104:107]
	v_mfma_f32_16x16x32_bf16 v[68:71], v[190:193], v[194:197], v[108:111]
	v_mfma_f32_16x16x32_bf16 v[64:67], v[124:127], v[198:201], v[64:67]
	v_mfma_f32_16x16x32_bf16 v[68:71], v[218:221], v[198:201], v[68:71]
	v_mfma_f32_16x16x32_bf16 v[104:107], v[222:225], v[88:91], v[112:115]
	v_mfma_f32_16x16x32_bf16 v[88:91], v[246:249], v[88:91], v[116:119]
	v_mfma_f32_16x16x32_bf16 v[124:127], v[250:253], v[92:95], v[88:91]
	v_mfma_f32_16x16x32_bf16 v[88:91], v[222:225], v[130:133], v[226:229]
	v_mfma_f32_16x16x32_bf16 v[112:115], v[242:245], v[134:137], v[88:91]
	v_mfma_f32_16x16x32_bf16 v[88:91], v[246:249], v[130:133], v[230:233]
	v_mfma_f32_16x16x32_bf16 v[116:119], v[250:253], v[134:137], v[88:91]
	v_mfma_f32_16x16x32_bf16 v[88:91], v[222:225], v[158:161], v[234:237]
	v_mfma_f32_16x16x32_bf16 v[120:123], v[242:245], v[92:95], v[104:107]
	v_mfma_f32_16x16x32_bf16 v[104:107], v[242:245], v[162:165], v[88:91]
	v_mfma_f32_16x16x32_bf16 v[88:91], v[246:249], v[158:161], v[214:217]
	v_mfma_f32_16x16x32_bf16 v[108:111], v[250:253], v[162:165], v[88:91]
	v_mfma_f32_16x16x32_bf16 v[88:91], v[222:225], v[194:197], v[238:241]
	v_mfma_f32_16x16x32_bf16 v[92:95], v[246:249], v[194:197], v[186:189]
	v_mfma_f32_16x16x32_bf16 v[88:91], v[242:245], v[198:201], v[88:91]
	v_mfma_f32_16x16x32_bf16 v[92:95], v[250:253], v[198:201], v[92:95]
	s_setprio 0
	s_barrier
	s_andn2_b64 vcc, exec, s[8:9]
	s_cbranch_vccnz .LBB0_681
	s_barrier

; #define PG8_STAGE(bufoff, gbase, voff, p64) do { _Pragma("unroll") for (int _i = 0; _i < 2; ++_i) { \
;         const char* _gb = (const char*)(gbase) + (size_t)_i * (p64); const unsigned _la = ldsbase + (unsigned)(bufoff) + (unsigned)_i * 8192u; \
;         asm volatile("s_mov_b32 m0, %0\n\ts_nop 0\n\tglobal_load_lds_dwordx4 %1, %2" :: "s"(_la), "v"(voff), "s"(_gb) : "memory"); } } while (0)
; #define PG8_LDA(dst, b, h) do { _Pragma("unroll") for (int m = 0; m < 4; ++m) _Pragma("unroll") for (int k = 0; k < 2; ++k) dst[m][k] = *(const LAS bf16x8*)(lds + PG8_SA(b, h) + aoff + m * 2048 + k * 1024); } while (0)
; #define PG8_LDB(dst, b, h) do { _Pragma("unroll") for (int n = 0; n < 2; ++n) _Pragma("unroll") for (int k = 0; k < 2; ++k) dst[n][k] = *(const LAS bf16x8*)(lds + PG8_SB(b, h) + boff + n * 2048 + k * 1024); } while (0)
; #define PG8_MMA(ai, bj, At, Bt) do { __builtin_amdgcn_s_setprio(1); _Pragma("unroll") for (int m = 0; m < 4; ++m) _Pragma("unroll") for (int n = 0; n < 2; ++n) _Pragma("unroll") for (int k = 0; k < 2; ++k) \
;         acc[ai][bj][m][n] = __builtin_amdgcn_mfma_f32_16x16x32_bf16(Bt[n][k], At[m][k], acc[ai][bj][m][n], 0, 0, 0); __builtin_amdgcn_s_setprio(0); } while (0)
; #define PG8_BAR __builtin_amdgcn_s_barrier()
; template <class Epi, class Sched>
; __device__ __forceinline__ void gemm_phase(LAS unsigned char* lds, const Sched& S, const Epi& E) {
;     ...
;         for (int t = 0; t < nt; t += 2) {
;             const bool last = (t == nt - 2);
;             const char* a1 = cA + (size_t)(t + 1) * kstep;
;             const char* a2 = last ? nA : cA + (size_t)(t + 2) * kstep; const char* b2 = last ? nB : cB + (size_t)(t + 2) * kstep;
;             const char* a3 = a2 + kstep; const char* b3 = b2 + kstep;
;             const unsigned vA2 = voffA, vB2 = voffB, hA2 = hA, hB2 = hB;
;             PG8_LDB(B0, 0, 0); PG8_LDB(B1, 0, 1); PG8_SCHED; PG8_LDA(At, 0, 0); PG8_STAGE(PG8_SA(1, 1), a1 + hA, voffA, hA / 2);
;             PG8_WAIT_V(8); PG8_WAIT_L(0); PG8_BAR; PG8_MMA(0, 0, At, B0); PG8_MMA(0, 1, At, B1); PG8_BAR; PG8_SCHED;
;     ...
; #pragma unroll
;             for (int a = 0; a < 2; ++a)
; #pragma unroll
;                 for (int b = 0; b < 2; ++b)
; #pragma unroll
;                     for (int m = 0; m < 4; ++m)
; #pragma unroll
;                         for (int n = 0; n < 2; ++n) acc[a][b][m][n] = (f32x4){0.f, 0.f, 0.f, 0.f};
.LBB0_756:
	s_add_u32 s56, s22, 0x40080
	s_addc_u32 s57, s23, 0
	s_add_u32 s69, s16, 0x100
	s_addc_u32 s72, s17, 0
	s_mov_b32 s73, -2
	v_mov_b64_e32 v[0:1], 0
	v_mov_b64_e32 v[2:3], 0
	v_mov_b64_e32 v[8:9], 0
	v_mov_b64_e32 v[10:11], 0
	v_mov_b64_e32 v[16:17], 0
	v_mov_b64_e32 v[18:19], 0
	v_mov_b64_e32 v[24:25], 0
	v_mov_b64_e32 v[26:27], 0
	v_mov_b64_e32 v[32:33], 0
	v_mov_b64_e32 v[34:35], 0
	v_mov_b64_e32 v[40:41], 0
	v_mov_b64_e32 v[42:43], 0
	v_mov_b64_e32 v[48:49], 0
	v_mov_b64_e32 v[50:51], 0
	v_mov_b64_e32 v[56:57], 0
	v_mov_b64_e32 v[58:59], 0
	v_mov_b64_e32 v[4:5], 0
	v_mov_b64_e32 v[6:7], 0
	v_mov_b64_e32 v[12:13], 0
	v_mov_b64_e32 v[14:15], 0
	v_mov_b64_e32 v[20:21], 0
	v_mov_b64_e32 v[22:23], 0
	v_mov_b64_e32 v[28:29], 0
	v_mov_b64_e32 v[30:31], 0
	v_mov_b64_e32 v[36:37], 0
	v_mov_b64_e32 v[38:39], 0
	v_mov_b64_e32 v[44:45], 0
	v_mov_b64_e32 v[46:47], 0
	v_mov_b64_e32 v[52:53], 0
	v_mov_b64_e32 v[54:55], 0
	v_mov_b64_e32 v[60:61], 0
	v_mov_b64_e32 v[62:63], 0
	v_mov_b64_e32 v[64:65], 0
	v_mov_b64_e32 v[66:67], 0
	v_mov_b64_e32 v[72:73], 0
	v_mov_b64_e32 v[74:75], 0
	v_mov_b64_e32 v[80:81], 0
	v_mov_b64_e32 v[82:83], 0
	v_mov_b64_e32 v[88:89], 0
	v_mov_b64_e32 v[90:91], 0
	v_mov_b64_e32 v[96:97], 0
	v_mov_b64_e32 v[98:99], 0
	v_mov_b64_e32 v[104:105], 0
	v_mov_b64_e32 v[106:107], 0
	v_mov_b64_e32 v[112:113], 0
	v_mov_b64_e32 v[114:115], 0
	v_mov_b64_e32 v[120:121], 0
	v_mov_b64_e32 v[122:123], 0
	v_mov_b64_e32 v[68:69], 0
	v_mov_b64_e32 v[70:71], 0
	v_mov_b64_e32 v[76:77], 0
	v_mov_b64_e32 v[78:79], 0
	v_mov_b64_e32 v[84:85], 0
	v_mov_b64_e32 v[86:87], 0
	v_mov_b64_e32 v[92:93], 0
	v_mov_b64_e32 v[94:95], 0
	v_mov_b64_e32 v[100:101], 0
	v_mov_b64_e32 v[102:103], 0
	v_mov_b64_e32 v[108:109], 0
	v_mov_b64_e32 v[110:111], 0
	v_mov_b64_e32 v[116:117], 0
	v_mov_b64_e32 v[118:119], 0
	v_mov_b64_e32 v[124:125], 0
	v_mov_b64_e32 v[126:127], 0
.LBB0_757:
	v_add_u32_e32 v128, 0x10000, v146
	ds_read_b128 v[130:133], v128
	ds_read_b128 v[134:137], v128 offset:1024
	ds_read_b128 v[138:141], v128 offset:2048
	ds_read_b128 v[148:151], v128 offset:3072
	v_add_u32_e32 v128, 0x14000, v146
	ds_read_b128 v[152:155], v128
	ds_read_b128 v[158:161], v128 offset:1024
	ds_read_b128 v[162:165], v128 offset:2048
	ds_read_b128 v[172:175], v128 offset:3072
	s_add_u32 s16, s56, 0xfffc0080
	s_addc_u32 s17, s57, -1
	s_cmp_eq_u32 s73, 12
	s_cselect_b32 s16, s40, s16
	s_cselect_b32 s17, s41, s17
	s_cselect_b32 s58, s54, s69
	s_cselect_b32 s59, s55, s72
	s_add_u32 s22, s16, 0x80
	s_addc_u32 s23, s17, 0
	ds_read_b128 v[178:181], v147
	ds_read_b128 v[182:185], v147 offset:1024
	ds_read_b128 v[186:189], v147 offset:2048
	ds_read_b128 v[190:193], v147 offset:3072
	ds_read_b128 v[194:197], v147 offset:4096
	ds_read_b128 v[198:201], v147 offset:5120
	ds_read_b128 v[202:205], v147 offset:6144
	ds_read_b128 v[206:209], v147 offset:7168
	s_mov_b32 m0, s62
	s_nop 0
	global_load_lds_dwordx4 v142, s[56:57]
	s_add_u32 s74, s56, 0x20000
	s_mov_b32 m0, s63
	s_addc_u32 s75, s57, 0
	global_load_lds_dwordx4 v142, s[74:75]
	s_waitcnt vmcnt(8)
	s_waitcnt lgkmcnt(0)
	s_barrier
	s_setprio 1
	v_mfma_f32_16x16x32_bf16 v[124:127], v[130:133], v[178:181], v[124:127]
	v_mfma_f32_16x16x32_bf16 v[116:119], v[138:141], v[178:181], v[116:119]
	v_mfma_f32_16x16x32_bf16 v[108:111], v[130:133], v[186:189], v[108:111]
	v_mfma_f32_16x16x32_bf16 v[100:103], v[138:141], v[186:189], v[100:103]
	v_mfma_f32_16x16x32_bf16 v[92:95], v[130:133], v[194:197], v[92:95]
	v_mfma_f32_16x16x32_bf16 v[84:87], v[138:141], v[194:197], v[84:87]
	v_mfma_f32_16x16x32_bf16 v[76:79], v[130:133], v[202:205], v[76:79]
	v_mfma_f32_16x16x32_bf16 v[68:71], v[138:141], v[202:205], v[68:71]
	v_mfma_f32_16x16x32_bf16 v[124:127], v[134:137], v[182:185], v[124:127]
	v_mfma_f32_16x16x32_bf16 v[116:119], v[148:151], v[182:185], v[116:119]
	v_mfma_f32_16x16x32_bf16 v[108:111], v[134:137], v[190:193], v[108:111]
	v_mfma_f32_16x16x32_bf16 v[100:103], v[148:151], v[190:193], v[100:103]
	v_mfma_f32_16x16x32_bf16 v[92:95], v[134:137], v[198:201], v[92:95]
	v_mfma_f32_16x16x32_bf16 v[84:87], v[148:151], v[198:201], v[84:87]
	v_mfma_f32_16x16x32_bf16 v[76:79], v[134:137], v[206:209], v[76:79]
	v_mfma_f32_16x16x32_bf16 v[68:71], v[148:151], v[206:209], v[68:71]
	v_mfma_f32_16x16x32_bf16 v[120:123], v[152:155], v[178:181], v[120:123]
	v_mfma_f32_16x16x32_bf16 v[112:115], v[162:165], v[178:181], v[112:115]
	v_mfma_f32_16x16x32_bf16 v[104:107], v[152:155], v[186:189], v[104:107]
	v_mfma_f32_16x16x32_bf16 v[96:99], v[162:165], v[186:189], v[96:99]
	v_mfma_f32_16x16x32_bf16 v[88:91], v[152:155], v[194:197], v[88:91]
	v_mfma_f32_16x16x32_bf16 v[80:83], v[162:165], v[194:197], v[80:83]
	v_mfma_f32_16x16x32_bf16 v[72:75], v[152:155], v[202:205], v[72:75]
	v_mfma_f32_16x16x32_bf16 v[64:67], v[162:165], v[202:205], v[64:67]
	v_mfma_f32_16x16x32_bf16 v[120:123], v[158:161], v[182:185], v[120:123]
	v_mfma_f32_16x16x32_bf16 v[112:115], v[172:175], v[182:185], v[112:115]
	v_mfma_f32_16x16x32_bf16 v[104:107], v[158:161], v[190:193], v[104:107]
	v_mfma_f32_16x16x32_bf16 v[96:99], v[172:175], v[190:193], v[96:99]
	v_mfma_f32_16x16x32_bf16 v[88:91], v[158:161], v[198:201], v[88:91]
	v_mfma_f32_16x16x32_bf16 v[80:83], v[172:175], v[198:201], v[80:83]
	v_mfma_f32_16x16x32_bf16 v[72:75], v[158:161], v[206:209], v[72:75]
	v_mfma_f32_16x16x32_bf16 v[64:67], v[172:175], v[206:209], v[64:67]
	s_setprio 0
	s_barrier
; #define PG8_STAGE(bufoff, gbase, voff, p64) do { _Pragma("unroll") for (int _i = 0; _i < 2; ++_i) { \
;         const char* _gb = (const char*)(gbase) + (size_t)_i * (p64); const unsigned _la = ldsbase + (unsigned)(bufoff) + (unsigned)_i * 8192u; \
;         asm volatile("s_mov_b32 m0, %0\n\ts_nop 0\n\tglobal_load_lds_dwordx4 %1, %2" :: "s"(_la), "v"(voff), "s"(_gb) : "memory"); } } while (0)
; #define PG8_LDA(dst, b, h) do { _Pragma("unroll") for (int m = 0; m < 4; ++m) _Pragma("unroll") for (int k = 0; k < 2; ++k) dst[m][k] = *(const LAS bf16x8*)(lds + PG8_SA(b, h) + aoff + m * 2048 + k * 1024); } while (0)
; #define PG8_LDB(dst, b, h) do { _Pragma("unroll") for (int n = 0; n < 2; ++n) _Pragma("unroll") for (int k = 0; k < 2; ++k) dst[n][k] = *(const LAS bf16x8*)(lds + PG8_SB(b, h) + boff + n * 2048 + k * 1024); } while (0)
; #define PG8_MMA(ai, bj, At, Bt) do { __builtin_amdgcn_s_setprio(1); _Pragma("unroll") for (int m = 0; m < 4; ++m) _Pragma("unroll") for (int n = 0; n < 2; ++n) _Pragma("unroll") for (int k = 0; k < 2; ++k) \
;         acc[ai][bj][m][n] = __builtin_amdgcn_mfma_f32_16x16x32_bf16(Bt[n][k], At[m][k], acc[ai][bj][m][n], 0, 0, 0); __builtin_amdgcn_s_setprio(0); } while (0)
; #define PG8_WAIT_V(n) asm volatile("s_waitcnt vmcnt(" #n ")" ::: "memory")
; #define PG8_WAIT_L(n) asm volatile("s_waitcnt lgkmcnt(" #n ")" ::: "memory")
; #define PG8_BAR __builtin_amdgcn_s_barrier()
; #define PG8_SCHED __builtin_amdgcn_sched_barrier(0)
; template <class Epi, class Sched>
; __device__ __forceinline__ void gemm_phase(LAS unsigned char* lds, const Sched& S, const Epi& E) {
;     ...
;             PG8_LDA(At, 0, 1); PG8_STAGE(PG8_SB(0, 0), b2, vB2, hB2 / 2); PG8_STAGE(PG8_SB(0, 1), b2 + hB2, vB2, hB2 / 2); PG8_STAGE(PG8_SA(0, 0), a2, vA2, hA2 / 2);
;             PG8_WAIT_V(8); PG8_WAIT_L(0); PG8_BAR; PG8_MMA(1, 0, At, B0); PG8_MMA(1, 1, At, B1); PG8_BAR; PG8_SCHED;
;             PG8_LDB(B0, 1, 0); PG8_LDB(B1, 1, 1); PG8_SCHED; PG8_LDA(At, 1, 0); PG8_STAGE(PG8_SA(0, 1), a2 + hA2, vA2, hA2 / 2);
;             PG8_WAIT_V(8); PG8_WAIT_L(0); PG8_BAR; PG8_MMA(0, 0, At, B0); PG8_MMA(0, 1, At, B1); PG8_BAR; PG8_SCHED;
	s_add_u32 s74, s58, 0x20000
	ds_read_b128 v[178:181], v147 offset:16384
	ds_read_b128 v[182:185], v147 offset:17408
	ds_read_b128 v[186:189], v147 offset:18432
	ds_read_b128 v[190:193], v147 offset:19456
	ds_read_b128 v[194:197], v147 offset:20480
	ds_read_b128 v[198:201], v147 offset:21504
	ds_read_b128 v[202:205], v147 offset:22528
	ds_read_b128 v[206:209], v147 offset:23552
	s_mov_b32 m0, s20
	s_nop 0
	global_load_lds_dwordx4 v143, s[58:59]
	s_mov_b32 m0, s24
	s_addc_u32 s75, s59, 0
	global_load_lds_dwordx4 v143, s[74:75]
	s_add_u32 s74, s58, 0x40000
	s_mov_b32 m0, s33
	s_addc_u32 s75, s59, 0
	global_load_lds_dwordx4 v143, s[74:75]
	s_add_u32 s74, s58, 0x60000
	s_mov_b32 m0, s34
	s_addc_u32 s75, s59, 0
	global_load_lds_dwordx4 v143, s[74:75]
	s_mov_b32 m0, s15
	s_nop 0
	global_load_lds_dwordx4 v142, s[16:17]
	s_add_u32 s74, s16, 0x20000
	s_mov_b32 m0, s35
	s_addc_u32 s75, s17, 0
	global_load_lds_dwordx4 v142, s[74:75]
	s_waitcnt vmcnt(8)
	s_waitcnt lgkmcnt(0)
	s_barrier
	s_setprio 1
	v_mfma_f32_16x16x32_bf16 v[60:63], v[130:133], v[178:181], v[60:63]
	v_mfma_f32_16x16x32_bf16 v[52:55], v[138:141], v[178:181], v[52:55]
	v_mfma_f32_16x16x32_bf16 v[44:47], v[130:133], v[186:189], v[44:47]
	v_mfma_f32_16x16x32_bf16 v[36:39], v[138:141], v[186:189], v[36:39]
	v_mfma_f32_16x16x32_bf16 v[28:31], v[130:133], v[194:197], v[28:31]
	v_mfma_f32_16x16x32_bf16 v[20:23], v[138:141], v[194:197], v[20:23]
	v_mfma_f32_16x16x32_bf16 v[12:15], v[130:133], v[202:205], v[12:15]
	v_mfma_f32_16x16x32_bf16 v[4:7], v[138:141], v[202:205], v[4:7]
	v_mfma_f32_16x16x32_bf16 v[60:63], v[134:137], v[182:185], v[60:63]
	v_mfma_f32_16x16x32_bf16 v[52:55], v[148:151], v[182:185], v[52:55]
	v_mfma_f32_16x16x32_bf16 v[44:47], v[134:137], v[190:193], v[44:47]
	v_mfma_f32_16x16x32_bf16 v[36:39], v[148:151], v[190:193], v[36:39]
	v_mfma_f32_16x16x32_bf16 v[28:31], v[134:137], v[198:201], v[28:31]
	v_mfma_f32_16x16x32_bf16 v[20:23], v[148:151], v[198:201], v[20:23]
	v_mfma_f32_16x16x32_bf16 v[12:15], v[134:137], v[206:209], v[12:15]
	v_mfma_f32_16x16x32_bf16 v[4:7], v[148:151], v[206:209], v[4:7]
	v_mfma_f32_16x16x32_bf16 v[56:59], v[152:155], v[178:181], v[56:59]
	v_mfma_f32_16x16x32_bf16 v[48:51], v[162:165], v[178:181], v[48:51]
	v_mfma_f32_16x16x32_bf16 v[40:43], v[152:155], v[186:189], v[40:43]
	v_mfma_f32_16x16x32_bf16 v[32:35], v[162:165], v[186:189], v[32:35]
	v_mfma_f32_16x16x32_bf16 v[24:27], v[152:155], v[194:197], v[24:27]
	v_mfma_f32_16x16x32_bf16 v[16:19], v[162:165], v[194:197], v[16:19]
	v_mfma_f32_16x16x32_bf16 v[8:11], v[152:155], v[202:205], v[8:11]
	v_mfma_f32_16x16x32_bf16 v[0:3], v[162:165], v[202:205], v[0:3]
	v_mfma_f32_16x16x32_bf16 v[56:59], v[158:161], v[182:185], v[56:59]
	v_mfma_f32_16x16x32_bf16 v[48:51], v[172:175], v[182:185], v[48:51]
	v_mfma_f32_16x16x32_bf16 v[40:43], v[158:161], v[190:193], v[40:43]
	v_mfma_f32_16x16x32_bf16 v[32:35], v[172:175], v[190:193], v[32:35]
	v_mfma_f32_16x16x32_bf16 v[24:27], v[158:161], v[198:201], v[24:27]
	v_mfma_f32_16x16x32_bf16 v[16:19], v[172:175], v[198:201], v[16:19]
	v_mfma_f32_16x16x32_bf16 v[8:11], v[158:161], v[206:209], v[8:11]
	v_mfma_f32_16x16x32_bf16 v[0:3], v[172:175], v[206:209], v[0:3]
	s_setprio 0
	s_barrier
	v_add_u32_e32 v128, 0x18000, v146
	ds_read_b128 v[130:133], v128
	ds_read_b128 v[134:137], v128 offset:1024
	ds_read_b128 v[138:141], v128 offset:2048
	ds_read_b128 v[148:151], v128 offset:3072
	v_add_u32_e32 v128, 0x1c000, v146
	ds_read_b128 v[152:155], v128
	ds_read_b128 v[158:161], v128 offset:1024
	ds_read_b128 v[162:165], v128 offset:2048
	ds_read_b128 v[172:175], v128 offset:3072
	ds_read_b128 v[178:181], v147 offset:32768
	ds_read_b128 v[182:185], v147 offset:33792
	ds_read_b128 v[186:189], v147 offset:34816
	ds_read_b128 v[190:193], v147 offset:35840
	ds_read_b128 v[194:197], v147 offset:36864
	ds_read_b128 v[198:201], v147 offset:37888
	ds_read_b128 v[202:205], v147 offset:38912
	ds_read_b128 v[206:209], v147 offset:39936
	s_add_u32 s74, s16, 0x40000
	s_mov_b32 m0, s36
	s_addc_u32 s75, s17, 0
	global_load_lds_dwordx4 v142, s[74:75]
	s_add_u32 s74, s16, 0x60000
	s_mov_b32 m0, s37
	s_addc_u32 s75, s17, 0
	global_load_lds_dwordx4 v142, s[74:75]
	s_waitcnt vmcnt(8)
	s_waitcnt lgkmcnt(0)
	s_barrier
; #define PG8_STAGE(bufoff, gbase, voff, p64) do { _Pragma("unroll") for (int _i = 0; _i < 2; ++_i) { \
;         const char* _gb = (const char*)(gbase) + (size_t)_i * (p64); const unsigned _la = ldsbase + (unsigned)(bufoff) + (unsigned)_i * 8192u; \
;         asm volatile("s_mov_b32 m0, %0\n\ts_nop 0\n\tglobal_load_lds_dwordx4 %1, %2" :: "s"(_la), "v"(voff), "s"(_gb) : "memory"); } } while (0)
; #define PG8_LDA(dst, b, h) do { _Pragma("unroll") for (int m = 0; m < 4; ++m) _Pragma("unroll") for (int k = 0; k < 2; ++k) dst[m][k] = *(const LAS bf16x8*)(lds + PG8_SA(b, h) + aoff + m * 2048 + k * 1024); } while (0)
; #define PG8_MMA(ai, bj, At, Bt) do { __builtin_amdgcn_s_setprio(1); _Pragma("unroll") for (int m = 0; m < 4; ++m) _Pragma("unroll") for (int n = 0; n < 2; ++n) _Pragma("unroll") for (int k = 0; k < 2; ++k) \
;         acc[ai][bj][m][n] = __builtin_amdgcn_mfma_f32_16x16x32_bf16(Bt[n][k], At[m][k], acc[ai][bj][m][n], 0, 0, 0); __builtin_amdgcn_s_setprio(0); } while (0)
; #define PG8_WAIT_V(n) asm volatile("s_waitcnt vmcnt(" #n ")" ::: "memory")
; #define PG8_WAIT_L(n) asm volatile("s_waitcnt lgkmcnt(" #n ")" ::: "memory")
; #define PG8_BAR __builtin_amdgcn_s_barrier()
; #define PG8_SCHED __builtin_amdgcn_sched_barrier(0)
; template <class Epi, class Sched>
; __device__ __forceinline__ void gemm_phase(LAS unsigned char* lds, const Sched& S, const Epi& E) {
;     ...
;             PG8_WAIT_V(8); PG8_WAIT_L(0); PG8_BAR; PG8_MMA(0, 0, At, B0); PG8_MMA(0, 1, At, B1); PG8_BAR; PG8_SCHED;
;             PG8_LDA(At, 1, 1); PG8_STAGE(PG8_SB(1, 0), b3, vB2, hB2 / 2); PG8_STAGE(PG8_SB(1, 1), b3 + hB2, vB2, hB2 / 2); PG8_STAGE(PG8_SA(1, 0), a3, vA2, hA2 / 2);
;             PG8_WAIT_V(8); PG8_WAIT_L(0); PG8_BAR; PG8_MMA(1, 0, At, B0); PG8_MMA(1, 1, At, B1); PG8_BAR; PG8_SCHED;
;         }
;         if (wr == 0) PG8_BAR;
	s_setprio 1
	v_mfma_f32_16x16x32_bf16 v[124:127], v[130:133], v[178:181], v[124:127]
	v_mfma_f32_16x16x32_bf16 v[116:119], v[138:141], v[178:181], v[116:119]
	v_mfma_f32_16x16x32_bf16 v[108:111], v[130:133], v[186:189], v[108:111]
	v_mfma_f32_16x16x32_bf16 v[100:103], v[138:141], v[186:189], v[100:103]
	v_mfma_f32_16x16x32_bf16 v[92:95], v[130:133], v[194:197], v[92:95]
	v_mfma_f32_16x16x32_bf16 v[84:87], v[138:141], v[194:197], v[84:87]
	v_mfma_f32_16x16x32_bf16 v[76:79], v[130:133], v[202:205], v[76:79]
	v_mfma_f32_16x16x32_bf16 v[68:71], v[138:141], v[202:205], v[68:71]
	v_mfma_f32_16x16x32_bf16 v[124:127], v[134:137], v[182:185], v[124:127]
	v_mfma_f32_16x16x32_bf16 v[116:119], v[148:151], v[182:185], v[116:119]
	v_mfma_f32_16x16x32_bf16 v[108:111], v[134:137], v[190:193], v[108:111]
	v_mfma_f32_16x16x32_bf16 v[100:103], v[148:151], v[190:193], v[100:103]
	v_mfma_f32_16x16x32_bf16 v[92:95], v[134:137], v[198:201], v[92:95]
	v_mfma_f32_16x16x32_bf16 v[84:87], v[148:151], v[198:201], v[84:87]
	v_mfma_f32_16x16x32_bf16 v[76:79], v[134:137], v[206:209], v[76:79]
	v_mfma_f32_16x16x32_bf16 v[68:71], v[148:151], v[206:209], v[68:71]
	v_mfma_f32_16x16x32_bf16 v[120:123], v[152:155], v[178:181], v[120:123]
	v_mfma_f32_16x16x32_bf16 v[112:115], v[162:165], v[178:181], v[112:115]
	v_mfma_f32_16x16x32_bf16 v[104:107], v[152:155], v[186:189], v[104:107]
	v_mfma_f32_16x16x32_bf16 v[96:99], v[162:165], v[186:189], v[96:99]
	v_mfma_f32_16x16x32_bf16 v[88:91], v[152:155], v[194:197], v[88:91]
	v_mfma_f32_16x16x32_bf16 v[80:83], v[162:165], v[194:197], v[80:83]
	v_mfma_f32_16x16x32_bf16 v[72:75], v[152:155], v[202:205], v[72:75]
	v_mfma_f32_16x16x32_bf16 v[64:67], v[162:165], v[202:205], v[64:67]
	v_mfma_f32_16x16x32_bf16 v[120:123], v[158:161], v[182:185], v[120:123]
	v_mfma_f32_16x16x32_bf16 v[112:115], v[172:175], v[182:185], v[112:115]
	v_mfma_f32_16x16x32_bf16 v[104:107], v[158:161], v[190:193], v[104:107]
	v_mfma_f32_16x16x32_bf16 v[96:99], v[172:175], v[190:193], v[96:99]
	v_mfma_f32_16x16x32_bf16 v[88:91], v[158:161], v[198:201], v[88:91]
	v_mfma_f32_16x16x32_bf16 v[80:83], v[172:175], v[198:201], v[80:83]
	v_mfma_f32_16x16x32_bf16 v[72:75], v[158:161], v[206:209], v[72:75]
	v_mfma_f32_16x16x32_bf16 v[64:67], v[172:175], v[206:209], v[64:67]
	s_setprio 0
	s_barrier
	s_add_u32 s74, s58, 0x80
	s_addc_u32 s75, s59, 0
	ds_read_b128 v[178:181], v147 offset:49152
	ds_read_b128 v[182:185], v147 offset:50176
	ds_read_b128 v[186:189], v147 offset:51200
	ds_read_b128 v[190:193], v147 offset:52224
	ds_read_b128 v[194:197], v147 offset:53248
	ds_read_b128 v[198:201], v147 offset:54272
	ds_read_b128 v[202:205], v147 offset:55296
	ds_read_b128 v[206:209], v147 offset:56320
	s_mov_b32 m0, s45
	s_nop 0
	global_load_lds_dwordx4 v143, s[74:75]
	s_add_u32 s74, s58, 0x20080
	s_mov_b32 m0, s47
	s_addc_u32 s75, s59, 0
	global_load_lds_dwordx4 v143, s[74:75]
	s_add_u32 s74, s58, 0x40080
	s_mov_b32 m0, s51
	s_addc_u32 s75, s59, 0
	global_load_lds_dwordx4 v143, s[74:75]
	s_add_u32 s58, s58, 0x60080
	s_mov_b32 m0, s61
	s_addc_u32 s59, s59, 0
	global_load_lds_dwordx4 v143, s[58:59]
	s_mov_b32 m0, s48
	s_nop 0
	global_load_lds_dwordx4 v142, s[22:23]
	s_add_u32 s16, s16, 0x20080
	s_mov_b32 m0, s50
	s_addc_u32 s17, s17, 0
	global_load_lds_dwordx4 v142, s[16:17]
	s_waitcnt vmcnt(8)
	s_waitcnt lgkmcnt(0)
	s_barrier
	s_setprio 1
	v_mfma_f32_16x16x32_bf16 v[60:63], v[130:133], v[178:181], v[60:63]
	v_mfma_f32_16x16x32_bf16 v[52:55], v[138:141], v[178:181], v[52:55]
	v_mfma_f32_16x16x32_bf16 v[44:47], v[130:133], v[186:189], v[44:47]
	v_mfma_f32_16x16x32_bf16 v[36:39], v[138:141], v[186:189], v[36:39]
	v_mfma_f32_16x16x32_bf16 v[28:31], v[130:133], v[194:197], v[28:31]
	v_mfma_f32_16x16x32_bf16 v[20:23], v[138:141], v[194:197], v[20:23]
	v_mfma_f32_16x16x32_bf16 v[12:15], v[130:133], v[202:205], v[12:15]
	v_mfma_f32_16x16x32_bf16 v[4:7], v[138:141], v[202:205], v[4:7]
	v_mfma_f32_16x16x32_bf16 v[60:63], v[134:137], v[182:185], v[60:63]
	v_mfma_f32_16x16x32_bf16 v[52:55], v[148:151], v[182:185], v[52:55]
	v_mfma_f32_16x16x32_bf16 v[44:47], v[134:137], v[190:193], v[44:47]
	v_mfma_f32_16x16x32_bf16 v[36:39], v[148:151], v[190:193], v[36:39]
	v_mfma_f32_16x16x32_bf16 v[28:31], v[134:137], v[198:201], v[28:31]
	v_mfma_f32_16x16x32_bf16 v[20:23], v[148:151], v[198:201], v[20:23]
	v_mfma_f32_16x16x32_bf16 v[12:15], v[134:137], v[206:209], v[12:15]
	v_mfma_f32_16x16x32_bf16 v[4:7], v[148:151], v[206:209], v[4:7]
	v_mfma_f32_16x16x32_bf16 v[56:59], v[152:155], v[178:181], v[56:59]
	v_mfma_f32_16x16x32_bf16 v[48:51], v[162:165], v[178:181], v[48:51]
	v_mfma_f32_16x16x32_bf16 v[40:43], v[152:155], v[186:189], v[40:43]
	v_mfma_f32_16x16x32_bf16 v[32:35], v[162:165], v[186:189], v[32:35]
	v_mfma_f32_16x16x32_bf16 v[24:27], v[152:155], v[194:197], v[24:27]
	v_mfma_f32_16x16x32_bf16 v[16:19], v[162:165], v[194:197], v[16:19]
	v_mfma_f32_16x16x32_bf16 v[8:11], v[152:155], v[202:205], v[8:11]
	v_mfma_f32_16x16x32_bf16 v[0:3], v[162:165], v[202:205], v[0:3]
	v_mfma_f32_16x16x32_bf16 v[56:59], v[158:161], v[182:185], v[56:59]
	v_mfma_f32_16x16x32_bf16 v[48:51], v[172:175], v[182:185], v[48:51]
	v_mfma_f32_16x16x32_bf16 v[40:43], v[158:161], v[190:193], v[40:43]
	v_mfma_f32_16x16x32_bf16 v[32:35], v[172:175], v[190:193], v[32:35]
	v_mfma_f32_16x16x32_bf16 v[24:27], v[158:161], v[198:201], v[24:27]
	v_mfma_f32_16x16x32_bf16 v[16:19], v[172:175], v[198:201], v[16:19]
	v_mfma_f32_16x16x32_bf16 v[8:11], v[158:161], v[206:209], v[8:11]
	v_mfma_f32_16x16x32_bf16 v[0:3], v[172:175], v[206:209], v[0:3]
	s_setprio 0
	s_barrier
	s_add_i32 s73, s73, 2
	s_add_u32 s56, s56, 0x100
	s_addc_u32 s57, s57, 0
	s_add_u32 s69, s69, 0x100
	s_addc_u32 s72, s72, 0
	s_cmp_gt_u32 s73, 13
	s_cbranch_scc0 .LBB0_757
	s_and_b64 vcc, exec, s[38:39]
	s_cbranch_vccz .LBB0_760
	s_barrier

; #define PG8_STAGE(bufoff, gbase, voff, p64) do { _Pragma("unroll") for (int _i = 0; _i < 2; ++_i) { \
;         const char* _gb = (const char*)(gbase) + (size_t)_i * (p64); const unsigned _la = ldsbase + (unsigned)(bufoff) + (unsigned)_i * 8192u; \
;         asm volatile("s_mov_b32 m0, %0\n\ts_nop 0\n\tglobal_load_lds_dwordx4 %1, %2" :: "s"(_la), "v"(voff), "s"(_gb) : "memory"); } } while (0)
; #define PG8_WAIT_V(n) asm volatile("s_waitcnt vmcnt(" #n ")" ::: "memory")
; #define PG8_BAR __builtin_amdgcn_s_barrier()
; template <class Epi, class Sched>
; __device__ __forceinline__ void gemm_phase(LAS unsigned char* lds, const Sched& S, const Epi& E) {
;     ...
;     { Unit u0; if (!S.next(0, u0)) return;
;       cA = u0.A; cB = u0.B; hA = (unsigned)HALF * u0.lda2; hB = (unsigned)HALF * u0.ldb2; nt = u0.nt;
;       voffA = (unsigned)(sR * u0.lda2 + sC2); voffB = (unsigned)(sRb * u0.ldb2 + sC2); }
;     f32x4 acc[2][2][4][2];
; #pragma unroll
;     for (int a = 0; a < 2; ++a)
; #pragma unroll
;         for (int b = 0; b < 2; ++b)
; #pragma unroll
;             for (int m = 0; m < 4; ++m)
; #pragma unroll
;                 for (int n = 0; n < 2; ++n) acc[a][b][m][n] = (f32x4){0.f, 0.f, 0.f, 0.f};
;     bf16x8 At[4][2], B0[2][2], B1[2][2];
;     PG8_STAGE(PG8_SB(0, 0), cB, voffB, hB / 2); PG8_STAGE(PG8_SB(0, 1), cB + hB, voffB, hB / 2); PG8_STAGE(PG8_SA(0, 0), cA, voffA, hA / 2); PG8_STAGE(PG8_SA(0, 1), cA + hA, voffA, hA / 2);
;     if (wr == 1) PG8_BAR;
;     PG8_WAIT_V(2); PG8_BAR;
;     PG8_STAGE(PG8_SB(1, 0), cB + kstep, voffB, hB / 2); PG8_STAGE(PG8_SA(1, 0), cA + kstep, voffA, hA / 2); PG8_STAGE(PG8_SB(1, 1), cB + hB + kstep, voffB, hB / 2);
;     PG8_WAIT_V(6); PG8_BAR;
; __global__ void __launch_bounds__(512, 2) fwd_megakernel(Params Parg) {
;     ...
;         for (int it5 = 0; it5 * (int)gridDim.x < NCH * 4 * 2; ++it5) {
;             const int g5 = gridDim.x, b5 = blockIdx.x, item = it5 * g5 + ((g5 % 8 == 0) ? (b5 % 8) * (g5 / 8) + b5 / 8 : b5);
;             if (item >= NCH * 4 * 2) break;
;             { PHASE_BEGIN
;               bf16_t* pscr = (bf16_t*)(ws + WS_PSCR + (size_t)(bid >> 1) * (256 * D * 2) + (size_t)(bid & 1) * (CH * 2));
;               QKSched S{(const char*)(ws + WS_KTQK), (const char*)(ws + WS_KTQK + 32 * MiB), item}; EpiP E; E.pscr = pscr; E.dec = WSP(float, WS_DEC); gemm_phase(lds, S, E); }
.LBB0_825:
	s_add_i32 s73, s43, s4
	s_cmpk_gt_i32 s73, 0xff
	s_mov_b64 s[6:7], -1
	s_cbranch_scc1 .LBB0_824
	s_mov_b64 s[4:5], s[0:1]
	s_load_dwordx2 s[16:17], s[4:5], 0xd0
	v_mov_b32_e32 v1, v176
	v_mov_b32_e32 v0, v176
	s_waitcnt lgkmcnt(0)
	s_add_u32 s22, s16, 0xa900000
	s_addc_u32 s23, s17, 0
	s_lshl_b32 s4, s73, 6
	s_lshl_b32 s7, s73, 8
	v_bfe_i32 v3, v0, 27, 1
	s_and_b32 s6, s4, 0xfffffe00
	s_and_b32 s51, s7, 0x100
	v_readfirstlane_b32 s24, v0
	v_lshlrev_b32_e32 v1, 4, v0
	v_lshrrev_b32_e32 v3, 22, v3
	s_or_b32 s4, s6, s51
	s_ashr_i32 s33, s24, 6
	v_add_u32_e32 v3, v1, v3
	s_ashr_i32 s5, s4, 31
	s_ashr_i32 s27, s24, 8
	v_and_b32_e32 v3, 0xfffffc00, v3
	s_lshl_b32 s47, s33, 10
	s_and_b32 s26, s7, 0x600
	s_lshl_b64 s[4:5], s[4:5], 11
	v_sub_u32_e32 v1, v1, v3
	s_add_u32 s8, s16, s4
	v_ashrrev_i32_e32 v2, 31, v0
	v_lshrrev_b32_e32 v3, 4, v1
	s_addc_u32 s9, s17, s5
	s_ashr_i32 s7, s6, 31
	v_lshrrev_b32_e32 v2, 26, v2
	v_bitop3_b32 v1, v3, v1, 32 bitop3:0x6c
	s_lshl_b64 s[4:5], s[6:7], 11
	v_add_u32_e32 v2, v0, v2
	v_ashrrev_i32_e32 v4, 31, v1
	s_add_u32 s4, s22, s4
	v_ashrrev_i32_e32 v2, 6, v2
	v_lshrrev_b32_e32 v4, 26, v4
	s_addc_u32 s5, s23, s5
	v_lshlrev_b32_e32 v3, 3, v2
	v_add_u32_e32 v4, v1, v4
	s_add_u32 s88, s4, s26
	v_and_b32_e32 v3, -16, v3
	v_ashrrev_i32_e32 v5, 6, v4
	s_addc_u32 s89, s5, 0
	s_add_i32 s47, s47, 0
	v_add_u32_e32 v3, v5, v3
	v_and_b32_e32 v5, 3, v5
	s_mov_b32 s4, 0x1fffe0
	s_add_i32 s12, s47, 0x10000
	v_and_b32_e32 v4, 0xc0, v4
	v_and_or_b32 v5, v3, s4, v5
	s_add_u32 s4, s88, 0x20000
	v_sub_u32_e32 v1, v1, v4
	s_addc_u32 s5, s89, 0
	s_add_i32 s44, s47, 0x12000
	v_lshlrev_b32_e32 v2, 5, v2
	v_ashrrev_i16_sdwa v1, v157, sext(v1) dst_sel:DWORD dst_unused:UNUSED_PAD src0_sel:DWORD src1_sel:BYTE_0
	v_lshlrev_b32_e32 v4, 1, v3
	v_lshrrev_b32_e32 v6, 2, v3
	s_add_u32 s7, s8, s26
	v_bfe_i32 v1, v1, 0, 16
	v_and_b32_e32 v4, 24, v4
	v_and_b32_e32 v6, 4, v6
	v_and_b32_e32 v2, 32, v2
	s_addc_u32 s15, s9, 0
	v_or3_b32 v4, v5, v6, v4
	v_add_lshl_u32 v1, v2, v1, 1
	s_add_u32 s8, s7, 0x8900000
	v_lshl_add_u32 v128, v4, 11, v1
	s_mov_b32 m0, s12
	s_nop 0
	global_load_lds_dwordx4 v128, s[88:89]
	s_mov_b32 m0, s44
	s_addc_u32 s9, s15, 0
	global_load_lds_dwordx4 v128, s[4:5]
	s_add_u32 s4, s88, 0x40000
	s_addc_u32 s5, s89, 0
	s_add_i32 s42, s47, 0x14000
	s_mov_b32 m0, s42
	s_nop 0
	global_load_lds_dwordx4 v128, s[4:5]
	s_add_u32 s4, s88, 0x60000
	s_addc_u32 s5, s89, 0
	s_add_i32 s48, s47, 0x16000
	s_mov_b32 m0, s48
	s_add_u32 s10, s7, 0x8920000
	global_load_lds_dwordx4 v128, s[4:5]
	s_addc_u32 s11, s15, 0
	s_add_i32 s61, s47, 0x2000
	v_lshl_add_u32 v144, v3, 11, v1
	s_mov_b32 m0, s47
	s_nop 0
	global_load_lds_dwordx4 v144, s[8:9]
	s_mov_b32 m0, s61
	s_add_u32 s74, s7, 0x8940000
	global_load_lds_dwordx4 v144, s[10:11]
	s_addc_u32 s75, s15, 0
	s_add_i32 s14, s47, 0x4000
	s_mov_b32 m0, s14
	s_nop 0
	global_load_lds_dwordx4 v144, s[74:75]
	s_add_u32 s76, s7, 0x8960000
	s_addc_u32 s77, s15, 0
	s_add_i32 s15, s47, 0x6000
	s_mov_b32 m0, s15
	s_nop 0
	global_load_lds_dwordx4 v144, s[76:77]
	s_cmp_eq_u32 s27, 1
	s_mov_b64 s[52:53], s[96:97]
	s_cselect_b64 s[78:79], -1, 0
	s_cmp_lg_u32 s27, 1
	s_cbranch_scc1 .LBB0_828
	s_barrier
.LBB0_828:
	s_add_u32 s4, s16, s18
	s_addc_u32 s5, s17, s19
	s_add_u32 s4, s4, s25
	s_addc_u32 s5, s5, 0
	s_add_u32 s80, s4, 0x14900000
	s_addc_u32 s81, s5, 0
	s_add_u32 s4, s16, 0x3d1e000
	s_addc_u32 s5, s17, 0
	v_bfe_u32 v146, v0, 4, 2
	s_lshl_b32 s7, s33, 5
	v_and_b32_e32 v145, 15, v0
	v_lshlrev_b32_e32 v1, 4, v146
	v_lshlrev_b32_e32 v0, 2, v0
	s_and_b32 s64, s7, 0x60
	s_lshl_b32 s68, s27, 6
	v_lshl_or_b32 v1, v145, 6, v1
	v_and_b32_e32 v0, 32, v0
	s_lshl_b32 s16, s27, 13
	s_lshl_b32 s7, s64, 7
	v_bitop3_b32 v2, v1, s7, v0 bitop3:0xde
	v_bitop3_b32 v0, v1, s16, v0 bitop3:0xde
	s_add_u32 s16, s88, 0x80
	s_addc_u32 s17, s89, 0
	s_add_i32 s65, s47, 0x18000
	s_waitcnt vmcnt(2)
	s_barrier
	s_mov_b32 m0, s65
	s_nop 0
	global_load_lds_dwordx4 v128, s[16:17]
	s_add_u32 s16, s88, 0x20080
	s_addc_u32 s17, s89, 0
	s_add_i32 s66, s47, 0x1a000
	s_add_u32 s82, s8, 0x80
	s_addc_u32 s83, s9, 0
	s_add_i32 s67, s47, 0x8000
	s_mov_b32 m0, s66
	s_add_u32 s84, s8, 0x20080
	global_load_lds_dwordx4 v128, s[16:17]
	s_addc_u32 s85, s9, 0
	s_mov_b32 m0, s67
	s_add_i32 s45, s47, 0xa000
	global_load_lds_dwordx4 v144, s[82:83]
	s_mov_b32 m0, s45
	s_add_u32 s16, s88, 0x40080
	global_load_lds_dwordx4 v144, s[84:85]
	s_addc_u32 s17, s89, 0
	s_add_i32 s36, s47, 0x1c000
	s_mov_b32 m0, s36
	s_nop 0
	global_load_lds_dwordx4 v128, s[16:17]
	s_add_u32 s16, s88, 0x60080
	s_addc_u32 s17, s89, 0
	s_add_i32 s37, s47, 0x1e000
	s_add_i32 s69, s47, 0xc000
	s_cmpk_lt_u32 s24, 0x100
	s_cselect_b64 s[86:87], -1, 0
	s_bitset1_b32 s6, 8
	s_ashr_i32 s7, s6, 31
	s_add_i32 s24, s47, 0xe000
	s_lshl_b64 s[6:7], s[6:7], 11
	s_add_u32 s6, s22, s6
	s_addc_u32 s7, s23, s7
	s_add_u32 s22, s6, s26
	s_addc_u32 s23, s7, 0
	s_and_b32 s50, s73, 1
	s_bfe_u32 s72, s73, 0x20001
	s_add_u32 s90, s8, 0x100
	s_addc_u32 s91, s9, 0
	s_add_u32 s92, s8, 0x180
	s_addc_u32 s93, s9, 0
	s_add_u32 s94, s8, 0x40080
	s_addc_u32 s95, s9, 0
	s_add_u32 s96, s8, 0x60080
	s_addc_u32 s97, s9, 0
	s_add_u32 s38, s8, 0x20100
	s_addc_u32 s39, s9, 0
	s_add_u32 s40, s8, 0x40100
	s_addc_u32 s41, s9, 0
	s_add_u32 s56, s8, 0x60100
	s_addc_u32 s57, s9, 0
	s_add_u32 s62, s8, 0x20180
	s_mov_b32 m0, s37
	s_addc_u32 s63, s9, 0
	global_load_lds_dwordx4 v128, s[16:17]
	s_add_u32 s26, s8, 0x40180
	s_waitcnt vmcnt(6)
	s_addc_u32 s27, s9, 0
	s_add_u32 s54, s8, 0x60180
	s_addc_u32 s55, s9, 0
	s_mov_b32 s35, 0
	s_mov_b64 s[6:7], -1
	v_add_u32_e32 v147, 0, v2
	v_add_u32_e32 v148, 0, v0
	s_barrier
	s_branch .LBB0_831

; #define PG8_STAGE(bufoff, gbase, voff, p64) do { _Pragma("unroll") for (int _i = 0; _i < 2; ++_i) { \
;         const char* _gb = (const char*)(gbase) + (size_t)_i * (p64); const unsigned _la = ldsbase + (unsigned)(bufoff) + (unsigned)_i * 8192u; \
;         asm volatile("s_mov_b32 m0, %0\n\ts_nop 0\n\tglobal_load_lds_dwordx4 %1, %2" :: "s"(_la), "v"(voff), "s"(_gb) : "memory"); } } while (0)
; #define PG8_LDA(dst, b, h) do { _Pragma("unroll") for (int m = 0; m < 4; ++m) _Pragma("unroll") for (int k = 0; k < 2; ++k) dst[m][k] = *(const LAS bf16x8*)(lds + PG8_SA(b, h) + aoff + m * 2048 + k * 1024); } while (0)
; #define PG8_LDB(dst, b, h) do { _Pragma("unroll") for (int n = 0; n < 2; ++n) _Pragma("unroll") for (int k = 0; k < 2; ++k) dst[n][k] = *(const LAS bf16x8*)(lds + PG8_SB(b, h) + boff + n * 2048 + k * 1024); } while (0)
; #define PG8_MMA(ai, bj, At, Bt) do { __builtin_amdgcn_s_setprio(1); _Pragma("unroll") for (int m = 0; m < 4; ++m) _Pragma("unroll") for (int n = 0; n < 2; ++n) _Pragma("unroll") for (int k = 0; k < 2; ++k) \
;         acc[ai][bj][m][n] = __builtin_amdgcn_mfma_f32_16x16x32_bf16(Bt[n][k], At[m][k], acc[ai][bj][m][n], 0, 0, 0); __builtin_amdgcn_s_setprio(0); } while (0)
; #define PG8_WAIT_V(n) asm volatile("s_waitcnt vmcnt(" #n ")" ::: "memory")
; #define PG8_WAIT_L(n) asm volatile("s_waitcnt lgkmcnt(" #n ")" ::: "memory")
; #define PG8_BAR __builtin_amdgcn_s_barrier()
; #define PG8_SCHED __builtin_amdgcn_sched_barrier(0)
; template <class Epi, class Sched>
; __device__ __forceinline__ void gemm_phase(LAS unsigned char* lds, const Sched& S, const Epi& E) {
;     ...
;             PG8_LDB(B0, 0, 0); PG8_LDB(B1, 0, 1); PG8_SCHED; PG8_LDA(At, 0, 0); PG8_STAGE(PG8_SA(1, 1), a1 + hA, voffA, hA / 2);
;             PG8_WAIT_V(8); PG8_WAIT_L(0); PG8_BAR; PG8_MMA(0, 0, At, B0); PG8_MMA(0, 1, At, B1); PG8_BAR; PG8_SCHED;
;             PG8_LDA(At, 0, 1); PG8_STAGE(PG8_SB(0, 0), b2, vB2, hB2 / 2); PG8_STAGE(PG8_SB(0, 1), b2 + hB2, vB2, hB2 / 2); PG8_STAGE(PG8_SA(0, 0), a2, vA2, hA2 / 2);
;             PG8_WAIT_V(8); PG8_WAIT_L(0); PG8_BAR; PG8_MMA(1, 0, At, B0); PG8_MMA(1, 1, At, B1); PG8_BAR; PG8_SCHED;
.LBB0_831:
	v_add_u32_e32 v142, 0x10000, v147
	v_add_u32_e32 v143, 0x14000, v147
	ds_read_b128 v[0:3], v142
	ds_read_b128 v[4:7], v142 offset:1024
	s_waitcnt vmcnt(3)
	ds_read_b128 v[8:11], v142 offset:2048
	s_waitcnt vmcnt(2)
	ds_read_b128 v[12:15], v142 offset:3072
	s_waitcnt vmcnt(1)
	ds_read_b128 v[16:19], v143
	s_waitcnt vmcnt(0)
	ds_read_b128 v[20:23], v143 offset:1024
	ds_read_b128 v[24:27], v143 offset:2048
	ds_read_b128 v[28:31], v143 offset:3072
	s_and_b64 s[16:17], s[6:7], exec
	s_cselect_b32 s17, s23, s89
	s_cselect_b32 s16, s22, s88
	s_add_u32 s30, s88, 0x100
	s_addc_u32 s31, s89, 0
	ds_read_b128 v[32:35], v148
	ds_read_b128 v[36:39], v148 offset:1024
	ds_read_b128 v[40:43], v148 offset:2048
	ds_read_b128 v[44:47], v148 offset:3072
	ds_read_b128 v[48:51], v148 offset:4096
	ds_read_b128 v[52:55], v148 offset:5120
	ds_read_b128 v[56:59], v148 offset:6144
	ds_read_b128 v[60:63], v148 offset:7168
	s_mov_b32 m0, s69
	s_nop 0
	global_load_lds_dwordx4 v144, s[94:95]
	s_mov_b32 m0, s24
	s_nop 0
	global_load_lds_dwordx4 v144, s[96:97]
	s_waitcnt vmcnt(8)
	s_waitcnt lgkmcnt(0)
	s_barrier
	s_setprio 1
	v_mfma_f32_16x16x32_bf16 v[64:67], v[0:3], v[32:35], 0
	v_mfma_f32_16x16x32_bf16 v[68:71], v[8:11], v[32:35], 0
	v_mfma_f32_16x16x32_bf16 v[72:75], v[0:3], v[40:43], 0
	v_mfma_f32_16x16x32_bf16 v[76:79], v[8:11], v[40:43], 0
	v_mfma_f32_16x16x32_bf16 v[80:83], v[0:3], v[48:51], 0
	v_mfma_f32_16x16x32_bf16 v[84:87], v[8:11], v[48:51], 0
	v_mfma_f32_16x16x32_bf16 v[88:91], v[0:3], v[56:59], 0
	v_mfma_f32_16x16x32_bf16 v[92:95], v[8:11], v[56:59], 0
	v_mfma_f32_16x16x32_bf16 v[64:67], v[4:7], v[36:39], v[64:67]
	v_mfma_f32_16x16x32_bf16 v[68:71], v[12:15], v[36:39], v[68:71]
	v_mfma_f32_16x16x32_bf16 v[72:75], v[4:7], v[44:47], v[72:75]
	v_mfma_f32_16x16x32_bf16 v[76:79], v[12:15], v[44:47], v[76:79]
	v_mfma_f32_16x16x32_bf16 v[80:83], v[4:7], v[52:55], v[80:83]
	v_mfma_f32_16x16x32_bf16 v[84:87], v[12:15], v[52:55], v[84:87]
	v_mfma_f32_16x16x32_bf16 v[88:91], v[4:7], v[60:63], v[88:91]
	v_mfma_f32_16x16x32_bf16 v[92:95], v[12:15], v[60:63], v[92:95]
	v_mfma_f32_16x16x32_bf16 v[96:99], v[16:19], v[32:35], 0
	v_mfma_f32_16x16x32_bf16 v[32:35], v[24:27], v[32:35], 0
	v_mfma_f32_16x16x32_bf16 v[96:99], v[20:23], v[36:39], v[96:99]
	v_mfma_f32_16x16x32_bf16 v[32:35], v[28:31], v[36:39], v[32:35]
	v_mfma_f32_16x16x32_bf16 v[36:39], v[16:19], v[40:43], 0
	v_mfma_f32_16x16x32_bf16 v[40:43], v[24:27], v[40:43], 0
	v_mfma_f32_16x16x32_bf16 v[36:39], v[20:23], v[44:47], v[36:39]
	v_mfma_f32_16x16x32_bf16 v[40:43], v[28:31], v[44:47], v[40:43]
	v_mfma_f32_16x16x32_bf16 v[44:47], v[16:19], v[48:51], 0
	v_mfma_f32_16x16x32_bf16 v[48:51], v[24:27], v[48:51], 0
	v_mfma_f32_16x16x32_bf16 v[44:47], v[20:23], v[52:55], v[44:47]
	v_mfma_f32_16x16x32_bf16 v[48:51], v[28:31], v[52:55], v[48:51]
	v_mfma_f32_16x16x32_bf16 v[52:55], v[16:19], v[56:59], 0
	v_mfma_f32_16x16x32_bf16 v[56:59], v[24:27], v[56:59], 0
	v_mfma_f32_16x16x32_bf16 v[52:55], v[20:23], v[60:63], v[52:55]
	v_mfma_f32_16x16x32_bf16 v[56:59], v[28:31], v[60:63], v[56:59]
	s_setprio 0
	s_barrier
	ds_read_b128 v[60:63], v148 offset:16384
	ds_read_b128 v[100:103], v148 offset:17408
	ds_read_b128 v[104:107], v148 offset:18432
	ds_read_b128 v[108:111], v148 offset:19456
	ds_read_b128 v[112:115], v148 offset:20480
	ds_read_b128 v[116:119], v148 offset:21504
	ds_read_b128 v[120:123], v148 offset:22528
	ds_read_b128 v[124:127], v148 offset:23552
	s_mov_b32 m0, s12
	s_nop 0
	global_load_lds_dwordx4 v128, s[30:31]
	s_add_u32 s30, s88, 0x20100
	s_mov_b32 m0, s44
	s_addc_u32 s31, s89, 0
	global_load_lds_dwordx4 v128, s[30:31]
	s_add_u32 s30, s88, 0x40100
	s_mov_b32 m0, s42
	s_addc_u32 s31, s89, 0
	global_load_lds_dwordx4 v128, s[30:31]
	s_add_u32 s30, s88, 0x60100
	s_mov_b32 m0, s48
	s_addc_u32 s31, s89, 0
	global_load_lds_dwordx4 v128, s[30:31]
	s_mov_b32 m0, s47
	s_nop 0
	global_load_lds_dwordx4 v144, s[90:91]
	s_mov_b32 m0, s61
	s_nop 0
	global_load_lds_dwordx4 v144, s[38:39]
	s_waitcnt vmcnt(8)
	s_waitcnt lgkmcnt(0)
	s_barrier
	s_setprio 1
	v_mfma_f32_16x16x32_bf16 v[130:133], v[0:3], v[60:63], 0
	v_mfma_f32_16x16x32_bf16 v[138:141], v[0:3], v[104:107], 0
	v_mfma_f32_16x16x32_bf16 v[158:161], v[0:3], v[112:115], 0
	v_mfma_f32_16x16x32_bf16 v[0:3], v[0:3], v[120:123], 0
	v_mfma_f32_16x16x32_bf16 v[130:133], v[4:7], v[100:103], v[130:133]
	v_mfma_f32_16x16x32_bf16 v[138:141], v[4:7], v[108:111], v[138:141]
	v_mfma_f32_16x16x32_bf16 v[158:161], v[4:7], v[116:119], v[158:161]
	v_mfma_f32_16x16x32_bf16 v[0:3], v[4:7], v[124:127], v[0:3]
	v_mfma_f32_16x16x32_bf16 v[4:7], v[8:11], v[120:123], 0
	v_mfma_f32_16x16x32_bf16 v[134:137], v[8:11], v[60:63], 0
	v_mfma_f32_16x16x32_bf16 v[150:153], v[8:11], v[104:107], 0
	v_mfma_f32_16x16x32_bf16 v[162:165], v[8:11], v[112:115], 0
	v_mfma_f32_16x16x32_bf16 v[4:7], v[12:15], v[124:127], v[4:7]
	v_mfma_f32_16x16x32_bf16 v[134:137], v[12:15], v[100:103], v[134:137]
	v_mfma_f32_16x16x32_bf16 v[150:153], v[12:15], v[108:111], v[150:153]
	v_mfma_f32_16x16x32_bf16 v[162:165], v[12:15], v[116:119], v[162:165]
	v_mfma_f32_16x16x32_bf16 v[8:11], v[16:19], v[60:63], 0
	v_mfma_f32_16x16x32_bf16 v[12:15], v[24:27], v[60:63], 0
	v_mfma_f32_16x16x32_bf16 v[8:11], v[20:23], v[100:103], v[8:11]
	v_mfma_f32_16x16x32_bf16 v[12:15], v[28:31], v[100:103], v[12:15]
	v_mfma_f32_16x16x32_bf16 v[60:63], v[16:19], v[104:107], 0
	v_mfma_f32_16x16x32_bf16 v[100:103], v[24:27], v[104:107], 0
	v_mfma_f32_16x16x32_bf16 v[104:107], v[16:19], v[112:115], 0
	v_mfma_f32_16x16x32_bf16 v[16:19], v[16:19], v[120:123], 0
	v_mfma_f32_16x16x32_bf16 v[60:63], v[20:23], v[108:111], v[60:63]
	v_mfma_f32_16x16x32_bf16 v[100:103], v[28:31], v[108:111], v[100:103]
	v_mfma_f32_16x16x32_bf16 v[104:107], v[20:23], v[116:119], v[104:107]
	v_mfma_f32_16x16x32_bf16 v[108:111], v[24:27], v[112:115], 0
	v_mfma_f32_16x16x32_bf16 v[16:19], v[20:23], v[124:127], v[16:19]
	v_mfma_f32_16x16x32_bf16 v[20:23], v[24:27], v[120:123], 0
	v_mfma_f32_16x16x32_bf16 v[108:111], v[28:31], v[116:119], v[108:111]
	v_mfma_f32_16x16x32_bf16 v[20:23], v[28:31], v[124:127], v[20:23]
	s_setprio 0
	s_barrier
; #define PG8_STAGE(bufoff, gbase, voff, p64) do { _Pragma("unroll") for (int _i = 0; _i < 2; ++_i) { \
;         const char* _gb = (const char*)(gbase) + (size_t)_i * (p64); const unsigned _la = ldsbase + (unsigned)(bufoff) + (unsigned)_i * 8192u; \
;         asm volatile("s_mov_b32 m0, %0\n\ts_nop 0\n\tglobal_load_lds_dwordx4 %1, %2" :: "s"(_la), "v"(voff), "s"(_gb) : "memory"); } } while (0)
; #define PG8_LDA(dst, b, h) do { _Pragma("unroll") for (int m = 0; m < 4; ++m) _Pragma("unroll") for (int k = 0; k < 2; ++k) dst[m][k] = *(const LAS bf16x8*)(lds + PG8_SA(b, h) + aoff + m * 2048 + k * 1024); } while (0)
; #define PG8_LDB(dst, b, h) do { _Pragma("unroll") for (int n = 0; n < 2; ++n) _Pragma("unroll") for (int k = 0; k < 2; ++k) dst[n][k] = *(const LAS bf16x8*)(lds + PG8_SB(b, h) + boff + n * 2048 + k * 1024); } while (0)
; #define PG8_MMA(ai, bj, At, Bt) do { __builtin_amdgcn_s_setprio(1); _Pragma("unroll") for (int m = 0; m < 4; ++m) _Pragma("unroll") for (int n = 0; n < 2; ++n) _Pragma("unroll") for (int k = 0; k < 2; ++k) \
;         acc[ai][bj][m][n] = __builtin_amdgcn_mfma_f32_16x16x32_bf16(Bt[n][k], At[m][k], acc[ai][bj][m][n], 0, 0, 0); __builtin_amdgcn_s_setprio(0); } while (0)
; #define PG8_WAIT_V(n) asm volatile("s_waitcnt vmcnt(" #n ")" ::: "memory")
; #define PG8_WAIT_L(n) asm volatile("s_waitcnt lgkmcnt(" #n ")" ::: "memory")
; #define PG8_BAR __builtin_amdgcn_s_barrier()
; #define PG8_SCHED __builtin_amdgcn_sched_barrier(0)
; template <class Epi, class Sched>
; __device__ __forceinline__ void gemm_phase(LAS unsigned char* lds, const Sched& S, const Epi& E) {
;     ...
;             PG8_LDB(B0, 1, 0); PG8_LDB(B1, 1, 1); PG8_SCHED; PG8_LDA(At, 1, 0); PG8_STAGE(PG8_SA(0, 1), a2 + hA2, vA2, hA2 / 2);
;             PG8_WAIT_V(8); PG8_WAIT_L(0); PG8_BAR; PG8_MMA(0, 0, At, B0); PG8_MMA(0, 1, At, B1); PG8_BAR; PG8_SCHED;
;             PG8_LDA(At, 1, 1); PG8_STAGE(PG8_SB(1, 0), b3, vB2, hB2 / 2); PG8_STAGE(PG8_SB(1, 1), b3 + hB2, vB2, hB2 / 2); PG8_STAGE(PG8_SA(1, 0), a3, vA2, hA2 / 2);
;             PG8_WAIT_V(8); PG8_WAIT_L(0); PG8_BAR; PG8_MMA(1, 0, At, B0); PG8_MMA(1, 1, At, B1); PG8_BAR; PG8_SCHED;
	v_add_u32_e32 v149, 0x18000, v147
	v_add_u32_e32 v154, 0x1c000, v147
	ds_read_b128 v[24:27], v149
	ds_read_b128 v[28:31], v149 offset:1024
	ds_read_b128 v[112:115], v149 offset:2048
	ds_read_b128 v[116:119], v149 offset:3072
	ds_read_b128 v[120:123], v154
	ds_read_b128 v[124:127], v154 offset:1024
	ds_read_b128 v[172:175], v154 offset:2048
	ds_read_b128 v[178:181], v154 offset:3072
	ds_read_b128 v[182:185], v148 offset:32768
	ds_read_b128 v[186:189], v148 offset:33792
	ds_read_b128 v[190:193], v148 offset:34816
	ds_read_b128 v[194:197], v148 offset:35840
	ds_read_b128 v[198:201], v148 offset:36864
	ds_read_b128 v[202:205], v148 offset:37888
	ds_read_b128 v[206:209], v148 offset:38912
	ds_read_b128 v[210:213], v148 offset:39936
	s_mov_b32 m0, s14
	s_nop 0
	global_load_lds_dwordx4 v144, s[40:41]
	s_mov_b32 m0, s15
	s_nop 0
	global_load_lds_dwordx4 v144, s[56:57]
	s_waitcnt vmcnt(8)
	s_waitcnt lgkmcnt(0)
	s_barrier
	s_setprio 1
	v_mfma_f32_16x16x32_bf16 v[64:67], v[24:27], v[182:185], v[64:67]
	v_mfma_f32_16x16x32_bf16 v[68:71], v[112:115], v[182:185], v[68:71]
	v_mfma_f32_16x16x32_bf16 v[72:75], v[24:27], v[190:193], v[72:75]
	v_mfma_f32_16x16x32_bf16 v[76:79], v[112:115], v[190:193], v[76:79]
	v_mfma_f32_16x16x32_bf16 v[80:83], v[24:27], v[198:201], v[80:83]
	v_mfma_f32_16x16x32_bf16 v[84:87], v[112:115], v[198:201], v[84:87]
	v_mfma_f32_16x16x32_bf16 v[88:91], v[24:27], v[206:209], v[88:91]
	v_mfma_f32_16x16x32_bf16 v[92:95], v[112:115], v[206:209], v[92:95]
	v_mfma_f32_16x16x32_bf16 v[64:67], v[28:31], v[186:189], v[64:67]
	v_mfma_f32_16x16x32_bf16 v[68:71], v[116:119], v[186:189], v[68:71]
	v_mfma_f32_16x16x32_bf16 v[72:75], v[28:31], v[194:197], v[72:75]
	v_mfma_f32_16x16x32_bf16 v[76:79], v[116:119], v[194:197], v[76:79]
	v_mfma_f32_16x16x32_bf16 v[80:83], v[28:31], v[202:205], v[80:83]
	v_mfma_f32_16x16x32_bf16 v[84:87], v[116:119], v[202:205], v[84:87]
	v_mfma_f32_16x16x32_bf16 v[88:91], v[28:31], v[210:213], v[88:91]
	v_mfma_f32_16x16x32_bf16 v[92:95], v[116:119], v[210:213], v[92:95]
	v_mfma_f32_16x16x32_bf16 v[96:99], v[120:123], v[182:185], v[96:99]
	v_mfma_f32_16x16x32_bf16 v[32:35], v[172:175], v[182:185], v[32:35]
	v_mfma_f32_16x16x32_bf16 v[36:39], v[120:123], v[190:193], v[36:39]
	v_mfma_f32_16x16x32_bf16 v[40:43], v[172:175], v[190:193], v[40:43]
	v_mfma_f32_16x16x32_bf16 v[44:47], v[120:123], v[198:201], v[44:47]
	v_mfma_f32_16x16x32_bf16 v[48:51], v[172:175], v[198:201], v[48:51]
	v_mfma_f32_16x16x32_bf16 v[52:55], v[120:123], v[206:209], v[52:55]
	v_mfma_f32_16x16x32_bf16 v[56:59], v[172:175], v[206:209], v[56:59]
	v_mfma_f32_16x16x32_bf16 v[96:99], v[124:127], v[186:189], v[96:99]
	v_mfma_f32_16x16x32_bf16 v[32:35], v[178:181], v[186:189], v[32:35]
	v_mfma_f32_16x16x32_bf16 v[36:39], v[124:127], v[194:197], v[36:39]
	v_mfma_f32_16x16x32_bf16 v[40:43], v[178:181], v[194:197], v[40:43]
	v_mfma_f32_16x16x32_bf16 v[44:47], v[124:127], v[202:205], v[44:47]
	v_mfma_f32_16x16x32_bf16 v[48:51], v[178:181], v[202:205], v[48:51]
	v_mfma_f32_16x16x32_bf16 v[52:55], v[124:127], v[210:213], v[52:55]
	v_mfma_f32_16x16x32_bf16 v[56:59], v[178:181], v[210:213], v[56:59]
	s_setprio 0
	s_barrier
	s_add_u32 s30, s88, 0x180
	s_addc_u32 s31, s89, 0
	ds_read_b128 v[182:185], v148 offset:49152
	ds_read_b128 v[186:189], v148 offset:50176
	ds_read_b128 v[190:193], v148 offset:51200
	ds_read_b128 v[194:197], v148 offset:52224
	ds_read_b128 v[198:201], v148 offset:53248
	ds_read_b128 v[202:205], v148 offset:54272
	ds_read_b128 v[206:209], v148 offset:55296
	ds_read_b128 v[210:213], v148 offset:56320
	s_mov_b32 m0, s65
	s_nop 0
	global_load_lds_dwordx4 v128, s[30:31]
	s_add_u32 s30, s88, 0x20180
	s_mov_b32 m0, s66
	s_addc_u32 s31, s89, 0
	global_load_lds_dwordx4 v128, s[30:31]
	s_add_u32 s30, s88, 0x40180
	s_mov_b32 m0, s36
	s_addc_u32 s31, s89, 0
	global_load_lds_dwordx4 v128, s[30:31]
	s_add_u32 s30, s88, 0x60180
	s_mov_b32 m0, s37
	s_addc_u32 s31, s89, 0
	global_load_lds_dwordx4 v128, s[30:31]
	s_mov_b32 m0, s67
	s_nop 0
	global_load_lds_dwordx4 v144, s[92:93]
	s_mov_b32 m0, s45
	s_nop 0
	global_load_lds_dwordx4 v144, s[62:63]
	s_waitcnt vmcnt(8)
	s_waitcnt lgkmcnt(0)
	s_barrier
	s_setprio 1
	v_mfma_f32_16x16x32_bf16 v[0:3], v[24:27], v[206:209], v[0:3]
	v_mfma_f32_16x16x32_bf16 v[4:7], v[112:115], v[206:209], v[4:7]
	v_mfma_f32_16x16x32_bf16 v[130:133], v[24:27], v[182:185], v[130:133]
	v_mfma_f32_16x16x32_bf16 v[134:137], v[112:115], v[182:185], v[134:137]
	v_mfma_f32_16x16x32_bf16 v[138:141], v[24:27], v[190:193], v[138:141]
	v_mfma_f32_16x16x32_bf16 v[150:153], v[112:115], v[190:193], v[150:153]
	v_mfma_f32_16x16x32_bf16 v[158:161], v[24:27], v[198:201], v[158:161]
	v_mfma_f32_16x16x32_bf16 v[162:165], v[112:115], v[198:201], v[162:165]
	v_mfma_f32_16x16x32_bf16 v[0:3], v[28:31], v[210:213], v[0:3]
	v_mfma_f32_16x16x32_bf16 v[4:7], v[116:119], v[210:213], v[4:7]
	v_mfma_f32_16x16x32_bf16 v[130:133], v[28:31], v[186:189], v[130:133]
	v_mfma_f32_16x16x32_bf16 v[134:137], v[116:119], v[186:189], v[134:137]
	v_mfma_f32_16x16x32_bf16 v[138:141], v[28:31], v[194:197], v[138:141]
	v_mfma_f32_16x16x32_bf16 v[150:153], v[116:119], v[194:197], v[150:153]
	v_mfma_f32_16x16x32_bf16 v[158:161], v[28:31], v[202:205], v[158:161]
	v_mfma_f32_16x16x32_bf16 v[162:165], v[116:119], v[202:205], v[162:165]
	v_mfma_f32_16x16x32_bf16 v[8:11], v[120:123], v[182:185], v[8:11]
	v_mfma_f32_16x16x32_bf16 v[12:15], v[172:175], v[182:185], v[12:15]
	v_mfma_f32_16x16x32_bf16 v[24:27], v[120:123], v[190:193], v[60:63]
	v_mfma_f32_16x16x32_bf16 v[28:31], v[172:175], v[190:193], v[100:103]
	v_mfma_f32_16x16x32_bf16 v[60:63], v[120:123], v[198:201], v[104:107]
	v_mfma_f32_16x16x32_bf16 v[100:103], v[172:175], v[198:201], v[108:111]
	v_mfma_f32_16x16x32_bf16 v[16:19], v[120:123], v[206:209], v[16:19]
	v_mfma_f32_16x16x32_bf16 v[20:23], v[172:175], v[206:209], v[20:23]
	v_mfma_f32_16x16x32_bf16 v[8:11], v[124:127], v[186:189], v[8:11]
	v_mfma_f32_16x16x32_bf16 v[12:15], v[178:181], v[186:189], v[12:15]
	v_mfma_f32_16x16x32_bf16 v[24:27], v[124:127], v[194:197], v[24:27]
	v_mfma_f32_16x16x32_bf16 v[28:31], v[178:181], v[194:197], v[28:31]
	v_mfma_f32_16x16x32_bf16 v[60:63], v[124:127], v[202:205], v[60:63]
	v_mfma_f32_16x16x32_bf16 v[100:103], v[178:181], v[202:205], v[100:103]
	v_mfma_f32_16x16x32_bf16 v[16:19], v[124:127], v[210:213], v[16:19]
	v_mfma_f32_16x16x32_bf16 v[20:23], v[178:181], v[210:213], v[20:23]
	s_setprio 0
	s_barrier
; #define PG8_STAGE(bufoff, gbase, voff, p64) do { _Pragma("unroll") for (int _i = 0; _i < 2; ++_i) { \
;         const char* _gb = (const char*)(gbase) + (size_t)_i * (p64); const unsigned _la = ldsbase + (unsigned)(bufoff) + (unsigned)_i * 8192u; \
;         asm volatile("s_mov_b32 m0, %0\n\ts_nop 0\n\tglobal_load_lds_dwordx4 %1, %2" :: "s"(_la), "v"(voff), "s"(_gb) : "memory"); } } while (0)
; #define PG8_LDA(dst, b, h) do { _Pragma("unroll") for (int m = 0; m < 4; ++m) _Pragma("unroll") for (int k = 0; k < 2; ++k) dst[m][k] = *(const LAS bf16x8*)(lds + PG8_SA(b, h) + aoff + m * 2048 + k * 1024); } while (0)
; #define PG8_LDB(dst, b, h) do { _Pragma("unroll") for (int n = 0; n < 2; ++n) _Pragma("unroll") for (int k = 0; k < 2; ++k) dst[n][k] = *(const LAS bf16x8*)(lds + PG8_SB(b, h) + boff + n * 2048 + k * 1024); } while (0)
; #define PG8_MMA(ai, bj, At, Bt) do { __builtin_amdgcn_s_setprio(1); _Pragma("unroll") for (int m = 0; m < 4; ++m) _Pragma("unroll") for (int n = 0; n < 2; ++n) _Pragma("unroll") for (int k = 0; k < 2; ++k) \
;         acc[ai][bj][m][n] = __builtin_amdgcn_mfma_f32_16x16x32_bf16(Bt[n][k], At[m][k], acc[ai][bj][m][n], 0, 0, 0); __builtin_amdgcn_s_setprio(0); } while (0)
; #define PG8_WAIT_V(n) asm volatile("s_waitcnt vmcnt(" #n ")" ::: "memory")
; #define PG8_WAIT_L(n) asm volatile("s_waitcnt lgkmcnt(" #n ")" ::: "memory")
; #define PG8_BAR __builtin_amdgcn_s_barrier()
; #define PG8_SCHED __builtin_amdgcn_sched_barrier(0)
; template <class Epi, class Sched>
; __device__ __forceinline__ void gemm_phase(LAS unsigned char* lds, const Sched& S, const Epi& E) {
;     ...
;             PG8_LDB(B0, 0, 0); PG8_LDB(B1, 0, 1); PG8_SCHED; PG8_LDA(At, 0, 0); PG8_STAGE(PG8_SA(1, 1), a1 + hA, voffA, hA / 2);
;             PG8_WAIT_V(8); PG8_WAIT_L(0); PG8_BAR; PG8_MMA(0, 0, At, B0); PG8_MMA(0, 1, At, B1); PG8_BAR; PG8_SCHED;
;             PG8_LDA(At, 0, 1); PG8_STAGE(PG8_SB(0, 0), b2, vB2, hB2 / 2); PG8_STAGE(PG8_SB(0, 1), b2 + hB2, vB2, hB2 / 2); PG8_STAGE(PG8_SA(0, 0), a2, vA2, hA2 / 2);
;             PG8_WAIT_V(8); PG8_WAIT_L(0); PG8_BAR; PG8_MMA(1, 0, At, B0); PG8_MMA(1, 1, At, B1); PG8_BAR; PG8_SCHED;
	ds_read_b128 v[104:107], v142
	ds_read_b128 v[108:111], v142 offset:1024
	ds_read_b128 v[112:115], v142 offset:2048
	ds_read_b128 v[116:119], v142 offset:3072
	ds_read_b128 v[120:123], v143
	ds_read_b128 v[124:127], v143 offset:1024
	ds_read_b128 v[172:175], v143 offset:2048
	ds_read_b128 v[178:181], v143 offset:3072
	ds_read_b128 v[182:185], v148
	ds_read_b128 v[186:189], v148 offset:1024
	ds_read_b128 v[190:193], v148 offset:2048
	ds_read_b128 v[194:197], v148 offset:3072
	ds_read_b128 v[198:201], v148 offset:4096
	ds_read_b128 v[202:205], v148 offset:5120
	ds_read_b128 v[206:209], v148 offset:6144
	ds_read_b128 v[210:213], v148 offset:7168
	s_mov_b32 m0, s69
	s_nop 0
	global_load_lds_dwordx4 v144, s[26:27]
	s_mov_b32 m0, s24
	s_nop 0
	global_load_lds_dwordx4 v144, s[54:55]
	s_waitcnt vmcnt(8)
	s_waitcnt lgkmcnt(0)
	s_barrier
	s_setprio 1
	v_mfma_f32_16x16x32_bf16 v[64:67], v[104:107], v[182:185], v[64:67]
	v_mfma_f32_16x16x32_bf16 v[68:71], v[112:115], v[182:185], v[68:71]
	v_mfma_f32_16x16x32_bf16 v[72:75], v[104:107], v[190:193], v[72:75]
	v_mfma_f32_16x16x32_bf16 v[76:79], v[112:115], v[190:193], v[76:79]
	v_mfma_f32_16x16x32_bf16 v[80:83], v[104:107], v[198:201], v[80:83]
	v_mfma_f32_16x16x32_bf16 v[84:87], v[112:115], v[198:201], v[84:87]
	v_mfma_f32_16x16x32_bf16 v[88:91], v[104:107], v[206:209], v[88:91]
	v_mfma_f32_16x16x32_bf16 v[64:67], v[108:111], v[186:189], v[64:67]
	v_mfma_f32_16x16x32_bf16 v[68:71], v[116:119], v[186:189], v[68:71]
	v_mfma_f32_16x16x32_bf16 v[72:75], v[108:111], v[194:197], v[72:75]
	v_mfma_f32_16x16x32_bf16 v[76:79], v[116:119], v[194:197], v[76:79]
	v_mfma_f32_16x16x32_bf16 v[80:83], v[108:111], v[202:205], v[80:83]
	v_mfma_f32_16x16x32_bf16 v[84:87], v[116:119], v[202:205], v[84:87]
	v_mfma_f32_16x16x32_bf16 v[214:217], v[108:111], v[210:213], v[88:91]
	v_mfma_f32_16x16x32_bf16 v[88:91], v[112:115], v[206:209], v[92:95]
	v_mfma_f32_16x16x32_bf16 v[218:221], v[116:119], v[210:213], v[88:91]
	v_mfma_f32_16x16x32_bf16 v[88:91], v[120:123], v[182:185], v[96:99]
	v_mfma_f32_16x16x32_bf16 v[32:35], v[172:175], v[182:185], v[32:35]
	v_mfma_f32_16x16x32_bf16 v[36:39], v[120:123], v[190:193], v[36:39]
	v_mfma_f32_16x16x32_bf16 v[40:43], v[172:175], v[190:193], v[40:43]
	v_mfma_f32_16x16x32_bf16 v[44:47], v[120:123], v[198:201], v[44:47]
	v_mfma_f32_16x16x32_bf16 v[48:51], v[172:175], v[198:201], v[48:51]
	v_mfma_f32_16x16x32_bf16 v[52:55], v[120:123], v[206:209], v[52:55]
	v_mfma_f32_16x16x32_bf16 v[56:59], v[172:175], v[206:209], v[56:59]
	v_mfma_f32_16x16x32_bf16 v[96:99], v[124:127], v[186:189], v[88:91]
	v_mfma_f32_16x16x32_bf16 v[32:35], v[178:181], v[186:189], v[32:35]
	v_mfma_f32_16x16x32_bf16 v[36:39], v[124:127], v[194:197], v[36:39]
	v_mfma_f32_16x16x32_bf16 v[40:43], v[178:181], v[194:197], v[40:43]
	v_mfma_f32_16x16x32_bf16 v[44:47], v[124:127], v[202:205], v[44:47]
	v_mfma_f32_16x16x32_bf16 v[48:51], v[178:181], v[202:205], v[48:51]
	v_mfma_f32_16x16x32_bf16 v[52:55], v[124:127], v[210:213], v[52:55]
	v_mfma_f32_16x16x32_bf16 v[56:59], v[178:181], v[210:213], v[56:59]
	s_setprio 0
	s_barrier
	s_add_u32 s30, s16, 0x20000
	ds_read_b128 v[88:91], v148 offset:16384
	ds_read_b128 v[92:95], v148 offset:17408
	ds_read_b128 v[182:185], v148 offset:18432
	ds_read_b128 v[186:189], v148 offset:19456
	ds_read_b128 v[190:193], v148 offset:20480
	ds_read_b128 v[194:197], v148 offset:21504
	ds_read_b128 v[198:201], v148 offset:22528
	ds_read_b128 v[202:205], v148 offset:23552
	s_mov_b32 m0, s12
	s_nop 0
	global_load_lds_dwordx4 v128, s[16:17]
	s_mov_b32 m0, s44
	s_addc_u32 s31, s17, 0
	global_load_lds_dwordx4 v128, s[30:31]
	s_add_u32 s30, s16, 0x40000
	s_mov_b32 m0, s42
	s_addc_u32 s31, s17, 0
	global_load_lds_dwordx4 v128, s[30:31]
	s_add_u32 s30, s16, 0x60000
	s_mov_b32 m0, s48
	s_addc_u32 s31, s17, 0
	global_load_lds_dwordx4 v128, s[30:31]
	s_mov_b32 m0, s47
	s_nop 0
	global_load_lds_dwordx4 v144, s[8:9]
	s_mov_b32 m0, s61
	s_nop 0
	global_load_lds_dwordx4 v144, s[10:11]
	s_waitcnt vmcnt(8)
	s_waitcnt lgkmcnt(0)
	s_barrier
	s_setprio 1
	v_mfma_f32_16x16x32_bf16 v[0:3], v[104:107], v[198:201], v[0:3]
	v_mfma_f32_16x16x32_bf16 v[4:7], v[112:115], v[198:201], v[4:7]
	v_mfma_f32_16x16x32_bf16 v[130:133], v[104:107], v[88:91], v[130:133]
	v_mfma_f32_16x16x32_bf16 v[134:137], v[112:115], v[88:91], v[134:137]
	v_mfma_f32_16x16x32_bf16 v[138:141], v[104:107], v[182:185], v[138:141]
	v_mfma_f32_16x16x32_bf16 v[150:153], v[112:115], v[182:185], v[150:153]
	v_mfma_f32_16x16x32_bf16 v[158:161], v[104:107], v[190:193], v[158:161]
	v_mfma_f32_16x16x32_bf16 v[162:165], v[112:115], v[190:193], v[162:165]
	v_mfma_f32_16x16x32_bf16 v[0:3], v[108:111], v[202:205], v[0:3]
	v_mfma_f32_16x16x32_bf16 v[4:7], v[116:119], v[202:205], v[4:7]
	v_mfma_f32_16x16x32_bf16 v[130:133], v[108:111], v[92:95], v[130:133]
	v_mfma_f32_16x16x32_bf16 v[134:137], v[116:119], v[92:95], v[134:137]
	v_mfma_f32_16x16x32_bf16 v[138:141], v[108:111], v[186:189], v[138:141]
	v_mfma_f32_16x16x32_bf16 v[150:153], v[116:119], v[186:189], v[150:153]
	v_mfma_f32_16x16x32_bf16 v[158:161], v[108:111], v[194:197], v[158:161]
	v_mfma_f32_16x16x32_bf16 v[162:165], v[116:119], v[194:197], v[162:165]
	v_mfma_f32_16x16x32_bf16 v[8:11], v[120:123], v[88:91], v[8:11]
	v_mfma_f32_16x16x32_bf16 v[206:209], v[124:127], v[92:95], v[8:11]
	v_mfma_f32_16x16x32_bf16 v[8:11], v[172:175], v[88:91], v[12:15]
	v_mfma_f32_16x16x32_bf16 v[210:213], v[178:181], v[92:95], v[8:11]
	v_mfma_f32_16x16x32_bf16 v[8:11], v[120:123], v[182:185], v[24:27]
	v_mfma_f32_16x16x32_bf16 v[222:225], v[124:127], v[186:189], v[8:11]
	v_mfma_f32_16x16x32_bf16 v[8:11], v[172:175], v[182:185], v[28:31]
	v_mfma_f32_16x16x32_bf16 v[182:185], v[178:181], v[186:189], v[8:11]
	v_mfma_f32_16x16x32_bf16 v[8:11], v[120:123], v[190:193], v[60:63]
	v_mfma_f32_16x16x32_bf16 v[186:189], v[124:127], v[194:197], v[8:11]
	v_mfma_f32_16x16x32_bf16 v[8:11], v[172:175], v[190:193], v[100:103]
	v_mfma_f32_16x16x32_bf16 v[190:193], v[178:181], v[194:197], v[8:11]
	v_mfma_f32_16x16x32_bf16 v[8:11], v[120:123], v[198:201], v[16:19]
	v_mfma_f32_16x16x32_bf16 v[194:197], v[124:127], v[202:205], v[8:11]
	v_mfma_f32_16x16x32_bf16 v[8:11], v[172:175], v[198:201], v[20:23]
	v_mfma_f32_16x16x32_bf16 v[172:175], v[178:181], v[202:205], v[8:11]
	s_setprio 0
	s_barrier
; #define PG8_STAGE(bufoff, gbase, voff, p64) do { _Pragma("unroll") for (int _i = 0; _i < 2; ++_i) { \
;         const char* _gb = (const char*)(gbase) + (size_t)_i * (p64); const unsigned _la = ldsbase + (unsigned)(bufoff) + (unsigned)_i * 8192u; \
;         asm volatile("s_mov_b32 m0, %0\n\ts_nop 0\n\tglobal_load_lds_dwordx4 %1, %2" :: "s"(_la), "v"(voff), "s"(_gb) : "memory"); } } while (0)
; #define PG8_LDA(dst, b, h) do { _Pragma("unroll") for (int m = 0; m < 4; ++m) _Pragma("unroll") for (int k = 0; k < 2; ++k) dst[m][k] = *(const LAS bf16x8*)(lds + PG8_SA(b, h) + aoff + m * 2048 + k * 1024); } while (0)
; #define PG8_LDB(dst, b, h) do { _Pragma("unroll") for (int n = 0; n < 2; ++n) _Pragma("unroll") for (int k = 0; k < 2; ++k) dst[n][k] = *(const LAS bf16x8*)(lds + PG8_SB(b, h) + boff + n * 2048 + k * 1024); } while (0)
; #define PG8_MMA(ai, bj, At, Bt) do { __builtin_amdgcn_s_setprio(1); _Pragma("unroll") for (int m = 0; m < 4; ++m) _Pragma("unroll") for (int n = 0; n < 2; ++n) _Pragma("unroll") for (int k = 0; k < 2; ++k) \
;         acc[ai][bj][m][n] = __builtin_amdgcn_mfma_f32_16x16x32_bf16(Bt[n][k], At[m][k], acc[ai][bj][m][n], 0, 0, 0); __builtin_amdgcn_s_setprio(0); } while (0)
; #define PG8_WAIT_V(n) asm volatile("s_waitcnt vmcnt(" #n ")" ::: "memory")
; #define PG8_WAIT_L(n) asm volatile("s_waitcnt lgkmcnt(" #n ")" ::: "memory")
; #define PG8_BAR __builtin_amdgcn_s_barrier()
; #define PG8_SCHED __builtin_amdgcn_sched_barrier(0)
; template <class Epi, class Sched>
; __device__ __forceinline__ void gemm_phase(LAS unsigned char* lds, const Sched& S, const Epi& E) {
;     ...
;             PG8_LDB(B0, 1, 0); PG8_LDB(B1, 1, 1); PG8_SCHED; PG8_LDA(At, 1, 0); PG8_STAGE(PG8_SA(0, 1), a2 + hA2, vA2, hA2 / 2);
;             PG8_WAIT_V(8); PG8_WAIT_L(0); PG8_BAR; PG8_MMA(0, 0, At, B0); PG8_MMA(0, 1, At, B1); PG8_BAR; PG8_SCHED;
;             PG8_LDA(At, 1, 1); PG8_STAGE(PG8_SB(1, 0), b3, vB2, hB2 / 2); PG8_STAGE(PG8_SB(1, 1), b3 + hB2, vB2, hB2 / 2); PG8_STAGE(PG8_SA(1, 0), a3, vA2, hA2 / 2);
;             PG8_WAIT_V(8); PG8_WAIT_L(0); PG8_BAR; PG8_MMA(1, 0, At, B0); PG8_MMA(1, 1, At, B1); PG8_BAR; PG8_SCHED;
;         }
;         if (wr == 0) PG8_BAR;
	s_nop 4
	ds_read_b128 v[8:11], v149
	ds_read_b128 v[12:15], v149 offset:1024
	ds_read_b128 v[16:19], v149 offset:2048
	ds_read_b128 v[20:23], v149 offset:3072
	ds_read_b128 v[178:181], v154
	ds_read_b128 v[198:201], v154 offset:1024
	ds_read_b128 v[202:205], v154 offset:2048
	ds_read_b128 v[226:229], v154 offset:3072
	ds_read_b128 v[24:27], v148 offset:32768
	ds_read_b128 v[28:31], v148 offset:33792
	ds_read_b128 v[60:63], v148 offset:34816
	ds_read_b128 v[230:233], v148 offset:35840
	ds_read_b128 v[234:237], v148 offset:36864
	ds_read_b128 v[238:241], v148 offset:37888
	ds_read_b128 v[242:245], v148 offset:38912
	ds_read_b128 v[246:249], v148 offset:39936
	s_mov_b32 m0, s14
	s_nop 0
	global_load_lds_dwordx4 v144, s[74:75]
	s_mov_b32 m0, s15
	s_nop 0
	global_load_lds_dwordx4 v144, s[76:77]
	s_waitcnt vmcnt(8)
	s_waitcnt lgkmcnt(0)
	s_barrier
	s_setprio 1
	v_mfma_f32_16x16x32_bf16 v[64:67], v[8:11], v[24:27], v[64:67]
	v_mfma_f32_16x16x32_bf16 v[124:127], v[12:15], v[28:31], v[64:67]
	v_mfma_f32_16x16x32_bf16 v[64:67], v[16:19], v[24:27], v[68:71]
	v_mfma_f32_16x16x32_bf16 v[120:123], v[20:23], v[28:31], v[64:67]
	v_mfma_f32_16x16x32_bf16 v[64:67], v[8:11], v[60:63], v[72:75]
	v_mfma_f32_16x16x32_bf16 v[108:111], v[12:15], v[230:233], v[64:67]
	v_mfma_f32_16x16x32_bf16 v[64:67], v[16:19], v[60:63], v[76:79]
	v_mfma_f32_16x16x32_bf16 v[104:107], v[20:23], v[230:233], v[64:67]
	v_mfma_f32_16x16x32_bf16 v[64:67], v[8:11], v[234:237], v[80:83]
	v_mfma_f32_16x16x32_bf16 v[92:95], v[12:15], v[238:241], v[64:67]
	v_mfma_f32_16x16x32_bf16 v[64:67], v[16:19], v[234:237], v[84:87]
	v_mfma_f32_16x16x32_bf16 v[88:91], v[20:23], v[238:241], v[64:67]
	v_mfma_f32_16x16x32_bf16 v[64:67], v[8:11], v[242:245], v[214:217]
	v_mfma_f32_16x16x32_bf16 v[76:79], v[12:15], v[246:249], v[64:67]
	v_mfma_f32_16x16x32_bf16 v[64:67], v[16:19], v[242:245], v[218:221]
	v_mfma_f32_16x16x32_bf16 v[72:75], v[20:23], v[246:249], v[64:67]
	v_mfma_f32_16x16x32_bf16 v[64:67], v[178:181], v[24:27], v[96:99]
	v_mfma_f32_16x16x32_bf16 v[24:27], v[202:205], v[24:27], v[32:35]
	v_mfma_f32_16x16x32_bf16 v[112:115], v[226:229], v[28:31], v[24:27]
	v_mfma_f32_16x16x32_bf16 v[24:27], v[178:181], v[60:63], v[36:39]
	v_mfma_f32_16x16x32_bf16 v[100:103], v[198:201], v[230:233], v[24:27]
	v_mfma_f32_16x16x32_bf16 v[24:27], v[202:205], v[60:63], v[40:43]
	v_mfma_f32_16x16x32_bf16 v[96:99], v[226:229], v[230:233], v[24:27]
	v_mfma_f32_16x16x32_bf16 v[24:27], v[178:181], v[234:237], v[44:47]
	v_mfma_f32_16x16x32_bf16 v[84:87], v[198:201], v[238:241], v[24:27]
	v_mfma_f32_16x16x32_bf16 v[24:27], v[202:205], v[234:237], v[48:51]
	v_mfma_f32_16x16x32_bf16 v[80:83], v[226:229], v[238:241], v[24:27]
	v_mfma_f32_16x16x32_bf16 v[24:27], v[178:181], v[242:245], v[52:55]
	v_mfma_f32_16x16x32_bf16 v[68:71], v[198:201], v[246:249], v[24:27]
	v_mfma_f32_16x16x32_bf16 v[24:27], v[202:205], v[242:245], v[56:59]
	v_mfma_f32_16x16x32_bf16 v[116:119], v[198:201], v[28:31], v[64:67]
	v_mfma_f32_16x16x32_bf16 v[64:67], v[226:229], v[246:249], v[24:27]
	s_setprio 0
	s_barrier
	s_add_u32 s30, s16, 0x80
	s_addc_u32 s31, s17, 0
	ds_read_b128 v[32:35], v148 offset:49152
	ds_read_b128 v[36:39], v148 offset:50176
	ds_read_b128 v[214:217], v148 offset:51200
	ds_read_b128 v[218:221], v148 offset:52224
	ds_read_b128 v[230:233], v148 offset:53248
	ds_read_b128 v[234:237], v148 offset:54272
	ds_read_b128 v[238:241], v148 offset:55296
	ds_read_b128 v[242:245], v148 offset:56320
	s_mov_b32 m0, s65
	s_nop 0
	global_load_lds_dwordx4 v128, s[30:31]
	s_add_u32 s30, s16, 0x20080
	s_mov_b32 m0, s66
	s_addc_u32 s31, s17, 0
	global_load_lds_dwordx4 v128, s[30:31]
	s_add_u32 s30, s16, 0x40080
	s_mov_b32 m0, s36
	s_addc_u32 s31, s17, 0
	global_load_lds_dwordx4 v128, s[30:31]
	s_add_u32 s16, s16, 0x60080
	s_mov_b32 m0, s37
	s_addc_u32 s17, s17, 0
	global_load_lds_dwordx4 v128, s[16:17]
	s_mov_b32 m0, s67
	s_nop 0
	global_load_lds_dwordx4 v144, s[82:83]
	s_mov_b32 m0, s45
	s_nop 0
	global_load_lds_dwordx4 v144, s[84:85]
	s_waitcnt vmcnt(8)
	s_waitcnt lgkmcnt(0)
	s_barrier
	s_setprio 1
	v_mfma_f32_16x16x32_bf16 v[24:27], v[8:11], v[32:35], v[130:133]
	v_mfma_f32_16x16x32_bf16 v[60:63], v[12:15], v[36:39], v[24:27]
	v_mfma_f32_16x16x32_bf16 v[24:27], v[16:19], v[32:35], v[134:137]
	v_mfma_f32_16x16x32_bf16 v[56:59], v[20:23], v[36:39], v[24:27]
	v_mfma_f32_16x16x32_bf16 v[24:27], v[8:11], v[214:217], v[138:141]
	v_mfma_f32_16x16x32_bf16 v[44:47], v[12:15], v[218:221], v[24:27]
	v_mfma_f32_16x16x32_bf16 v[24:27], v[16:19], v[214:217], v[150:153]
	v_mfma_f32_16x16x32_bf16 v[40:43], v[20:23], v[218:221], v[24:27]
	v_mfma_f32_16x16x32_bf16 v[24:27], v[8:11], v[230:233], v[158:161]
	v_mfma_f32_16x16x32_bf16 v[0:3], v[8:11], v[238:241], v[0:3]
	v_mfma_f32_16x16x32_bf16 v[28:31], v[12:15], v[234:237], v[24:27]
	v_mfma_f32_16x16x32_bf16 v[24:27], v[16:19], v[230:233], v[162:165]
	v_mfma_f32_16x16x32_bf16 v[12:15], v[12:15], v[242:245], v[0:3]
	v_mfma_f32_16x16x32_bf16 v[0:3], v[16:19], v[238:241], v[4:7]
	v_mfma_f32_16x16x32_bf16 v[24:27], v[20:23], v[234:237], v[24:27]
	v_mfma_f32_16x16x32_bf16 v[8:11], v[20:23], v[242:245], v[0:3]
	v_mfma_f32_16x16x32_bf16 v[0:3], v[178:181], v[32:35], v[206:209]
	v_mfma_f32_16x16x32_bf16 v[52:55], v[198:201], v[36:39], v[0:3]
	v_mfma_f32_16x16x32_bf16 v[0:3], v[202:205], v[32:35], v[210:213]
	v_mfma_f32_16x16x32_bf16 v[48:51], v[226:229], v[36:39], v[0:3]
	v_mfma_f32_16x16x32_bf16 v[0:3], v[178:181], v[214:217], v[222:225]
	v_mfma_f32_16x16x32_bf16 v[36:39], v[198:201], v[218:221], v[0:3]
	v_mfma_f32_16x16x32_bf16 v[0:3], v[202:205], v[214:217], v[182:185]
	v_mfma_f32_16x16x32_bf16 v[32:35], v[226:229], v[218:221], v[0:3]
	v_mfma_f32_16x16x32_bf16 v[0:3], v[178:181], v[230:233], v[186:189]
	v_mfma_f32_16x16x32_bf16 v[20:23], v[198:201], v[234:237], v[0:3]
	v_mfma_f32_16x16x32_bf16 v[0:3], v[202:205], v[230:233], v[190:193]
	v_mfma_f32_16x16x32_bf16 v[16:19], v[226:229], v[234:237], v[0:3]
	v_mfma_f32_16x16x32_bf16 v[0:3], v[178:181], v[238:241], v[194:197]
	v_mfma_f32_16x16x32_bf16 v[4:7], v[198:201], v[242:245], v[0:3]
	v_mfma_f32_16x16x32_bf16 v[0:3], v[202:205], v[238:241], v[172:175]
	v_mfma_f32_16x16x32_bf16 v[0:3], v[226:229], v[242:245], v[0:3]
	s_setprio 0
	s_barrier
	s_andn2_b64 vcc, exec, s[86:87]
	s_cbranch_vccnz .LBB0_833
	s_barrier

; #define PG8_STAGE(bufoff, gbase, voff, p64) do { _Pragma("unroll") for (int _i = 0; _i < 2; ++_i) { \
;         const char* _gb = (const char*)(gbase) + (size_t)_i * (p64); const unsigned _la = ldsbase + (unsigned)(bufoff) + (unsigned)_i * 8192u; \
;         asm volatile("s_mov_b32 m0, %0\n\ts_nop 0\n\tglobal_load_lds_dwordx4 %1, %2" :: "s"(_la), "v"(voff), "s"(_gb) : "memory"); } } while (0)
; #define PG8_WAIT_V(n) asm volatile("s_waitcnt vmcnt(" #n ")" ::: "memory")
; #define PG8_BAR __builtin_amdgcn_s_barrier()
; template <class Epi, class Sched>
; __device__ __forceinline__ void gemm_phase(LAS unsigned char* lds, const Sched& S, const Epi& E) {
;     ...
;     { Unit u0; if (!S.next(0, u0)) return;
;       cA = u0.A; cB = u0.B; hA = (unsigned)HALF * u0.lda2; hB = (unsigned)HALF * u0.ldb2; nt = u0.nt;
;       voffA = (unsigned)(sR * u0.lda2 + sC2); voffB = (unsigned)(sRb * u0.ldb2 + sC2); }
;     f32x4 acc[2][2][4][2];
; #pragma unroll
;     for (int a = 0; a < 2; ++a)
; #pragma unroll
;         for (int b = 0; b < 2; ++b)
; #pragma unroll
;             for (int m = 0; m < 4; ++m)
; #pragma unroll
;                 for (int n = 0; n < 2; ++n) acc[a][b][m][n] = (f32x4){0.f, 0.f, 0.f, 0.f};
;     bf16x8 At[4][2], B0[2][2], B1[2][2];
;     PG8_STAGE(PG8_SB(0, 0), cB, voffB, hB / 2); PG8_STAGE(PG8_SB(0, 1), cB + hB, voffB, hB / 2); PG8_STAGE(PG8_SA(0, 0), cA, voffA, hA / 2); PG8_STAGE(PG8_SA(0, 1), cA + hA, voffA, hA / 2);
;     if (wr == 1) PG8_BAR;
;     PG8_WAIT_V(2); PG8_BAR;
; __global__ void __launch_bounds__(512, 2) fwd_megakernel(Params Parg) {
;     ...
;             __builtin_amdgcn_fence(__ATOMIC_ACQUIRE, "agent");
;             { PHASE_BEGIN
;               bf16_t* pscr = (bf16_t*)(ws + WS_PSCR + (size_t)(bid >> 1) * (256 * D * 2) + (size_t)(bid & 1) * (CH * 2));
;               const int ib = item & 1, h = (item >> 1) & 3, n = item >> 3;
;               SVSched S{(const char*)(ws + WS_KTQK) + ((size_t)(n * CH + ib * 256) * D + h * 256) * 2, (const char*)(ws + WS_SB) + ((size_t)((h * NCH + n) * 512) * 512) * 2,
;                         (const char*)(ws + WS_VT) + ((size_t)((h * NCH + n) * 512) * 512) * 2, (const char*)pscr, item};
;               EpiSV E; E.o = (bf16_t*)pp->out + (size_t)b * L * 2048; E.dec = WSP(float, WS_DEC); gemm_phase(lds, S, E); }
.LBB0_836:
	v_readlane_b32 s0, v254, 62
	v_readlane_b32 s1, v254, 63
	s_mov_b64 s[4:5], s[0:1]
	s_waitcnt vmcnt(0)
	s_barrier
	s_waitcnt vmcnt(0)
	buffer_inv sc1
	s_load_dwordx4 s[8:11], s[4:5], 0xc8
	s_ashr_i32 s6, s73, 3
	s_lshl_b32 s7, s6, 9
	s_or_b32 s4, s7, s51
	s_ashr_i32 s5, s4, 31
	s_lshl_b32 s12, s72, 9
	s_lshl_b64 s[4:5], s[4:5], 11
	v_mov_b32_e32 v0, v176
	s_waitcnt lgkmcnt(0)
	s_add_u32 s4, s10, s4
	s_addc_u32 s5, s11, s5
	s_add_u32 s34, s4, s12
	v_mov_b32_e32 v0, v176
	s_addc_u32 s35, s5, 0
	s_add_u32 s26, s34, 0x8900000
	v_bfe_i32 v3, v0, 27, 1
	v_lshlrev_b32_e32 v1, 4, v0
	v_lshrrev_b32_e32 v3, 22, v3
	s_addc_u32 s27, s35, 0
	s_lshl_b32 s4, s72, 14
	v_add_u32_e32 v3, v1, v3
	s_add_i32 s4, s4, s7
	v_and_b32_e32 v3, 0xfffffc00, v3
	s_ashr_i32 s5, s4, 31
	v_sub_u32_e32 v1, v1, v3
	s_lshl_b64 s[16:17], s[4:5], 10
	v_ashrrev_i32_e32 v2, 31, v0
	v_lshrrev_b32_e32 v3, 4, v1
	s_add_u32 s7, s10, s16
	v_lshrrev_b32_e32 v2, 26, v2
	v_bitop3_b32 v1, v3, v1, 32 bitop3:0x6c
	s_addc_u32 s24, s11, s17
	v_add_u32_e32 v2, v0, v2
	v_ashrrev_i32_e32 v4, 31, v1
	s_add_u32 s38, s7, 0x10900000
	v_readfirstlane_b32 s22, v0
	v_ashrrev_i32_e32 v2, 6, v2
	v_lshrrev_b32_e32 v4, 26, v4
	s_addc_u32 s39, s24, 0
	s_ashr_i32 s48, s22, 6
	v_lshlrev_b32_e32 v3, 3, v2
	v_add_u32_e32 v4, v1, v4
	v_and_b32_e32 v3, -16, v3
	v_ashrrev_i32_e32 v5, 6, v4
	v_and_b32_e32 v4, 0xc0, v4
	s_lshl_b32 s4, s48, 10
	v_add_u32_e32 v3, v5, v3
	v_sub_u32_e32 v1, v1, v4
	v_and_b32_e32 v5, 3, v5
	s_mov_b32 s5, 0x3fffe0
	s_add_i32 s4, s4, 0
	s_ashr_i32 s23, s22, 8
	v_lshlrev_b32_e32 v2, 5, v2
	v_ashrrev_i16_sdwa v1, v157, sext(v1) dst_sel:DWORD dst_unused:UNUSED_PAD src0_sel:DWORD src1_sel:BYTE_0
	v_lshlrev_b32_e32 v4, 1, v3
	v_lshrrev_b32_e32 v6, 2, v3
	v_and_or_b32 v5, v3, s5, v5
	s_add_i32 s5, s4, 0x10000
	v_bfe_i32 v1, v1, 0, 16
	v_and_b32_e32 v4, 24, v4
	v_and_b32_e32 v6, 4, v6
	v_and_b32_e32 v2, 32, v2
	s_add_u32 s14, s7, 0x10910000
	v_or3_b32 v4, v5, v6, v4
	v_add_lshl_u32 v1, v2, v1, 1
	s_addc_u32 s15, s24, 0
	s_add_i32 s12, s4, 0x12000
	v_lshl_add_u32 v128, v4, 10, v1
	s_mov_b32 m0, s5
	s_nop 0
	global_load_lds_dwordx4 v128, s[38:39]
	s_mov_b32 m0, s12
	s_add_u32 s30, s7, 0x10920000
	global_load_lds_dwordx4 v128, s[14:15]
	s_addc_u32 s31, s24, 0
	s_add_i32 s14, s4, 0x14000
	s_mov_b32 m0, s14
	s_nop 0
	global_load_lds_dwordx4 v128, s[30:31]
	s_add_u32 s30, s7, 0x10930000
	s_addc_u32 s31, s24, 0
	s_add_i32 s15, s4, 0x16000
	s_mov_b32 m0, s15
	s_nop 0
	global_load_lds_dwordx4 v128, s[30:31]
	s_add_u32 s30, s34, 0x8920000
	v_lshl_add_u32 v172, v3, 11, v1
	s_mov_b32 m0, s4
	s_nop 0
	global_load_lds_dwordx4 v172, s[26:27]
	s_addc_u32 s31, s35, 0
	s_add_i32 s24, s4, 0x2000
	s_mov_b32 m0, s24
	s_nop 0
	global_load_lds_dwordx4 v172, s[30:31]
	s_add_u32 s30, s34, 0x8940000
	s_addc_u32 s31, s35, 0
	s_add_i32 s33, s4, 0x4000
	s_mov_b32 m0, s33
	s_nop 0
	global_load_lds_dwordx4 v172, s[30:31]
	s_add_u32 s30, s34, 0x8960000
	s_addc_u32 s31, s35, 0
	s_add_i32 s34, s4, 0x6000
	s_mov_b32 m0, s34
	s_nop 0
	global_load_lds_dwordx4 v172, s[30:31]
	s_cmp_eq_u32 s23, 1
	s_cselect_b64 s[40:41], -1, 0
	s_cmp_lg_u32 s23, 1
	s_cbranch_scc1 .LBB0_838
	s_barrier

; #define PG8_STAGE(bufoff, gbase, voff, p64) do { _Pragma("unroll") for (int _i = 0; _i < 2; ++_i) { \
;         const char* _gb = (const char*)(gbase) + (size_t)_i * (p64); const unsigned _la = ldsbase + (unsigned)(bufoff) + (unsigned)_i * 8192u; \
;         asm volatile("s_mov_b32 m0, %0\n\ts_nop 0\n\tglobal_load_lds_dwordx4 %1, %2" :: "s"(_la), "v"(voff), "s"(_gb) : "memory"); } } while (0)
; #define PG8_LDA(dst, b, h) do { _Pragma("unroll") for (int m = 0; m < 4; ++m) _Pragma("unroll") for (int k = 0; k < 2; ++k) dst[m][k] = *(const LAS bf16x8*)(lds + PG8_SA(b, h) + aoff + m * 2048 + k * 1024); } while (0)
; #define PG8_LDB(dst, b, h) do { _Pragma("unroll") for (int n = 0; n < 2; ++n) _Pragma("unroll") for (int k = 0; k < 2; ++k) dst[n][k] = *(const LAS bf16x8*)(lds + PG8_SB(b, h) + boff + n * 2048 + k * 1024); } while (0)
; #define PG8_MMA(ai, bj, At, Bt) do { __builtin_amdgcn_s_setprio(1); _Pragma("unroll") for (int m = 0; m < 4; ++m) _Pragma("unroll") for (int n = 0; n < 2; ++n) _Pragma("unroll") for (int k = 0; k < 2; ++k) \
;         acc[ai][bj][m][n] = __builtin_amdgcn_mfma_f32_16x16x32_bf16(Bt[n][k], At[m][k], acc[ai][bj][m][n], 0, 0, 0); __builtin_amdgcn_s_setprio(0); } while (0)
; #define PG8_WAIT_V(n) asm volatile("s_waitcnt vmcnt(" #n ")" ::: "memory")
; #define PG8_WAIT_L(n) asm volatile("s_waitcnt lgkmcnt(" #n ")" ::: "memory")
; #define PG8_BAR __builtin_amdgcn_s_barrier()
; #define PG8_SCHED __builtin_amdgcn_sched_barrier(0)
; template <class Epi, class Sched>
; __device__ __forceinline__ void gemm_phase(LAS unsigned char* lds, const Sched& S, const Epi& E) {
;     ...
;             PG8_LDB(B0, 0, 0); PG8_LDB(B1, 0, 1); PG8_SCHED; PG8_LDA(At, 0, 0); PG8_STAGE(PG8_SA(1, 1), a1 + hA, voffA, hA / 2);
;             PG8_WAIT_V(8); PG8_WAIT_L(0); PG8_BAR; PG8_MMA(0, 0, At, B0); PG8_MMA(0, 1, At, B1); PG8_BAR; PG8_SCHED;
;             PG8_LDA(At, 0, 1); PG8_STAGE(PG8_SB(0, 0), b2, vB2, hB2 / 2); PG8_STAGE(PG8_SB(0, 1), b2 + hB2, vB2, hB2 / 2); PG8_STAGE(PG8_SA(0, 0), a2, vA2, hA2 / 2);
;             PG8_WAIT_V(8); PG8_WAIT_L(0); PG8_BAR; PG8_MMA(1, 0, At, B0); PG8_MMA(1, 1, At, B1); PG8_BAR; PG8_SCHED;
.LBB0_844:
	v_add_u32_e32 v142, 0x10000, v175
	v_add_u32_e32 v154, 0x14000, v175
	ds_read_b128 v[130:133], v142
	ds_read_b128 v[134:137], v142 offset:1024
	ds_read_b128 v[138:141], v142 offset:2048
	ds_read_b128 v[142:145], v142 offset:3072
	ds_read_b128 v[146:149], v154
	ds_read_b128 v[150:153], v154 offset:1024
	ds_read_b128 v[158:161], v154 offset:2048
	ds_read_b128 v[162:165], v154 offset:3072
	s_add_i32 s80, s8, 2
	s_cmp_eq_u32 s73, s8
	s_cselect_b32 s8, s56, s76
	s_cselect_b32 s9, s57, s77
	s_cselect_b32 s22, s58, s78
	s_cselect_b32 s23, s59, s79
	s_add_u32 s16, s8, 0x80
	s_addc_u32 s17, s9, 0
	ds_read_b128 v[180:183], v177
	ds_read_b128 v[184:187], v177 offset:1024
	ds_read_b128 v[188:191], v177 offset:2048
	ds_read_b128 v[192:195], v177 offset:3072
	ds_read_b128 v[196:199], v177 offset:4096
	ds_read_b128 v[200:203], v177 offset:5120
	ds_read_b128 v[204:207], v177 offset:6144
	ds_read_b128 v[208:211], v177 offset:7168
	s_add_u32 s30, s76, 0x3ff80
	s_mov_b32 m0, s66
	s_addc_u32 s31, s77, 0
	global_load_lds_dwordx4 v172, s[30:31]
	s_add_u32 s30, s76, 0x5ff80
	s_mov_b32 m0, s67
	s_addc_u32 s31, s77, 0
	global_load_lds_dwordx4 v172, s[30:31]
	s_waitcnt vmcnt(8)
	s_waitcnt lgkmcnt(0)
	s_barrier
	s_setprio 1
	v_mfma_f32_16x16x32_bf16 v[124:127], v[130:133], v[180:183], v[124:127]
	v_mfma_f32_16x16x32_bf16 v[120:123], v[138:141], v[180:183], v[120:123]
	v_mfma_f32_16x16x32_bf16 v[116:119], v[130:133], v[188:191], v[116:119]
	v_mfma_f32_16x16x32_bf16 v[112:115], v[138:141], v[188:191], v[112:115]
	v_mfma_f32_16x16x32_bf16 v[108:111], v[130:133], v[196:199], v[108:111]
	v_mfma_f32_16x16x32_bf16 v[104:107], v[138:141], v[196:199], v[104:107]
	v_mfma_f32_16x16x32_bf16 v[100:103], v[130:133], v[204:207], v[100:103]
	v_mfma_f32_16x16x32_bf16 v[96:99], v[138:141], v[204:207], v[96:99]
	v_mfma_f32_16x16x32_bf16 v[124:127], v[134:137], v[184:187], v[124:127]
	v_mfma_f32_16x16x32_bf16 v[120:123], v[142:145], v[184:187], v[120:123]
	v_mfma_f32_16x16x32_bf16 v[116:119], v[134:137], v[192:195], v[116:119]
	v_mfma_f32_16x16x32_bf16 v[112:115], v[142:145], v[192:195], v[112:115]
	v_mfma_f32_16x16x32_bf16 v[108:111], v[134:137], v[200:203], v[108:111]
	v_mfma_f32_16x16x32_bf16 v[104:107], v[142:145], v[200:203], v[104:107]
	v_mfma_f32_16x16x32_bf16 v[100:103], v[134:137], v[208:211], v[100:103]
	v_mfma_f32_16x16x32_bf16 v[96:99], v[142:145], v[208:211], v[96:99]
	v_mfma_f32_16x16x32_bf16 v[92:95], v[146:149], v[180:183], v[92:95]
	v_mfma_f32_16x16x32_bf16 v[88:91], v[158:161], v[180:183], v[88:91]
	v_mfma_f32_16x16x32_bf16 v[84:87], v[146:149], v[188:191], v[84:87]
	v_mfma_f32_16x16x32_bf16 v[80:83], v[158:161], v[188:191], v[80:83]
	v_mfma_f32_16x16x32_bf16 v[76:79], v[146:149], v[196:199], v[76:79]
	v_mfma_f32_16x16x32_bf16 v[72:75], v[158:161], v[196:199], v[72:75]
	v_mfma_f32_16x16x32_bf16 v[68:71], v[146:149], v[204:207], v[68:71]
	v_mfma_f32_16x16x32_bf16 v[64:67], v[158:161], v[204:207], v[64:67]
	v_mfma_f32_16x16x32_bf16 v[92:95], v[150:153], v[184:187], v[92:95]
	v_mfma_f32_16x16x32_bf16 v[88:91], v[162:165], v[184:187], v[88:91]
	v_mfma_f32_16x16x32_bf16 v[84:87], v[150:153], v[192:195], v[84:87]
	v_mfma_f32_16x16x32_bf16 v[80:83], v[162:165], v[192:195], v[80:83]
	v_mfma_f32_16x16x32_bf16 v[76:79], v[150:153], v[200:203], v[76:79]
	v_mfma_f32_16x16x32_bf16 v[72:75], v[162:165], v[200:203], v[72:75]
	v_mfma_f32_16x16x32_bf16 v[68:71], v[150:153], v[208:211], v[68:71]
	v_mfma_f32_16x16x32_bf16 v[64:67], v[162:165], v[208:211], v[64:67]
	s_setprio 0
	s_barrier
	s_add_u32 s30, s22, 0x10000
	ds_read_b128 v[180:183], v177 offset:16384
	ds_read_b128 v[184:187], v177 offset:17408
	ds_read_b128 v[188:191], v177 offset:18432
	ds_read_b128 v[192:195], v177 offset:19456
	ds_read_b128 v[196:199], v177 offset:20480
	ds_read_b128 v[200:203], v177 offset:21504
	ds_read_b128 v[204:207], v177 offset:22528
	ds_read_b128 v[208:211], v177 offset:23552
	s_mov_b32 m0, s5
	s_nop 0
	global_load_lds_dwordx4 v128, s[22:23]
	s_mov_b32 m0, s12
	s_addc_u32 s31, s23, 0
	global_load_lds_dwordx4 v128, s[30:31]
	s_add_u32 s30, s22, 0x20000
	s_mov_b32 m0, s14
	s_addc_u32 s31, s23, 0
	global_load_lds_dwordx4 v128, s[30:31]
	s_add_u32 s30, s22, 0x30000
	s_mov_b32 m0, s15
	s_addc_u32 s31, s23, 0
	global_load_lds_dwordx4 v128, s[30:31]
	s_mov_b32 m0, s4
	s_nop 0
	global_load_lds_dwordx4 v172, s[8:9]
	s_add_u32 s30, s8, 0x20000
	s_mov_b32 m0, s24
	s_addc_u32 s31, s9, 0
	global_load_lds_dwordx4 v172, s[30:31]
	s_waitcnt vmcnt(8)
	s_waitcnt lgkmcnt(0)
	s_barrier
	s_setprio 1
	v_mfma_f32_16x16x32_bf16 v[60:63], v[130:133], v[180:183], v[60:63]
	v_mfma_f32_16x16x32_bf16 v[56:59], v[138:141], v[180:183], v[56:59]
	v_mfma_f32_16x16x32_bf16 v[52:55], v[130:133], v[188:191], v[52:55]
	v_mfma_f32_16x16x32_bf16 v[48:51], v[138:141], v[188:191], v[48:51]
	v_mfma_f32_16x16x32_bf16 v[44:47], v[130:133], v[196:199], v[44:47]
	v_mfma_f32_16x16x32_bf16 v[40:43], v[138:141], v[196:199], v[40:43]
	v_mfma_f32_16x16x32_bf16 v[36:39], v[130:133], v[204:207], v[36:39]
	v_mfma_f32_16x16x32_bf16 v[32:35], v[138:141], v[204:207], v[32:35]
	v_mfma_f32_16x16x32_bf16 v[60:63], v[134:137], v[184:187], v[60:63]
	v_mfma_f32_16x16x32_bf16 v[56:59], v[142:145], v[184:187], v[56:59]
	v_mfma_f32_16x16x32_bf16 v[52:55], v[134:137], v[192:195], v[52:55]
	v_mfma_f32_16x16x32_bf16 v[48:51], v[142:145], v[192:195], v[48:51]
	v_mfma_f32_16x16x32_bf16 v[44:47], v[134:137], v[200:203], v[44:47]
	v_mfma_f32_16x16x32_bf16 v[40:43], v[142:145], v[200:203], v[40:43]
	v_mfma_f32_16x16x32_bf16 v[36:39], v[134:137], v[208:211], v[36:39]
	v_mfma_f32_16x16x32_bf16 v[32:35], v[142:145], v[208:211], v[32:35]
	v_mfma_f32_16x16x32_bf16 v[28:31], v[146:149], v[180:183], v[28:31]
	v_mfma_f32_16x16x32_bf16 v[24:27], v[158:161], v[180:183], v[24:27]
	v_mfma_f32_16x16x32_bf16 v[20:23], v[146:149], v[188:191], v[20:23]
	v_mfma_f32_16x16x32_bf16 v[16:19], v[158:161], v[188:191], v[16:19]
	v_mfma_f32_16x16x32_bf16 v[12:15], v[146:149], v[196:199], v[12:15]
	v_mfma_f32_16x16x32_bf16 v[8:11], v[158:161], v[196:199], v[8:11]
	v_mfma_f32_16x16x32_bf16 v[4:7], v[146:149], v[204:207], v[4:7]
	v_mfma_f32_16x16x32_bf16 v[0:3], v[158:161], v[204:207], v[0:3]
	v_mfma_f32_16x16x32_bf16 v[28:31], v[150:153], v[184:187], v[28:31]
	v_mfma_f32_16x16x32_bf16 v[24:27], v[162:165], v[184:187], v[24:27]
	v_mfma_f32_16x16x32_bf16 v[20:23], v[150:153], v[192:195], v[20:23]
	v_mfma_f32_16x16x32_bf16 v[16:19], v[162:165], v[192:195], v[16:19]
	v_mfma_f32_16x16x32_bf16 v[12:15], v[150:153], v[200:203], v[12:15]
	v_mfma_f32_16x16x32_bf16 v[8:11], v[162:165], v[200:203], v[8:11]
	v_mfma_f32_16x16x32_bf16 v[4:7], v[150:153], v[208:211], v[4:7]
	v_mfma_f32_16x16x32_bf16 v[0:3], v[162:165], v[208:211], v[0:3]
	s_setprio 0
	s_barrier
; #define PG8_STAGE(bufoff, gbase, voff, p64) do { _Pragma("unroll") for (int _i = 0; _i < 2; ++_i) { \
;         const char* _gb = (const char*)(gbase) + (size_t)_i * (p64); const unsigned _la = ldsbase + (unsigned)(bufoff) + (unsigned)_i * 8192u; \
;         asm volatile("s_mov_b32 m0, %0\n\ts_nop 0\n\tglobal_load_lds_dwordx4 %1, %2" :: "s"(_la), "v"(voff), "s"(_gb) : "memory"); } } while (0)
; #define PG8_LDA(dst, b, h) do { _Pragma("unroll") for (int m = 0; m < 4; ++m) _Pragma("unroll") for (int k = 0; k < 2; ++k) dst[m][k] = *(const LAS bf16x8*)(lds + PG8_SA(b, h) + aoff + m * 2048 + k * 1024); } while (0)
; #define PG8_LDB(dst, b, h) do { _Pragma("unroll") for (int n = 0; n < 2; ++n) _Pragma("unroll") for (int k = 0; k < 2; ++k) dst[n][k] = *(const LAS bf16x8*)(lds + PG8_SB(b, h) + boff + n * 2048 + k * 1024); } while (0)
; #define PG8_MMA(ai, bj, At, Bt) do { __builtin_amdgcn_s_setprio(1); _Pragma("unroll") for (int m = 0; m < 4; ++m) _Pragma("unroll") for (int n = 0; n < 2; ++n) _Pragma("unroll") for (int k = 0; k < 2; ++k) \
;         acc[ai][bj][m][n] = __builtin_amdgcn_mfma_f32_16x16x32_bf16(Bt[n][k], At[m][k], acc[ai][bj][m][n], 0, 0, 0); __builtin_amdgcn_s_setprio(0); } while (0)
; #define PG8_WAIT_V(n) asm volatile("s_waitcnt vmcnt(" #n ")" ::: "memory")
; #define PG8_WAIT_L(n) asm volatile("s_waitcnt lgkmcnt(" #n ")" ::: "memory")
; #define PG8_BAR __builtin_amdgcn_s_barrier()
; #define PG8_SCHED __builtin_amdgcn_sched_barrier(0)
; template <class Epi, class Sched>
; __device__ __forceinline__ void gemm_phase(LAS unsigned char* lds, const Sched& S, const Epi& E) {
;     ...
;             PG8_LDB(B0, 1, 0); PG8_LDB(B1, 1, 1); PG8_SCHED; PG8_LDA(At, 1, 0); PG8_STAGE(PG8_SA(0, 1), a2 + hA2, vA2, hA2 / 2);
;             PG8_WAIT_V(8); PG8_WAIT_L(0); PG8_BAR; PG8_MMA(0, 0, At, B0); PG8_MMA(0, 1, At, B1); PG8_BAR; PG8_SCHED;
;             PG8_LDA(At, 1, 1); PG8_STAGE(PG8_SB(1, 0), b3, vB2, hB2 / 2); PG8_STAGE(PG8_SB(1, 1), b3 + hB2, vB2, hB2 / 2); PG8_STAGE(PG8_SA(1, 0), a3, vA2, hA2 / 2);
;             PG8_WAIT_V(8); PG8_WAIT_L(0); PG8_BAR; PG8_MMA(1, 0, At, B0); PG8_MMA(1, 1, At, B1); PG8_BAR; PG8_SCHED;
;         }
	v_add_u32_e32 v142, 0x18000, v175
	v_add_u32_e32 v154, 0x1c000, v175
	ds_read_b128 v[130:133], v142
	ds_read_b128 v[134:137], v142 offset:1024
	ds_read_b128 v[138:141], v142 offset:2048
	ds_read_b128 v[142:145], v142 offset:3072
	ds_read_b128 v[146:149], v154
	ds_read_b128 v[150:153], v154 offset:1024
	ds_read_b128 v[158:161], v154 offset:2048
	ds_read_b128 v[162:165], v154 offset:3072
	ds_read_b128 v[180:183], v177 offset:32768
	ds_read_b128 v[184:187], v177 offset:33792
	ds_read_b128 v[188:191], v177 offset:34816
	ds_read_b128 v[192:195], v177 offset:35840
	ds_read_b128 v[196:199], v177 offset:36864
	ds_read_b128 v[200:203], v177 offset:37888
	ds_read_b128 v[204:207], v177 offset:38912
	ds_read_b128 v[208:211], v177 offset:39936
	s_add_u32 s30, s8, 0x40000
	s_mov_b32 m0, s33
	s_addc_u32 s31, s9, 0
	global_load_lds_dwordx4 v172, s[30:31]
	s_add_u32 s30, s8, 0x60000
	s_mov_b32 m0, s34
	s_addc_u32 s31, s9, 0
	global_load_lds_dwordx4 v172, s[30:31]
	s_waitcnt vmcnt(8)
	s_waitcnt lgkmcnt(0)
	s_barrier
	s_setprio 1
	v_mfma_f32_16x16x32_bf16 v[124:127], v[130:133], v[180:183], v[124:127]
	v_mfma_f32_16x16x32_bf16 v[120:123], v[138:141], v[180:183], v[120:123]
	v_mfma_f32_16x16x32_bf16 v[116:119], v[130:133], v[188:191], v[116:119]
	v_mfma_f32_16x16x32_bf16 v[112:115], v[138:141], v[188:191], v[112:115]
	v_mfma_f32_16x16x32_bf16 v[108:111], v[130:133], v[196:199], v[108:111]
	v_mfma_f32_16x16x32_bf16 v[104:107], v[138:141], v[196:199], v[104:107]
	v_mfma_f32_16x16x32_bf16 v[100:103], v[130:133], v[204:207], v[100:103]
	v_mfma_f32_16x16x32_bf16 v[96:99], v[138:141], v[204:207], v[96:99]
	v_mfma_f32_16x16x32_bf16 v[124:127], v[134:137], v[184:187], v[124:127]
	v_mfma_f32_16x16x32_bf16 v[120:123], v[142:145], v[184:187], v[120:123]
	v_mfma_f32_16x16x32_bf16 v[116:119], v[134:137], v[192:195], v[116:119]
	v_mfma_f32_16x16x32_bf16 v[112:115], v[142:145], v[192:195], v[112:115]
	v_mfma_f32_16x16x32_bf16 v[108:111], v[134:137], v[200:203], v[108:111]
	v_mfma_f32_16x16x32_bf16 v[104:107], v[142:145], v[200:203], v[104:107]
	v_mfma_f32_16x16x32_bf16 v[100:103], v[134:137], v[208:211], v[100:103]
	v_mfma_f32_16x16x32_bf16 v[96:99], v[142:145], v[208:211], v[96:99]
	v_mfma_f32_16x16x32_bf16 v[92:95], v[146:149], v[180:183], v[92:95]
	v_mfma_f32_16x16x32_bf16 v[88:91], v[158:161], v[180:183], v[88:91]
	v_mfma_f32_16x16x32_bf16 v[84:87], v[146:149], v[188:191], v[84:87]
	v_mfma_f32_16x16x32_bf16 v[80:83], v[158:161], v[188:191], v[80:83]
	v_mfma_f32_16x16x32_bf16 v[76:79], v[146:149], v[196:199], v[76:79]
	v_mfma_f32_16x16x32_bf16 v[72:75], v[158:161], v[196:199], v[72:75]
	v_mfma_f32_16x16x32_bf16 v[68:71], v[146:149], v[204:207], v[68:71]
	v_mfma_f32_16x16x32_bf16 v[64:67], v[158:161], v[204:207], v[64:67]
	v_mfma_f32_16x16x32_bf16 v[92:95], v[150:153], v[184:187], v[92:95]
	v_mfma_f32_16x16x32_bf16 v[88:91], v[162:165], v[184:187], v[88:91]
	v_mfma_f32_16x16x32_bf16 v[84:87], v[150:153], v[192:195], v[84:87]
	v_mfma_f32_16x16x32_bf16 v[80:83], v[162:165], v[192:195], v[80:83]
	v_mfma_f32_16x16x32_bf16 v[76:79], v[150:153], v[200:203], v[76:79]
	v_mfma_f32_16x16x32_bf16 v[72:75], v[162:165], v[200:203], v[72:75]
	v_mfma_f32_16x16x32_bf16 v[68:71], v[150:153], v[208:211], v[68:71]
	v_mfma_f32_16x16x32_bf16 v[64:67], v[162:165], v[208:211], v[64:67]
	s_setprio 0
	s_barrier
	s_add_u32 s30, s22, 0x80
	s_addc_u32 s31, s23, 0
	ds_read_b128 v[180:183], v177 offset:49152
	ds_read_b128 v[184:187], v177 offset:50176
	ds_read_b128 v[188:191], v177 offset:51200
	ds_read_b128 v[192:195], v177 offset:52224
	ds_read_b128 v[196:199], v177 offset:53248
	ds_read_b128 v[200:203], v177 offset:54272
	ds_read_b128 v[204:207], v177 offset:55296
	ds_read_b128 v[208:211], v177 offset:56320
	s_mov_b32 m0, s51
	s_nop 0
	global_load_lds_dwordx4 v128, s[30:31]
	s_add_u32 s30, s22, 0x10080
	s_mov_b32 m0, s61
	s_addc_u32 s31, s23, 0
	global_load_lds_dwordx4 v128, s[30:31]
	s_add_u32 s30, s22, 0x20080
	s_mov_b32 m0, s64
	s_addc_u32 s31, s23, 0
	global_load_lds_dwordx4 v128, s[30:31]
	s_add_u32 s22, s22, 0x30080
	s_mov_b32 m0, s65
	s_addc_u32 s23, s23, 0
	global_load_lds_dwordx4 v128, s[22:23]
	s_mov_b32 m0, s62
	s_nop 0
	global_load_lds_dwordx4 v172, s[16:17]
	s_add_u32 s8, s8, 0x20080
	s_mov_b32 m0, s63
	s_addc_u32 s9, s9, 0
	global_load_lds_dwordx4 v172, s[8:9]
	s_waitcnt vmcnt(8)
	s_waitcnt lgkmcnt(0)
	s_barrier
	s_setprio 1
	v_mfma_f32_16x16x32_bf16 v[60:63], v[130:133], v[180:183], v[60:63]
	v_mfma_f32_16x16x32_bf16 v[56:59], v[138:141], v[180:183], v[56:59]
	v_mfma_f32_16x16x32_bf16 v[52:55], v[130:133], v[188:191], v[52:55]
	v_mfma_f32_16x16x32_bf16 v[48:51], v[138:141], v[188:191], v[48:51]
	v_mfma_f32_16x16x32_bf16 v[44:47], v[130:133], v[196:199], v[44:47]
	v_mfma_f32_16x16x32_bf16 v[40:43], v[138:141], v[196:199], v[40:43]
	v_mfma_f32_16x16x32_bf16 v[36:39], v[130:133], v[204:207], v[36:39]
	v_mfma_f32_16x16x32_bf16 v[32:35], v[138:141], v[204:207], v[32:35]
	v_mfma_f32_16x16x32_bf16 v[60:63], v[134:137], v[184:187], v[60:63]
	v_mfma_f32_16x16x32_bf16 v[56:59], v[142:145], v[184:187], v[56:59]
	v_mfma_f32_16x16x32_bf16 v[52:55], v[134:137], v[192:195], v[52:55]
	v_mfma_f32_16x16x32_bf16 v[48:51], v[142:145], v[192:195], v[48:51]
	v_mfma_f32_16x16x32_bf16 v[44:47], v[134:137], v[200:203], v[44:47]
	v_mfma_f32_16x16x32_bf16 v[40:43], v[142:145], v[200:203], v[40:43]
	v_mfma_f32_16x16x32_bf16 v[36:39], v[134:137], v[208:211], v[36:39]
	v_mfma_f32_16x16x32_bf16 v[32:35], v[142:145], v[208:211], v[32:35]
	v_mfma_f32_16x16x32_bf16 v[28:31], v[146:149], v[180:183], v[28:31]
	v_mfma_f32_16x16x32_bf16 v[24:27], v[158:161], v[180:183], v[24:27]
	v_mfma_f32_16x16x32_bf16 v[20:23], v[146:149], v[188:191], v[20:23]
	v_mfma_f32_16x16x32_bf16 v[16:19], v[158:161], v[188:191], v[16:19]
	v_mfma_f32_16x16x32_bf16 v[12:15], v[146:149], v[196:199], v[12:15]
	v_mfma_f32_16x16x32_bf16 v[8:11], v[158:161], v[196:199], v[8:11]
	v_mfma_f32_16x16x32_bf16 v[4:7], v[146:149], v[204:207], v[4:7]
	v_mfma_f32_16x16x32_bf16 v[0:3], v[158:161], v[204:207], v[0:3]
	v_mfma_f32_16x16x32_bf16 v[28:31], v[150:153], v[184:187], v[28:31]
	v_mfma_f32_16x16x32_bf16 v[24:27], v[162:165], v[184:187], v[24:27]
	v_mfma_f32_16x16x32_bf16 v[20:23], v[150:153], v[192:195], v[20:23]
	v_mfma_f32_16x16x32_bf16 v[16:19], v[162:165], v[192:195], v[16:19]
	v_mfma_f32_16x16x32_bf16 v[12:15], v[150:153], v[200:203], v[12:15]
	v_mfma_f32_16x16x32_bf16 v[8:11], v[162:165], v[200:203], v[8:11]
	v_mfma_f32_16x16x32_bf16 v[4:7], v[150:153], v[208:211], v[4:7]
	v_mfma_f32_16x16x32_bf16 v[0:3], v[162:165], v[208:211], v[0:3]
	s_setprio 0
	s_barrier
	s_add_u32 s76, s76, 0x100
	s_addc_u32 s77, s77, 0
	s_add_u32 s78, s78, 0x100
	s_addc_u32 s79, s79, 0
	s_cmp_ge_u32 s80, s7
	s_mov_b32 s8, s80
	s_cbranch_scc0 .LBB0_844
	s_and_b64 vcc, exec, s[10:11]
	s_cbranch_vccz .LBB0_847
	s_barrier

; template <class Epi, class Sched>
; __device__ __forceinline__ void gemm_phase(LAS unsigned char* lds, const Sched& S, const Epi& E) {
;     ...
;         if (!has_next) break;
;         if (!keep) {
; #pragma unroll
;             for (int a = 0; a < 2; ++a)
; #pragma unroll
;                 for (int b = 0; b < 2; ++b)
; #pragma unroll
;                     for (int m = 0; m < 4; ++m)
; #pragma unroll
;                         for (int n = 0; n < 2; ++n) acc[a][b][m][n] = (f32x4){0.f, 0.f, 0.f, 0.f};
;         }
.LBB0_851:
	s_cmp_eq_u32 s75, 5
	s_mov_b64 s[16:17], -1
	s_cbranch_scc1 .LBB0_840
	s_andn2_b64 vcc, exec, s[8:9]
	s_cbranch_vccnz .LBB0_854
	v_mov_b64_e32 v[0:1], 0
	v_mov_b64_e32 v[2:3], 0
	v_mov_b64_e32 v[4:5], 0
	v_mov_b64_e32 v[6:7], 0
	v_mov_b64_e32 v[8:9], 0
	v_mov_b64_e32 v[10:11], 0
	v_mov_b64_e32 v[12:13], 0
	v_mov_b64_e32 v[14:15], 0
	v_mov_b64_e32 v[16:17], 0
	v_mov_b64_e32 v[18:19], 0
	v_mov_b64_e32 v[20:21], 0
	v_mov_b64_e32 v[22:23], 0
	v_mov_b64_e32 v[24:25], 0
	v_mov_b64_e32 v[26:27], 0
	v_mov_b64_e32 v[28:29], 0
	v_mov_b64_e32 v[30:31], 0
	v_mov_b64_e32 v[32:33], 0
	v_mov_b64_e32 v[34:35], 0
	v_mov_b64_e32 v[36:37], 0
	v_mov_b64_e32 v[38:39], 0
	v_mov_b64_e32 v[40:41], 0
	v_mov_b64_e32 v[42:43], 0
	v_mov_b64_e32 v[44:45], 0
	v_mov_b64_e32 v[46:47], 0
	v_mov_b64_e32 v[48:49], 0
	v_mov_b64_e32 v[50:51], 0
	v_mov_b64_e32 v[52:53], 0
	v_mov_b64_e32 v[54:55], 0
	v_mov_b64_e32 v[56:57], 0
	v_mov_b64_e32 v[58:59], 0
	v_mov_b64_e32 v[60:61], 0
	v_mov_b64_e32 v[62:63], 0
	v_mov_b64_e32 v[64:65], 0
	v_mov_b64_e32 v[66:67], 0
	v_mov_b64_e32 v[68:69], 0
	v_mov_b64_e32 v[70:71], 0
	v_mov_b64_e32 v[72:73], 0
	v_mov_b64_e32 v[74:75], 0
	v_mov_b64_e32 v[76:77], 0
	v_mov_b64_e32 v[78:79], 0
	v_mov_b64_e32 v[80:81], 0
	v_mov_b64_e32 v[82:83], 0
	v_mov_b64_e32 v[84:85], 0
	v_mov_b64_e32 v[86:87], 0
	v_mov_b64_e32 v[88:89], 0
	v_mov_b64_e32 v[90:91], 0
	v_mov_b64_e32 v[92:93], 0
	v_mov_b64_e32 v[94:95], 0
	v_mov_b64_e32 v[96:97], 0
	v_mov_b64_e32 v[98:99], 0
	v_mov_b64_e32 v[100:101], 0
	v_mov_b64_e32 v[102:103], 0
	v_mov_b64_e32 v[104:105], 0
	v_mov_b64_e32 v[106:107], 0
	v_mov_b64_e32 v[108:109], 0
	v_mov_b64_e32 v[110:111], 0
	v_mov_b64_e32 v[112:113], 0
	v_mov_b64_e32 v[114:115], 0
	v_mov_b64_e32 v[116:117], 0
	v_mov_b64_e32 v[118:119], 0
	v_mov_b64_e32 v[120:121], 0
	v_mov_b64_e32 v[122:123], 0
	v_mov_b64_e32 v[124:125], 0
	v_mov_b64_e32 v[126:127], 0

; #define PG8_STAGE(bufoff, gbase, voff, p64) do { _Pragma("unroll") for (int _i = 0; _i < 2; ++_i) { \
;         const char* _gb = (const char*)(gbase) + (size_t)_i * (p64); const unsigned _la = ldsbase + (unsigned)(bufoff) + (unsigned)_i * 8192u; \
;         asm volatile("s_mov_b32 m0, %0\n\ts_nop 0\n\tglobal_load_lds_dwordx4 %1, %2" :: "s"(_la), "v"(voff), "s"(_gb) : "memory"); } } while (0)
; #define PG8_LDA(dst, b, h) do { _Pragma("unroll") for (int m = 0; m < 4; ++m) _Pragma("unroll") for (int k = 0; k < 2; ++k) dst[m][k] = *(const LAS bf16x8*)(lds + PG8_SA(b, h) + aoff + m * 2048 + k * 1024); } while (0)
; #define PG8_LDB(dst, b, h) do { _Pragma("unroll") for (int n = 0; n < 2; ++n) _Pragma("unroll") for (int k = 0; k < 2; ++k) dst[n][k] = *(const LAS bf16x8*)(lds + PG8_SB(b, h) + boff + n * 2048 + k * 1024); } while (0)
; #define PG8_MMA(ai, bj, At, Bt) do { __builtin_amdgcn_s_setprio(1); _Pragma("unroll") for (int m = 0; m < 4; ++m) _Pragma("unroll") for (int n = 0; n < 2; ++n) _Pragma("unroll") for (int k = 0; k < 2; ++k) \
;         acc[ai][bj][m][n] = __builtin_amdgcn_mfma_f32_16x16x32_bf16(Bt[n][k], At[m][k], acc[ai][bj][m][n], 0, 0, 0); __builtin_amdgcn_s_setprio(0); } while (0)
; #define PG8_BAR __builtin_amdgcn_s_barrier()
; template <class Epi, class Sched>
; __device__ __forceinline__ void gemm_phase(LAS unsigned char* lds, const Sched& S, const Epi& E) {
;     ...
;         for (int t = 0; t < nt; t += 2) {
;             const bool last = (t == nt - 2);
;             const char* a1 = cA + (size_t)(t + 1) * kstep;
;             const char* a2 = last ? nA : cA + (size_t)(t + 2) * kstep; const char* b2 = last ? nB : cB + (size_t)(t + 2) * kstep;
;             const char* a3 = a2 + kstep; const char* b3 = b2 + kstep;
;             const unsigned vA2 = voffA, vB2 = voffB, hA2 = hA, hB2 = hB;
;             PG8_LDB(B0, 0, 0); PG8_LDB(B1, 0, 1); PG8_SCHED; PG8_LDA(At, 0, 0); PG8_STAGE(PG8_SA(1, 1), a1 + hA, voffA, hA / 2);
;             PG8_WAIT_V(8); PG8_WAIT_L(0); PG8_BAR; PG8_MMA(0, 0, At, B0); PG8_MMA(0, 1, At, B1); PG8_BAR; PG8_SCHED;
;     ...
; #pragma unroll
;             for (int a = 0; a < 2; ++a)
; #pragma unroll
;                 for (int b = 0; b < 2; ++b)
; #pragma unroll
;                     for (int m = 0; m < 4; ++m)
; #pragma unroll
;                         for (int n = 0; n < 2; ++n) acc[a][b][m][n] = (f32x4){0.f, 0.f, 0.f, 0.f};
.LBB0_980:
	s_add_u32 s26, s26, 0x40080
	s_addc_u32 s27, s27, 0
	s_add_u32 s62, s38, 0x100
	s_addc_u32 s63, s39, 0
	s_mov_b32 s65, -2
	v_mov_b64_e32 v[0:1], 0
	v_mov_b64_e32 v[2:3], 0
	v_mov_b64_e32 v[4:5], 0
	v_mov_b64_e32 v[6:7], 0
	s_waitcnt vmcnt(3)
	v_mov_b64_e32 v[8:9], 0
	v_mov_b64_e32 v[10:11], 0
	s_waitcnt vmcnt(2)
	v_mov_b64_e32 v[12:13], 0
	v_mov_b64_e32 v[14:15], 0
	s_waitcnt vmcnt(1)
	v_mov_b64_e32 v[16:17], 0
	v_mov_b64_e32 v[18:19], 0
	s_waitcnt vmcnt(0)
	v_mov_b64_e32 v[20:21], 0
	v_mov_b64_e32 v[22:23], 0
	v_mov_b64_e32 v[24:25], 0
	v_mov_b64_e32 v[26:27], 0
	v_mov_b64_e32 v[28:29], 0
	v_mov_b64_e32 v[30:31], 0
	v_mov_b64_e32 v[64:65], 0
	v_mov_b64_e32 v[66:67], 0
	v_mov_b64_e32 v[68:69], 0
	v_mov_b64_e32 v[70:71], 0
	v_mov_b64_e32 v[72:73], 0
	v_mov_b64_e32 v[74:75], 0
	v_mov_b64_e32 v[76:77], 0
	v_mov_b64_e32 v[78:79], 0
	v_mov_b64_e32 v[80:81], 0
	v_mov_b64_e32 v[82:83], 0
	v_mov_b64_e32 v[84:85], 0
	v_mov_b64_e32 v[86:87], 0
	v_mov_b64_e32 v[88:89], 0
	v_mov_b64_e32 v[90:91], 0
	v_mov_b64_e32 v[92:93], 0
	v_mov_b64_e32 v[94:95], 0
	v_mov_b64_e32 v[32:33], 0
	v_mov_b64_e32 v[34:35], 0
	v_mov_b64_e32 v[36:37], 0
	v_mov_b64_e32 v[38:39], 0
	v_mov_b64_e32 v[40:41], 0
	v_mov_b64_e32 v[42:43], 0
	v_mov_b64_e32 v[44:45], 0
	v_mov_b64_e32 v[46:47], 0
	v_mov_b64_e32 v[48:49], 0
	v_mov_b64_e32 v[50:51], 0
	v_mov_b64_e32 v[52:53], 0
	v_mov_b64_e32 v[54:55], 0
	v_mov_b64_e32 v[56:57], 0
	v_mov_b64_e32 v[58:59], 0
	v_mov_b64_e32 v[60:61], 0
	v_mov_b64_e32 v[62:63], 0
	v_mov_b64_e32 v[96:97], 0
	v_mov_b64_e32 v[98:99], 0
	v_mov_b64_e32 v[100:101], 0
	v_mov_b64_e32 v[102:103], 0
	v_mov_b64_e32 v[104:105], 0
	v_mov_b64_e32 v[106:107], 0
	v_mov_b64_e32 v[108:109], 0
	v_mov_b64_e32 v[110:111], 0
	v_mov_b64_e32 v[120:121], 0
	v_mov_b64_e32 v[122:123], 0
	v_mov_b64_e32 v[124:125], 0
	v_mov_b64_e32 v[126:127], 0
	v_mov_b64_e32 v[128:129], 0
	v_mov_b64_e32 v[130:131], 0
	v_mov_b64_e32 v[132:133], 0
	v_mov_b64_e32 v[134:135], 0
.LBB0_981:
	ds_read_b128 v[112:115], v162
	ds_read_b128 v[116:119], v162 offset:1024
	ds_read_b128 v[140:143], v162 offset:2048
	ds_read_b128 v[144:147], v162 offset:3072
	ds_read_b128 v[148:151], v163
	ds_read_b128 v[152:155], v163 offset:1024
	ds_read_b128 v[168:171], v163 offset:2048
	ds_read_b128 v[172:175], v163 offset:3072
	s_add_u32 s30, s26, 0xfffc0080
	s_addc_u32 s38, s27, -1
	s_cmp_eq_u32 s65, 12
	s_cselect_b32 s39, s23, s38
	s_cselect_b32 s38, s22, s30
	s_cselect_b32 s42, s24, s62
	s_cselect_b32 s43, s25, s63
	s_add_u32 s40, s38, 0x80
	s_addc_u32 s41, s39, 0
	ds_read_b128 v[178:181], v164
	ds_read_b128 v[182:185], v164 offset:1024
	ds_read_b128 v[186:189], v164 offset:2048
	ds_read_b128 v[190:193], v164 offset:3072
	ds_read_b128 v[194:197], v164 offset:4096
	ds_read_b128 v[198:201], v164 offset:5120
	ds_read_b128 v[202:205], v164 offset:6144
	ds_read_b128 v[206:209], v164 offset:7168
	s_mov_b32 m0, s58
	s_nop 0
	global_load_lds_dwordx4 v158, s[26:27]
	s_add_u32 s66, s26, 0x20000
	s_mov_b32 m0, s59
	s_addc_u32 s67, s27, 0
	global_load_lds_dwordx4 v158, s[66:67]
	s_waitcnt vmcnt(8)
	s_waitcnt lgkmcnt(0)
	s_barrier
	s_setprio 1
	v_mfma_f32_16x16x32_bf16 v[132:135], v[112:115], v[178:181], v[132:135]
	v_mfma_f32_16x16x32_bf16 v[128:131], v[140:143], v[178:181], v[128:131]
	v_mfma_f32_16x16x32_bf16 v[124:127], v[112:115], v[186:189], v[124:127]
	v_mfma_f32_16x16x32_bf16 v[120:123], v[140:143], v[186:189], v[120:123]
	v_mfma_f32_16x16x32_bf16 v[108:111], v[112:115], v[194:197], v[108:111]
	v_mfma_f32_16x16x32_bf16 v[104:107], v[140:143], v[194:197], v[104:107]
	v_mfma_f32_16x16x32_bf16 v[100:103], v[112:115], v[202:205], v[100:103]
	v_mfma_f32_16x16x32_bf16 v[96:99], v[140:143], v[202:205], v[96:99]
	v_mfma_f32_16x16x32_bf16 v[132:135], v[116:119], v[182:185], v[132:135]
	v_mfma_f32_16x16x32_bf16 v[128:131], v[144:147], v[182:185], v[128:131]
	v_mfma_f32_16x16x32_bf16 v[124:127], v[116:119], v[190:193], v[124:127]
	v_mfma_f32_16x16x32_bf16 v[120:123], v[144:147], v[190:193], v[120:123]
	v_mfma_f32_16x16x32_bf16 v[108:111], v[116:119], v[198:201], v[108:111]
	v_mfma_f32_16x16x32_bf16 v[104:107], v[144:147], v[198:201], v[104:107]
	v_mfma_f32_16x16x32_bf16 v[100:103], v[116:119], v[206:209], v[100:103]
	v_mfma_f32_16x16x32_bf16 v[96:99], v[144:147], v[206:209], v[96:99]
	v_mfma_f32_16x16x32_bf16 v[60:63], v[148:151], v[178:181], v[60:63]
	v_mfma_f32_16x16x32_bf16 v[56:59], v[168:171], v[178:181], v[56:59]
	v_mfma_f32_16x16x32_bf16 v[52:55], v[148:151], v[186:189], v[52:55]
	v_mfma_f32_16x16x32_bf16 v[48:51], v[168:171], v[186:189], v[48:51]
	v_mfma_f32_16x16x32_bf16 v[44:47], v[148:151], v[194:197], v[44:47]
	v_mfma_f32_16x16x32_bf16 v[40:43], v[168:171], v[194:197], v[40:43]
	v_mfma_f32_16x16x32_bf16 v[36:39], v[148:151], v[202:205], v[36:39]
	v_mfma_f32_16x16x32_bf16 v[32:35], v[168:171], v[202:205], v[32:35]
	v_mfma_f32_16x16x32_bf16 v[60:63], v[152:155], v[182:185], v[60:63]
	v_mfma_f32_16x16x32_bf16 v[56:59], v[172:175], v[182:185], v[56:59]
	v_mfma_f32_16x16x32_bf16 v[52:55], v[152:155], v[190:193], v[52:55]
	v_mfma_f32_16x16x32_bf16 v[48:51], v[172:175], v[190:193], v[48:51]
	v_mfma_f32_16x16x32_bf16 v[44:47], v[152:155], v[198:201], v[44:47]
	v_mfma_f32_16x16x32_bf16 v[40:43], v[172:175], v[198:201], v[40:43]
	v_mfma_f32_16x16x32_bf16 v[36:39], v[152:155], v[206:209], v[36:39]
	v_mfma_f32_16x16x32_bf16 v[32:35], v[172:175], v[206:209], v[32:35]
	s_setprio 0
	s_barrier
; #define PG8_STAGE(bufoff, gbase, voff, p64) do { _Pragma("unroll") for (int _i = 0; _i < 2; ++_i) { \
;         const char* _gb = (const char*)(gbase) + (size_t)_i * (p64); const unsigned _la = ldsbase + (unsigned)(bufoff) + (unsigned)_i * 8192u; \
;         asm volatile("s_mov_b32 m0, %0\n\ts_nop 0\n\tglobal_load_lds_dwordx4 %1, %2" :: "s"(_la), "v"(voff), "s"(_gb) : "memory"); } } while (0)
; #define PG8_LDA(dst, b, h) do { _Pragma("unroll") for (int m = 0; m < 4; ++m) _Pragma("unroll") for (int k = 0; k < 2; ++k) dst[m][k] = *(const LAS bf16x8*)(lds + PG8_SA(b, h) + aoff + m * 2048 + k * 1024); } while (0)
; #define PG8_LDB(dst, b, h) do { _Pragma("unroll") for (int n = 0; n < 2; ++n) _Pragma("unroll") for (int k = 0; k < 2; ++k) dst[n][k] = *(const LAS bf16x8*)(lds + PG8_SB(b, h) + boff + n * 2048 + k * 1024); } while (0)
; #define PG8_MMA(ai, bj, At, Bt) do { __builtin_amdgcn_s_setprio(1); _Pragma("unroll") for (int m = 0; m < 4; ++m) _Pragma("unroll") for (int n = 0; n < 2; ++n) _Pragma("unroll") for (int k = 0; k < 2; ++k) \
;         acc[ai][bj][m][n] = __builtin_amdgcn_mfma_f32_16x16x32_bf16(Bt[n][k], At[m][k], acc[ai][bj][m][n], 0, 0, 0); __builtin_amdgcn_s_setprio(0); } while (0)
; #define PG8_WAIT_V(n) asm volatile("s_waitcnt vmcnt(" #n ")" ::: "memory")
; #define PG8_WAIT_L(n) asm volatile("s_waitcnt lgkmcnt(" #n ")" ::: "memory")
; #define PG8_BAR __builtin_amdgcn_s_barrier()
; #define PG8_SCHED __builtin_amdgcn_sched_barrier(0)
; template <class Epi, class Sched>
; __device__ __forceinline__ void gemm_phase(LAS unsigned char* lds, const Sched& S, const Epi& E) {
;     ...
;             PG8_LDA(At, 0, 1); PG8_STAGE(PG8_SB(0, 0), b2, vB2, hB2 / 2); PG8_STAGE(PG8_SB(0, 1), b2 + hB2, vB2, hB2 / 2); PG8_STAGE(PG8_SA(0, 0), a2, vA2, hA2 / 2);
;             PG8_WAIT_V(8); PG8_WAIT_L(0); PG8_BAR; PG8_MMA(1, 0, At, B0); PG8_MMA(1, 1, At, B1); PG8_BAR; PG8_SCHED;
;             PG8_LDB(B0, 1, 0); PG8_LDB(B1, 1, 1); PG8_SCHED; PG8_LDA(At, 1, 0); PG8_STAGE(PG8_SA(0, 1), a2 + hA2, vA2, hA2 / 2);
;             PG8_WAIT_V(8); PG8_WAIT_L(0); PG8_BAR; PG8_MMA(0, 0, At, B0); PG8_MMA(0, 1, At, B1); PG8_BAR; PG8_SCHED;
	s_add_u32 s66, s42, 0x20000
	ds_read_b128 v[178:181], v164 offset:16384
	ds_read_b128 v[182:185], v164 offset:17408
	ds_read_b128 v[186:189], v164 offset:18432
	ds_read_b128 v[190:193], v164 offset:19456
	ds_read_b128 v[194:197], v164 offset:20480
	ds_read_b128 v[198:201], v164 offset:21504
	ds_read_b128 v[202:205], v164 offset:22528
	ds_read_b128 v[206:209], v164 offset:23552
	s_mov_b32 m0, s35
	s_nop 0
	global_load_lds_dwordx4 v159, s[42:43]
	s_mov_b32 m0, s36
	s_addc_u32 s67, s43, 0
	global_load_lds_dwordx4 v159, s[66:67]
	s_add_u32 s66, s42, 0x40000
	s_mov_b32 m0, s37
	s_addc_u32 s67, s43, 0
	global_load_lds_dwordx4 v159, s[66:67]
	s_add_u32 s66, s42, 0x60000
	s_mov_b32 m0, s44
	s_addc_u32 s67, s43, 0
	global_load_lds_dwordx4 v159, s[66:67]
	s_mov_b32 m0, s34
	s_nop 0
	global_load_lds_dwordx4 v158, s[38:39]
	s_add_u32 s66, s38, 0x20000
	s_mov_b32 m0, s45
	s_addc_u32 s67, s39, 0
	global_load_lds_dwordx4 v158, s[66:67]
	s_waitcnt vmcnt(8)
	s_waitcnt lgkmcnt(0)
	s_barrier
	s_setprio 1
	v_mfma_f32_16x16x32_bf16 v[92:95], v[112:115], v[178:181], v[92:95]
	v_mfma_f32_16x16x32_bf16 v[88:91], v[140:143], v[178:181], v[88:91]
	v_mfma_f32_16x16x32_bf16 v[84:87], v[112:115], v[186:189], v[84:87]
	v_mfma_f32_16x16x32_bf16 v[80:83], v[140:143], v[186:189], v[80:83]
	v_mfma_f32_16x16x32_bf16 v[76:79], v[112:115], v[194:197], v[76:79]
	v_mfma_f32_16x16x32_bf16 v[72:75], v[140:143], v[194:197], v[72:75]
	v_mfma_f32_16x16x32_bf16 v[68:71], v[112:115], v[202:205], v[68:71]
	v_mfma_f32_16x16x32_bf16 v[64:67], v[140:143], v[202:205], v[64:67]
	v_mfma_f32_16x16x32_bf16 v[92:95], v[116:119], v[182:185], v[92:95]
	v_mfma_f32_16x16x32_bf16 v[88:91], v[144:147], v[182:185], v[88:91]
	v_mfma_f32_16x16x32_bf16 v[84:87], v[116:119], v[190:193], v[84:87]
	v_mfma_f32_16x16x32_bf16 v[80:83], v[144:147], v[190:193], v[80:83]
	v_mfma_f32_16x16x32_bf16 v[76:79], v[116:119], v[198:201], v[76:79]
	v_mfma_f32_16x16x32_bf16 v[72:75], v[144:147], v[198:201], v[72:75]
	v_mfma_f32_16x16x32_bf16 v[68:71], v[116:119], v[206:209], v[68:71]
	v_mfma_f32_16x16x32_bf16 v[64:67], v[144:147], v[206:209], v[64:67]
	v_mfma_f32_16x16x32_bf16 v[28:31], v[148:151], v[178:181], v[28:31]
	v_mfma_f32_16x16x32_bf16 v[24:27], v[168:171], v[178:181], v[24:27]
	v_mfma_f32_16x16x32_bf16 v[20:23], v[148:151], v[186:189], v[20:23]
	v_mfma_f32_16x16x32_bf16 v[16:19], v[168:171], v[186:189], v[16:19]
	v_mfma_f32_16x16x32_bf16 v[12:15], v[148:151], v[194:197], v[12:15]
	v_mfma_f32_16x16x32_bf16 v[8:11], v[168:171], v[194:197], v[8:11]
	v_mfma_f32_16x16x32_bf16 v[4:7], v[148:151], v[202:205], v[4:7]
	v_mfma_f32_16x16x32_bf16 v[0:3], v[168:171], v[202:205], v[0:3]
	v_mfma_f32_16x16x32_bf16 v[28:31], v[152:155], v[182:185], v[28:31]
	v_mfma_f32_16x16x32_bf16 v[24:27], v[172:175], v[182:185], v[24:27]
	v_mfma_f32_16x16x32_bf16 v[20:23], v[152:155], v[190:193], v[20:23]
	v_mfma_f32_16x16x32_bf16 v[16:19], v[172:175], v[190:193], v[16:19]
	v_mfma_f32_16x16x32_bf16 v[12:15], v[152:155], v[198:201], v[12:15]
	v_mfma_f32_16x16x32_bf16 v[8:11], v[172:175], v[198:201], v[8:11]
	v_mfma_f32_16x16x32_bf16 v[4:7], v[152:155], v[206:209], v[4:7]
	v_mfma_f32_16x16x32_bf16 v[0:3], v[172:175], v[206:209], v[0:3]
	s_setprio 0
	s_barrier
	ds_read_b128 v[112:115], v165
	ds_read_b128 v[116:119], v165 offset:1024
	ds_read_b128 v[140:143], v165 offset:2048
	ds_read_b128 v[144:147], v165 offset:3072
	ds_read_b128 v[148:151], v166
	ds_read_b128 v[152:155], v166 offset:1024
	ds_read_b128 v[168:171], v166 offset:2048
	ds_read_b128 v[172:175], v166 offset:3072
	ds_read_b128 v[178:181], v164 offset:32768
	ds_read_b128 v[182:185], v164 offset:33792
	ds_read_b128 v[186:189], v164 offset:34816
	ds_read_b128 v[190:193], v164 offset:35840
	ds_read_b128 v[194:197], v164 offset:36864
	ds_read_b128 v[198:201], v164 offset:37888
	ds_read_b128 v[202:205], v164 offset:38912
	ds_read_b128 v[206:209], v164 offset:39936
	s_add_u32 s66, s38, 0x40000
	s_mov_b32 m0, s46
	s_addc_u32 s67, s39, 0
	global_load_lds_dwordx4 v158, s[66:67]
	s_add_u32 s66, s38, 0x60000
	s_mov_b32 m0, s47
	s_addc_u32 s67, s39, 0
	global_load_lds_dwordx4 v158, s[66:67]
	s_waitcnt vmcnt(8)
	s_waitcnt lgkmcnt(0)
	s_barrier
; #define PG8_STAGE(bufoff, gbase, voff, p64) do { _Pragma("unroll") for (int _i = 0; _i < 2; ++_i) { \
;         const char* _gb = (const char*)(gbase) + (size_t)_i * (p64); const unsigned _la = ldsbase + (unsigned)(bufoff) + (unsigned)_i * 8192u; \
;         asm volatile("s_mov_b32 m0, %0\n\ts_nop 0\n\tglobal_load_lds_dwordx4 %1, %2" :: "s"(_la), "v"(voff), "s"(_gb) : "memory"); } } while (0)
; #define PG8_LDA(dst, b, h) do { _Pragma("unroll") for (int m = 0; m < 4; ++m) _Pragma("unroll") for (int k = 0; k < 2; ++k) dst[m][k] = *(const LAS bf16x8*)(lds + PG8_SA(b, h) + aoff + m * 2048 + k * 1024); } while (0)
; #define PG8_MMA(ai, bj, At, Bt) do { __builtin_amdgcn_s_setprio(1); _Pragma("unroll") for (int m = 0; m < 4; ++m) _Pragma("unroll") for (int n = 0; n < 2; ++n) _Pragma("unroll") for (int k = 0; k < 2; ++k) \
;         acc[ai][bj][m][n] = __builtin_amdgcn_mfma_f32_16x16x32_bf16(Bt[n][k], At[m][k], acc[ai][bj][m][n], 0, 0, 0); __builtin_amdgcn_s_setprio(0); } while (0)
; #define PG8_WAIT_V(n) asm volatile("s_waitcnt vmcnt(" #n ")" ::: "memory")
; #define PG8_WAIT_L(n) asm volatile("s_waitcnt lgkmcnt(" #n ")" ::: "memory")
; #define PG8_BAR __builtin_amdgcn_s_barrier()
; #define PG8_SCHED __builtin_amdgcn_sched_barrier(0)
; template <class Epi, class Sched>
; __device__ __forceinline__ void gemm_phase(LAS unsigned char* lds, const Sched& S, const Epi& E) {
;     ...
;             PG8_WAIT_V(8); PG8_WAIT_L(0); PG8_BAR; PG8_MMA(0, 0, At, B0); PG8_MMA(0, 1, At, B1); PG8_BAR; PG8_SCHED;
;             PG8_LDA(At, 1, 1); PG8_STAGE(PG8_SB(1, 0), b3, vB2, hB2 / 2); PG8_STAGE(PG8_SB(1, 1), b3 + hB2, vB2, hB2 / 2); PG8_STAGE(PG8_SA(1, 0), a3, vA2, hA2 / 2);
;             PG8_WAIT_V(8); PG8_WAIT_L(0); PG8_BAR; PG8_MMA(1, 0, At, B0); PG8_MMA(1, 1, At, B1); PG8_BAR; PG8_SCHED;
;         }
;         if (wr == 0) PG8_BAR;
	s_setprio 1
	v_mfma_f32_16x16x32_bf16 v[132:135], v[112:115], v[178:181], v[132:135]
	v_mfma_f32_16x16x32_bf16 v[128:131], v[140:143], v[178:181], v[128:131]
	v_mfma_f32_16x16x32_bf16 v[124:127], v[112:115], v[186:189], v[124:127]
	v_mfma_f32_16x16x32_bf16 v[120:123], v[140:143], v[186:189], v[120:123]
	v_mfma_f32_16x16x32_bf16 v[108:111], v[112:115], v[194:197], v[108:111]
	v_mfma_f32_16x16x32_bf16 v[104:107], v[140:143], v[194:197], v[104:107]
	v_mfma_f32_16x16x32_bf16 v[100:103], v[112:115], v[202:205], v[100:103]
	v_mfma_f32_16x16x32_bf16 v[96:99], v[140:143], v[202:205], v[96:99]
	v_mfma_f32_16x16x32_bf16 v[132:135], v[116:119], v[182:185], v[132:135]
	v_mfma_f32_16x16x32_bf16 v[128:131], v[144:147], v[182:185], v[128:131]
	v_mfma_f32_16x16x32_bf16 v[124:127], v[116:119], v[190:193], v[124:127]
	v_mfma_f32_16x16x32_bf16 v[120:123], v[144:147], v[190:193], v[120:123]
	v_mfma_f32_16x16x32_bf16 v[108:111], v[116:119], v[198:201], v[108:111]
	v_mfma_f32_16x16x32_bf16 v[104:107], v[144:147], v[198:201], v[104:107]
	v_mfma_f32_16x16x32_bf16 v[100:103], v[116:119], v[206:209], v[100:103]
	v_mfma_f32_16x16x32_bf16 v[96:99], v[144:147], v[206:209], v[96:99]
	v_mfma_f32_16x16x32_bf16 v[60:63], v[148:151], v[178:181], v[60:63]
	v_mfma_f32_16x16x32_bf16 v[56:59], v[168:171], v[178:181], v[56:59]
	v_mfma_f32_16x16x32_bf16 v[52:55], v[148:151], v[186:189], v[52:55]
	v_mfma_f32_16x16x32_bf16 v[48:51], v[168:171], v[186:189], v[48:51]
	v_mfma_f32_16x16x32_bf16 v[44:47], v[148:151], v[194:197], v[44:47]
	v_mfma_f32_16x16x32_bf16 v[40:43], v[168:171], v[194:197], v[40:43]
	v_mfma_f32_16x16x32_bf16 v[36:39], v[148:151], v[202:205], v[36:39]
	v_mfma_f32_16x16x32_bf16 v[32:35], v[168:171], v[202:205], v[32:35]
	v_mfma_f32_16x16x32_bf16 v[60:63], v[152:155], v[182:185], v[60:63]
	v_mfma_f32_16x16x32_bf16 v[56:59], v[172:175], v[182:185], v[56:59]
	v_mfma_f32_16x16x32_bf16 v[52:55], v[152:155], v[190:193], v[52:55]
	v_mfma_f32_16x16x32_bf16 v[48:51], v[172:175], v[190:193], v[48:51]
	v_mfma_f32_16x16x32_bf16 v[44:47], v[152:155], v[198:201], v[44:47]
	v_mfma_f32_16x16x32_bf16 v[40:43], v[172:175], v[198:201], v[40:43]
	v_mfma_f32_16x16x32_bf16 v[36:39], v[152:155], v[206:209], v[36:39]
	v_mfma_f32_16x16x32_bf16 v[32:35], v[172:175], v[206:209], v[32:35]
	s_setprio 0
	s_barrier
	s_add_u32 s66, s42, 0x80
	s_addc_u32 s67, s43, 0
	ds_read_b128 v[178:181], v164 offset:49152
	ds_read_b128 v[182:185], v164 offset:50176
	ds_read_b128 v[186:189], v164 offset:51200
	ds_read_b128 v[190:193], v164 offset:52224
	ds_read_b128 v[194:197], v164 offset:53248
	ds_read_b128 v[198:201], v164 offset:54272
	ds_read_b128 v[202:205], v164 offset:55296
	ds_read_b128 v[206:209], v164 offset:56320
	s_mov_b32 m0, s52
	s_nop 0
	global_load_lds_dwordx4 v159, s[66:67]
	s_add_u32 s66, s42, 0x20080
	s_mov_b32 m0, s53
	s_addc_u32 s67, s43, 0
	global_load_lds_dwordx4 v159, s[66:67]
	s_add_u32 s66, s42, 0x40080
	s_mov_b32 m0, s56
	s_addc_u32 s67, s43, 0
	global_load_lds_dwordx4 v159, s[66:67]
	s_add_u32 s42, s42, 0x60080
	s_mov_b32 m0, s57
	s_addc_u32 s43, s43, 0
	global_load_lds_dwordx4 v159, s[42:43]
	s_mov_b32 m0, s54
	s_nop 0
	global_load_lds_dwordx4 v158, s[40:41]
	s_add_u32 s38, s38, 0x20080
	s_mov_b32 m0, s55
	s_addc_u32 s39, s39, 0
	global_load_lds_dwordx4 v158, s[38:39]
	s_waitcnt vmcnt(8)
	s_waitcnt lgkmcnt(0)
	s_barrier
	s_setprio 1
	v_mfma_f32_16x16x32_bf16 v[92:95], v[112:115], v[178:181], v[92:95]
	v_mfma_f32_16x16x32_bf16 v[88:91], v[140:143], v[178:181], v[88:91]
	v_mfma_f32_16x16x32_bf16 v[84:87], v[112:115], v[186:189], v[84:87]
	v_mfma_f32_16x16x32_bf16 v[80:83], v[140:143], v[186:189], v[80:83]
	v_mfma_f32_16x16x32_bf16 v[76:79], v[112:115], v[194:197], v[76:79]
	v_mfma_f32_16x16x32_bf16 v[72:75], v[140:143], v[194:197], v[72:75]
	v_mfma_f32_16x16x32_bf16 v[68:71], v[112:115], v[202:205], v[68:71]
	v_mfma_f32_16x16x32_bf16 v[64:67], v[140:143], v[202:205], v[64:67]
	v_mfma_f32_16x16x32_bf16 v[92:95], v[116:119], v[182:185], v[92:95]
	v_mfma_f32_16x16x32_bf16 v[88:91], v[144:147], v[182:185], v[88:91]
	v_mfma_f32_16x16x32_bf16 v[84:87], v[116:119], v[190:193], v[84:87]
	v_mfma_f32_16x16x32_bf16 v[80:83], v[144:147], v[190:193], v[80:83]
	v_mfma_f32_16x16x32_bf16 v[76:79], v[116:119], v[198:201], v[76:79]
	v_mfma_f32_16x16x32_bf16 v[72:75], v[144:147], v[198:201], v[72:75]
	v_mfma_f32_16x16x32_bf16 v[68:71], v[116:119], v[206:209], v[68:71]
	v_mfma_f32_16x16x32_bf16 v[64:67], v[144:147], v[206:209], v[64:67]
	v_mfma_f32_16x16x32_bf16 v[28:31], v[148:151], v[178:181], v[28:31]
	v_mfma_f32_16x16x32_bf16 v[24:27], v[168:171], v[178:181], v[24:27]
	v_mfma_f32_16x16x32_bf16 v[20:23], v[148:151], v[186:189], v[20:23]
	v_mfma_f32_16x16x32_bf16 v[16:19], v[168:171], v[186:189], v[16:19]
	v_mfma_f32_16x16x32_bf16 v[12:15], v[148:151], v[194:197], v[12:15]
	v_mfma_f32_16x16x32_bf16 v[8:11], v[168:171], v[194:197], v[8:11]
	v_mfma_f32_16x16x32_bf16 v[4:7], v[148:151], v[202:205], v[4:7]
	v_mfma_f32_16x16x32_bf16 v[0:3], v[168:171], v[202:205], v[0:3]
	v_mfma_f32_16x16x32_bf16 v[28:31], v[152:155], v[182:185], v[28:31]
	v_mfma_f32_16x16x32_bf16 v[24:27], v[172:175], v[182:185], v[24:27]
	v_mfma_f32_16x16x32_bf16 v[20:23], v[152:155], v[190:193], v[20:23]
	v_mfma_f32_16x16x32_bf16 v[16:19], v[172:175], v[190:193], v[16:19]
	v_mfma_f32_16x16x32_bf16 v[12:15], v[152:155], v[198:201], v[12:15]
	v_mfma_f32_16x16x32_bf16 v[8:11], v[172:175], v[198:201], v[8:11]
	v_mfma_f32_16x16x32_bf16 v[4:7], v[152:155], v[206:209], v[4:7]
	v_mfma_f32_16x16x32_bf16 v[0:3], v[172:175], v[206:209], v[0:3]
	s_setprio 0
	s_barrier
	s_add_i32 s65, s65, 2
	s_add_u32 s26, s26, 0x100
	s_addc_u32 s27, s27, 0
	s_add_u32 s62, s62, 0x100
	s_addc_u32 s63, s63, 0
	s_cmp_gt_u32 s65, 13
	s_cbranch_scc0 .LBB0_981
	s_and_b64 vcc, exec, s[14:15]
	s_cbranch_vccz .LBB0_984
	s_barrier

; #define PG8_STAGE(bufoff, gbase, voff, p64) do { _Pragma("unroll") for (int _i = 0; _i < 2; ++_i) { \
;         const char* _gb = (const char*)(gbase) + (size_t)_i * (p64); const unsigned _la = ldsbase + (unsigned)(bufoff) + (unsigned)_i * 8192u; \
;         asm volatile("s_mov_b32 m0, %0\n\ts_nop 0\n\tglobal_load_lds_dwordx4 %1, %2" :: "s"(_la), "v"(voff), "s"(_gb) : "memory"); } } while (0)
; #define PG8_LDA(dst, b, h) do { _Pragma("unroll") for (int m = 0; m < 4; ++m) _Pragma("unroll") for (int k = 0; k < 2; ++k) dst[m][k] = *(const LAS bf16x8*)(lds + PG8_SA(b, h) + aoff + m * 2048 + k * 1024); } while (0)
; #define PG8_LDB(dst, b, h) do { _Pragma("unroll") for (int n = 0; n < 2; ++n) _Pragma("unroll") for (int k = 0; k < 2; ++k) dst[n][k] = *(const LAS bf16x8*)(lds + PG8_SB(b, h) + boff + n * 2048 + k * 1024); } while (0)
; #define PG8_WAIT_V(n) asm volatile("s_waitcnt vmcnt(" #n ")" ::: "memory")
; #define PG8_WAIT_L(n) asm volatile("s_waitcnt lgkmcnt(" #n ")" ::: "memory")
; #define PG8_BAR __builtin_amdgcn_s_barrier()
; #define PG8_SCHED __builtin_amdgcn_sched_barrier(0)
; template <class Epi, class Sched>
; __device__ __forceinline__ void gemm_phase(LAS unsigned char* lds, const Sched& S, const Epi& E) {
;     ...
;         for (int t = 0; t < nt; t += 2) {
;             const bool last = (t == nt - 2);
;             const char* a1 = cA + (size_t)(t + 1) * kstep;
;             const char* a2 = last ? nA : cA + (size_t)(t + 2) * kstep; const char* b2 = last ? nB : cB + (size_t)(t + 2) * kstep;
;             const char* a3 = a2 + kstep; const char* b3 = b2 + kstep;
;             const unsigned vA2 = voffA, vB2 = voffB, hA2 = hA, hB2 = hB;
;             PG8_LDB(B0, 0, 0); PG8_LDB(B1, 0, 1); PG8_SCHED; PG8_LDA(At, 0, 0); PG8_STAGE(PG8_SA(1, 1), a1 + hA, voffA, hA / 2);
;             PG8_WAIT_V(8); PG8_WAIT_L(0); PG8_BAR; PG8_MMA(0, 0, At, B0); PG8_MMA(0, 1, At, B1); PG8_BAR; PG8_SCHED;
;     ...
;         if (!keep) {
; #pragma unroll
;             for (int a = 0; a < 2; ++a)
; #pragma unroll
;                 for (int b = 0; b < 2; ++b)
; #pragma unroll
;                     for (int m = 0; m < 4; ++m)
; #pragma unroll
;                         for (int n = 0; n < 2; ++n) acc[a][b][m][n] = (f32x4){0.f, 0.f, 0.f, 0.f};
;         }
;         cA = nA; cB = nB; nt = nnt; ++ui;
;         if (wr == 1) PG8_BAR;
.LBB0_1010:
	s_add_u32 s26, s26, 0x40080
	s_addc_u32 s27, s27, 0
	s_add_u32 s61, s38, 0x100
	s_addc_u32 s62, s39, 0
	s_mov_b32 s63, -2
	v_mov_b64_e32 v[0:1], 0
	v_mov_b64_e32 v[2:3], 0
	v_mov_b64_e32 v[12:13], 0
	v_mov_b64_e32 v[14:15], 0
	v_mov_b64_e32 v[16:17], 0
	v_mov_b64_e32 v[18:19], 0
	v_mov_b64_e32 v[28:29], 0
	v_mov_b64_e32 v[30:31], 0
	v_mov_b64_e32 v[32:33], 0
	v_mov_b64_e32 v[34:35], 0
	v_mov_b64_e32 v[44:45], 0
	v_mov_b64_e32 v[46:47], 0
	v_mov_b64_e32 v[48:49], 0
	v_mov_b64_e32 v[50:51], 0
	v_mov_b64_e32 v[60:61], 0
	v_mov_b64_e32 v[62:63], 0
	v_mov_b64_e32 v[4:5], 0
	v_mov_b64_e32 v[6:7], 0
	v_mov_b64_e32 v[8:9], 0
	v_mov_b64_e32 v[10:11], 0
	v_mov_b64_e32 v[20:21], 0
	v_mov_b64_e32 v[22:23], 0
	v_mov_b64_e32 v[24:25], 0
	v_mov_b64_e32 v[26:27], 0
	v_mov_b64_e32 v[36:37], 0
	v_mov_b64_e32 v[38:39], 0
	v_mov_b64_e32 v[40:41], 0
	v_mov_b64_e32 v[42:43], 0
	v_mov_b64_e32 v[52:53], 0
	v_mov_b64_e32 v[54:55], 0
	v_mov_b64_e32 v[56:57], 0
	v_mov_b64_e32 v[58:59], 0
	v_mov_b64_e32 v[64:65], 0
	v_mov_b64_e32 v[66:67], 0
	v_mov_b64_e32 v[76:77], 0
	v_mov_b64_e32 v[78:79], 0
	v_mov_b64_e32 v[80:81], 0
	v_mov_b64_e32 v[82:83], 0
	v_mov_b64_e32 v[92:93], 0
	v_mov_b64_e32 v[94:95], 0
	v_mov_b64_e32 v[96:97], 0
	v_mov_b64_e32 v[98:99], 0
	v_mov_b64_e32 v[108:109], 0
	v_mov_b64_e32 v[110:111], 0
	v_mov_b64_e32 v[112:113], 0
	v_mov_b64_e32 v[114:115], 0
	v_mov_b64_e32 v[124:125], 0
	v_mov_b64_e32 v[126:127], 0
	v_mov_b64_e32 v[68:69], 0
	v_mov_b64_e32 v[70:71], 0
	v_mov_b64_e32 v[72:73], 0
	v_mov_b64_e32 v[74:75], 0
	v_mov_b64_e32 v[84:85], 0
	v_mov_b64_e32 v[86:87], 0
	v_mov_b64_e32 v[88:89], 0
	v_mov_b64_e32 v[90:91], 0
	v_mov_b64_e32 v[100:101], 0
	v_mov_b64_e32 v[102:103], 0
	v_mov_b64_e32 v[104:105], 0
	v_mov_b64_e32 v[106:107], 0
	v_mov_b64_e32 v[116:117], 0
	v_mov_b64_e32 v[118:119], 0
	v_mov_b64_e32 v[120:121], 0
	v_mov_b64_e32 v[122:123], 0
.LBB0_1011:
	ds_read_b128 v[144:147], v138
	ds_read_b128 v[148:151], v138 offset:1024
	ds_read_b128 v[152:155], v138 offset:2048
	ds_read_b128 v[156:159], v138 offset:3072
	ds_read_b128 v[160:163], v139
	ds_read_b128 v[164:167], v139 offset:1024
	ds_read_b128 v[168:171], v139 offset:2048
	ds_read_b128 v[172:175], v139 offset:3072
	s_add_u32 s30, s26, 0xfffc0080
	s_addc_u32 s38, s27, -1
	s_cmp_eq_u32 s63, 12
	s_cselect_b32 s39, s23, s38
	s_cselect_b32 s38, s22, s30
	s_cselect_b32 s42, s24, s61
	s_cselect_b32 s43, s25, s62
	s_add_u32 s40, s38, 0x80
	s_addc_u32 s41, s39, 0
	ds_read_b128 v[178:181], v140
	ds_read_b128 v[182:185], v140 offset:1024
	ds_read_b128 v[186:189], v140 offset:2048
	ds_read_b128 v[190:193], v140 offset:3072
	ds_read_b128 v[194:197], v140 offset:4096
	ds_read_b128 v[198:201], v140 offset:5120
	ds_read_b128 v[202:205], v140 offset:6144
	ds_read_b128 v[206:209], v140 offset:7168
	s_mov_b32 m0, s57
	s_nop 0
	global_load_lds_dwordx4 v134, s[26:27]
	s_add_u32 s66, s26, 0x20000
	s_mov_b32 m0, s58
	s_addc_u32 s67, s27, 0
	global_load_lds_dwordx4 v134, s[66:67]
	s_waitcnt vmcnt(8)
	s_waitcnt lgkmcnt(0)
	s_barrier
	s_setprio 1
	v_mfma_f32_16x16x32_bf16 v[120:123], v[144:147], v[178:181], v[120:123]
	v_mfma_f32_16x16x32_bf16 v[116:119], v[152:155], v[178:181], v[116:119]
	v_mfma_f32_16x16x32_bf16 v[104:107], v[144:147], v[186:189], v[104:107]
	v_mfma_f32_16x16x32_bf16 v[100:103], v[152:155], v[186:189], v[100:103]
	v_mfma_f32_16x16x32_bf16 v[88:91], v[144:147], v[194:197], v[88:91]
	v_mfma_f32_16x16x32_bf16 v[84:87], v[152:155], v[194:197], v[84:87]
	v_mfma_f32_16x16x32_bf16 v[72:75], v[144:147], v[202:205], v[72:75]
	v_mfma_f32_16x16x32_bf16 v[68:71], v[152:155], v[202:205], v[68:71]
	v_mfma_f32_16x16x32_bf16 v[120:123], v[148:151], v[182:185], v[120:123]
	v_mfma_f32_16x16x32_bf16 v[116:119], v[156:159], v[182:185], v[116:119]
	v_mfma_f32_16x16x32_bf16 v[104:107], v[148:151], v[190:193], v[104:107]
	v_mfma_f32_16x16x32_bf16 v[100:103], v[156:159], v[190:193], v[100:103]
	v_mfma_f32_16x16x32_bf16 v[88:91], v[148:151], v[198:201], v[88:91]
	v_mfma_f32_16x16x32_bf16 v[84:87], v[156:159], v[198:201], v[84:87]
	v_mfma_f32_16x16x32_bf16 v[72:75], v[148:151], v[206:209], v[72:75]
	v_mfma_f32_16x16x32_bf16 v[68:71], v[156:159], v[206:209], v[68:71]
	v_mfma_f32_16x16x32_bf16 v[124:127], v[160:163], v[178:181], v[124:127]
	v_mfma_f32_16x16x32_bf16 v[112:115], v[168:171], v[178:181], v[112:115]
	v_mfma_f32_16x16x32_bf16 v[108:111], v[160:163], v[186:189], v[108:111]
	v_mfma_f32_16x16x32_bf16 v[96:99], v[168:171], v[186:189], v[96:99]
	v_mfma_f32_16x16x32_bf16 v[92:95], v[160:163], v[194:197], v[92:95]
	v_mfma_f32_16x16x32_bf16 v[80:83], v[168:171], v[194:197], v[80:83]
	v_mfma_f32_16x16x32_bf16 v[76:79], v[160:163], v[202:205], v[76:79]
	v_mfma_f32_16x16x32_bf16 v[64:67], v[168:171], v[202:205], v[64:67]
	v_mfma_f32_16x16x32_bf16 v[124:127], v[164:167], v[182:185], v[124:127]
	v_mfma_f32_16x16x32_bf16 v[112:115], v[172:175], v[182:185], v[112:115]
	v_mfma_f32_16x16x32_bf16 v[108:111], v[164:167], v[190:193], v[108:111]
	v_mfma_f32_16x16x32_bf16 v[96:99], v[172:175], v[190:193], v[96:99]
	v_mfma_f32_16x16x32_bf16 v[92:95], v[164:167], v[198:201], v[92:95]
	v_mfma_f32_16x16x32_bf16 v[80:83], v[172:175], v[198:201], v[80:83]
	v_mfma_f32_16x16x32_bf16 v[76:79], v[164:167], v[206:209], v[76:79]
	v_mfma_f32_16x16x32_bf16 v[64:67], v[172:175], v[206:209], v[64:67]
	s_setprio 0
	s_barrier
; #define PG8_STAGE(bufoff, gbase, voff, p64) do { _Pragma("unroll") for (int _i = 0; _i < 2; ++_i) { \
;         const char* _gb = (const char*)(gbase) + (size_t)_i * (p64); const unsigned _la = ldsbase + (unsigned)(bufoff) + (unsigned)_i * 8192u; \
;         asm volatile("s_mov_b32 m0, %0\n\ts_nop 0\n\tglobal_load_lds_dwordx4 %1, %2" :: "s"(_la), "v"(voff), "s"(_gb) : "memory"); } } while (0)
; #define PG8_LDA(dst, b, h) do { _Pragma("unroll") for (int m = 0; m < 4; ++m) _Pragma("unroll") for (int k = 0; k < 2; ++k) dst[m][k] = *(const LAS bf16x8*)(lds + PG8_SA(b, h) + aoff + m * 2048 + k * 1024); } while (0)
; #define PG8_LDB(dst, b, h) do { _Pragma("unroll") for (int n = 0; n < 2; ++n) _Pragma("unroll") for (int k = 0; k < 2; ++k) dst[n][k] = *(const LAS bf16x8*)(lds + PG8_SB(b, h) + boff + n * 2048 + k * 1024); } while (0)
; #define PG8_MMA(ai, bj, At, Bt) do { __builtin_amdgcn_s_setprio(1); _Pragma("unroll") for (int m = 0; m < 4; ++m) _Pragma("unroll") for (int n = 0; n < 2; ++n) _Pragma("unroll") for (int k = 0; k < 2; ++k) \
;         acc[ai][bj][m][n] = __builtin_amdgcn_mfma_f32_16x16x32_bf16(Bt[n][k], At[m][k], acc[ai][bj][m][n], 0, 0, 0); __builtin_amdgcn_s_setprio(0); } while (0)
; #define PG8_WAIT_V(n) asm volatile("s_waitcnt vmcnt(" #n ")" ::: "memory")
; #define PG8_WAIT_L(n) asm volatile("s_waitcnt lgkmcnt(" #n ")" ::: "memory")
; #define PG8_BAR __builtin_amdgcn_s_barrier()
; #define PG8_SCHED __builtin_amdgcn_sched_barrier(0)
; template <class Epi, class Sched>
; __device__ __forceinline__ void gemm_phase(LAS unsigned char* lds, const Sched& S, const Epi& E) {
;     ...
;             PG8_LDA(At, 0, 1); PG8_STAGE(PG8_SB(0, 0), b2, vB2, hB2 / 2); PG8_STAGE(PG8_SB(0, 1), b2 + hB2, vB2, hB2 / 2); PG8_STAGE(PG8_SA(0, 0), a2, vA2, hA2 / 2);
;             PG8_WAIT_V(8); PG8_WAIT_L(0); PG8_BAR; PG8_MMA(1, 0, At, B0); PG8_MMA(1, 1, At, B1); PG8_BAR; PG8_SCHED;
;             PG8_LDB(B0, 1, 0); PG8_LDB(B1, 1, 1); PG8_SCHED; PG8_LDA(At, 1, 0); PG8_STAGE(PG8_SA(0, 1), a2 + hA2, vA2, hA2 / 2);
;             PG8_WAIT_V(8); PG8_WAIT_L(0); PG8_BAR; PG8_MMA(0, 0, At, B0); PG8_MMA(0, 1, At, B1); PG8_BAR; PG8_SCHED;
	s_add_u32 s66, s42, 0x20000
	ds_read_b128 v[178:181], v140 offset:16384
	ds_read_b128 v[182:185], v140 offset:17408
	ds_read_b128 v[186:189], v140 offset:18432
	ds_read_b128 v[190:193], v140 offset:19456
	ds_read_b128 v[194:197], v140 offset:20480
	ds_read_b128 v[198:201], v140 offset:21504
	ds_read_b128 v[202:205], v140 offset:22528
	ds_read_b128 v[206:209], v140 offset:23552
	s_mov_b32 m0, s35
	s_nop 0
	global_load_lds_dwordx4 v135, s[42:43]
	s_mov_b32 m0, s36
	s_addc_u32 s67, s43, 0
	global_load_lds_dwordx4 v135, s[66:67]
	s_add_u32 s66, s42, 0x40000
	s_mov_b32 m0, s37
	s_addc_u32 s67, s43, 0
	global_load_lds_dwordx4 v135, s[66:67]
	s_add_u32 s66, s42, 0x60000
	s_mov_b32 m0, s44
	s_addc_u32 s67, s43, 0
	global_load_lds_dwordx4 v135, s[66:67]
	s_mov_b32 m0, s34
	s_nop 0
	global_load_lds_dwordx4 v134, s[38:39]
	s_add_u32 s66, s38, 0x20000
	s_mov_b32 m0, s45
	s_addc_u32 s67, s39, 0
	global_load_lds_dwordx4 v134, s[66:67]
	s_waitcnt vmcnt(8)
	s_waitcnt lgkmcnt(0)
	s_barrier
	s_setprio 1
	v_mfma_f32_16x16x32_bf16 v[56:59], v[144:147], v[178:181], v[56:59]
	v_mfma_f32_16x16x32_bf16 v[52:55], v[152:155], v[178:181], v[52:55]
	v_mfma_f32_16x16x32_bf16 v[40:43], v[144:147], v[186:189], v[40:43]
	v_mfma_f32_16x16x32_bf16 v[36:39], v[152:155], v[186:189], v[36:39]
	v_mfma_f32_16x16x32_bf16 v[24:27], v[144:147], v[194:197], v[24:27]
	v_mfma_f32_16x16x32_bf16 v[20:23], v[152:155], v[194:197], v[20:23]
	v_mfma_f32_16x16x32_bf16 v[8:11], v[144:147], v[202:205], v[8:11]
	v_mfma_f32_16x16x32_bf16 v[4:7], v[152:155], v[202:205], v[4:7]
	v_mfma_f32_16x16x32_bf16 v[56:59], v[148:151], v[182:185], v[56:59]
	v_mfma_f32_16x16x32_bf16 v[52:55], v[156:159], v[182:185], v[52:55]
	v_mfma_f32_16x16x32_bf16 v[40:43], v[148:151], v[190:193], v[40:43]
	v_mfma_f32_16x16x32_bf16 v[36:39], v[156:159], v[190:193], v[36:39]
	v_mfma_f32_16x16x32_bf16 v[24:27], v[148:151], v[198:201], v[24:27]
	v_mfma_f32_16x16x32_bf16 v[20:23], v[156:159], v[198:201], v[20:23]
	v_mfma_f32_16x16x32_bf16 v[8:11], v[148:151], v[206:209], v[8:11]
	v_mfma_f32_16x16x32_bf16 v[4:7], v[156:159], v[206:209], v[4:7]
	v_mfma_f32_16x16x32_bf16 v[60:63], v[160:163], v[178:181], v[60:63]
	v_mfma_f32_16x16x32_bf16 v[48:51], v[168:171], v[178:181], v[48:51]
	v_mfma_f32_16x16x32_bf16 v[44:47], v[160:163], v[186:189], v[44:47]
	v_mfma_f32_16x16x32_bf16 v[32:35], v[168:171], v[186:189], v[32:35]
	v_mfma_f32_16x16x32_bf16 v[28:31], v[160:163], v[194:197], v[28:31]
	v_mfma_f32_16x16x32_bf16 v[16:19], v[168:171], v[194:197], v[16:19]
	v_mfma_f32_16x16x32_bf16 v[12:15], v[160:163], v[202:205], v[12:15]
	v_mfma_f32_16x16x32_bf16 v[0:3], v[168:171], v[202:205], v[0:3]
	v_mfma_f32_16x16x32_bf16 v[60:63], v[164:167], v[182:185], v[60:63]
	v_mfma_f32_16x16x32_bf16 v[48:51], v[172:175], v[182:185], v[48:51]
	v_mfma_f32_16x16x32_bf16 v[44:47], v[164:167], v[190:193], v[44:47]
	v_mfma_f32_16x16x32_bf16 v[32:35], v[172:175], v[190:193], v[32:35]
	v_mfma_f32_16x16x32_bf16 v[28:31], v[164:167], v[198:201], v[28:31]
	v_mfma_f32_16x16x32_bf16 v[16:19], v[172:175], v[198:201], v[16:19]
	v_mfma_f32_16x16x32_bf16 v[12:15], v[164:167], v[206:209], v[12:15]
	v_mfma_f32_16x16x32_bf16 v[0:3], v[172:175], v[206:209], v[0:3]
	s_setprio 0
	s_barrier
	ds_read_b128 v[144:147], v141
	ds_read_b128 v[148:151], v141 offset:1024
	ds_read_b128 v[152:155], v141 offset:2048
	ds_read_b128 v[156:159], v141 offset:3072
	ds_read_b128 v[160:163], v142
	ds_read_b128 v[164:167], v142 offset:1024
	ds_read_b128 v[168:171], v142 offset:2048
	ds_read_b128 v[172:175], v142 offset:3072
	ds_read_b128 v[178:181], v140 offset:32768
	ds_read_b128 v[182:185], v140 offset:33792
	ds_read_b128 v[186:189], v140 offset:34816
	ds_read_b128 v[190:193], v140 offset:35840
	ds_read_b128 v[194:197], v140 offset:36864
	ds_read_b128 v[198:201], v140 offset:37888
	ds_read_b128 v[202:205], v140 offset:38912
	ds_read_b128 v[206:209], v140 offset:39936
	s_add_u32 s66, s38, 0x40000
	s_mov_b32 m0, s46
	s_addc_u32 s67, s39, 0
	global_load_lds_dwordx4 v134, s[66:67]
	s_add_u32 s66, s38, 0x60000
	s_mov_b32 m0, s47
	s_addc_u32 s67, s39, 0
	global_load_lds_dwordx4 v134, s[66:67]
	s_waitcnt vmcnt(8)
	s_waitcnt lgkmcnt(0)
	s_barrier
; #define PG8_STAGE(bufoff, gbase, voff, p64) do { _Pragma("unroll") for (int _i = 0; _i < 2; ++_i) { \
;         const char* _gb = (const char*)(gbase) + (size_t)_i * (p64); const unsigned _la = ldsbase + (unsigned)(bufoff) + (unsigned)_i * 8192u; \
;         asm volatile("s_mov_b32 m0, %0\n\ts_nop 0\n\tglobal_load_lds_dwordx4 %1, %2" :: "s"(_la), "v"(voff), "s"(_gb) : "memory"); } } while (0)
; #define PG8_LDA(dst, b, h) do { _Pragma("unroll") for (int m = 0; m < 4; ++m) _Pragma("unroll") for (int k = 0; k < 2; ++k) dst[m][k] = *(const LAS bf16x8*)(lds + PG8_SA(b, h) + aoff + m * 2048 + k * 1024); } while (0)
; #define PG8_MMA(ai, bj, At, Bt) do { __builtin_amdgcn_s_setprio(1); _Pragma("unroll") for (int m = 0; m < 4; ++m) _Pragma("unroll") for (int n = 0; n < 2; ++n) _Pragma("unroll") for (int k = 0; k < 2; ++k) \
;         acc[ai][bj][m][n] = __builtin_amdgcn_mfma_f32_16x16x32_bf16(Bt[n][k], At[m][k], acc[ai][bj][m][n], 0, 0, 0); __builtin_amdgcn_s_setprio(0); } while (0)
; #define PG8_WAIT_V(n) asm volatile("s_waitcnt vmcnt(" #n ")" ::: "memory")
; #define PG8_WAIT_L(n) asm volatile("s_waitcnt lgkmcnt(" #n ")" ::: "memory")
; #define PG8_BAR __builtin_amdgcn_s_barrier()
; #define PG8_SCHED __builtin_amdgcn_sched_barrier(0)
; template <class Epi, class Sched>
; __device__ __forceinline__ void gemm_phase(LAS unsigned char* lds, const Sched& S, const Epi& E) {
;     ...
;             PG8_WAIT_V(8); PG8_WAIT_L(0); PG8_BAR; PG8_MMA(0, 0, At, B0); PG8_MMA(0, 1, At, B1); PG8_BAR; PG8_SCHED;
;             PG8_LDA(At, 1, 1); PG8_STAGE(PG8_SB(1, 0), b3, vB2, hB2 / 2); PG8_STAGE(PG8_SB(1, 1), b3 + hB2, vB2, hB2 / 2); PG8_STAGE(PG8_SA(1, 0), a3, vA2, hA2 / 2);
;             PG8_WAIT_V(8); PG8_WAIT_L(0); PG8_BAR; PG8_MMA(1, 0, At, B0); PG8_MMA(1, 1, At, B1); PG8_BAR; PG8_SCHED;
;         }
;         if (wr == 0) PG8_BAR;
	s_setprio 1
	v_mfma_f32_16x16x32_bf16 v[120:123], v[144:147], v[178:181], v[120:123]
	v_mfma_f32_16x16x32_bf16 v[116:119], v[152:155], v[178:181], v[116:119]
	v_mfma_f32_16x16x32_bf16 v[104:107], v[144:147], v[186:189], v[104:107]
	v_mfma_f32_16x16x32_bf16 v[100:103], v[152:155], v[186:189], v[100:103]
	v_mfma_f32_16x16x32_bf16 v[88:91], v[144:147], v[194:197], v[88:91]
	v_mfma_f32_16x16x32_bf16 v[84:87], v[152:155], v[194:197], v[84:87]
	v_mfma_f32_16x16x32_bf16 v[72:75], v[144:147], v[202:205], v[72:75]
	v_mfma_f32_16x16x32_bf16 v[68:71], v[152:155], v[202:205], v[68:71]
	v_mfma_f32_16x16x32_bf16 v[120:123], v[148:151], v[182:185], v[120:123]
	v_mfma_f32_16x16x32_bf16 v[116:119], v[156:159], v[182:185], v[116:119]
	v_mfma_f32_16x16x32_bf16 v[104:107], v[148:151], v[190:193], v[104:107]
	v_mfma_f32_16x16x32_bf16 v[100:103], v[156:159], v[190:193], v[100:103]
	v_mfma_f32_16x16x32_bf16 v[88:91], v[148:151], v[198:201], v[88:91]
	v_mfma_f32_16x16x32_bf16 v[84:87], v[156:159], v[198:201], v[84:87]
	v_mfma_f32_16x16x32_bf16 v[72:75], v[148:151], v[206:209], v[72:75]
	v_mfma_f32_16x16x32_bf16 v[68:71], v[156:159], v[206:209], v[68:71]
	v_mfma_f32_16x16x32_bf16 v[124:127], v[160:163], v[178:181], v[124:127]
	v_mfma_f32_16x16x32_bf16 v[112:115], v[168:171], v[178:181], v[112:115]
	v_mfma_f32_16x16x32_bf16 v[108:111], v[160:163], v[186:189], v[108:111]
	v_mfma_f32_16x16x32_bf16 v[96:99], v[168:171], v[186:189], v[96:99]
	v_mfma_f32_16x16x32_bf16 v[92:95], v[160:163], v[194:197], v[92:95]
	v_mfma_f32_16x16x32_bf16 v[80:83], v[168:171], v[194:197], v[80:83]
	v_mfma_f32_16x16x32_bf16 v[76:79], v[160:163], v[202:205], v[76:79]
	v_mfma_f32_16x16x32_bf16 v[64:67], v[168:171], v[202:205], v[64:67]
	v_mfma_f32_16x16x32_bf16 v[124:127], v[164:167], v[182:185], v[124:127]
	v_mfma_f32_16x16x32_bf16 v[112:115], v[172:175], v[182:185], v[112:115]
	v_mfma_f32_16x16x32_bf16 v[108:111], v[164:167], v[190:193], v[108:111]
	v_mfma_f32_16x16x32_bf16 v[96:99], v[172:175], v[190:193], v[96:99]
	v_mfma_f32_16x16x32_bf16 v[92:95], v[164:167], v[198:201], v[92:95]
	v_mfma_f32_16x16x32_bf16 v[80:83], v[172:175], v[198:201], v[80:83]
	v_mfma_f32_16x16x32_bf16 v[76:79], v[164:167], v[206:209], v[76:79]
	v_mfma_f32_16x16x32_bf16 v[64:67], v[172:175], v[206:209], v[64:67]
	s_setprio 0
	s_barrier
	s_add_u32 s66, s42, 0x80
	s_addc_u32 s67, s43, 0
	ds_read_b128 v[178:181], v140 offset:49152
	ds_read_b128 v[182:185], v140 offset:50176
	ds_read_b128 v[186:189], v140 offset:51200
	ds_read_b128 v[190:193], v140 offset:52224
	ds_read_b128 v[194:197], v140 offset:53248
	ds_read_b128 v[198:201], v140 offset:54272
	ds_read_b128 v[202:205], v140 offset:55296
	ds_read_b128 v[206:209], v140 offset:56320
	s_mov_b32 m0, s51
	s_nop 0
	global_load_lds_dwordx4 v135, s[66:67]
	s_add_u32 s66, s42, 0x20080
	s_mov_b32 m0, s52
	s_addc_u32 s67, s43, 0
	global_load_lds_dwordx4 v135, s[66:67]
	s_add_u32 s66, s42, 0x40080
	s_mov_b32 m0, s55
	s_addc_u32 s67, s43, 0
	global_load_lds_dwordx4 v135, s[66:67]
	s_add_u32 s42, s42, 0x60080
	s_mov_b32 m0, s56
	s_addc_u32 s43, s43, 0
	global_load_lds_dwordx4 v135, s[42:43]
	s_mov_b32 m0, s53
	s_nop 0
	global_load_lds_dwordx4 v134, s[40:41]
	s_add_u32 s38, s38, 0x20080
	s_mov_b32 m0, s54
	s_addc_u32 s39, s39, 0
	global_load_lds_dwordx4 v134, s[38:39]
	s_waitcnt vmcnt(8)
	s_waitcnt lgkmcnt(0)
	s_barrier
	s_setprio 1
	v_mfma_f32_16x16x32_bf16 v[56:59], v[144:147], v[178:181], v[56:59]
	v_mfma_f32_16x16x32_bf16 v[52:55], v[152:155], v[178:181], v[52:55]
	v_mfma_f32_16x16x32_bf16 v[40:43], v[144:147], v[186:189], v[40:43]
	v_mfma_f32_16x16x32_bf16 v[36:39], v[152:155], v[186:189], v[36:39]
	v_mfma_f32_16x16x32_bf16 v[24:27], v[144:147], v[194:197], v[24:27]
	v_mfma_f32_16x16x32_bf16 v[20:23], v[152:155], v[194:197], v[20:23]
	v_mfma_f32_16x16x32_bf16 v[8:11], v[144:147], v[202:205], v[8:11]
	v_mfma_f32_16x16x32_bf16 v[4:7], v[152:155], v[202:205], v[4:7]
	v_mfma_f32_16x16x32_bf16 v[56:59], v[148:151], v[182:185], v[56:59]
	v_mfma_f32_16x16x32_bf16 v[52:55], v[156:159], v[182:185], v[52:55]
	v_mfma_f32_16x16x32_bf16 v[40:43], v[148:151], v[190:193], v[40:43]
	v_mfma_f32_16x16x32_bf16 v[36:39], v[156:159], v[190:193], v[36:39]
	v_mfma_f32_16x16x32_bf16 v[24:27], v[148:151], v[198:201], v[24:27]
	v_mfma_f32_16x16x32_bf16 v[20:23], v[156:159], v[198:201], v[20:23]
	v_mfma_f32_16x16x32_bf16 v[8:11], v[148:151], v[206:209], v[8:11]
	v_mfma_f32_16x16x32_bf16 v[4:7], v[156:159], v[206:209], v[4:7]
	v_mfma_f32_16x16x32_bf16 v[60:63], v[160:163], v[178:181], v[60:63]
	v_mfma_f32_16x16x32_bf16 v[48:51], v[168:171], v[178:181], v[48:51]
	v_mfma_f32_16x16x32_bf16 v[44:47], v[160:163], v[186:189], v[44:47]
	v_mfma_f32_16x16x32_bf16 v[32:35], v[168:171], v[186:189], v[32:35]
	v_mfma_f32_16x16x32_bf16 v[28:31], v[160:163], v[194:197], v[28:31]
	v_mfma_f32_16x16x32_bf16 v[16:19], v[168:171], v[194:197], v[16:19]
	v_mfma_f32_16x16x32_bf16 v[12:15], v[160:163], v[202:205], v[12:15]
	v_mfma_f32_16x16x32_bf16 v[0:3], v[168:171], v[202:205], v[0:3]
	v_mfma_f32_16x16x32_bf16 v[60:63], v[164:167], v[182:185], v[60:63]
	v_mfma_f32_16x16x32_bf16 v[48:51], v[172:175], v[182:185], v[48:51]
	v_mfma_f32_16x16x32_bf16 v[44:47], v[164:167], v[190:193], v[44:47]
	v_mfma_f32_16x16x32_bf16 v[32:35], v[172:175], v[190:193], v[32:35]
	v_mfma_f32_16x16x32_bf16 v[28:31], v[164:167], v[198:201], v[28:31]
	v_mfma_f32_16x16x32_bf16 v[16:19], v[172:175], v[198:201], v[16:19]
	v_mfma_f32_16x16x32_bf16 v[12:15], v[164:167], v[206:209], v[12:15]
	v_mfma_f32_16x16x32_bf16 v[0:3], v[172:175], v[206:209], v[0:3]
	s_setprio 0
	s_barrier
	s_add_i32 s63, s63, 2
	s_add_u32 s26, s26, 0x100
	s_addc_u32 s27, s27, 0
	s_add_u32 s61, s61, 0x100
	s_addc_u32 s62, s62, 0
	s_cmp_gt_u32 s63, 13
	s_cbranch_scc0 .LBB0_1011
	s_and_b64 vcc, exec, s[14:15]
	s_cbranch_vccz .LBB0_1014
	s_barrier

; #define PG8_STAGE(bufoff, gbase, voff, p64) do { _Pragma("unroll") for (int _i = 0; _i < 2; ++_i) { \
;         const char* _gb = (const char*)(gbase) + (size_t)_i * (p64); const unsigned _la = ldsbase + (unsigned)(bufoff) + (unsigned)_i * 8192u; \
;         asm volatile("s_mov_b32 m0, %0\n\ts_nop 0\n\tglobal_load_lds_dwordx4 %1, %2" :: "s"(_la), "v"(voff), "s"(_gb) : "memory"); } } while (0)
; #define PG8_LDA(dst, b, h) do { _Pragma("unroll") for (int m = 0; m < 4; ++m) _Pragma("unroll") for (int k = 0; k < 2; ++k) dst[m][k] = *(const LAS bf16x8*)(lds + PG8_SA(b, h) + aoff + m * 2048 + k * 1024); } while (0)
; #define PG8_LDB(dst, b, h) do { _Pragma("unroll") for (int n = 0; n < 2; ++n) _Pragma("unroll") for (int k = 0; k < 2; ++k) dst[n][k] = *(const LAS bf16x8*)(lds + PG8_SB(b, h) + boff + n * 2048 + k * 1024); } while (0)
; #define PG8_WAIT_V(n) asm volatile("s_waitcnt vmcnt(" #n ")" ::: "memory")
; #define PG8_WAIT_L(n) asm volatile("s_waitcnt lgkmcnt(" #n ")" ::: "memory")
; #define PG8_BAR __builtin_amdgcn_s_barrier()
; #define PG8_SCHED __builtin_amdgcn_sched_barrier(0)
; template <class Epi, class Sched>
; __device__ __forceinline__ void gemm_phase(LAS unsigned char* lds, const Sched& S, const Epi& E) {
;     ...
;         for (int t = 0; t < nt; t += 2) {
;             const bool last = (t == nt - 2);
;             const char* a1 = cA + (size_t)(t + 1) * kstep;
;             const char* a2 = last ? nA : cA + (size_t)(t + 2) * kstep; const char* b2 = last ? nB : cB + (size_t)(t + 2) * kstep;
;             const char* a3 = a2 + kstep; const char* b3 = b2 + kstep;
;             const unsigned vA2 = voffA, vB2 = voffB, hA2 = hA, hB2 = hB;
;             PG8_LDB(B0, 0, 0); PG8_LDB(B1, 0, 1); PG8_SCHED; PG8_LDA(At, 0, 0); PG8_STAGE(PG8_SA(1, 1), a1 + hA, voffA, hA / 2);
;             PG8_WAIT_V(8); PG8_WAIT_L(0); PG8_BAR; PG8_MMA(0, 0, At, B0); PG8_MMA(0, 1, At, B1); PG8_BAR; PG8_SCHED;
;     ...
;         if (!keep) {
; #pragma unroll
;             for (int a = 0; a < 2; ++a)
; #pragma unroll
;                 for (int b = 0; b < 2; ++b)
; #pragma unroll
;                     for (int m = 0; m < 4; ++m)
; #pragma unroll
;                         for (int n = 0; n < 2; ++n) acc[a][b][m][n] = (f32x4){0.f, 0.f, 0.f, 0.f};
;         }
;         cA = nA; cB = nB; nt = nnt; ++ui;
;         if (wr == 1) PG8_BAR;
.LBB0_1088:
	s_add_u32 s38, s38, 0x80080
	s_addc_u32 s39, s39, 0
	s_add_u32 s60, s40, 0x100
	s_addc_u32 s61, s41, 0
	s_mov_b32 s62, -2
	v_mov_b64_e32 v[0:1], 0
	v_mov_b64_e32 v[2:3], 0
	v_mov_b64_e32 v[4:5], 0
	v_mov_b64_e32 v[6:7], 0
	v_mov_b64_e32 v[8:9], 0
	v_mov_b64_e32 v[10:11], 0
	v_mov_b64_e32 v[16:17], 0
	v_mov_b64_e32 v[18:19], 0
	v_mov_b64_e32 v[24:25], 0
	v_mov_b64_e32 v[26:27], 0
	v_mov_b64_e32 v[32:33], 0
	v_mov_b64_e32 v[34:35], 0
	v_mov_b64_e32 v[40:41], 0
	v_mov_b64_e32 v[42:43], 0
	v_mov_b64_e32 v[48:49], 0
	v_mov_b64_e32 v[50:51], 0
	v_mov_b64_e32 v[12:13], 0
	v_mov_b64_e32 v[14:15], 0
	v_mov_b64_e32 v[20:21], 0
	v_mov_b64_e32 v[22:23], 0
	v_mov_b64_e32 v[28:29], 0
	v_mov_b64_e32 v[30:31], 0
	v_mov_b64_e32 v[36:37], 0
	v_mov_b64_e32 v[38:39], 0
	v_mov_b64_e32 v[44:45], 0
	v_mov_b64_e32 v[46:47], 0
	v_mov_b64_e32 v[52:53], 0
	v_mov_b64_e32 v[54:55], 0
	v_mov_b64_e32 v[56:57], 0
	v_mov_b64_e32 v[58:59], 0
	v_mov_b64_e32 v[60:61], 0
	v_mov_b64_e32 v[62:63], 0
	v_mov_b64_e32 v[64:65], 0
	v_mov_b64_e32 v[66:67], 0
	v_mov_b64_e32 v[68:69], 0
	v_mov_b64_e32 v[70:71], 0
	v_mov_b64_e32 v[72:73], 0
	v_mov_b64_e32 v[74:75], 0
	v_mov_b64_e32 v[80:81], 0
	v_mov_b64_e32 v[82:83], 0
	v_mov_b64_e32 v[88:89], 0
	v_mov_b64_e32 v[90:91], 0
	v_mov_b64_e32 v[96:97], 0
	v_mov_b64_e32 v[98:99], 0
	v_mov_b64_e32 v[104:105], 0
	v_mov_b64_e32 v[106:107], 0
	v_mov_b64_e32 v[112:113], 0
	v_mov_b64_e32 v[114:115], 0
	v_mov_b64_e32 v[76:77], 0
	v_mov_b64_e32 v[78:79], 0
	v_mov_b64_e32 v[84:85], 0
	v_mov_b64_e32 v[86:87], 0
	v_mov_b64_e32 v[92:93], 0
	v_mov_b64_e32 v[94:95], 0
	v_mov_b64_e32 v[100:101], 0
	v_mov_b64_e32 v[102:103], 0
	v_mov_b64_e32 v[108:109], 0
	v_mov_b64_e32 v[110:111], 0
	v_mov_b64_e32 v[116:117], 0
	v_mov_b64_e32 v[118:119], 0
	v_mov_b64_e32 v[120:121], 0
	v_mov_b64_e32 v[122:123], 0
	v_mov_b64_e32 v[124:125], 0
	v_mov_b64_e32 v[126:127], 0
.LBB0_1089:
	ds_read_b128 v[144:147], v138
	ds_read_b128 v[148:151], v138 offset:1024
	ds_read_b128 v[152:155], v138 offset:2048
	ds_read_b128 v[156:159], v138 offset:3072
	ds_read_b128 v[160:163], v139
	ds_read_b128 v[164:167], v139 offset:1024
	ds_read_b128 v[168:171], v139 offset:2048
	ds_read_b128 v[172:175], v139 offset:3072
	s_add_u32 s30, s38, 0xfff80080
	s_addc_u32 s40, s39, -1
	s_cmp_eq_u32 s62, 28
	s_cselect_b32 s41, s25, s40
	s_cselect_b32 s40, s24, s30
	s_cselect_b32 s44, s26, s60
	s_cselect_b32 s45, s27, s61
	s_add_u32 s42, s40, 0x80
	s_addc_u32 s43, s41, 0
	ds_read_b128 v[178:181], v140
	ds_read_b128 v[182:185], v140 offset:1024
	ds_read_b128 v[186:189], v140 offset:2048
	ds_read_b128 v[190:193], v140 offset:3072
	ds_read_b128 v[194:197], v140 offset:4096
	ds_read_b128 v[198:201], v140 offset:5120
	ds_read_b128 v[202:205], v140 offset:6144
	ds_read_b128 v[206:209], v140 offset:7168
	s_mov_b32 m0, s56
	s_nop 0
	global_load_lds_dwordx4 v134, s[38:39]
	s_add_u32 s66, s38, 0x40000
	s_mov_b32 m0, s57
	s_addc_u32 s67, s39, 0
	global_load_lds_dwordx4 v134, s[66:67]
	s_waitcnt vmcnt(8)
	s_waitcnt lgkmcnt(0)
	s_barrier
	s_setprio 1
	v_mfma_f32_16x16x32_bf16 v[124:127], v[144:147], v[178:181], v[124:127]
	v_mfma_f32_16x16x32_bf16 v[120:123], v[152:155], v[178:181], v[120:123]
	v_mfma_f32_16x16x32_bf16 v[116:119], v[144:147], v[186:189], v[116:119]
	v_mfma_f32_16x16x32_bf16 v[108:111], v[152:155], v[186:189], v[108:111]
	v_mfma_f32_16x16x32_bf16 v[100:103], v[144:147], v[194:197], v[100:103]
	v_mfma_f32_16x16x32_bf16 v[92:95], v[152:155], v[194:197], v[92:95]
	v_mfma_f32_16x16x32_bf16 v[84:87], v[144:147], v[202:205], v[84:87]
	v_mfma_f32_16x16x32_bf16 v[76:79], v[152:155], v[202:205], v[76:79]
	v_mfma_f32_16x16x32_bf16 v[124:127], v[148:151], v[182:185], v[124:127]
	v_mfma_f32_16x16x32_bf16 v[120:123], v[156:159], v[182:185], v[120:123]
	v_mfma_f32_16x16x32_bf16 v[116:119], v[148:151], v[190:193], v[116:119]
	v_mfma_f32_16x16x32_bf16 v[108:111], v[156:159], v[190:193], v[108:111]
	v_mfma_f32_16x16x32_bf16 v[100:103], v[148:151], v[198:201], v[100:103]
	v_mfma_f32_16x16x32_bf16 v[92:95], v[156:159], v[198:201], v[92:95]
	v_mfma_f32_16x16x32_bf16 v[84:87], v[148:151], v[206:209], v[84:87]
	v_mfma_f32_16x16x32_bf16 v[76:79], v[156:159], v[206:209], v[76:79]
	v_mfma_f32_16x16x32_bf16 v[112:115], v[160:163], v[178:181], v[112:115]
	v_mfma_f32_16x16x32_bf16 v[104:107], v[168:171], v[178:181], v[104:107]
	v_mfma_f32_16x16x32_bf16 v[96:99], v[160:163], v[186:189], v[96:99]
	v_mfma_f32_16x16x32_bf16 v[88:91], v[168:171], v[186:189], v[88:91]
	v_mfma_f32_16x16x32_bf16 v[80:83], v[160:163], v[194:197], v[80:83]
	v_mfma_f32_16x16x32_bf16 v[72:75], v[168:171], v[194:197], v[72:75]
	v_mfma_f32_16x16x32_bf16 v[68:71], v[160:163], v[202:205], v[68:71]
	v_mfma_f32_16x16x32_bf16 v[64:67], v[168:171], v[202:205], v[64:67]
	v_mfma_f32_16x16x32_bf16 v[112:115], v[164:167], v[182:185], v[112:115]
	v_mfma_f32_16x16x32_bf16 v[104:107], v[172:175], v[182:185], v[104:107]
	v_mfma_f32_16x16x32_bf16 v[96:99], v[164:167], v[190:193], v[96:99]
	v_mfma_f32_16x16x32_bf16 v[88:91], v[172:175], v[190:193], v[88:91]
	v_mfma_f32_16x16x32_bf16 v[80:83], v[164:167], v[198:201], v[80:83]
	v_mfma_f32_16x16x32_bf16 v[72:75], v[172:175], v[198:201], v[72:75]
	v_mfma_f32_16x16x32_bf16 v[68:71], v[164:167], v[206:209], v[68:71]
	v_mfma_f32_16x16x32_bf16 v[64:67], v[172:175], v[206:209], v[64:67]
	s_setprio 0
	s_barrier
; #define PG8_STAGE(bufoff, gbase, voff, p64) do { _Pragma("unroll") for (int _i = 0; _i < 2; ++_i) { \
;         const char* _gb = (const char*)(gbase) + (size_t)_i * (p64); const unsigned _la = ldsbase + (unsigned)(bufoff) + (unsigned)_i * 8192u; \
;         asm volatile("s_mov_b32 m0, %0\n\ts_nop 0\n\tglobal_load_lds_dwordx4 %1, %2" :: "s"(_la), "v"(voff), "s"(_gb) : "memory"); } } while (0)
; #define PG8_LDA(dst, b, h) do { _Pragma("unroll") for (int m = 0; m < 4; ++m) _Pragma("unroll") for (int k = 0; k < 2; ++k) dst[m][k] = *(const LAS bf16x8*)(lds + PG8_SA(b, h) + aoff + m * 2048 + k * 1024); } while (0)
; #define PG8_LDB(dst, b, h) do { _Pragma("unroll") for (int n = 0; n < 2; ++n) _Pragma("unroll") for (int k = 0; k < 2; ++k) dst[n][k] = *(const LAS bf16x8*)(lds + PG8_SB(b, h) + boff + n * 2048 + k * 1024); } while (0)
; #define PG8_MMA(ai, bj, At, Bt) do { __builtin_amdgcn_s_setprio(1); _Pragma("unroll") for (int m = 0; m < 4; ++m) _Pragma("unroll") for (int n = 0; n < 2; ++n) _Pragma("unroll") for (int k = 0; k < 2; ++k) \
;         acc[ai][bj][m][n] = __builtin_amdgcn_mfma_f32_16x16x32_bf16(Bt[n][k], At[m][k], acc[ai][bj][m][n], 0, 0, 0); __builtin_amdgcn_s_setprio(0); } while (0)
; #define PG8_WAIT_V(n) asm volatile("s_waitcnt vmcnt(" #n ")" ::: "memory")
; #define PG8_WAIT_L(n) asm volatile("s_waitcnt lgkmcnt(" #n ")" ::: "memory")
; #define PG8_BAR __builtin_amdgcn_s_barrier()
; #define PG8_SCHED __builtin_amdgcn_sched_barrier(0)
; template <class Epi, class Sched>
; __device__ __forceinline__ void gemm_phase(LAS unsigned char* lds, const Sched& S, const Epi& E) {
;     ...
;             PG8_LDA(At, 0, 1); PG8_STAGE(PG8_SB(0, 0), b2, vB2, hB2 / 2); PG8_STAGE(PG8_SB(0, 1), b2 + hB2, vB2, hB2 / 2); PG8_STAGE(PG8_SA(0, 0), a2, vA2, hA2 / 2);
;             PG8_WAIT_V(8); PG8_WAIT_L(0); PG8_BAR; PG8_MMA(1, 0, At, B0); PG8_MMA(1, 1, At, B1); PG8_BAR; PG8_SCHED;
;             PG8_LDB(B0, 1, 0); PG8_LDB(B1, 1, 1); PG8_SCHED; PG8_LDA(At, 1, 0); PG8_STAGE(PG8_SA(0, 1), a2 + hA2, vA2, hA2 / 2);
;             PG8_WAIT_V(8); PG8_WAIT_L(0); PG8_BAR; PG8_MMA(0, 0, At, B0); PG8_MMA(0, 1, At, B1); PG8_BAR; PG8_SCHED;
	s_add_u32 s66, s44, 0x40000
	ds_read_b128 v[178:181], v140 offset:16384
	ds_read_b128 v[182:185], v140 offset:17408
	ds_read_b128 v[186:189], v140 offset:18432
	ds_read_b128 v[190:193], v140 offset:19456
	ds_read_b128 v[194:197], v140 offset:20480
	ds_read_b128 v[198:201], v140 offset:21504
	ds_read_b128 v[202:205], v140 offset:22528
	ds_read_b128 v[206:209], v140 offset:23552
	s_mov_b32 m0, s33
	s_nop 0
	global_load_lds_dwordx4 v135, s[44:45]
	s_mov_b32 m0, s34
	s_addc_u32 s67, s45, 0
	global_load_lds_dwordx4 v135, s[66:67]
	s_add_u32 s66, s44, 0x80000
	s_mov_b32 m0, s35
	s_addc_u32 s67, s45, 0
	global_load_lds_dwordx4 v135, s[66:67]
	s_add_u32 s66, s44, 0xc0000
	s_mov_b32 m0, s36
	s_addc_u32 s67, s45, 0
	global_load_lds_dwordx4 v135, s[66:67]
	s_mov_b32 m0, s31
	s_nop 0
	global_load_lds_dwordx4 v134, s[40:41]
	s_add_u32 s66, s40, 0x40000
	s_mov_b32 m0, s37
	s_addc_u32 s67, s41, 0
	global_load_lds_dwordx4 v134, s[66:67]
	s_waitcnt vmcnt(8)
	s_waitcnt lgkmcnt(0)
	s_barrier
	s_setprio 1
	v_mfma_f32_16x16x32_bf16 v[60:63], v[144:147], v[178:181], v[60:63]
	v_mfma_f32_16x16x32_bf16 v[56:59], v[152:155], v[178:181], v[56:59]
	v_mfma_f32_16x16x32_bf16 v[52:55], v[144:147], v[186:189], v[52:55]
	v_mfma_f32_16x16x32_bf16 v[44:47], v[152:155], v[186:189], v[44:47]
	v_mfma_f32_16x16x32_bf16 v[36:39], v[144:147], v[194:197], v[36:39]
	v_mfma_f32_16x16x32_bf16 v[28:31], v[152:155], v[194:197], v[28:31]
	v_mfma_f32_16x16x32_bf16 v[20:23], v[144:147], v[202:205], v[20:23]
	v_mfma_f32_16x16x32_bf16 v[12:15], v[152:155], v[202:205], v[12:15]
	v_mfma_f32_16x16x32_bf16 v[60:63], v[148:151], v[182:185], v[60:63]
	v_mfma_f32_16x16x32_bf16 v[56:59], v[156:159], v[182:185], v[56:59]
	v_mfma_f32_16x16x32_bf16 v[52:55], v[148:151], v[190:193], v[52:55]
	v_mfma_f32_16x16x32_bf16 v[44:47], v[156:159], v[190:193], v[44:47]
	v_mfma_f32_16x16x32_bf16 v[36:39], v[148:151], v[198:201], v[36:39]
	v_mfma_f32_16x16x32_bf16 v[28:31], v[156:159], v[198:201], v[28:31]
	v_mfma_f32_16x16x32_bf16 v[20:23], v[148:151], v[206:209], v[20:23]
	v_mfma_f32_16x16x32_bf16 v[12:15], v[156:159], v[206:209], v[12:15]
	v_mfma_f32_16x16x32_bf16 v[48:51], v[160:163], v[178:181], v[48:51]
	v_mfma_f32_16x16x32_bf16 v[40:43], v[168:171], v[178:181], v[40:43]
	v_mfma_f32_16x16x32_bf16 v[32:35], v[160:163], v[186:189], v[32:35]
	v_mfma_f32_16x16x32_bf16 v[24:27], v[168:171], v[186:189], v[24:27]
	v_mfma_f32_16x16x32_bf16 v[16:19], v[160:163], v[194:197], v[16:19]
	v_mfma_f32_16x16x32_bf16 v[8:11], v[168:171], v[194:197], v[8:11]
	v_mfma_f32_16x16x32_bf16 v[4:7], v[160:163], v[202:205], v[4:7]
	v_mfma_f32_16x16x32_bf16 v[0:3], v[168:171], v[202:205], v[0:3]
	v_mfma_f32_16x16x32_bf16 v[48:51], v[164:167], v[182:185], v[48:51]
	v_mfma_f32_16x16x32_bf16 v[40:43], v[172:175], v[182:185], v[40:43]
	v_mfma_f32_16x16x32_bf16 v[32:35], v[164:167], v[190:193], v[32:35]
	v_mfma_f32_16x16x32_bf16 v[24:27], v[172:175], v[190:193], v[24:27]
	v_mfma_f32_16x16x32_bf16 v[16:19], v[164:167], v[198:201], v[16:19]
	v_mfma_f32_16x16x32_bf16 v[8:11], v[172:175], v[198:201], v[8:11]
	v_mfma_f32_16x16x32_bf16 v[4:7], v[164:167], v[206:209], v[4:7]
	v_mfma_f32_16x16x32_bf16 v[0:3], v[172:175], v[206:209], v[0:3]
	s_setprio 0
	s_barrier
	ds_read_b128 v[144:147], v141
	ds_read_b128 v[148:151], v141 offset:1024
	ds_read_b128 v[152:155], v141 offset:2048
	ds_read_b128 v[156:159], v141 offset:3072
	ds_read_b128 v[160:163], v142
	ds_read_b128 v[164:167], v142 offset:1024
	ds_read_b128 v[168:171], v142 offset:2048
	ds_read_b128 v[172:175], v142 offset:3072
	ds_read_b128 v[178:181], v140 offset:32768
	ds_read_b128 v[182:185], v140 offset:33792
	ds_read_b128 v[186:189], v140 offset:34816
	ds_read_b128 v[190:193], v140 offset:35840
	ds_read_b128 v[194:197], v140 offset:36864
	ds_read_b128 v[198:201], v140 offset:37888
	ds_read_b128 v[202:205], v140 offset:38912
	ds_read_b128 v[206:209], v140 offset:39936
	s_add_u32 s66, s40, 0x80000
	s_mov_b32 m0, s46
	s_addc_u32 s67, s41, 0
	global_load_lds_dwordx4 v134, s[66:67]
	s_add_u32 s66, s40, 0xc0000
	s_mov_b32 m0, s47
	s_addc_u32 s67, s41, 0
	global_load_lds_dwordx4 v134, s[66:67]
	s_waitcnt vmcnt(8)
	s_waitcnt lgkmcnt(0)
	s_barrier
; #define PG8_STAGE(bufoff, gbase, voff, p64) do { _Pragma("unroll") for (int _i = 0; _i < 2; ++_i) { \
;         const char* _gb = (const char*)(gbase) + (size_t)_i * (p64); const unsigned _la = ldsbase + (unsigned)(bufoff) + (unsigned)_i * 8192u; \
;         asm volatile("s_mov_b32 m0, %0\n\ts_nop 0\n\tglobal_load_lds_dwordx4 %1, %2" :: "s"(_la), "v"(voff), "s"(_gb) : "memory"); } } while (0)
; #define PG8_LDA(dst, b, h) do { _Pragma("unroll") for (int m = 0; m < 4; ++m) _Pragma("unroll") for (int k = 0; k < 2; ++k) dst[m][k] = *(const LAS bf16x8*)(lds + PG8_SA(b, h) + aoff + m * 2048 + k * 1024); } while (0)
; #define PG8_MMA(ai, bj, At, Bt) do { __builtin_amdgcn_s_setprio(1); _Pragma("unroll") for (int m = 0; m < 4; ++m) _Pragma("unroll") for (int n = 0; n < 2; ++n) _Pragma("unroll") for (int k = 0; k < 2; ++k) \
;         acc[ai][bj][m][n] = __builtin_amdgcn_mfma_f32_16x16x32_bf16(Bt[n][k], At[m][k], acc[ai][bj][m][n], 0, 0, 0); __builtin_amdgcn_s_setprio(0); } while (0)
; #define PG8_WAIT_V(n) asm volatile("s_waitcnt vmcnt(" #n ")" ::: "memory")
; #define PG8_WAIT_L(n) asm volatile("s_waitcnt lgkmcnt(" #n ")" ::: "memory")
; #define PG8_BAR __builtin_amdgcn_s_barrier()
; #define PG8_SCHED __builtin_amdgcn_sched_barrier(0)
; template <class Epi, class Sched>
; __device__ __forceinline__ void gemm_phase(LAS unsigned char* lds, const Sched& S, const Epi& E) {
;     ...
;             PG8_WAIT_V(8); PG8_WAIT_L(0); PG8_BAR; PG8_MMA(0, 0, At, B0); PG8_MMA(0, 1, At, B1); PG8_BAR; PG8_SCHED;
;             PG8_LDA(At, 1, 1); PG8_STAGE(PG8_SB(1, 0), b3, vB2, hB2 / 2); PG8_STAGE(PG8_SB(1, 1), b3 + hB2, vB2, hB2 / 2); PG8_STAGE(PG8_SA(1, 0), a3, vA2, hA2 / 2);
;             PG8_WAIT_V(8); PG8_WAIT_L(0); PG8_BAR; PG8_MMA(1, 0, At, B0); PG8_MMA(1, 1, At, B1); PG8_BAR; PG8_SCHED;
;         }
;         if (wr == 0) PG8_BAR;
	s_setprio 1
	v_mfma_f32_16x16x32_bf16 v[124:127], v[144:147], v[178:181], v[124:127]
	v_mfma_f32_16x16x32_bf16 v[120:123], v[152:155], v[178:181], v[120:123]
	v_mfma_f32_16x16x32_bf16 v[116:119], v[144:147], v[186:189], v[116:119]
	v_mfma_f32_16x16x32_bf16 v[108:111], v[152:155], v[186:189], v[108:111]
	v_mfma_f32_16x16x32_bf16 v[100:103], v[144:147], v[194:197], v[100:103]
	v_mfma_f32_16x16x32_bf16 v[92:95], v[152:155], v[194:197], v[92:95]
	v_mfma_f32_16x16x32_bf16 v[84:87], v[144:147], v[202:205], v[84:87]
	v_mfma_f32_16x16x32_bf16 v[76:79], v[152:155], v[202:205], v[76:79]
	v_mfma_f32_16x16x32_bf16 v[124:127], v[148:151], v[182:185], v[124:127]
	v_mfma_f32_16x16x32_bf16 v[120:123], v[156:159], v[182:185], v[120:123]
	v_mfma_f32_16x16x32_bf16 v[116:119], v[148:151], v[190:193], v[116:119]
	v_mfma_f32_16x16x32_bf16 v[108:111], v[156:159], v[190:193], v[108:111]
	v_mfma_f32_16x16x32_bf16 v[100:103], v[148:151], v[198:201], v[100:103]
	v_mfma_f32_16x16x32_bf16 v[92:95], v[156:159], v[198:201], v[92:95]
	v_mfma_f32_16x16x32_bf16 v[84:87], v[148:151], v[206:209], v[84:87]
	v_mfma_f32_16x16x32_bf16 v[76:79], v[156:159], v[206:209], v[76:79]
	v_mfma_f32_16x16x32_bf16 v[112:115], v[160:163], v[178:181], v[112:115]
	v_mfma_f32_16x16x32_bf16 v[104:107], v[168:171], v[178:181], v[104:107]
	v_mfma_f32_16x16x32_bf16 v[96:99], v[160:163], v[186:189], v[96:99]
	v_mfma_f32_16x16x32_bf16 v[88:91], v[168:171], v[186:189], v[88:91]
	v_mfma_f32_16x16x32_bf16 v[80:83], v[160:163], v[194:197], v[80:83]
	v_mfma_f32_16x16x32_bf16 v[72:75], v[168:171], v[194:197], v[72:75]
	v_mfma_f32_16x16x32_bf16 v[68:71], v[160:163], v[202:205], v[68:71]
	v_mfma_f32_16x16x32_bf16 v[64:67], v[168:171], v[202:205], v[64:67]
	v_mfma_f32_16x16x32_bf16 v[112:115], v[164:167], v[182:185], v[112:115]
	v_mfma_f32_16x16x32_bf16 v[104:107], v[172:175], v[182:185], v[104:107]
	v_mfma_f32_16x16x32_bf16 v[96:99], v[164:167], v[190:193], v[96:99]
	v_mfma_f32_16x16x32_bf16 v[88:91], v[172:175], v[190:193], v[88:91]
	v_mfma_f32_16x16x32_bf16 v[80:83], v[164:167], v[198:201], v[80:83]
	v_mfma_f32_16x16x32_bf16 v[72:75], v[172:175], v[198:201], v[72:75]
	v_mfma_f32_16x16x32_bf16 v[68:71], v[164:167], v[206:209], v[68:71]
	v_mfma_f32_16x16x32_bf16 v[64:67], v[172:175], v[206:209], v[64:67]
	s_setprio 0
	s_barrier
	s_add_u32 s66, s44, 0x80
	s_addc_u32 s67, s45, 0
	ds_read_b128 v[178:181], v140 offset:49152
	ds_read_b128 v[182:185], v140 offset:50176
	ds_read_b128 v[186:189], v140 offset:51200
	ds_read_b128 v[190:193], v140 offset:52224
	ds_read_b128 v[194:197], v140 offset:53248
	ds_read_b128 v[198:201], v140 offset:54272
	ds_read_b128 v[202:205], v140 offset:55296
	ds_read_b128 v[206:209], v140 offset:56320
	s_mov_b32 m0, s50
	s_nop 0
	global_load_lds_dwordx4 v135, s[66:67]
	s_add_u32 s66, s44, 0x40080
	s_mov_b32 m0, s51
	s_addc_u32 s67, s45, 0
	global_load_lds_dwordx4 v135, s[66:67]
	s_add_u32 s66, s44, 0x80080
	s_mov_b32 m0, s54
	s_addc_u32 s67, s45, 0
	global_load_lds_dwordx4 v135, s[66:67]
	s_add_u32 s44, s44, 0xc0080
	s_mov_b32 m0, s55
	s_addc_u32 s45, s45, 0
	global_load_lds_dwordx4 v135, s[44:45]
	s_mov_b32 m0, s52
	s_nop 0
	global_load_lds_dwordx4 v134, s[42:43]
	s_add_u32 s40, s40, 0x40080
	s_mov_b32 m0, s53
	s_addc_u32 s41, s41, 0
	global_load_lds_dwordx4 v134, s[40:41]
	s_waitcnt vmcnt(8)
	s_waitcnt lgkmcnt(0)
	s_barrier
	s_setprio 1
	v_mfma_f32_16x16x32_bf16 v[60:63], v[144:147], v[178:181], v[60:63]
	v_mfma_f32_16x16x32_bf16 v[56:59], v[152:155], v[178:181], v[56:59]
	v_mfma_f32_16x16x32_bf16 v[52:55], v[144:147], v[186:189], v[52:55]
	v_mfma_f32_16x16x32_bf16 v[44:47], v[152:155], v[186:189], v[44:47]
	v_mfma_f32_16x16x32_bf16 v[36:39], v[144:147], v[194:197], v[36:39]
	v_mfma_f32_16x16x32_bf16 v[28:31], v[152:155], v[194:197], v[28:31]
	v_mfma_f32_16x16x32_bf16 v[20:23], v[144:147], v[202:205], v[20:23]
	v_mfma_f32_16x16x32_bf16 v[12:15], v[152:155], v[202:205], v[12:15]
	v_mfma_f32_16x16x32_bf16 v[60:63], v[148:151], v[182:185], v[60:63]
	v_mfma_f32_16x16x32_bf16 v[56:59], v[156:159], v[182:185], v[56:59]
	v_mfma_f32_16x16x32_bf16 v[52:55], v[148:151], v[190:193], v[52:55]
	v_mfma_f32_16x16x32_bf16 v[44:47], v[156:159], v[190:193], v[44:47]
	v_mfma_f32_16x16x32_bf16 v[36:39], v[148:151], v[198:201], v[36:39]
	v_mfma_f32_16x16x32_bf16 v[28:31], v[156:159], v[198:201], v[28:31]
	v_mfma_f32_16x16x32_bf16 v[20:23], v[148:151], v[206:209], v[20:23]
	v_mfma_f32_16x16x32_bf16 v[12:15], v[156:159], v[206:209], v[12:15]
	v_mfma_f32_16x16x32_bf16 v[48:51], v[160:163], v[178:181], v[48:51]
	v_mfma_f32_16x16x32_bf16 v[40:43], v[168:171], v[178:181], v[40:43]
	v_mfma_f32_16x16x32_bf16 v[32:35], v[160:163], v[186:189], v[32:35]
	v_mfma_f32_16x16x32_bf16 v[24:27], v[168:171], v[186:189], v[24:27]
	v_mfma_f32_16x16x32_bf16 v[16:19], v[160:163], v[194:197], v[16:19]
	v_mfma_f32_16x16x32_bf16 v[8:11], v[168:171], v[194:197], v[8:11]
	v_mfma_f32_16x16x32_bf16 v[4:7], v[160:163], v[202:205], v[4:7]
	v_mfma_f32_16x16x32_bf16 v[0:3], v[168:171], v[202:205], v[0:3]
	v_mfma_f32_16x16x32_bf16 v[48:51], v[164:167], v[182:185], v[48:51]
	v_mfma_f32_16x16x32_bf16 v[40:43], v[172:175], v[182:185], v[40:43]
	v_mfma_f32_16x16x32_bf16 v[32:35], v[164:167], v[190:193], v[32:35]
	v_mfma_f32_16x16x32_bf16 v[24:27], v[172:175], v[190:193], v[24:27]
	v_mfma_f32_16x16x32_bf16 v[16:19], v[164:167], v[198:201], v[16:19]
	v_mfma_f32_16x16x32_bf16 v[8:11], v[172:175], v[198:201], v[8:11]
	v_mfma_f32_16x16x32_bf16 v[4:7], v[164:167], v[206:209], v[4:7]
	v_mfma_f32_16x16x32_bf16 v[0:3], v[172:175], v[206:209], v[0:3]
	s_setprio 0
	s_barrier
	s_add_i32 s62, s62, 2
	s_add_u32 s38, s38, 0x100
	s_addc_u32 s39, s39, 0
	s_add_u32 s60, s60, 0x100
	s_addc_u32 s61, s61, 0
	s_cmp_gt_u32 s62, 29
	s_cbranch_scc0 .LBB0_1089
	s_and_b64 vcc, exec, s[18:19]
	s_cbranch_vccz .LBB0_1092
	s_barrier

; #define PG8_STAGE(bufoff, gbase, voff, p64) do { _Pragma("unroll") for (int _i = 0; _i < 2; ++_i) { \
;         const char* _gb = (const char*)(gbase) + (size_t)_i * (p64); const unsigned _la = ldsbase + (unsigned)(bufoff) + (unsigned)_i * 8192u; \
;         asm volatile("s_mov_b32 m0, %0\n\ts_nop 0\n\tglobal_load_lds_dwordx4 %1, %2" :: "s"(_la), "v"(voff), "s"(_gb) : "memory"); } } while (0)
; #define PG8_LDA(dst, b, h) do { _Pragma("unroll") for (int m = 0; m < 4; ++m) _Pragma("unroll") for (int k = 0; k < 2; ++k) dst[m][k] = *(const LAS bf16x8*)(lds + PG8_SA(b, h) + aoff + m * 2048 + k * 1024); } while (0)
; #define PG8_LDB(dst, b, h) do { _Pragma("unroll") for (int n = 0; n < 2; ++n) _Pragma("unroll") for (int k = 0; k < 2; ++k) dst[n][k] = *(const LAS bf16x8*)(lds + PG8_SB(b, h) + boff + n * 2048 + k * 1024); } while (0)
; #define PG8_WAIT_V(n) asm volatile("s_waitcnt vmcnt(" #n ")" ::: "memory")
; #define PG8_WAIT_L(n) asm volatile("s_waitcnt lgkmcnt(" #n ")" ::: "memory")
; #define PG8_BAR __builtin_amdgcn_s_barrier()
; #define PG8_SCHED __builtin_amdgcn_sched_barrier(0)
; template <class Epi, class Sched>
; __device__ __forceinline__ void gemm_phase(LAS unsigned char* lds, const Sched& S, const Epi& E) {
;     ...
;         for (int t = 0; t < nt; t += 2) {
;             const bool last = (t == nt - 2);
;             const char* a1 = cA + (size_t)(t + 1) * kstep;
;             const char* a2 = last ? nA : cA + (size_t)(t + 2) * kstep; const char* b2 = last ? nB : cB + (size_t)(t + 2) * kstep;
;             const char* a3 = a2 + kstep; const char* b3 = b2 + kstep;
;             const unsigned vA2 = voffA, vB2 = voffB, hA2 = hA, hB2 = hB;
;             PG8_LDB(B0, 0, 0); PG8_LDB(B1, 0, 1); PG8_SCHED; PG8_LDA(At, 0, 0); PG8_STAGE(PG8_SA(1, 1), a1 + hA, voffA, hA / 2);
;             PG8_WAIT_V(8); PG8_WAIT_L(0); PG8_BAR; PG8_MMA(0, 0, At, B0); PG8_MMA(0, 1, At, B1); PG8_BAR; PG8_SCHED;
;     ...
;         if (!keep) {
; #pragma unroll
;             for (int a = 0; a < 2; ++a)
; #pragma unroll
;                 for (int b = 0; b < 2; ++b)
; #pragma unroll
;                     for (int m = 0; m < 4; ++m)
; #pragma unroll
;                         for (int n = 0; n < 2; ++n) acc[a][b][m][n] = (f32x4){0.f, 0.f, 0.f, 0.f};
;         }
;         cA = nA; cB = nB; nt = nnt; ++ui;
;         if (wr == 1) PG8_BAR;
.LBB0_1191:
	s_add_u32 s24, s24, 0x40080
	s_addc_u32 s25, s25, 0
	s_add_u32 s58, s26, 0x100
	s_addc_u32 s59, s27, 0
	s_mov_b32 s60, -2
	v_mov_b64_e32 v[0:1], 0
	v_mov_b64_e32 v[2:3], 0
	v_mov_b64_e32 v[4:5], 0
	v_mov_b64_e32 v[6:7], 0
	v_mov_b64_e32 v[8:9], 0
	v_mov_b64_e32 v[10:11], 0
	v_mov_b64_e32 v[16:17], 0
	v_mov_b64_e32 v[18:19], 0
	v_mov_b64_e32 v[24:25], 0
	v_mov_b64_e32 v[26:27], 0
	v_mov_b64_e32 v[32:33], 0
	v_mov_b64_e32 v[34:35], 0
	v_mov_b64_e32 v[40:41], 0
	v_mov_b64_e32 v[42:43], 0
	v_mov_b64_e32 v[48:49], 0
	v_mov_b64_e32 v[50:51], 0
	v_mov_b64_e32 v[12:13], 0
	v_mov_b64_e32 v[14:15], 0
	v_mov_b64_e32 v[20:21], 0
	v_mov_b64_e32 v[22:23], 0
	v_mov_b64_e32 v[28:29], 0
	v_mov_b64_e32 v[30:31], 0
	v_mov_b64_e32 v[36:37], 0
	v_mov_b64_e32 v[38:39], 0
	v_mov_b64_e32 v[44:45], 0
	v_mov_b64_e32 v[46:47], 0
	v_mov_b64_e32 v[52:53], 0
	v_mov_b64_e32 v[54:55], 0
	v_mov_b64_e32 v[56:57], 0
	v_mov_b64_e32 v[58:59], 0
	v_mov_b64_e32 v[60:61], 0
	v_mov_b64_e32 v[62:63], 0
	v_mov_b64_e32 v[64:65], 0
	v_mov_b64_e32 v[66:67], 0
	v_mov_b64_e32 v[68:69], 0
	v_mov_b64_e32 v[70:71], 0
	v_mov_b64_e32 v[72:73], 0
	v_mov_b64_e32 v[74:75], 0
	v_mov_b64_e32 v[80:81], 0
	v_mov_b64_e32 v[82:83], 0
	v_mov_b64_e32 v[88:89], 0
	v_mov_b64_e32 v[90:91], 0
	v_mov_b64_e32 v[96:97], 0
	v_mov_b64_e32 v[98:99], 0
	v_mov_b64_e32 v[104:105], 0
	v_mov_b64_e32 v[106:107], 0
	v_mov_b64_e32 v[112:113], 0
	v_mov_b64_e32 v[114:115], 0
	v_mov_b64_e32 v[76:77], 0
	v_mov_b64_e32 v[78:79], 0
	v_mov_b64_e32 v[84:85], 0
	v_mov_b64_e32 v[86:87], 0
	v_mov_b64_e32 v[92:93], 0
	v_mov_b64_e32 v[94:95], 0
	v_mov_b64_e32 v[100:101], 0
	v_mov_b64_e32 v[102:103], 0
	v_mov_b64_e32 v[108:109], 0
	v_mov_b64_e32 v[110:111], 0
	v_mov_b64_e32 v[116:117], 0
	v_mov_b64_e32 v[118:119], 0
	v_mov_b64_e32 v[120:121], 0
	v_mov_b64_e32 v[122:123], 0
	v_mov_b64_e32 v[124:125], 0
	v_mov_b64_e32 v[126:127], 0
.LBB0_1192:
	ds_read_b128 v[144:147], v138
	ds_read_b128 v[148:151], v138 offset:1024
	ds_read_b128 v[152:155], v138 offset:2048
	ds_read_b128 v[156:159], v138 offset:3072
	ds_read_b128 v[160:163], v139
	ds_read_b128 v[164:167], v139 offset:1024
	ds_read_b128 v[168:171], v139 offset:2048
	ds_read_b128 v[172:175], v139 offset:3072
	s_add_u32 s26, s24, 0xfffc0080
	s_addc_u32 s27, s25, -1
	s_cmp_eq_u32 s60, 12
	s_cselect_b32 s26, s20, s26
	s_cselect_b32 s27, s21, s27
	s_cselect_b32 s40, s22, s58
	s_cselect_b32 s41, s23, s59
	s_add_u32 s38, s26, 0x80
	s_addc_u32 s39, s27, 0
	ds_read_b128 v[178:181], v140
	ds_read_b128 v[182:185], v140 offset:1024
	ds_read_b128 v[186:189], v140 offset:2048
	ds_read_b128 v[190:193], v140 offset:3072
	ds_read_b128 v[194:197], v140 offset:4096
	ds_read_b128 v[198:201], v140 offset:5120
	ds_read_b128 v[202:205], v140 offset:6144
	ds_read_b128 v[206:209], v140 offset:7168
	s_mov_b32 m0, s54
	s_nop 0
	global_load_lds_dwordx4 v134, s[24:25]
	s_add_u32 s62, s24, 0x20000
	s_mov_b32 m0, s55
	s_addc_u32 s63, s25, 0
	global_load_lds_dwordx4 v134, s[62:63]
	s_waitcnt vmcnt(8)
	s_waitcnt lgkmcnt(0)
	s_barrier
	s_setprio 1
	v_mfma_f32_16x16x32_bf16 v[124:127], v[144:147], v[178:181], v[124:127]
	v_mfma_f32_16x16x32_bf16 v[120:123], v[152:155], v[178:181], v[120:123]
	v_mfma_f32_16x16x32_bf16 v[116:119], v[144:147], v[186:189], v[116:119]
	v_mfma_f32_16x16x32_bf16 v[108:111], v[152:155], v[186:189], v[108:111]
	v_mfma_f32_16x16x32_bf16 v[100:103], v[144:147], v[194:197], v[100:103]
	v_mfma_f32_16x16x32_bf16 v[92:95], v[152:155], v[194:197], v[92:95]
	v_mfma_f32_16x16x32_bf16 v[84:87], v[144:147], v[202:205], v[84:87]
	v_mfma_f32_16x16x32_bf16 v[76:79], v[152:155], v[202:205], v[76:79]
	v_mfma_f32_16x16x32_bf16 v[124:127], v[148:151], v[182:185], v[124:127]
	v_mfma_f32_16x16x32_bf16 v[120:123], v[156:159], v[182:185], v[120:123]
	v_mfma_f32_16x16x32_bf16 v[116:119], v[148:151], v[190:193], v[116:119]
	v_mfma_f32_16x16x32_bf16 v[108:111], v[156:159], v[190:193], v[108:111]
	v_mfma_f32_16x16x32_bf16 v[100:103], v[148:151], v[198:201], v[100:103]
	v_mfma_f32_16x16x32_bf16 v[92:95], v[156:159], v[198:201], v[92:95]
	v_mfma_f32_16x16x32_bf16 v[84:87], v[148:151], v[206:209], v[84:87]
	v_mfma_f32_16x16x32_bf16 v[76:79], v[156:159], v[206:209], v[76:79]
	v_mfma_f32_16x16x32_bf16 v[112:115], v[160:163], v[178:181], v[112:115]
	v_mfma_f32_16x16x32_bf16 v[104:107], v[168:171], v[178:181], v[104:107]
	v_mfma_f32_16x16x32_bf16 v[96:99], v[160:163], v[186:189], v[96:99]
	v_mfma_f32_16x16x32_bf16 v[88:91], v[168:171], v[186:189], v[88:91]
	v_mfma_f32_16x16x32_bf16 v[80:83], v[160:163], v[194:197], v[80:83]
	v_mfma_f32_16x16x32_bf16 v[72:75], v[168:171], v[194:197], v[72:75]
	v_mfma_f32_16x16x32_bf16 v[68:71], v[160:163], v[202:205], v[68:71]
	v_mfma_f32_16x16x32_bf16 v[64:67], v[168:171], v[202:205], v[64:67]
	v_mfma_f32_16x16x32_bf16 v[112:115], v[164:167], v[182:185], v[112:115]
	v_mfma_f32_16x16x32_bf16 v[104:107], v[172:175], v[182:185], v[104:107]
	v_mfma_f32_16x16x32_bf16 v[96:99], v[164:167], v[190:193], v[96:99]
	v_mfma_f32_16x16x32_bf16 v[88:91], v[172:175], v[190:193], v[88:91]
	v_mfma_f32_16x16x32_bf16 v[80:83], v[164:167], v[198:201], v[80:83]
	v_mfma_f32_16x16x32_bf16 v[72:75], v[172:175], v[198:201], v[72:75]
	v_mfma_f32_16x16x32_bf16 v[68:71], v[164:167], v[206:209], v[68:71]
	v_mfma_f32_16x16x32_bf16 v[64:67], v[172:175], v[206:209], v[64:67]
	s_setprio 0
	s_barrier
; #define PG8_STAGE(bufoff, gbase, voff, p64) do { _Pragma("unroll") for (int _i = 0; _i < 2; ++_i) { \
;         const char* _gb = (const char*)(gbase) + (size_t)_i * (p64); const unsigned _la = ldsbase + (unsigned)(bufoff) + (unsigned)_i * 8192u; \
;         asm volatile("s_mov_b32 m0, %0\n\ts_nop 0\n\tglobal_load_lds_dwordx4 %1, %2" :: "s"(_la), "v"(voff), "s"(_gb) : "memory"); } } while (0)
; #define PG8_LDA(dst, b, h) do { _Pragma("unroll") for (int m = 0; m < 4; ++m) _Pragma("unroll") for (int k = 0; k < 2; ++k) dst[m][k] = *(const LAS bf16x8*)(lds + PG8_SA(b, h) + aoff + m * 2048 + k * 1024); } while (0)
; #define PG8_LDB(dst, b, h) do { _Pragma("unroll") for (int n = 0; n < 2; ++n) _Pragma("unroll") for (int k = 0; k < 2; ++k) dst[n][k] = *(const LAS bf16x8*)(lds + PG8_SB(b, h) + boff + n * 2048 + k * 1024); } while (0)
; #define PG8_MMA(ai, bj, At, Bt) do { __builtin_amdgcn_s_setprio(1); _Pragma("unroll") for (int m = 0; m < 4; ++m) _Pragma("unroll") for (int n = 0; n < 2; ++n) _Pragma("unroll") for (int k = 0; k < 2; ++k) \
;         acc[ai][bj][m][n] = __builtin_amdgcn_mfma_f32_16x16x32_bf16(Bt[n][k], At[m][k], acc[ai][bj][m][n], 0, 0, 0); __builtin_amdgcn_s_setprio(0); } while (0)
; #define PG8_WAIT_V(n) asm volatile("s_waitcnt vmcnt(" #n ")" ::: "memory")
; #define PG8_WAIT_L(n) asm volatile("s_waitcnt lgkmcnt(" #n ")" ::: "memory")
; #define PG8_BAR __builtin_amdgcn_s_barrier()
; #define PG8_SCHED __builtin_amdgcn_sched_barrier(0)
; template <class Epi, class Sched>
; __device__ __forceinline__ void gemm_phase(LAS unsigned char* lds, const Sched& S, const Epi& E) {
;     ...
;             PG8_LDA(At, 0, 1); PG8_STAGE(PG8_SB(0, 0), b2, vB2, hB2 / 2); PG8_STAGE(PG8_SB(0, 1), b2 + hB2, vB2, hB2 / 2); PG8_STAGE(PG8_SA(0, 0), a2, vA2, hA2 / 2);
;             PG8_WAIT_V(8); PG8_WAIT_L(0); PG8_BAR; PG8_MMA(1, 0, At, B0); PG8_MMA(1, 1, At, B1); PG8_BAR; PG8_SCHED;
;             PG8_LDB(B0, 1, 0); PG8_LDB(B1, 1, 1); PG8_SCHED; PG8_LDA(At, 1, 0); PG8_STAGE(PG8_SA(0, 1), a2 + hA2, vA2, hA2 / 2);
;             PG8_WAIT_V(8); PG8_WAIT_L(0); PG8_BAR; PG8_MMA(0, 0, At, B0); PG8_MMA(0, 1, At, B1); PG8_BAR; PG8_SCHED;
	s_add_u32 s62, s40, 0x20000
	ds_read_b128 v[178:181], v140 offset:16384
	ds_read_b128 v[182:185], v140 offset:17408
	ds_read_b128 v[186:189], v140 offset:18432
	ds_read_b128 v[190:193], v140 offset:19456
	ds_read_b128 v[194:197], v140 offset:20480
	ds_read_b128 v[198:201], v140 offset:21504
	ds_read_b128 v[202:205], v140 offset:22528
	ds_read_b128 v[206:209], v140 offset:23552
	s_mov_b32 m0, s35
	s_nop 0
	global_load_lds_dwordx4 v135, s[40:41]
	s_mov_b32 m0, s36
	s_addc_u32 s63, s41, 0
	global_load_lds_dwordx4 v135, s[62:63]
	s_add_u32 s62, s40, 0x40000
	s_mov_b32 m0, s37
	s_addc_u32 s63, s41, 0
	global_load_lds_dwordx4 v135, s[62:63]
	s_add_u32 s62, s40, 0x60000
	s_mov_b32 m0, s42
	s_addc_u32 s63, s41, 0
	global_load_lds_dwordx4 v135, s[62:63]
	s_mov_b32 m0, s34
	s_nop 0
	global_load_lds_dwordx4 v134, s[26:27]
	s_add_u32 s62, s26, 0x20000
	s_mov_b32 m0, s43
	s_addc_u32 s63, s27, 0
	global_load_lds_dwordx4 v134, s[62:63]
	s_waitcnt vmcnt(8)
	s_waitcnt lgkmcnt(0)
	s_barrier
	s_setprio 1
	v_mfma_f32_16x16x32_bf16 v[60:63], v[144:147], v[178:181], v[60:63]
	v_mfma_f32_16x16x32_bf16 v[56:59], v[152:155], v[178:181], v[56:59]
	v_mfma_f32_16x16x32_bf16 v[52:55], v[144:147], v[186:189], v[52:55]
	v_mfma_f32_16x16x32_bf16 v[44:47], v[152:155], v[186:189], v[44:47]
	v_mfma_f32_16x16x32_bf16 v[36:39], v[144:147], v[194:197], v[36:39]
	v_mfma_f32_16x16x32_bf16 v[28:31], v[152:155], v[194:197], v[28:31]
	v_mfma_f32_16x16x32_bf16 v[20:23], v[144:147], v[202:205], v[20:23]
	v_mfma_f32_16x16x32_bf16 v[12:15], v[152:155], v[202:205], v[12:15]
	v_mfma_f32_16x16x32_bf16 v[60:63], v[148:151], v[182:185], v[60:63]
	v_mfma_f32_16x16x32_bf16 v[56:59], v[156:159], v[182:185], v[56:59]
	v_mfma_f32_16x16x32_bf16 v[52:55], v[148:151], v[190:193], v[52:55]
	v_mfma_f32_16x16x32_bf16 v[44:47], v[156:159], v[190:193], v[44:47]
	v_mfma_f32_16x16x32_bf16 v[36:39], v[148:151], v[198:201], v[36:39]
	v_mfma_f32_16x16x32_bf16 v[28:31], v[156:159], v[198:201], v[28:31]
	v_mfma_f32_16x16x32_bf16 v[20:23], v[148:151], v[206:209], v[20:23]
	v_mfma_f32_16x16x32_bf16 v[12:15], v[156:159], v[206:209], v[12:15]
	v_mfma_f32_16x16x32_bf16 v[48:51], v[160:163], v[178:181], v[48:51]
	v_mfma_f32_16x16x32_bf16 v[40:43], v[168:171], v[178:181], v[40:43]
	v_mfma_f32_16x16x32_bf16 v[32:35], v[160:163], v[186:189], v[32:35]
	v_mfma_f32_16x16x32_bf16 v[24:27], v[168:171], v[186:189], v[24:27]
	v_mfma_f32_16x16x32_bf16 v[16:19], v[160:163], v[194:197], v[16:19]
	v_mfma_f32_16x16x32_bf16 v[8:11], v[168:171], v[194:197], v[8:11]
	v_mfma_f32_16x16x32_bf16 v[4:7], v[160:163], v[202:205], v[4:7]
	v_mfma_f32_16x16x32_bf16 v[0:3], v[168:171], v[202:205], v[0:3]
	v_mfma_f32_16x16x32_bf16 v[48:51], v[164:167], v[182:185], v[48:51]
	v_mfma_f32_16x16x32_bf16 v[40:43], v[172:175], v[182:185], v[40:43]
	v_mfma_f32_16x16x32_bf16 v[32:35], v[164:167], v[190:193], v[32:35]
	v_mfma_f32_16x16x32_bf16 v[24:27], v[172:175], v[190:193], v[24:27]
	v_mfma_f32_16x16x32_bf16 v[16:19], v[164:167], v[198:201], v[16:19]
	v_mfma_f32_16x16x32_bf16 v[8:11], v[172:175], v[198:201], v[8:11]
	v_mfma_f32_16x16x32_bf16 v[4:7], v[164:167], v[206:209], v[4:7]
	v_mfma_f32_16x16x32_bf16 v[0:3], v[172:175], v[206:209], v[0:3]
	s_setprio 0
	s_barrier
	ds_read_b128 v[144:147], v141
	ds_read_b128 v[148:151], v141 offset:1024
	ds_read_b128 v[152:155], v141 offset:2048
	ds_read_b128 v[156:159], v141 offset:3072
	ds_read_b128 v[160:163], v142
	ds_read_b128 v[164:167], v142 offset:1024
	ds_read_b128 v[168:171], v142 offset:2048
	ds_read_b128 v[172:175], v142 offset:3072
	ds_read_b128 v[178:181], v140 offset:32768
	ds_read_b128 v[182:185], v140 offset:33792
	ds_read_b128 v[186:189], v140 offset:34816
	ds_read_b128 v[190:193], v140 offset:35840
	ds_read_b128 v[194:197], v140 offset:36864
	ds_read_b128 v[198:201], v140 offset:37888
	ds_read_b128 v[202:205], v140 offset:38912
	ds_read_b128 v[206:209], v140 offset:39936
	s_add_u32 s62, s26, 0x40000
	s_mov_b32 m0, s44
	s_addc_u32 s63, s27, 0
	global_load_lds_dwordx4 v134, s[62:63]
	s_add_u32 s62, s26, 0x60000
	s_mov_b32 m0, s45
	s_addc_u32 s63, s27, 0
	global_load_lds_dwordx4 v134, s[62:63]
	s_waitcnt vmcnt(8)
	s_waitcnt lgkmcnt(0)
	s_barrier
; #define PG8_STAGE(bufoff, gbase, voff, p64) do { _Pragma("unroll") for (int _i = 0; _i < 2; ++_i) { \
;         const char* _gb = (const char*)(gbase) + (size_t)_i * (p64); const unsigned _la = ldsbase + (unsigned)(bufoff) + (unsigned)_i * 8192u; \
;         asm volatile("s_mov_b32 m0, %0\n\ts_nop 0\n\tglobal_load_lds_dwordx4 %1, %2" :: "s"(_la), "v"(voff), "s"(_gb) : "memory"); } } while (0)
; #define PG8_LDA(dst, b, h) do { _Pragma("unroll") for (int m = 0; m < 4; ++m) _Pragma("unroll") for (int k = 0; k < 2; ++k) dst[m][k] = *(const LAS bf16x8*)(lds + PG8_SA(b, h) + aoff + m * 2048 + k * 1024); } while (0)
; #define PG8_MMA(ai, bj, At, Bt) do { __builtin_amdgcn_s_setprio(1); _Pragma("unroll") for (int m = 0; m < 4; ++m) _Pragma("unroll") for (int n = 0; n < 2; ++n) _Pragma("unroll") for (int k = 0; k < 2; ++k) \
;         acc[ai][bj][m][n] = __builtin_amdgcn_mfma_f32_16x16x32_bf16(Bt[n][k], At[m][k], acc[ai][bj][m][n], 0, 0, 0); __builtin_amdgcn_s_setprio(0); } while (0)
; #define PG8_WAIT_V(n) asm volatile("s_waitcnt vmcnt(" #n ")" ::: "memory")
; #define PG8_WAIT_L(n) asm volatile("s_waitcnt lgkmcnt(" #n ")" ::: "memory")
; #define PG8_BAR __builtin_amdgcn_s_barrier()
; #define PG8_SCHED __builtin_amdgcn_sched_barrier(0)
; template <class Epi, class Sched>
; __device__ __forceinline__ void gemm_phase(LAS unsigned char* lds, const Sched& S, const Epi& E) {
;     ...
;             PG8_WAIT_V(8); PG8_WAIT_L(0); PG8_BAR; PG8_MMA(0, 0, At, B0); PG8_MMA(0, 1, At, B1); PG8_BAR; PG8_SCHED;
;             PG8_LDA(At, 1, 1); PG8_STAGE(PG8_SB(1, 0), b3, vB2, hB2 / 2); PG8_STAGE(PG8_SB(1, 1), b3 + hB2, vB2, hB2 / 2); PG8_STAGE(PG8_SA(1, 0), a3, vA2, hA2 / 2);
;             PG8_WAIT_V(8); PG8_WAIT_L(0); PG8_BAR; PG8_MMA(1, 0, At, B0); PG8_MMA(1, 1, At, B1); PG8_BAR; PG8_SCHED;
;         }
;         if (wr == 0) PG8_BAR;
	s_setprio 1
	v_mfma_f32_16x16x32_bf16 v[124:127], v[144:147], v[178:181], v[124:127]
	v_mfma_f32_16x16x32_bf16 v[120:123], v[152:155], v[178:181], v[120:123]
	v_mfma_f32_16x16x32_bf16 v[116:119], v[144:147], v[186:189], v[116:119]
	v_mfma_f32_16x16x32_bf16 v[108:111], v[152:155], v[186:189], v[108:111]
	v_mfma_f32_16x16x32_bf16 v[100:103], v[144:147], v[194:197], v[100:103]
	v_mfma_f32_16x16x32_bf16 v[92:95], v[152:155], v[194:197], v[92:95]
	v_mfma_f32_16x16x32_bf16 v[84:87], v[144:147], v[202:205], v[84:87]
	v_mfma_f32_16x16x32_bf16 v[76:79], v[152:155], v[202:205], v[76:79]
	v_mfma_f32_16x16x32_bf16 v[124:127], v[148:151], v[182:185], v[124:127]
	v_mfma_f32_16x16x32_bf16 v[120:123], v[156:159], v[182:185], v[120:123]
	v_mfma_f32_16x16x32_bf16 v[116:119], v[148:151], v[190:193], v[116:119]
	v_mfma_f32_16x16x32_bf16 v[108:111], v[156:159], v[190:193], v[108:111]
	v_mfma_f32_16x16x32_bf16 v[100:103], v[148:151], v[198:201], v[100:103]
	v_mfma_f32_16x16x32_bf16 v[92:95], v[156:159], v[198:201], v[92:95]
	v_mfma_f32_16x16x32_bf16 v[84:87], v[148:151], v[206:209], v[84:87]
	v_mfma_f32_16x16x32_bf16 v[76:79], v[156:159], v[206:209], v[76:79]
	v_mfma_f32_16x16x32_bf16 v[112:115], v[160:163], v[178:181], v[112:115]
	v_mfma_f32_16x16x32_bf16 v[104:107], v[168:171], v[178:181], v[104:107]
	v_mfma_f32_16x16x32_bf16 v[96:99], v[160:163], v[186:189], v[96:99]
	v_mfma_f32_16x16x32_bf16 v[88:91], v[168:171], v[186:189], v[88:91]
	v_mfma_f32_16x16x32_bf16 v[80:83], v[160:163], v[194:197], v[80:83]
	v_mfma_f32_16x16x32_bf16 v[72:75], v[168:171], v[194:197], v[72:75]
	v_mfma_f32_16x16x32_bf16 v[68:71], v[160:163], v[202:205], v[68:71]
	v_mfma_f32_16x16x32_bf16 v[64:67], v[168:171], v[202:205], v[64:67]
	v_mfma_f32_16x16x32_bf16 v[112:115], v[164:167], v[182:185], v[112:115]
	v_mfma_f32_16x16x32_bf16 v[104:107], v[172:175], v[182:185], v[104:107]
	v_mfma_f32_16x16x32_bf16 v[96:99], v[164:167], v[190:193], v[96:99]
	v_mfma_f32_16x16x32_bf16 v[88:91], v[172:175], v[190:193], v[88:91]
	v_mfma_f32_16x16x32_bf16 v[80:83], v[164:167], v[198:201], v[80:83]
	v_mfma_f32_16x16x32_bf16 v[72:75], v[172:175], v[198:201], v[72:75]
	v_mfma_f32_16x16x32_bf16 v[68:71], v[164:167], v[206:209], v[68:71]
	v_mfma_f32_16x16x32_bf16 v[64:67], v[172:175], v[206:209], v[64:67]
	s_setprio 0
	s_barrier
	s_add_u32 s62, s40, 0x80
	s_addc_u32 s63, s41, 0
	ds_read_b128 v[178:181], v140 offset:49152
	ds_read_b128 v[182:185], v140 offset:50176
	ds_read_b128 v[186:189], v140 offset:51200
	ds_read_b128 v[190:193], v140 offset:52224
	ds_read_b128 v[194:197], v140 offset:53248
	ds_read_b128 v[198:201], v140 offset:54272
	ds_read_b128 v[202:205], v140 offset:55296
	ds_read_b128 v[206:209], v140 offset:56320
	s_mov_b32 m0, s48
	s_nop 0
	global_load_lds_dwordx4 v135, s[62:63]
	s_add_u32 s62, s40, 0x20080
	s_mov_b32 m0, s49
	s_addc_u32 s63, s41, 0
	global_load_lds_dwordx4 v135, s[62:63]
	s_add_u32 s62, s40, 0x40080
	s_mov_b32 m0, s52
	s_addc_u32 s63, s41, 0
	global_load_lds_dwordx4 v135, s[62:63]
	s_add_u32 s40, s40, 0x60080
	s_mov_b32 m0, s53
	s_addc_u32 s41, s41, 0
	global_load_lds_dwordx4 v135, s[40:41]
	s_mov_b32 m0, s50
	s_nop 0
	global_load_lds_dwordx4 v134, s[38:39]
	s_add_u32 s26, s26, 0x20080
	s_mov_b32 m0, s51
	s_addc_u32 s27, s27, 0
	global_load_lds_dwordx4 v134, s[26:27]
	s_waitcnt vmcnt(8)
	s_waitcnt lgkmcnt(0)
	s_barrier
	s_setprio 1
	v_mfma_f32_16x16x32_bf16 v[60:63], v[144:147], v[178:181], v[60:63]
	v_mfma_f32_16x16x32_bf16 v[56:59], v[152:155], v[178:181], v[56:59]
	v_mfma_f32_16x16x32_bf16 v[52:55], v[144:147], v[186:189], v[52:55]
	v_mfma_f32_16x16x32_bf16 v[44:47], v[152:155], v[186:189], v[44:47]
	v_mfma_f32_16x16x32_bf16 v[36:39], v[144:147], v[194:197], v[36:39]
	v_mfma_f32_16x16x32_bf16 v[28:31], v[152:155], v[194:197], v[28:31]
	v_mfma_f32_16x16x32_bf16 v[20:23], v[144:147], v[202:205], v[20:23]
	v_mfma_f32_16x16x32_bf16 v[12:15], v[152:155], v[202:205], v[12:15]
	v_mfma_f32_16x16x32_bf16 v[60:63], v[148:151], v[182:185], v[60:63]
	v_mfma_f32_16x16x32_bf16 v[56:59], v[156:159], v[182:185], v[56:59]
	v_mfma_f32_16x16x32_bf16 v[52:55], v[148:151], v[190:193], v[52:55]
	v_mfma_f32_16x16x32_bf16 v[44:47], v[156:159], v[190:193], v[44:47]
	v_mfma_f32_16x16x32_bf16 v[36:39], v[148:151], v[198:201], v[36:39]
	v_mfma_f32_16x16x32_bf16 v[28:31], v[156:159], v[198:201], v[28:31]
	v_mfma_f32_16x16x32_bf16 v[20:23], v[148:151], v[206:209], v[20:23]
	v_mfma_f32_16x16x32_bf16 v[12:15], v[156:159], v[206:209], v[12:15]
	v_mfma_f32_16x16x32_bf16 v[48:51], v[160:163], v[178:181], v[48:51]
	v_mfma_f32_16x16x32_bf16 v[40:43], v[168:171], v[178:181], v[40:43]
	v_mfma_f32_16x16x32_bf16 v[32:35], v[160:163], v[186:189], v[32:35]
	v_mfma_f32_16x16x32_bf16 v[24:27], v[168:171], v[186:189], v[24:27]
	v_mfma_f32_16x16x32_bf16 v[16:19], v[160:163], v[194:197], v[16:19]
	v_mfma_f32_16x16x32_bf16 v[8:11], v[168:171], v[194:197], v[8:11]
	v_mfma_f32_16x16x32_bf16 v[4:7], v[160:163], v[202:205], v[4:7]
	v_mfma_f32_16x16x32_bf16 v[0:3], v[168:171], v[202:205], v[0:3]
	v_mfma_f32_16x16x32_bf16 v[48:51], v[164:167], v[182:185], v[48:51]
	v_mfma_f32_16x16x32_bf16 v[40:43], v[172:175], v[182:185], v[40:43]
	v_mfma_f32_16x16x32_bf16 v[32:35], v[164:167], v[190:193], v[32:35]
	v_mfma_f32_16x16x32_bf16 v[24:27], v[172:175], v[190:193], v[24:27]
	v_mfma_f32_16x16x32_bf16 v[16:19], v[164:167], v[198:201], v[16:19]
	v_mfma_f32_16x16x32_bf16 v[8:11], v[172:175], v[198:201], v[8:11]
	v_mfma_f32_16x16x32_bf16 v[4:7], v[164:167], v[206:209], v[4:7]
	v_mfma_f32_16x16x32_bf16 v[0:3], v[172:175], v[206:209], v[0:3]
	s_setprio 0
	s_barrier
	s_add_i32 s60, s60, 2
	s_add_u32 s24, s24, 0x100
	s_addc_u32 s25, s25, 0
	s_add_u32 s58, s58, 0x100
	s_addc_u32 s59, s59, 0
	s_cmp_gt_u32 s60, 13
	s_cbranch_scc0 .LBB0_1192
	s_and_b64 vcc, exec, s[14:15]
	s_cbranch_vccz .LBB0_1195
	s_barrier

; #define PG8_STAGE(bufoff, gbase, voff, p64) do { _Pragma("unroll") for (int _i = 0; _i < 2; ++_i) { \
;         const char* _gb = (const char*)(gbase) + (size_t)_i * (p64); const unsigned _la = ldsbase + (unsigned)(bufoff) + (unsigned)_i * 8192u; \
;         asm volatile("s_mov_b32 m0, %0\n\ts_nop 0\n\tglobal_load_lds_dwordx4 %1, %2" :: "s"(_la), "v"(voff), "s"(_gb) : "memory"); } } while (0)
; #define PG8_LDA(dst, b, h) do { _Pragma("unroll") for (int m = 0; m < 4; ++m) _Pragma("unroll") for (int k = 0; k < 2; ++k) dst[m][k] = *(const LAS bf16x8*)(lds + PG8_SA(b, h) + aoff + m * 2048 + k * 1024); } while (0)
; #define PG8_LDB(dst, b, h) do { _Pragma("unroll") for (int n = 0; n < 2; ++n) _Pragma("unroll") for (int k = 0; k < 2; ++k) dst[n][k] = *(const LAS bf16x8*)(lds + PG8_SB(b, h) + boff + n * 2048 + k * 1024); } while (0)
; #define PG8_WAIT_V(n) asm volatile("s_waitcnt vmcnt(" #n ")" ::: "memory")
; #define PG8_WAIT_L(n) asm volatile("s_waitcnt lgkmcnt(" #n ")" ::: "memory")
; #define PG8_BAR __builtin_amdgcn_s_barrier()
; #define PG8_SCHED __builtin_amdgcn_sched_barrier(0)
; template <class Epi, class Sched>
; __device__ __forceinline__ void gemm_phase(LAS unsigned char* lds, const Sched& S, const Epi& E) {
;     ...
;         for (int t = 0; t < nt; t += 2) {
;             const bool last = (t == nt - 2);
;             const char* a1 = cA + (size_t)(t + 1) * kstep;
;             const char* a2 = last ? nA : cA + (size_t)(t + 2) * kstep; const char* b2 = last ? nB : cB + (size_t)(t + 2) * kstep;
;             const char* a3 = a2 + kstep; const char* b3 = b2 + kstep;
;             const unsigned vA2 = voffA, vB2 = voffB, hA2 = hA, hB2 = hB;
;             PG8_LDB(B0, 0, 0); PG8_LDB(B1, 0, 1); PG8_SCHED; PG8_LDA(At, 0, 0); PG8_STAGE(PG8_SA(1, 1), a1 + hA, voffA, hA / 2);
;             PG8_WAIT_V(8); PG8_WAIT_L(0); PG8_BAR; PG8_MMA(0, 0, At, B0); PG8_MMA(0, 1, At, B1); PG8_BAR; PG8_SCHED;
;     ...
;         if (!keep) {
; #pragma unroll
;             for (int a = 0; a < 2; ++a)
; #pragma unroll
;                 for (int b = 0; b < 2; ++b)
; #pragma unroll
;                     for (int m = 0; m < 4; ++m)
; #pragma unroll
;                         for (int n = 0; n < 2; ++n) acc[a][b][m][n] = (f32x4){0.f, 0.f, 0.f, 0.f};
;         }
;         cA = nA; cB = nB; nt = nnt; ++ui;
;         if (wr == 1) PG8_BAR;
.LBB0_1273:
	s_add_u32 s38, s38, 0x40080
	s_addc_u32 s39, s39, 0
	s_add_u32 s61, s40, 0x100
	s_addc_u32 s62, s41, 0
	s_mov_b32 s63, -2
	v_mov_b64_e32 v[0:1], 0
	v_mov_b64_e32 v[2:3], 0
	s_waitcnt vmcnt(3)
	v_mov_b64_e32 v[8:9], 0
	v_mov_b64_e32 v[10:11], 0
	s_waitcnt vmcnt(1)
	v_mov_b64_e32 v[16:17], 0
	v_mov_b64_e32 v[18:19], 0
	v_mov_b64_e32 v[24:25], 0
	v_mov_b64_e32 v[26:27], 0
	v_mov_b64_e32 v[32:33], 0
	v_mov_b64_e32 v[34:35], 0
	v_mov_b64_e32 v[40:41], 0
	v_mov_b64_e32 v[42:43], 0
	v_mov_b64_e32 v[48:49], 0
	v_mov_b64_e32 v[50:51], 0
	v_mov_b64_e32 v[56:57], 0
	v_mov_b64_e32 v[58:59], 0
	v_mov_b64_e32 v[4:5], 0
	v_mov_b64_e32 v[6:7], 0
	v_mov_b64_e32 v[12:13], 0
	v_mov_b64_e32 v[14:15], 0
	s_waitcnt vmcnt(0)
	v_mov_b64_e32 v[20:21], 0
	v_mov_b64_e32 v[22:23], 0
	v_mov_b64_e32 v[28:29], 0
	v_mov_b64_e32 v[30:31], 0
	v_mov_b64_e32 v[36:37], 0
	v_mov_b64_e32 v[38:39], 0
	v_mov_b64_e32 v[44:45], 0
	v_mov_b64_e32 v[46:47], 0
	v_mov_b64_e32 v[52:53], 0
	v_mov_b64_e32 v[54:55], 0
	v_mov_b64_e32 v[60:61], 0
	v_mov_b64_e32 v[62:63], 0
	v_mov_b64_e32 v[64:65], 0
	v_mov_b64_e32 v[66:67], 0
	v_mov_b64_e32 v[72:73], 0
	v_mov_b64_e32 v[74:75], 0
	v_mov_b64_e32 v[80:81], 0
	v_mov_b64_e32 v[82:83], 0
	v_mov_b64_e32 v[88:89], 0
	v_mov_b64_e32 v[90:91], 0
	v_mov_b64_e32 v[96:97], 0
	v_mov_b64_e32 v[98:99], 0
	v_mov_b64_e32 v[104:105], 0
	v_mov_b64_e32 v[106:107], 0
	v_mov_b64_e32 v[112:113], 0
	v_mov_b64_e32 v[114:115], 0
	v_mov_b64_e32 v[120:121], 0
	v_mov_b64_e32 v[122:123], 0
	v_mov_b64_e32 v[68:69], 0
	v_mov_b64_e32 v[70:71], 0
	v_mov_b64_e32 v[76:77], 0
	v_mov_b64_e32 v[78:79], 0
	v_mov_b64_e32 v[84:85], 0
	v_mov_b64_e32 v[86:87], 0
	v_mov_b64_e32 v[92:93], 0
	v_mov_b64_e32 v[94:95], 0
	v_mov_b64_e32 v[100:101], 0
	v_mov_b64_e32 v[102:103], 0
	v_mov_b64_e32 v[108:109], 0
	v_mov_b64_e32 v[110:111], 0
	v_mov_b64_e32 v[116:117], 0
	v_mov_b64_e32 v[118:119], 0
	v_mov_b64_e32 v[124:125], 0
	v_mov_b64_e32 v[126:127], 0
.LBB0_1274:
	ds_read_b128 v[128:131], v156
	ds_read_b128 v[132:135], v156 offset:1024
	ds_read_b128 v[140:143], v156 offset:2048
	ds_read_b128 v[144:147], v156 offset:3072
	ds_read_b128 v[148:151], v157
	ds_read_b128 v[162:165], v157 offset:1024
	ds_read_b128 v[166:169], v157 offset:2048
	ds_read_b128 v[170:173], v157 offset:3072
	s_add_u32 s30, s38, 0xfffc0080
	s_addc_u32 s40, s39, -1
	s_cmp_eq_u32 s63, 12
	s_cselect_b32 s41, s25, s40
	s_cselect_b32 s40, s24, s30
	s_cselect_b32 s44, s26, s61
	s_cselect_b32 s45, s27, s62
	s_add_u32 s42, s40, 0x80
	s_addc_u32 s43, s41, 0
	ds_read_b128 v[178:181], v158
	ds_read_b128 v[182:185], v158 offset:1024
	ds_read_b128 v[186:189], v158 offset:2048
	ds_read_b128 v[190:193], v158 offset:3072
	ds_read_b128 v[194:197], v158 offset:4096
	ds_read_b128 v[198:201], v158 offset:5120
	ds_read_b128 v[202:205], v158 offset:6144
	ds_read_b128 v[206:209], v158 offset:7168
	s_mov_b32 m0, s57
	s_nop 0
	global_load_lds_dwordx4 v152, s[38:39]
	s_add_u32 s66, s38, 0x20000
	s_mov_b32 m0, s58
	s_addc_u32 s67, s39, 0
	global_load_lds_dwordx4 v152, s[66:67]
	s_waitcnt vmcnt(8)
	s_waitcnt lgkmcnt(0)
	s_barrier
	s_setprio 1
	v_mfma_f32_16x16x32_bf16 v[124:127], v[128:131], v[178:181], v[124:127]
	v_mfma_f32_16x16x32_bf16 v[116:119], v[140:143], v[178:181], v[116:119]
	v_mfma_f32_16x16x32_bf16 v[108:111], v[128:131], v[186:189], v[108:111]
	v_mfma_f32_16x16x32_bf16 v[100:103], v[140:143], v[186:189], v[100:103]
	v_mfma_f32_16x16x32_bf16 v[92:95], v[128:131], v[194:197], v[92:95]
	v_mfma_f32_16x16x32_bf16 v[84:87], v[140:143], v[194:197], v[84:87]
	v_mfma_f32_16x16x32_bf16 v[76:79], v[128:131], v[202:205], v[76:79]
	v_mfma_f32_16x16x32_bf16 v[68:71], v[140:143], v[202:205], v[68:71]
	v_mfma_f32_16x16x32_bf16 v[124:127], v[132:135], v[182:185], v[124:127]
	v_mfma_f32_16x16x32_bf16 v[116:119], v[144:147], v[182:185], v[116:119]
	v_mfma_f32_16x16x32_bf16 v[108:111], v[132:135], v[190:193], v[108:111]
	v_mfma_f32_16x16x32_bf16 v[100:103], v[144:147], v[190:193], v[100:103]
	v_mfma_f32_16x16x32_bf16 v[92:95], v[132:135], v[198:201], v[92:95]
	v_mfma_f32_16x16x32_bf16 v[84:87], v[144:147], v[198:201], v[84:87]
	v_mfma_f32_16x16x32_bf16 v[76:79], v[132:135], v[206:209], v[76:79]
	v_mfma_f32_16x16x32_bf16 v[68:71], v[144:147], v[206:209], v[68:71]
	v_mfma_f32_16x16x32_bf16 v[120:123], v[148:151], v[178:181], v[120:123]
	v_mfma_f32_16x16x32_bf16 v[112:115], v[166:169], v[178:181], v[112:115]
	v_mfma_f32_16x16x32_bf16 v[104:107], v[148:151], v[186:189], v[104:107]
	v_mfma_f32_16x16x32_bf16 v[96:99], v[166:169], v[186:189], v[96:99]
	v_mfma_f32_16x16x32_bf16 v[88:91], v[148:151], v[194:197], v[88:91]
	v_mfma_f32_16x16x32_bf16 v[80:83], v[166:169], v[194:197], v[80:83]
	v_mfma_f32_16x16x32_bf16 v[72:75], v[148:151], v[202:205], v[72:75]
	v_mfma_f32_16x16x32_bf16 v[64:67], v[166:169], v[202:205], v[64:67]
	v_mfma_f32_16x16x32_bf16 v[120:123], v[162:165], v[182:185], v[120:123]
	v_mfma_f32_16x16x32_bf16 v[112:115], v[170:173], v[182:185], v[112:115]
	v_mfma_f32_16x16x32_bf16 v[104:107], v[162:165], v[190:193], v[104:107]
	v_mfma_f32_16x16x32_bf16 v[96:99], v[170:173], v[190:193], v[96:99]
	v_mfma_f32_16x16x32_bf16 v[88:91], v[162:165], v[198:201], v[88:91]
	v_mfma_f32_16x16x32_bf16 v[80:83], v[170:173], v[198:201], v[80:83]
	v_mfma_f32_16x16x32_bf16 v[72:75], v[162:165], v[206:209], v[72:75]
	v_mfma_f32_16x16x32_bf16 v[64:67], v[170:173], v[206:209], v[64:67]
	s_setprio 0
	s_barrier
; #define PG8_STAGE(bufoff, gbase, voff, p64) do { _Pragma("unroll") for (int _i = 0; _i < 2; ++_i) { \
;         const char* _gb = (const char*)(gbase) + (size_t)_i * (p64); const unsigned _la = ldsbase + (unsigned)(bufoff) + (unsigned)_i * 8192u; \
;         asm volatile("s_mov_b32 m0, %0\n\ts_nop 0\n\tglobal_load_lds_dwordx4 %1, %2" :: "s"(_la), "v"(voff), "s"(_gb) : "memory"); } } while (0)
; #define PG8_LDA(dst, b, h) do { _Pragma("unroll") for (int m = 0; m < 4; ++m) _Pragma("unroll") for (int k = 0; k < 2; ++k) dst[m][k] = *(const LAS bf16x8*)(lds + PG8_SA(b, h) + aoff + m * 2048 + k * 1024); } while (0)
; #define PG8_LDB(dst, b, h) do { _Pragma("unroll") for (int n = 0; n < 2; ++n) _Pragma("unroll") for (int k = 0; k < 2; ++k) dst[n][k] = *(const LAS bf16x8*)(lds + PG8_SB(b, h) + boff + n * 2048 + k * 1024); } while (0)
; #define PG8_MMA(ai, bj, At, Bt) do { __builtin_amdgcn_s_setprio(1); _Pragma("unroll") for (int m = 0; m < 4; ++m) _Pragma("unroll") for (int n = 0; n < 2; ++n) _Pragma("unroll") for (int k = 0; k < 2; ++k) \
;         acc[ai][bj][m][n] = __builtin_amdgcn_mfma_f32_16x16x32_bf16(Bt[n][k], At[m][k], acc[ai][bj][m][n], 0, 0, 0); __builtin_amdgcn_s_setprio(0); } while (0)
; #define PG8_WAIT_V(n) asm volatile("s_waitcnt vmcnt(" #n ")" ::: "memory")
; #define PG8_WAIT_L(n) asm volatile("s_waitcnt lgkmcnt(" #n ")" ::: "memory")
; #define PG8_BAR __builtin_amdgcn_s_barrier()
; #define PG8_SCHED __builtin_amdgcn_sched_barrier(0)
; template <class Epi, class Sched>
; __device__ __forceinline__ void gemm_phase(LAS unsigned char* lds, const Sched& S, const Epi& E) {
;     ...
;             PG8_LDA(At, 0, 1); PG8_STAGE(PG8_SB(0, 0), b2, vB2, hB2 / 2); PG8_STAGE(PG8_SB(0, 1), b2 + hB2, vB2, hB2 / 2); PG8_STAGE(PG8_SA(0, 0), a2, vA2, hA2 / 2);
;             PG8_WAIT_V(8); PG8_WAIT_L(0); PG8_BAR; PG8_MMA(1, 0, At, B0); PG8_MMA(1, 1, At, B1); PG8_BAR; PG8_SCHED;
;             PG8_LDB(B0, 1, 0); PG8_LDB(B1, 1, 1); PG8_SCHED; PG8_LDA(At, 1, 0); PG8_STAGE(PG8_SA(0, 1), a2 + hA2, vA2, hA2 / 2);
;             PG8_WAIT_V(8); PG8_WAIT_L(0); PG8_BAR; PG8_MMA(0, 0, At, B0); PG8_MMA(0, 1, At, B1); PG8_BAR; PG8_SCHED;
	s_add_u32 s66, s44, 0x20000
	ds_read_b128 v[178:181], v158 offset:16384
	ds_read_b128 v[182:185], v158 offset:17408
	ds_read_b128 v[186:189], v158 offset:18432
	ds_read_b128 v[190:193], v158 offset:19456
	ds_read_b128 v[194:197], v158 offset:20480
	ds_read_b128 v[198:201], v158 offset:21504
	ds_read_b128 v[202:205], v158 offset:22528
	ds_read_b128 v[206:209], v158 offset:23552
	s_mov_b32 m0, s35
	s_nop 0
	global_load_lds_dwordx4 v153, s[44:45]
	s_mov_b32 m0, s36
	s_addc_u32 s67, s45, 0
	global_load_lds_dwordx4 v153, s[66:67]
	s_add_u32 s66, s44, 0x40000
	s_mov_b32 m0, s37
	s_addc_u32 s67, s45, 0
	global_load_lds_dwordx4 v153, s[66:67]
	s_add_u32 s66, s44, 0x60000
	s_mov_b32 m0, s46
	s_addc_u32 s67, s45, 0
	global_load_lds_dwordx4 v153, s[66:67]
	s_mov_b32 m0, s34
	s_nop 0
	global_load_lds_dwordx4 v152, s[40:41]
	s_add_u32 s66, s40, 0x20000
	s_mov_b32 m0, s47
	s_addc_u32 s67, s41, 0
	global_load_lds_dwordx4 v152, s[66:67]
	s_waitcnt vmcnt(8)
	s_waitcnt lgkmcnt(0)
	s_barrier
	s_setprio 1
	v_mfma_f32_16x16x32_bf16 v[60:63], v[128:131], v[178:181], v[60:63]
	v_mfma_f32_16x16x32_bf16 v[52:55], v[140:143], v[178:181], v[52:55]
	v_mfma_f32_16x16x32_bf16 v[44:47], v[128:131], v[186:189], v[44:47]
	v_mfma_f32_16x16x32_bf16 v[36:39], v[140:143], v[186:189], v[36:39]
	v_mfma_f32_16x16x32_bf16 v[28:31], v[128:131], v[194:197], v[28:31]
	v_mfma_f32_16x16x32_bf16 v[20:23], v[140:143], v[194:197], v[20:23]
	v_mfma_f32_16x16x32_bf16 v[12:15], v[128:131], v[202:205], v[12:15]
	v_mfma_f32_16x16x32_bf16 v[4:7], v[140:143], v[202:205], v[4:7]
	v_mfma_f32_16x16x32_bf16 v[60:63], v[132:135], v[182:185], v[60:63]
	v_mfma_f32_16x16x32_bf16 v[52:55], v[144:147], v[182:185], v[52:55]
	v_mfma_f32_16x16x32_bf16 v[44:47], v[132:135], v[190:193], v[44:47]
	v_mfma_f32_16x16x32_bf16 v[36:39], v[144:147], v[190:193], v[36:39]
	v_mfma_f32_16x16x32_bf16 v[28:31], v[132:135], v[198:201], v[28:31]
	v_mfma_f32_16x16x32_bf16 v[20:23], v[144:147], v[198:201], v[20:23]
	v_mfma_f32_16x16x32_bf16 v[12:15], v[132:135], v[206:209], v[12:15]
	v_mfma_f32_16x16x32_bf16 v[4:7], v[144:147], v[206:209], v[4:7]
	v_mfma_f32_16x16x32_bf16 v[56:59], v[148:151], v[178:181], v[56:59]
	v_mfma_f32_16x16x32_bf16 v[48:51], v[166:169], v[178:181], v[48:51]
	v_mfma_f32_16x16x32_bf16 v[40:43], v[148:151], v[186:189], v[40:43]
	v_mfma_f32_16x16x32_bf16 v[32:35], v[166:169], v[186:189], v[32:35]
	v_mfma_f32_16x16x32_bf16 v[24:27], v[148:151], v[194:197], v[24:27]
	v_mfma_f32_16x16x32_bf16 v[16:19], v[166:169], v[194:197], v[16:19]
	v_mfma_f32_16x16x32_bf16 v[8:11], v[148:151], v[202:205], v[8:11]
	v_mfma_f32_16x16x32_bf16 v[0:3], v[166:169], v[202:205], v[0:3]
	v_mfma_f32_16x16x32_bf16 v[56:59], v[162:165], v[182:185], v[56:59]
	v_mfma_f32_16x16x32_bf16 v[48:51], v[170:173], v[182:185], v[48:51]
	v_mfma_f32_16x16x32_bf16 v[40:43], v[162:165], v[190:193], v[40:43]
	v_mfma_f32_16x16x32_bf16 v[32:35], v[170:173], v[190:193], v[32:35]
	v_mfma_f32_16x16x32_bf16 v[24:27], v[162:165], v[198:201], v[24:27]
	v_mfma_f32_16x16x32_bf16 v[16:19], v[170:173], v[198:201], v[16:19]
	v_mfma_f32_16x16x32_bf16 v[8:11], v[162:165], v[206:209], v[8:11]
	v_mfma_f32_16x16x32_bf16 v[0:3], v[170:173], v[206:209], v[0:3]
	s_setprio 0
	s_barrier
	ds_read_b128 v[128:131], v159
	ds_read_b128 v[132:135], v159 offset:1024
	ds_read_b128 v[140:143], v159 offset:2048
	ds_read_b128 v[144:147], v159 offset:3072
	ds_read_b128 v[148:151], v160
	ds_read_b128 v[162:165], v160 offset:1024
	ds_read_b128 v[166:169], v160 offset:2048
	ds_read_b128 v[170:173], v160 offset:3072
	ds_read_b128 v[178:181], v158 offset:32768
	ds_read_b128 v[182:185], v158 offset:33792
	ds_read_b128 v[186:189], v158 offset:34816
	ds_read_b128 v[190:193], v158 offset:35840
	ds_read_b128 v[194:197], v158 offset:36864
	ds_read_b128 v[198:201], v158 offset:37888
	ds_read_b128 v[202:205], v158 offset:38912
	ds_read_b128 v[206:209], v158 offset:39936
	s_add_u32 s66, s40, 0x40000
	s_mov_b32 m0, s48
	s_addc_u32 s67, s41, 0
	global_load_lds_dwordx4 v152, s[66:67]
	s_add_u32 s66, s40, 0x60000
	s_mov_b32 m0, s49
	s_addc_u32 s67, s41, 0
	global_load_lds_dwordx4 v152, s[66:67]
	s_waitcnt vmcnt(8)
	s_waitcnt lgkmcnt(0)
	s_barrier
; #define PG8_STAGE(bufoff, gbase, voff, p64) do { _Pragma("unroll") for (int _i = 0; _i < 2; ++_i) { \
;         const char* _gb = (const char*)(gbase) + (size_t)_i * (p64); const unsigned _la = ldsbase + (unsigned)(bufoff) + (unsigned)_i * 8192u; \
;         asm volatile("s_mov_b32 m0, %0\n\ts_nop 0\n\tglobal_load_lds_dwordx4 %1, %2" :: "s"(_la), "v"(voff), "s"(_gb) : "memory"); } } while (0)
; #define PG8_LDA(dst, b, h) do { _Pragma("unroll") for (int m = 0; m < 4; ++m) _Pragma("unroll") for (int k = 0; k < 2; ++k) dst[m][k] = *(const LAS bf16x8*)(lds + PG8_SA(b, h) + aoff + m * 2048 + k * 1024); } while (0)
; #define PG8_MMA(ai, bj, At, Bt) do { __builtin_amdgcn_s_setprio(1); _Pragma("unroll") for (int m = 0; m < 4; ++m) _Pragma("unroll") for (int n = 0; n < 2; ++n) _Pragma("unroll") for (int k = 0; k < 2; ++k) \
;         acc[ai][bj][m][n] = __builtin_amdgcn_mfma_f32_16x16x32_bf16(Bt[n][k], At[m][k], acc[ai][bj][m][n], 0, 0, 0); __builtin_amdgcn_s_setprio(0); } while (0)
; #define PG8_WAIT_V(n) asm volatile("s_waitcnt vmcnt(" #n ")" ::: "memory")
; #define PG8_WAIT_L(n) asm volatile("s_waitcnt lgkmcnt(" #n ")" ::: "memory")
; #define PG8_BAR __builtin_amdgcn_s_barrier()
; #define PG8_SCHED __builtin_amdgcn_sched_barrier(0)
; template <class Epi, class Sched>
; __device__ __forceinline__ void gemm_phase(LAS unsigned char* lds, const Sched& S, const Epi& E) {
;     ...
;             PG8_WAIT_V(8); PG8_WAIT_L(0); PG8_BAR; PG8_MMA(0, 0, At, B0); PG8_MMA(0, 1, At, B1); PG8_BAR; PG8_SCHED;
;             PG8_LDA(At, 1, 1); PG8_STAGE(PG8_SB(1, 0), b3, vB2, hB2 / 2); PG8_STAGE(PG8_SB(1, 1), b3 + hB2, vB2, hB2 / 2); PG8_STAGE(PG8_SA(1, 0), a3, vA2, hA2 / 2);
;             PG8_WAIT_V(8); PG8_WAIT_L(0); PG8_BAR; PG8_MMA(1, 0, At, B0); PG8_MMA(1, 1, At, B1); PG8_BAR; PG8_SCHED;
;         }
;         if (wr == 0) PG8_BAR;
	s_setprio 1
	v_mfma_f32_16x16x32_bf16 v[124:127], v[128:131], v[178:181], v[124:127]
	v_mfma_f32_16x16x32_bf16 v[116:119], v[140:143], v[178:181], v[116:119]
	v_mfma_f32_16x16x32_bf16 v[108:111], v[128:131], v[186:189], v[108:111]
	v_mfma_f32_16x16x32_bf16 v[100:103], v[140:143], v[186:189], v[100:103]
	v_mfma_f32_16x16x32_bf16 v[92:95], v[128:131], v[194:197], v[92:95]
	v_mfma_f32_16x16x32_bf16 v[84:87], v[140:143], v[194:197], v[84:87]
	v_mfma_f32_16x16x32_bf16 v[76:79], v[128:131], v[202:205], v[76:79]
	v_mfma_f32_16x16x32_bf16 v[68:71], v[140:143], v[202:205], v[68:71]
	v_mfma_f32_16x16x32_bf16 v[124:127], v[132:135], v[182:185], v[124:127]
	v_mfma_f32_16x16x32_bf16 v[116:119], v[144:147], v[182:185], v[116:119]
	v_mfma_f32_16x16x32_bf16 v[108:111], v[132:135], v[190:193], v[108:111]
	v_mfma_f32_16x16x32_bf16 v[100:103], v[144:147], v[190:193], v[100:103]
	v_mfma_f32_16x16x32_bf16 v[92:95], v[132:135], v[198:201], v[92:95]
	v_mfma_f32_16x16x32_bf16 v[84:87], v[144:147], v[198:201], v[84:87]
	v_mfma_f32_16x16x32_bf16 v[76:79], v[132:135], v[206:209], v[76:79]
	v_mfma_f32_16x16x32_bf16 v[68:71], v[144:147], v[206:209], v[68:71]
	v_mfma_f32_16x16x32_bf16 v[120:123], v[148:151], v[178:181], v[120:123]
	v_mfma_f32_16x16x32_bf16 v[112:115], v[166:169], v[178:181], v[112:115]
	v_mfma_f32_16x16x32_bf16 v[104:107], v[148:151], v[186:189], v[104:107]
	v_mfma_f32_16x16x32_bf16 v[96:99], v[166:169], v[186:189], v[96:99]
	v_mfma_f32_16x16x32_bf16 v[88:91], v[148:151], v[194:197], v[88:91]
	v_mfma_f32_16x16x32_bf16 v[80:83], v[166:169], v[194:197], v[80:83]
	v_mfma_f32_16x16x32_bf16 v[72:75], v[148:151], v[202:205], v[72:75]
	v_mfma_f32_16x16x32_bf16 v[64:67], v[166:169], v[202:205], v[64:67]
	v_mfma_f32_16x16x32_bf16 v[120:123], v[162:165], v[182:185], v[120:123]
	v_mfma_f32_16x16x32_bf16 v[112:115], v[170:173], v[182:185], v[112:115]
	v_mfma_f32_16x16x32_bf16 v[104:107], v[162:165], v[190:193], v[104:107]
	v_mfma_f32_16x16x32_bf16 v[96:99], v[170:173], v[190:193], v[96:99]
	v_mfma_f32_16x16x32_bf16 v[88:91], v[162:165], v[198:201], v[88:91]
	v_mfma_f32_16x16x32_bf16 v[80:83], v[170:173], v[198:201], v[80:83]
	v_mfma_f32_16x16x32_bf16 v[72:75], v[162:165], v[206:209], v[72:75]
	v_mfma_f32_16x16x32_bf16 v[64:67], v[170:173], v[206:209], v[64:67]
	s_setprio 0
	s_barrier
	s_add_u32 s66, s44, 0x80
	s_addc_u32 s67, s45, 0
	ds_read_b128 v[178:181], v158 offset:49152
	ds_read_b128 v[182:185], v158 offset:50176
	ds_read_b128 v[186:189], v158 offset:51200
	ds_read_b128 v[190:193], v158 offset:52224
	ds_read_b128 v[194:197], v158 offset:53248
	ds_read_b128 v[198:201], v158 offset:54272
	ds_read_b128 v[202:205], v158 offset:55296
	ds_read_b128 v[206:209], v158 offset:56320
	s_mov_b32 m0, s51
	s_nop 0
	global_load_lds_dwordx4 v153, s[66:67]
	s_add_u32 s66, s44, 0x20080
	s_mov_b32 m0, s52
	s_addc_u32 s67, s45, 0
	global_load_lds_dwordx4 v153, s[66:67]
	s_add_u32 s66, s44, 0x40080
	s_mov_b32 m0, s55
	s_addc_u32 s67, s45, 0
	global_load_lds_dwordx4 v153, s[66:67]
	s_add_u32 s44, s44, 0x60080
	s_mov_b32 m0, s56
	s_addc_u32 s45, s45, 0
	global_load_lds_dwordx4 v153, s[44:45]
	s_mov_b32 m0, s53
	s_nop 0
	global_load_lds_dwordx4 v152, s[42:43]
	s_add_u32 s40, s40, 0x20080
	s_mov_b32 m0, s54
	s_addc_u32 s41, s41, 0
	global_load_lds_dwordx4 v152, s[40:41]
	s_waitcnt vmcnt(8)
	s_waitcnt lgkmcnt(0)
	s_barrier
	s_setprio 1
	v_mfma_f32_16x16x32_bf16 v[60:63], v[128:131], v[178:181], v[60:63]
	v_mfma_f32_16x16x32_bf16 v[52:55], v[140:143], v[178:181], v[52:55]
	v_mfma_f32_16x16x32_bf16 v[44:47], v[128:131], v[186:189], v[44:47]
	v_mfma_f32_16x16x32_bf16 v[36:39], v[140:143], v[186:189], v[36:39]
	v_mfma_f32_16x16x32_bf16 v[28:31], v[128:131], v[194:197], v[28:31]
	v_mfma_f32_16x16x32_bf16 v[20:23], v[140:143], v[194:197], v[20:23]
	v_mfma_f32_16x16x32_bf16 v[12:15], v[128:131], v[202:205], v[12:15]
	v_mfma_f32_16x16x32_bf16 v[4:7], v[140:143], v[202:205], v[4:7]
	v_mfma_f32_16x16x32_bf16 v[60:63], v[132:135], v[182:185], v[60:63]
	v_mfma_f32_16x16x32_bf16 v[52:55], v[144:147], v[182:185], v[52:55]
	v_mfma_f32_16x16x32_bf16 v[44:47], v[132:135], v[190:193], v[44:47]
	v_mfma_f32_16x16x32_bf16 v[36:39], v[144:147], v[190:193], v[36:39]
	v_mfma_f32_16x16x32_bf16 v[28:31], v[132:135], v[198:201], v[28:31]
	v_mfma_f32_16x16x32_bf16 v[20:23], v[144:147], v[198:201], v[20:23]
	v_mfma_f32_16x16x32_bf16 v[12:15], v[132:135], v[206:209], v[12:15]
	v_mfma_f32_16x16x32_bf16 v[4:7], v[144:147], v[206:209], v[4:7]
	v_mfma_f32_16x16x32_bf16 v[56:59], v[148:151], v[178:181], v[56:59]
	v_mfma_f32_16x16x32_bf16 v[48:51], v[166:169], v[178:181], v[48:51]
	v_mfma_f32_16x16x32_bf16 v[40:43], v[148:151], v[186:189], v[40:43]
	v_mfma_f32_16x16x32_bf16 v[32:35], v[166:169], v[186:189], v[32:35]
	v_mfma_f32_16x16x32_bf16 v[24:27], v[148:151], v[194:197], v[24:27]
	v_mfma_f32_16x16x32_bf16 v[16:19], v[166:169], v[194:197], v[16:19]
	v_mfma_f32_16x16x32_bf16 v[8:11], v[148:151], v[202:205], v[8:11]
	v_mfma_f32_16x16x32_bf16 v[0:3], v[166:169], v[202:205], v[0:3]
	v_mfma_f32_16x16x32_bf16 v[56:59], v[162:165], v[182:185], v[56:59]
	v_mfma_f32_16x16x32_bf16 v[48:51], v[170:173], v[182:185], v[48:51]
	v_mfma_f32_16x16x32_bf16 v[40:43], v[162:165], v[190:193], v[40:43]
	v_mfma_f32_16x16x32_bf16 v[32:35], v[170:173], v[190:193], v[32:35]
	v_mfma_f32_16x16x32_bf16 v[24:27], v[162:165], v[198:201], v[24:27]
	v_mfma_f32_16x16x32_bf16 v[16:19], v[170:173], v[198:201], v[16:19]
	v_mfma_f32_16x16x32_bf16 v[8:11], v[162:165], v[206:209], v[8:11]
	v_mfma_f32_16x16x32_bf16 v[0:3], v[170:173], v[206:209], v[0:3]
	s_setprio 0
	s_barrier
	s_add_i32 s63, s63, 2
	s_add_u32 s38, s38, 0x100
	s_addc_u32 s39, s39, 0
	s_add_u32 s61, s61, 0x100
	s_addc_u32 s62, s62, 0
	s_cmp_gt_u32 s63, 13
	s_cbranch_scc0 .LBB0_1274
	s_and_b64 vcc, exec, s[18:19]
	s_cbranch_vccz .LBB0_1277
	s_barrier

; #define PG8_STAGE(bufoff, gbase, voff, p64) do { _Pragma("unroll") for (int _i = 0; _i < 2; ++_i) { \
;         const char* _gb = (const char*)(gbase) + (size_t)_i * (p64); const unsigned _la = ldsbase + (unsigned)(bufoff) + (unsigned)_i * 8192u; \
;         asm volatile("s_mov_b32 m0, %0\n\ts_nop 0\n\tglobal_load_lds_dwordx4 %1, %2" :: "s"(_la), "v"(voff), "s"(_gb) : "memory"); } } while (0)
; #define PG8_LDA(dst, b, h) do { _Pragma("unroll") for (int m = 0; m < 4; ++m) _Pragma("unroll") for (int k = 0; k < 2; ++k) dst[m][k] = *(const LAS bf16x8*)(lds + PG8_SA(b, h) + aoff + m * 2048 + k * 1024); } while (0)
; #define PG8_LDB(dst, b, h) do { _Pragma("unroll") for (int n = 0; n < 2; ++n) _Pragma("unroll") for (int k = 0; k < 2; ++k) dst[n][k] = *(const LAS bf16x8*)(lds + PG8_SB(b, h) + boff + n * 2048 + k * 1024); } while (0)
; #define PG8_WAIT_V(n) asm volatile("s_waitcnt vmcnt(" #n ")" ::: "memory")
; #define PG8_WAIT_L(n) asm volatile("s_waitcnt lgkmcnt(" #n ")" ::: "memory")
; #define PG8_BAR __builtin_amdgcn_s_barrier()
; #define PG8_SCHED __builtin_amdgcn_sched_barrier(0)
; template <class Epi, class Sched>
; __device__ __forceinline__ void gemm_phase(LAS unsigned char* lds, const Sched& S, const Epi& E) {
;     ...
;         for (int t = 0; t < nt; t += 2) {
;             const bool last = (t == nt - 2);
;             const char* a1 = cA + (size_t)(t + 1) * kstep;
;             const char* a2 = last ? nA : cA + (size_t)(t + 2) * kstep; const char* b2 = last ? nB : cB + (size_t)(t + 2) * kstep;
;             const char* a3 = a2 + kstep; const char* b3 = b2 + kstep;
;             const unsigned vA2 = voffA, vB2 = voffB, hA2 = hA, hB2 = hB;
;             PG8_LDB(B0, 0, 0); PG8_LDB(B1, 0, 1); PG8_SCHED; PG8_LDA(At, 0, 0); PG8_STAGE(PG8_SA(1, 1), a1 + hA, voffA, hA / 2);
;             PG8_WAIT_V(8); PG8_WAIT_L(0); PG8_BAR; PG8_MMA(0, 0, At, B0); PG8_MMA(0, 1, At, B1); PG8_BAR; PG8_SCHED;
;     ...
;         if (!keep) {
; #pragma unroll
;             for (int a = 0; a < 2; ++a)
; #pragma unroll
;                 for (int b = 0; b < 2; ++b)
; #pragma unroll
;                     for (int m = 0; m < 4; ++m)
; #pragma unroll
;                         for (int n = 0; n < 2; ++n) acc[a][b][m][n] = (f32x4){0.f, 0.f, 0.f, 0.f};
;         }
;         cA = nA; cB = nB; nt = nnt; ++ui;
;         if (wr == 1) PG8_BAR;
.LBB0_1351:
	s_add_u32 s22, s22, 0x40080
	s_addc_u32 s23, s23, 0
	s_add_u32 s59, s24, 0x100
	s_addc_u32 s60, s25, 0
	s_mov_b32 s61, -2
	v_mov_b64_e32 v[0:1], 0
	v_mov_b64_e32 v[2:3], 0
	v_mov_b64_e32 v[4:5], 0
	v_mov_b64_e32 v[6:7], 0
	s_waitcnt vmcnt(3)
	v_mov_b64_e32 v[8:9], 0
	v_mov_b64_e32 v[10:11], 0
	s_waitcnt vmcnt(2)
	v_mov_b64_e32 v[12:13], 0
	v_mov_b64_e32 v[14:15], 0
	s_waitcnt vmcnt(1)
	v_mov_b64_e32 v[16:17], 0
	v_mov_b64_e32 v[18:19], 0
	s_waitcnt vmcnt(0)
	v_mov_b64_e32 v[20:21], 0
	v_mov_b64_e32 v[22:23], 0
	v_mov_b64_e32 v[24:25], 0
	v_mov_b64_e32 v[26:27], 0
	v_mov_b64_e32 v[28:29], 0
	v_mov_b64_e32 v[30:31], 0
	v_mov_b64_e32 v[64:65], 0
	v_mov_b64_e32 v[66:67], 0
	v_mov_b64_e32 v[68:69], 0
	v_mov_b64_e32 v[70:71], 0
	v_mov_b64_e32 v[72:73], 0
	v_mov_b64_e32 v[74:75], 0
	v_mov_b64_e32 v[80:81], 0
	v_mov_b64_e32 v[82:83], 0
	v_mov_b64_e32 v[88:89], 0
	v_mov_b64_e32 v[90:91], 0
	v_mov_b64_e32 v[92:93], 0
	v_mov_b64_e32 v[94:95], 0
	v_mov_b64_e32 v[96:97], 0
	v_mov_b64_e32 v[98:99], 0
	v_mov_b64_e32 v[100:101], 0
	v_mov_b64_e32 v[102:103], 0
	v_mov_b64_e32 v[32:33], 0
	v_mov_b64_e32 v[34:35], 0
	v_mov_b64_e32 v[36:37], 0
	v_mov_b64_e32 v[38:39], 0
	v_mov_b64_e32 v[40:41], 0
	v_mov_b64_e32 v[42:43], 0
	v_mov_b64_e32 v[44:45], 0
	v_mov_b64_e32 v[46:47], 0
	v_mov_b64_e32 v[48:49], 0
	v_mov_b64_e32 v[50:51], 0
	v_mov_b64_e32 v[52:53], 0
	v_mov_b64_e32 v[54:55], 0
	v_mov_b64_e32 v[56:57], 0
	v_mov_b64_e32 v[58:59], 0
	v_mov_b64_e32 v[60:61], 0
	v_mov_b64_e32 v[62:63], 0
	v_mov_b64_e32 v[104:105], 0
	v_mov_b64_e32 v[106:107], 0
	v_mov_b64_e32 v[108:109], 0
	v_mov_b64_e32 v[110:111], 0
	v_mov_b64_e32 v[112:113], 0
	v_mov_b64_e32 v[114:115], 0
	v_mov_b64_e32 v[116:117], 0
	v_mov_b64_e32 v[118:119], 0
	v_mov_b64_e32 v[120:121], 0
	v_mov_b64_e32 v[122:123], 0
	v_mov_b64_e32 v[124:125], 0
	v_mov_b64_e32 v[126:127], 0
	v_mov_b64_e32 v[76:77], 0
	v_mov_b64_e32 v[78:79], 0
	v_mov_b64_e32 v[84:85], 0
	v_mov_b64_e32 v[86:87], 0
.LBB0_1352:
	ds_read_b128 v[128:131], v174
	ds_read_b128 v[132:135], v174 offset:1024
	ds_read_b128 v[136:139], v174 offset:2048
	ds_read_b128 v[144:147], v174 offset:3072
	ds_read_b128 v[148:151], v175
	ds_read_b128 v[152:155], v175 offset:1024
	ds_read_b128 v[156:159], v175 offset:2048
	ds_read_b128 v[160:163], v175 offset:3072
	s_add_u32 s24, s22, 0xfffc0080
	s_addc_u32 s25, s23, -1
	s_cmp_eq_u32 s61, 12
	s_cselect_b32 s24, s18, s24
	s_cselect_b32 s25, s19, s25
	s_cselect_b32 s38, s20, s59
	s_cselect_b32 s39, s21, s60
	s_add_u32 s26, s24, 0x80
	s_addc_u32 s27, s25, 0
	ds_read_b128 v[164:167], v177
	ds_read_b128 v[180:183], v177 offset:1024
	ds_read_b128 v[184:187], v177 offset:2048
	ds_read_b128 v[188:191], v177 offset:3072
	ds_read_b128 v[192:195], v177 offset:4096
	ds_read_b128 v[196:199], v177 offset:5120
	ds_read_b128 v[200:203], v177 offset:6144
	ds_read_b128 v[204:207], v177 offset:7168
	s_mov_b32 m0, s54
	s_nop 0
	global_load_lds_dwordx4 v170, s[22:23]
	s_add_u32 s62, s22, 0x20000
	s_mov_b32 m0, s55
	s_addc_u32 s63, s23, 0
	global_load_lds_dwordx4 v170, s[62:63]
	s_waitcnt vmcnt(8)
	s_waitcnt lgkmcnt(0)
	s_barrier
	s_setprio 1
	v_mfma_f32_16x16x32_bf16 v[84:87], v[128:131], v[164:167], v[84:87]
	v_mfma_f32_16x16x32_bf16 v[76:79], v[136:139], v[164:167], v[76:79]
	v_mfma_f32_16x16x32_bf16 v[124:127], v[128:131], v[184:187], v[124:127]
	v_mfma_f32_16x16x32_bf16 v[120:123], v[136:139], v[184:187], v[120:123]
	v_mfma_f32_16x16x32_bf16 v[116:119], v[128:131], v[192:195], v[116:119]
	v_mfma_f32_16x16x32_bf16 v[112:115], v[136:139], v[192:195], v[112:115]
	v_mfma_f32_16x16x32_bf16 v[108:111], v[128:131], v[200:203], v[108:111]
	v_mfma_f32_16x16x32_bf16 v[104:107], v[136:139], v[200:203], v[104:107]
	v_mfma_f32_16x16x32_bf16 v[84:87], v[132:135], v[180:183], v[84:87]
	v_mfma_f32_16x16x32_bf16 v[76:79], v[144:147], v[180:183], v[76:79]
	v_mfma_f32_16x16x32_bf16 v[124:127], v[132:135], v[188:191], v[124:127]
	v_mfma_f32_16x16x32_bf16 v[120:123], v[144:147], v[188:191], v[120:123]
	v_mfma_f32_16x16x32_bf16 v[116:119], v[132:135], v[196:199], v[116:119]
	v_mfma_f32_16x16x32_bf16 v[112:115], v[144:147], v[196:199], v[112:115]
	v_mfma_f32_16x16x32_bf16 v[108:111], v[132:135], v[204:207], v[108:111]
	v_mfma_f32_16x16x32_bf16 v[104:107], v[144:147], v[204:207], v[104:107]
	v_mfma_f32_16x16x32_bf16 v[60:63], v[148:151], v[164:167], v[60:63]
	v_mfma_f32_16x16x32_bf16 v[56:59], v[156:159], v[164:167], v[56:59]
	v_mfma_f32_16x16x32_bf16 v[52:55], v[148:151], v[184:187], v[52:55]
	v_mfma_f32_16x16x32_bf16 v[48:51], v[156:159], v[184:187], v[48:51]
	v_mfma_f32_16x16x32_bf16 v[44:47], v[148:151], v[192:195], v[44:47]
	v_mfma_f32_16x16x32_bf16 v[40:43], v[156:159], v[192:195], v[40:43]
	v_mfma_f32_16x16x32_bf16 v[36:39], v[148:151], v[200:203], v[36:39]
	v_mfma_f32_16x16x32_bf16 v[32:35], v[156:159], v[200:203], v[32:35]
	v_mfma_f32_16x16x32_bf16 v[60:63], v[152:155], v[180:183], v[60:63]
	v_mfma_f32_16x16x32_bf16 v[56:59], v[160:163], v[180:183], v[56:59]
	v_mfma_f32_16x16x32_bf16 v[52:55], v[152:155], v[188:191], v[52:55]
	v_mfma_f32_16x16x32_bf16 v[48:51], v[160:163], v[188:191], v[48:51]
	v_mfma_f32_16x16x32_bf16 v[44:47], v[152:155], v[196:199], v[44:47]
	v_mfma_f32_16x16x32_bf16 v[40:43], v[160:163], v[196:199], v[40:43]
	v_mfma_f32_16x16x32_bf16 v[36:39], v[152:155], v[204:207], v[36:39]
	v_mfma_f32_16x16x32_bf16 v[32:35], v[160:163], v[204:207], v[32:35]
	s_setprio 0
	s_barrier
; #define PG8_STAGE(bufoff, gbase, voff, p64) do { _Pragma("unroll") for (int _i = 0; _i < 2; ++_i) { \
;         const char* _gb = (const char*)(gbase) + (size_t)_i * (p64); const unsigned _la = ldsbase + (unsigned)(bufoff) + (unsigned)_i * 8192u; \
;         asm volatile("s_mov_b32 m0, %0\n\ts_nop 0\n\tglobal_load_lds_dwordx4 %1, %2" :: "s"(_la), "v"(voff), "s"(_gb) : "memory"); } } while (0)
; #define PG8_LDA(dst, b, h) do { _Pragma("unroll") for (int m = 0; m < 4; ++m) _Pragma("unroll") for (int k = 0; k < 2; ++k) dst[m][k] = *(const LAS bf16x8*)(lds + PG8_SA(b, h) + aoff + m * 2048 + k * 1024); } while (0)
; #define PG8_LDB(dst, b, h) do { _Pragma("unroll") for (int n = 0; n < 2; ++n) _Pragma("unroll") for (int k = 0; k < 2; ++k) dst[n][k] = *(const LAS bf16x8*)(lds + PG8_SB(b, h) + boff + n * 2048 + k * 1024); } while (0)
; #define PG8_MMA(ai, bj, At, Bt) do { __builtin_amdgcn_s_setprio(1); _Pragma("unroll") for (int m = 0; m < 4; ++m) _Pragma("unroll") for (int n = 0; n < 2; ++n) _Pragma("unroll") for (int k = 0; k < 2; ++k) \
;         acc[ai][bj][m][n] = __builtin_amdgcn_mfma_f32_16x16x32_bf16(Bt[n][k], At[m][k], acc[ai][bj][m][n], 0, 0, 0); __builtin_amdgcn_s_setprio(0); } while (0)
; #define PG8_WAIT_V(n) asm volatile("s_waitcnt vmcnt(" #n ")" ::: "memory")
; #define PG8_WAIT_L(n) asm volatile("s_waitcnt lgkmcnt(" #n ")" ::: "memory")
; #define PG8_BAR __builtin_amdgcn_s_barrier()
; #define PG8_SCHED __builtin_amdgcn_sched_barrier(0)
; template <class Epi, class Sched>
; __device__ __forceinline__ void gemm_phase(LAS unsigned char* lds, const Sched& S, const Epi& E) {
;     ...
;             PG8_LDA(At, 0, 1); PG8_STAGE(PG8_SB(0, 0), b2, vB2, hB2 / 2); PG8_STAGE(PG8_SB(0, 1), b2 + hB2, vB2, hB2 / 2); PG8_STAGE(PG8_SA(0, 0), a2, vA2, hA2 / 2);
;             PG8_WAIT_V(8); PG8_WAIT_L(0); PG8_BAR; PG8_MMA(1, 0, At, B0); PG8_MMA(1, 1, At, B1); PG8_BAR; PG8_SCHED;
;             PG8_LDB(B0, 1, 0); PG8_LDB(B1, 1, 1); PG8_SCHED; PG8_LDA(At, 1, 0); PG8_STAGE(PG8_SA(0, 1), a2 + hA2, vA2, hA2 / 2);
;             PG8_WAIT_V(8); PG8_WAIT_L(0); PG8_BAR; PG8_MMA(0, 0, At, B0); PG8_MMA(0, 1, At, B1); PG8_BAR; PG8_SCHED;
	s_add_u32 s62, s38, 0x20000
	ds_read_b128 v[164:167], v177 offset:16384
	ds_read_b128 v[180:183], v177 offset:17408
	ds_read_b128 v[184:187], v177 offset:18432
	ds_read_b128 v[188:191], v177 offset:19456
	ds_read_b128 v[192:195], v177 offset:20480
	ds_read_b128 v[196:199], v177 offset:21504
	ds_read_b128 v[200:203], v177 offset:22528
	ds_read_b128 v[204:207], v177 offset:23552
	s_mov_b32 m0, s35
	s_nop 0
	global_load_lds_dwordx4 v171, s[38:39]
	s_mov_b32 m0, s36
	s_addc_u32 s63, s39, 0
	global_load_lds_dwordx4 v171, s[62:63]
	s_add_u32 s62, s38, 0x40000
	s_mov_b32 m0, s37
	s_addc_u32 s63, s39, 0
	global_load_lds_dwordx4 v171, s[62:63]
	s_add_u32 s62, s38, 0x60000
	s_mov_b32 m0, s40
	s_addc_u32 s63, s39, 0
	global_load_lds_dwordx4 v171, s[62:63]
	s_mov_b32 m0, s34
	s_nop 0
	global_load_lds_dwordx4 v170, s[24:25]
	s_add_u32 s62, s24, 0x20000
	s_mov_b32 m0, s41
	s_addc_u32 s63, s25, 0
	global_load_lds_dwordx4 v170, s[62:63]
	s_waitcnt vmcnt(8)
	s_waitcnt lgkmcnt(0)
	s_barrier
	s_setprio 1
	v_mfma_f32_16x16x32_bf16 v[100:103], v[128:131], v[164:167], v[100:103]
	v_mfma_f32_16x16x32_bf16 v[96:99], v[136:139], v[164:167], v[96:99]
	v_mfma_f32_16x16x32_bf16 v[92:95], v[128:131], v[184:187], v[92:95]
	v_mfma_f32_16x16x32_bf16 v[88:91], v[136:139], v[184:187], v[88:91]
	v_mfma_f32_16x16x32_bf16 v[80:83], v[128:131], v[192:195], v[80:83]
	v_mfma_f32_16x16x32_bf16 v[72:75], v[136:139], v[192:195], v[72:75]
	v_mfma_f32_16x16x32_bf16 v[68:71], v[128:131], v[200:203], v[68:71]
	v_mfma_f32_16x16x32_bf16 v[64:67], v[136:139], v[200:203], v[64:67]
	v_mfma_f32_16x16x32_bf16 v[100:103], v[132:135], v[180:183], v[100:103]
	v_mfma_f32_16x16x32_bf16 v[96:99], v[144:147], v[180:183], v[96:99]
	v_mfma_f32_16x16x32_bf16 v[92:95], v[132:135], v[188:191], v[92:95]
	v_mfma_f32_16x16x32_bf16 v[88:91], v[144:147], v[188:191], v[88:91]
	v_mfma_f32_16x16x32_bf16 v[80:83], v[132:135], v[196:199], v[80:83]
	v_mfma_f32_16x16x32_bf16 v[72:75], v[144:147], v[196:199], v[72:75]
	v_mfma_f32_16x16x32_bf16 v[68:71], v[132:135], v[204:207], v[68:71]
	v_mfma_f32_16x16x32_bf16 v[64:67], v[144:147], v[204:207], v[64:67]
	v_mfma_f32_16x16x32_bf16 v[28:31], v[148:151], v[164:167], v[28:31]
	v_mfma_f32_16x16x32_bf16 v[24:27], v[156:159], v[164:167], v[24:27]
	v_mfma_f32_16x16x32_bf16 v[20:23], v[148:151], v[184:187], v[20:23]
	v_mfma_f32_16x16x32_bf16 v[16:19], v[156:159], v[184:187], v[16:19]
	v_mfma_f32_16x16x32_bf16 v[12:15], v[148:151], v[192:195], v[12:15]
	v_mfma_f32_16x16x32_bf16 v[8:11], v[156:159], v[192:195], v[8:11]
	v_mfma_f32_16x16x32_bf16 v[4:7], v[148:151], v[200:203], v[4:7]
	v_mfma_f32_16x16x32_bf16 v[0:3], v[156:159], v[200:203], v[0:3]
	v_mfma_f32_16x16x32_bf16 v[28:31], v[152:155], v[180:183], v[28:31]
	v_mfma_f32_16x16x32_bf16 v[24:27], v[160:163], v[180:183], v[24:27]
	v_mfma_f32_16x16x32_bf16 v[20:23], v[152:155], v[188:191], v[20:23]
	v_mfma_f32_16x16x32_bf16 v[16:19], v[160:163], v[188:191], v[16:19]
	v_mfma_f32_16x16x32_bf16 v[12:15], v[152:155], v[196:199], v[12:15]
	v_mfma_f32_16x16x32_bf16 v[8:11], v[160:163], v[196:199], v[8:11]
	v_mfma_f32_16x16x32_bf16 v[4:7], v[152:155], v[204:207], v[4:7]
	v_mfma_f32_16x16x32_bf16 v[0:3], v[160:163], v[204:207], v[0:3]
	s_setprio 0
	s_barrier
	ds_read_b128 v[128:131], v178
	ds_read_b128 v[132:135], v178 offset:1024
	ds_read_b128 v[136:139], v178 offset:2048
	ds_read_b128 v[144:147], v178 offset:3072
	ds_read_b128 v[148:151], v179
	ds_read_b128 v[152:155], v179 offset:1024
	ds_read_b128 v[156:159], v179 offset:2048
	ds_read_b128 v[160:163], v179 offset:3072
	ds_read_b128 v[164:167], v177 offset:32768
	ds_read_b128 v[180:183], v177 offset:33792
	ds_read_b128 v[184:187], v177 offset:34816
	ds_read_b128 v[188:191], v177 offset:35840
	ds_read_b128 v[192:195], v177 offset:36864
	ds_read_b128 v[196:199], v177 offset:37888
	ds_read_b128 v[200:203], v177 offset:38912
	ds_read_b128 v[204:207], v177 offset:39936
	s_add_u32 s62, s24, 0x40000
	s_mov_b32 m0, s42
	s_addc_u32 s63, s25, 0
	global_load_lds_dwordx4 v170, s[62:63]
	s_add_u32 s62, s24, 0x60000
	s_mov_b32 m0, s43
	s_addc_u32 s63, s25, 0
	global_load_lds_dwordx4 v170, s[62:63]
	s_waitcnt vmcnt(8)
	s_waitcnt lgkmcnt(0)
	s_barrier
; #define PG8_STAGE(bufoff, gbase, voff, p64) do { _Pragma("unroll") for (int _i = 0; _i < 2; ++_i) { \
;         const char* _gb = (const char*)(gbase) + (size_t)_i * (p64); const unsigned _la = ldsbase + (unsigned)(bufoff) + (unsigned)_i * 8192u; \
;         asm volatile("s_mov_b32 m0, %0\n\ts_nop 0\n\tglobal_load_lds_dwordx4 %1, %2" :: "s"(_la), "v"(voff), "s"(_gb) : "memory"); } } while (0)
; #define PG8_LDA(dst, b, h) do { _Pragma("unroll") for (int m = 0; m < 4; ++m) _Pragma("unroll") for (int k = 0; k < 2; ++k) dst[m][k] = *(const LAS bf16x8*)(lds + PG8_SA(b, h) + aoff + m * 2048 + k * 1024); } while (0)
; #define PG8_MMA(ai, bj, At, Bt) do { __builtin_amdgcn_s_setprio(1); _Pragma("unroll") for (int m = 0; m < 4; ++m) _Pragma("unroll") for (int n = 0; n < 2; ++n) _Pragma("unroll") for (int k = 0; k < 2; ++k) \
;         acc[ai][bj][m][n] = __builtin_amdgcn_mfma_f32_16x16x32_bf16(Bt[n][k], At[m][k], acc[ai][bj][m][n], 0, 0, 0); __builtin_amdgcn_s_setprio(0); } while (0)
; #define PG8_WAIT_V(n) asm volatile("s_waitcnt vmcnt(" #n ")" ::: "memory")
; #define PG8_WAIT_L(n) asm volatile("s_waitcnt lgkmcnt(" #n ")" ::: "memory")
; #define PG8_BAR __builtin_amdgcn_s_barrier()
; #define PG8_SCHED __builtin_amdgcn_sched_barrier(0)
; template <class Epi, class Sched>
; __device__ __forceinline__ void gemm_phase(LAS unsigned char* lds, const Sched& S, const Epi& E) {
;     ...
;             PG8_WAIT_V(8); PG8_WAIT_L(0); PG8_BAR; PG8_MMA(0, 0, At, B0); PG8_MMA(0, 1, At, B1); PG8_BAR; PG8_SCHED;
;             PG8_LDA(At, 1, 1); PG8_STAGE(PG8_SB(1, 0), b3, vB2, hB2 / 2); PG8_STAGE(PG8_SB(1, 1), b3 + hB2, vB2, hB2 / 2); PG8_STAGE(PG8_SA(1, 0), a3, vA2, hA2 / 2);
;             PG8_WAIT_V(8); PG8_WAIT_L(0); PG8_BAR; PG8_MMA(1, 0, At, B0); PG8_MMA(1, 1, At, B1); PG8_BAR; PG8_SCHED;
;         }
;         if (wr == 0) PG8_BAR;
	s_setprio 1
	v_mfma_f32_16x16x32_bf16 v[84:87], v[128:131], v[164:167], v[84:87]
	v_mfma_f32_16x16x32_bf16 v[76:79], v[136:139], v[164:167], v[76:79]
	v_mfma_f32_16x16x32_bf16 v[124:127], v[128:131], v[184:187], v[124:127]
	v_mfma_f32_16x16x32_bf16 v[120:123], v[136:139], v[184:187], v[120:123]
	v_mfma_f32_16x16x32_bf16 v[116:119], v[128:131], v[192:195], v[116:119]
	v_mfma_f32_16x16x32_bf16 v[112:115], v[136:139], v[192:195], v[112:115]
	v_mfma_f32_16x16x32_bf16 v[108:111], v[128:131], v[200:203], v[108:111]
	v_mfma_f32_16x16x32_bf16 v[104:107], v[136:139], v[200:203], v[104:107]
	v_mfma_f32_16x16x32_bf16 v[84:87], v[132:135], v[180:183], v[84:87]
	v_mfma_f32_16x16x32_bf16 v[76:79], v[144:147], v[180:183], v[76:79]
	v_mfma_f32_16x16x32_bf16 v[124:127], v[132:135], v[188:191], v[124:127]
	v_mfma_f32_16x16x32_bf16 v[120:123], v[144:147], v[188:191], v[120:123]
	v_mfma_f32_16x16x32_bf16 v[116:119], v[132:135], v[196:199], v[116:119]
	v_mfma_f32_16x16x32_bf16 v[112:115], v[144:147], v[196:199], v[112:115]
	v_mfma_f32_16x16x32_bf16 v[108:111], v[132:135], v[204:207], v[108:111]
	v_mfma_f32_16x16x32_bf16 v[104:107], v[144:147], v[204:207], v[104:107]
	v_mfma_f32_16x16x32_bf16 v[60:63], v[148:151], v[164:167], v[60:63]
	v_mfma_f32_16x16x32_bf16 v[56:59], v[156:159], v[164:167], v[56:59]
	v_mfma_f32_16x16x32_bf16 v[52:55], v[148:151], v[184:187], v[52:55]
	v_mfma_f32_16x16x32_bf16 v[48:51], v[156:159], v[184:187], v[48:51]
	v_mfma_f32_16x16x32_bf16 v[44:47], v[148:151], v[192:195], v[44:47]
	v_mfma_f32_16x16x32_bf16 v[40:43], v[156:159], v[192:195], v[40:43]
	v_mfma_f32_16x16x32_bf16 v[36:39], v[148:151], v[200:203], v[36:39]
	v_mfma_f32_16x16x32_bf16 v[32:35], v[156:159], v[200:203], v[32:35]
	v_mfma_f32_16x16x32_bf16 v[60:63], v[152:155], v[180:183], v[60:63]
	v_mfma_f32_16x16x32_bf16 v[56:59], v[160:163], v[180:183], v[56:59]
	v_mfma_f32_16x16x32_bf16 v[52:55], v[152:155], v[188:191], v[52:55]
	v_mfma_f32_16x16x32_bf16 v[48:51], v[160:163], v[188:191], v[48:51]
	v_mfma_f32_16x16x32_bf16 v[44:47], v[152:155], v[196:199], v[44:47]
	v_mfma_f32_16x16x32_bf16 v[40:43], v[160:163], v[196:199], v[40:43]
	v_mfma_f32_16x16x32_bf16 v[36:39], v[152:155], v[204:207], v[36:39]
	v_mfma_f32_16x16x32_bf16 v[32:35], v[160:163], v[204:207], v[32:35]
	s_setprio 0
	s_barrier
	s_add_u32 s62, s38, 0x80
	s_addc_u32 s63, s39, 0
	ds_read_b128 v[164:167], v177 offset:49152
	ds_read_b128 v[180:183], v177 offset:50176
	ds_read_b128 v[184:187], v177 offset:51200
	ds_read_b128 v[188:191], v177 offset:52224
	ds_read_b128 v[192:195], v177 offset:53248
	ds_read_b128 v[196:199], v177 offset:54272
	ds_read_b128 v[200:203], v177 offset:55296
	ds_read_b128 v[204:207], v177 offset:56320
	s_mov_b32 m0, s48
	s_nop 0
	global_load_lds_dwordx4 v171, s[62:63]
	s_add_u32 s62, s38, 0x20080
	s_mov_b32 m0, s49
	s_addc_u32 s63, s39, 0
	global_load_lds_dwordx4 v171, s[62:63]
	s_add_u32 s62, s38, 0x40080
	s_mov_b32 m0, s52
	s_addc_u32 s63, s39, 0
	global_load_lds_dwordx4 v171, s[62:63]
	s_add_u32 s38, s38, 0x60080
	s_mov_b32 m0, s53
	s_addc_u32 s39, s39, 0
	global_load_lds_dwordx4 v171, s[38:39]
	s_mov_b32 m0, s50
	s_nop 0
	global_load_lds_dwordx4 v170, s[26:27]
	s_add_u32 s24, s24, 0x20080
	s_mov_b32 m0, s51
	s_addc_u32 s25, s25, 0
	global_load_lds_dwordx4 v170, s[24:25]
	s_waitcnt vmcnt(8)
	s_waitcnt lgkmcnt(0)
	s_barrier
	s_setprio 1
	v_mfma_f32_16x16x32_bf16 v[100:103], v[128:131], v[164:167], v[100:103]
	v_mfma_f32_16x16x32_bf16 v[96:99], v[136:139], v[164:167], v[96:99]
	v_mfma_f32_16x16x32_bf16 v[92:95], v[128:131], v[184:187], v[92:95]
	v_mfma_f32_16x16x32_bf16 v[88:91], v[136:139], v[184:187], v[88:91]
	v_mfma_f32_16x16x32_bf16 v[80:83], v[128:131], v[192:195], v[80:83]
	v_mfma_f32_16x16x32_bf16 v[72:75], v[136:139], v[192:195], v[72:75]
	v_mfma_f32_16x16x32_bf16 v[68:71], v[128:131], v[200:203], v[68:71]
	v_mfma_f32_16x16x32_bf16 v[64:67], v[136:139], v[200:203], v[64:67]
	v_mfma_f32_16x16x32_bf16 v[100:103], v[132:135], v[180:183], v[100:103]
	v_mfma_f32_16x16x32_bf16 v[96:99], v[144:147], v[180:183], v[96:99]
	v_mfma_f32_16x16x32_bf16 v[92:95], v[132:135], v[188:191], v[92:95]
	v_mfma_f32_16x16x32_bf16 v[88:91], v[144:147], v[188:191], v[88:91]
	v_mfma_f32_16x16x32_bf16 v[80:83], v[132:135], v[196:199], v[80:83]
	v_mfma_f32_16x16x32_bf16 v[72:75], v[144:147], v[196:199], v[72:75]
	v_mfma_f32_16x16x32_bf16 v[68:71], v[132:135], v[204:207], v[68:71]
	v_mfma_f32_16x16x32_bf16 v[64:67], v[144:147], v[204:207], v[64:67]
	v_mfma_f32_16x16x32_bf16 v[28:31], v[148:151], v[164:167], v[28:31]
	v_mfma_f32_16x16x32_bf16 v[24:27], v[156:159], v[164:167], v[24:27]
	v_mfma_f32_16x16x32_bf16 v[20:23], v[148:151], v[184:187], v[20:23]
	v_mfma_f32_16x16x32_bf16 v[16:19], v[156:159], v[184:187], v[16:19]
	v_mfma_f32_16x16x32_bf16 v[12:15], v[148:151], v[192:195], v[12:15]
	v_mfma_f32_16x16x32_bf16 v[8:11], v[156:159], v[192:195], v[8:11]
	v_mfma_f32_16x16x32_bf16 v[4:7], v[148:151], v[200:203], v[4:7]
	v_mfma_f32_16x16x32_bf16 v[0:3], v[156:159], v[200:203], v[0:3]
	v_mfma_f32_16x16x32_bf16 v[28:31], v[152:155], v[180:183], v[28:31]
	v_mfma_f32_16x16x32_bf16 v[24:27], v[160:163], v[180:183], v[24:27]
	v_mfma_f32_16x16x32_bf16 v[20:23], v[152:155], v[188:191], v[20:23]
	v_mfma_f32_16x16x32_bf16 v[16:19], v[160:163], v[188:191], v[16:19]
	v_mfma_f32_16x16x32_bf16 v[12:15], v[152:155], v[196:199], v[12:15]
	v_mfma_f32_16x16x32_bf16 v[8:11], v[160:163], v[196:199], v[8:11]
	v_mfma_f32_16x16x32_bf16 v[4:7], v[152:155], v[204:207], v[4:7]
	v_mfma_f32_16x16x32_bf16 v[0:3], v[160:163], v[204:207], v[0:3]
	s_setprio 0
	s_barrier
	s_add_i32 s61, s61, 2
	s_add_u32 s22, s22, 0x100
	s_addc_u32 s23, s23, 0
	s_add_u32 s59, s59, 0x100
	s_addc_u32 s60, s60, 0
	s_cmp_gt_u32 s61, 13
	s_cbranch_scc0 .LBB0_1352
	s_and_b64 vcc, exec, s[12:13]
	s_cbranch_vccz .LBB0_1355
	s_barrier

; #define PG8_STAGE(bufoff, gbase, voff, p64) do { _Pragma("unroll") for (int _i = 0; _i < 2; ++_i) { \
;         const char* _gb = (const char*)(gbase) + (size_t)_i * (p64); const unsigned _la = ldsbase + (unsigned)(bufoff) + (unsigned)_i * 8192u; \
;         asm volatile("s_mov_b32 m0, %0\n\ts_nop 0\n\tglobal_load_lds_dwordx4 %1, %2" :: "s"(_la), "v"(voff), "s"(_gb) : "memory"); } } while (0)
; #define PG8_LDA(dst, b, h) do { _Pragma("unroll") for (int m = 0; m < 4; ++m) _Pragma("unroll") for (int k = 0; k < 2; ++k) dst[m][k] = *(const LAS bf16x8*)(lds + PG8_SA(b, h) + aoff + m * 2048 + k * 1024); } while (0)
; #define PG8_LDB(dst, b, h) do { _Pragma("unroll") for (int n = 0; n < 2; ++n) _Pragma("unroll") for (int k = 0; k < 2; ++k) dst[n][k] = *(const LAS bf16x8*)(lds + PG8_SB(b, h) + boff + n * 2048 + k * 1024); } while (0)
; #define PG8_WAIT_V(n) asm volatile("s_waitcnt vmcnt(" #n ")" ::: "memory")
; #define PG8_WAIT_L(n) asm volatile("s_waitcnt lgkmcnt(" #n ")" ::: "memory")
; #define PG8_BAR __builtin_amdgcn_s_barrier()
; #define PG8_SCHED __builtin_amdgcn_sched_barrier(0)
; template <class Epi, class Sched>
; __device__ __forceinline__ void gemm_phase(LAS unsigned char* lds, const Sched& S, const Epi& E) {
;     ...
;         for (int t = 0; t < nt; t += 2) {
;             const bool last = (t == nt - 2);
;             const char* a1 = cA + (size_t)(t + 1) * kstep;
;             const char* a2 = last ? nA : cA + (size_t)(t + 2) * kstep; const char* b2 = last ? nB : cB + (size_t)(t + 2) * kstep;
;             const char* a3 = a2 + kstep; const char* b3 = b2 + kstep;
;             const unsigned vA2 = voffA, vB2 = voffB, hA2 = hA, hB2 = hB;
;             PG8_LDB(B0, 0, 0); PG8_LDB(B1, 0, 1); PG8_SCHED; PG8_LDA(At, 0, 0); PG8_STAGE(PG8_SA(1, 1), a1 + hA, voffA, hA / 2);
;             PG8_WAIT_V(8); PG8_WAIT_L(0); PG8_BAR; PG8_MMA(0, 0, At, B0); PG8_MMA(0, 1, At, B1); PG8_BAR; PG8_SCHED;
;     ...
;         if (!keep) {
; #pragma unroll
;             for (int a = 0; a < 2; ++a)
; #pragma unroll
;                 for (int b = 0; b < 2; ++b)
; #pragma unroll
;                     for (int m = 0; m < 4; ++m)
; #pragma unroll
;                         for (int n = 0; n < 2; ++n) acc[a][b][m][n] = (f32x4){0.f, 0.f, 0.f, 0.f};
;         }
;         cA = nA; cB = nB; nt = nnt; ++ui;
;         if (wr == 1) PG8_BAR;
.LBB0_1484:
	s_add_u32 s24, s24, 0x40080
	s_addc_u32 s25, s25, 0
	s_add_u32 s59, s26, 0x100
	s_addc_u32 s60, s27, 0
	s_mov_b32 s61, -2
	v_mov_b64_e32 v[0:1], 0
	v_mov_b64_e32 v[2:3], 0
	v_mov_b64_e32 v[4:5], 0
	v_mov_b64_e32 v[6:7], 0
	v_mov_b64_e32 v[16:17], 0
	v_mov_b64_e32 v[18:19], 0
	v_mov_b64_e32 v[20:21], 0
	v_mov_b64_e32 v[22:23], 0
	v_mov_b64_e32 v[32:33], 0
	v_mov_b64_e32 v[34:35], 0
	v_mov_b64_e32 v[36:37], 0
	v_mov_b64_e32 v[38:39], 0
	v_mov_b64_e32 v[48:49], 0
	v_mov_b64_e32 v[50:51], 0
	v_mov_b64_e32 v[52:53], 0
	v_mov_b64_e32 v[54:55], 0
	v_mov_b64_e32 v[8:9], 0
	v_mov_b64_e32 v[10:11], 0
	v_mov_b64_e32 v[12:13], 0
	v_mov_b64_e32 v[14:15], 0
	v_mov_b64_e32 v[24:25], 0
	v_mov_b64_e32 v[26:27], 0
	v_mov_b64_e32 v[28:29], 0
	v_mov_b64_e32 v[30:31], 0
	v_mov_b64_e32 v[40:41], 0
	v_mov_b64_e32 v[42:43], 0
	v_mov_b64_e32 v[44:45], 0
	v_mov_b64_e32 v[46:47], 0
	v_mov_b64_e32 v[56:57], 0
	v_mov_b64_e32 v[58:59], 0
	v_mov_b64_e32 v[60:61], 0
	v_mov_b64_e32 v[62:63], 0
	v_mov_b64_e32 v[64:65], 0
	v_mov_b64_e32 v[66:67], 0
	v_mov_b64_e32 v[68:69], 0
	v_mov_b64_e32 v[70:71], 0
	v_mov_b64_e32 v[80:81], 0
	v_mov_b64_e32 v[82:83], 0
	v_mov_b64_e32 v[84:85], 0
	v_mov_b64_e32 v[86:87], 0
	v_mov_b64_e32 v[96:97], 0
	v_mov_b64_e32 v[98:99], 0
	v_mov_b64_e32 v[100:101], 0
	v_mov_b64_e32 v[102:103], 0
	v_mov_b64_e32 v[112:113], 0
	v_mov_b64_e32 v[114:115], 0
	v_mov_b64_e32 v[116:117], 0
	v_mov_b64_e32 v[118:119], 0
	v_mov_b64_e32 v[72:73], 0
	v_mov_b64_e32 v[74:75], 0
	v_mov_b64_e32 v[76:77], 0
	v_mov_b64_e32 v[78:79], 0
	v_mov_b64_e32 v[88:89], 0
	v_mov_b64_e32 v[90:91], 0
	v_mov_b64_e32 v[92:93], 0
	v_mov_b64_e32 v[94:95], 0
	v_mov_b64_e32 v[104:105], 0
	v_mov_b64_e32 v[106:107], 0
	v_mov_b64_e32 v[108:109], 0
	v_mov_b64_e32 v[110:111], 0
	v_mov_b64_e32 v[120:121], 0
	v_mov_b64_e32 v[122:123], 0
	v_mov_b64_e32 v[124:125], 0
	v_mov_b64_e32 v[126:127], 0
.LBB0_1485:
	ds_read_b128 v[144:147], v138
	ds_read_b128 v[148:151], v138 offset:1024
	ds_read_b128 v[152:155], v138 offset:2048
	ds_read_b128 v[156:159], v138 offset:3072
	ds_read_b128 v[160:163], v139
	ds_read_b128 v[164:167], v139 offset:1024
	ds_read_b128 v[168:171], v139 offset:2048
	ds_read_b128 v[172:175], v139 offset:3072
	s_add_u32 s26, s24, 0xfffc0080
	s_addc_u32 s27, s25, -1
	s_cmp_eq_u32 s61, 12
	s_cselect_b32 s26, s20, s26
	s_cselect_b32 s27, s21, s27
	s_cselect_b32 s40, s22, s59
	s_cselect_b32 s41, s23, s60
	s_add_u32 s38, s26, 0x80
	s_addc_u32 s39, s27, 0
	ds_read_b128 v[178:181], v140
	ds_read_b128 v[182:185], v140 offset:1024
	ds_read_b128 v[186:189], v140 offset:2048
	ds_read_b128 v[190:193], v140 offset:3072
	ds_read_b128 v[194:197], v140 offset:4096
	ds_read_b128 v[198:201], v140 offset:5120
	ds_read_b128 v[202:205], v140 offset:6144
	ds_read_b128 v[206:209], v140 offset:7168
	s_mov_b32 m0, s54
	s_nop 0
	global_load_lds_dwordx4 v134, s[24:25]
	s_add_u32 s62, s24, 0x20000
	s_mov_b32 m0, s55
	s_addc_u32 s63, s25, 0
	global_load_lds_dwordx4 v134, s[62:63]
	s_waitcnt vmcnt(8)
	s_waitcnt lgkmcnt(0)
	s_barrier
	s_setprio 1
	v_mfma_f32_16x16x32_bf16 v[124:127], v[144:147], v[178:181], v[124:127]
	v_mfma_f32_16x16x32_bf16 v[120:123], v[152:155], v[178:181], v[120:123]
	v_mfma_f32_16x16x32_bf16 v[108:111], v[144:147], v[186:189], v[108:111]
	v_mfma_f32_16x16x32_bf16 v[104:107], v[152:155], v[186:189], v[104:107]
	v_mfma_f32_16x16x32_bf16 v[92:95], v[144:147], v[194:197], v[92:95]
	v_mfma_f32_16x16x32_bf16 v[88:91], v[152:155], v[194:197], v[88:91]
	v_mfma_f32_16x16x32_bf16 v[76:79], v[144:147], v[202:205], v[76:79]
	v_mfma_f32_16x16x32_bf16 v[72:75], v[152:155], v[202:205], v[72:75]
	v_mfma_f32_16x16x32_bf16 v[124:127], v[148:151], v[182:185], v[124:127]
	v_mfma_f32_16x16x32_bf16 v[120:123], v[156:159], v[182:185], v[120:123]
	v_mfma_f32_16x16x32_bf16 v[108:111], v[148:151], v[190:193], v[108:111]
	v_mfma_f32_16x16x32_bf16 v[104:107], v[156:159], v[190:193], v[104:107]
	v_mfma_f32_16x16x32_bf16 v[92:95], v[148:151], v[198:201], v[92:95]
	v_mfma_f32_16x16x32_bf16 v[88:91], v[156:159], v[198:201], v[88:91]
	v_mfma_f32_16x16x32_bf16 v[76:79], v[148:151], v[206:209], v[76:79]
	v_mfma_f32_16x16x32_bf16 v[72:75], v[156:159], v[206:209], v[72:75]
	v_mfma_f32_16x16x32_bf16 v[116:119], v[160:163], v[178:181], v[116:119]
	v_mfma_f32_16x16x32_bf16 v[112:115], v[168:171], v[178:181], v[112:115]
	v_mfma_f32_16x16x32_bf16 v[100:103], v[160:163], v[186:189], v[100:103]
	v_mfma_f32_16x16x32_bf16 v[96:99], v[168:171], v[186:189], v[96:99]
	v_mfma_f32_16x16x32_bf16 v[84:87], v[160:163], v[194:197], v[84:87]
	v_mfma_f32_16x16x32_bf16 v[80:83], v[168:171], v[194:197], v[80:83]
	v_mfma_f32_16x16x32_bf16 v[68:71], v[160:163], v[202:205], v[68:71]
	v_mfma_f32_16x16x32_bf16 v[64:67], v[168:171], v[202:205], v[64:67]
	v_mfma_f32_16x16x32_bf16 v[116:119], v[164:167], v[182:185], v[116:119]
	v_mfma_f32_16x16x32_bf16 v[112:115], v[172:175], v[182:185], v[112:115]
	v_mfma_f32_16x16x32_bf16 v[100:103], v[164:167], v[190:193], v[100:103]
	v_mfma_f32_16x16x32_bf16 v[96:99], v[172:175], v[190:193], v[96:99]
	v_mfma_f32_16x16x32_bf16 v[84:87], v[164:167], v[198:201], v[84:87]
	v_mfma_f32_16x16x32_bf16 v[80:83], v[172:175], v[198:201], v[80:83]
	v_mfma_f32_16x16x32_bf16 v[68:71], v[164:167], v[206:209], v[68:71]
	v_mfma_f32_16x16x32_bf16 v[64:67], v[172:175], v[206:209], v[64:67]
	s_setprio 0
	s_barrier
; #define PG8_STAGE(bufoff, gbase, voff, p64) do { _Pragma("unroll") for (int _i = 0; _i < 2; ++_i) { \
;         const char* _gb = (const char*)(gbase) + (size_t)_i * (p64); const unsigned _la = ldsbase + (unsigned)(bufoff) + (unsigned)_i * 8192u; \
;         asm volatile("s_mov_b32 m0, %0\n\ts_nop 0\n\tglobal_load_lds_dwordx4 %1, %2" :: "s"(_la), "v"(voff), "s"(_gb) : "memory"); } } while (0)
; #define PG8_LDA(dst, b, h) do { _Pragma("unroll") for (int m = 0; m < 4; ++m) _Pragma("unroll") for (int k = 0; k < 2; ++k) dst[m][k] = *(const LAS bf16x8*)(lds + PG8_SA(b, h) + aoff + m * 2048 + k * 1024); } while (0)
; #define PG8_LDB(dst, b, h) do { _Pragma("unroll") for (int n = 0; n < 2; ++n) _Pragma("unroll") for (int k = 0; k < 2; ++k) dst[n][k] = *(const LAS bf16x8*)(lds + PG8_SB(b, h) + boff + n * 2048 + k * 1024); } while (0)
; #define PG8_MMA(ai, bj, At, Bt) do { __builtin_amdgcn_s_setprio(1); _Pragma("unroll") for (int m = 0; m < 4; ++m) _Pragma("unroll") for (int n = 0; n < 2; ++n) _Pragma("unroll") for (int k = 0; k < 2; ++k) \
;         acc[ai][bj][m][n] = __builtin_amdgcn_mfma_f32_16x16x32_bf16(Bt[n][k], At[m][k], acc[ai][bj][m][n], 0, 0, 0); __builtin_amdgcn_s_setprio(0); } while (0)
; #define PG8_WAIT_V(n) asm volatile("s_waitcnt vmcnt(" #n ")" ::: "memory")
; #define PG8_WAIT_L(n) asm volatile("s_waitcnt lgkmcnt(" #n ")" ::: "memory")
; #define PG8_BAR __builtin_amdgcn_s_barrier()
; #define PG8_SCHED __builtin_amdgcn_sched_barrier(0)
; template <class Epi, class Sched>
; __device__ __forceinline__ void gemm_phase(LAS unsigned char* lds, const Sched& S, const Epi& E) {
;     ...
;             PG8_LDA(At, 0, 1); PG8_STAGE(PG8_SB(0, 0), b2, vB2, hB2 / 2); PG8_STAGE(PG8_SB(0, 1), b2 + hB2, vB2, hB2 / 2); PG8_STAGE(PG8_SA(0, 0), a2, vA2, hA2 / 2);
;             PG8_WAIT_V(8); PG8_WAIT_L(0); PG8_BAR; PG8_MMA(1, 0, At, B0); PG8_MMA(1, 1, At, B1); PG8_BAR; PG8_SCHED;
;             PG8_LDB(B0, 1, 0); PG8_LDB(B1, 1, 1); PG8_SCHED; PG8_LDA(At, 1, 0); PG8_STAGE(PG8_SA(0, 1), a2 + hA2, vA2, hA2 / 2);
;             PG8_WAIT_V(8); PG8_WAIT_L(0); PG8_BAR; PG8_MMA(0, 0, At, B0); PG8_MMA(0, 1, At, B1); PG8_BAR; PG8_SCHED;
	s_add_u32 s62, s40, 0x20000
	ds_read_b128 v[178:181], v140 offset:16384
	ds_read_b128 v[182:185], v140 offset:17408
	ds_read_b128 v[186:189], v140 offset:18432
	ds_read_b128 v[190:193], v140 offset:19456
	ds_read_b128 v[194:197], v140 offset:20480
	ds_read_b128 v[198:201], v140 offset:21504
	ds_read_b128 v[202:205], v140 offset:22528
	ds_read_b128 v[206:209], v140 offset:23552
	s_mov_b32 m0, s36
	s_nop 0
	global_load_lds_dwordx4 v135, s[40:41]
	s_mov_b32 m0, s37
	s_addc_u32 s63, s41, 0
	global_load_lds_dwordx4 v135, s[62:63]
	s_add_u32 s62, s40, 0x40000
	s_mov_b32 m0, s42
	s_addc_u32 s63, s41, 0
	global_load_lds_dwordx4 v135, s[62:63]
	s_add_u32 s62, s40, 0x60000
	s_mov_b32 m0, s43
	s_addc_u32 s63, s41, 0
	global_load_lds_dwordx4 v135, s[62:63]
	s_mov_b32 m0, s34
	s_nop 0
	global_load_lds_dwordx4 v134, s[26:27]
	s_add_u32 s62, s26, 0x20000
	s_mov_b32 m0, s44
	s_addc_u32 s63, s27, 0
	global_load_lds_dwordx4 v134, s[62:63]
	s_waitcnt vmcnt(8)
	s_waitcnt lgkmcnt(0)
	s_barrier
	s_setprio 1
	v_mfma_f32_16x16x32_bf16 v[60:63], v[144:147], v[178:181], v[60:63]
	v_mfma_f32_16x16x32_bf16 v[56:59], v[152:155], v[178:181], v[56:59]
	v_mfma_f32_16x16x32_bf16 v[44:47], v[144:147], v[186:189], v[44:47]
	v_mfma_f32_16x16x32_bf16 v[40:43], v[152:155], v[186:189], v[40:43]
	v_mfma_f32_16x16x32_bf16 v[28:31], v[144:147], v[194:197], v[28:31]
	v_mfma_f32_16x16x32_bf16 v[24:27], v[152:155], v[194:197], v[24:27]
	v_mfma_f32_16x16x32_bf16 v[12:15], v[144:147], v[202:205], v[12:15]
	v_mfma_f32_16x16x32_bf16 v[8:11], v[152:155], v[202:205], v[8:11]
	v_mfma_f32_16x16x32_bf16 v[60:63], v[148:151], v[182:185], v[60:63]
	v_mfma_f32_16x16x32_bf16 v[56:59], v[156:159], v[182:185], v[56:59]
	v_mfma_f32_16x16x32_bf16 v[44:47], v[148:151], v[190:193], v[44:47]
	v_mfma_f32_16x16x32_bf16 v[40:43], v[156:159], v[190:193], v[40:43]
	v_mfma_f32_16x16x32_bf16 v[28:31], v[148:151], v[198:201], v[28:31]
	v_mfma_f32_16x16x32_bf16 v[24:27], v[156:159], v[198:201], v[24:27]
	v_mfma_f32_16x16x32_bf16 v[12:15], v[148:151], v[206:209], v[12:15]
	v_mfma_f32_16x16x32_bf16 v[8:11], v[156:159], v[206:209], v[8:11]
	v_mfma_f32_16x16x32_bf16 v[52:55], v[160:163], v[178:181], v[52:55]
	v_mfma_f32_16x16x32_bf16 v[48:51], v[168:171], v[178:181], v[48:51]
	v_mfma_f32_16x16x32_bf16 v[36:39], v[160:163], v[186:189], v[36:39]
	v_mfma_f32_16x16x32_bf16 v[32:35], v[168:171], v[186:189], v[32:35]
	v_mfma_f32_16x16x32_bf16 v[20:23], v[160:163], v[194:197], v[20:23]
	v_mfma_f32_16x16x32_bf16 v[16:19], v[168:171], v[194:197], v[16:19]
	v_mfma_f32_16x16x32_bf16 v[4:7], v[160:163], v[202:205], v[4:7]
	v_mfma_f32_16x16x32_bf16 v[0:3], v[168:171], v[202:205], v[0:3]
	v_mfma_f32_16x16x32_bf16 v[52:55], v[164:167], v[182:185], v[52:55]
	v_mfma_f32_16x16x32_bf16 v[48:51], v[172:175], v[182:185], v[48:51]
	v_mfma_f32_16x16x32_bf16 v[36:39], v[164:167], v[190:193], v[36:39]
	v_mfma_f32_16x16x32_bf16 v[32:35], v[172:175], v[190:193], v[32:35]
	v_mfma_f32_16x16x32_bf16 v[20:23], v[164:167], v[198:201], v[20:23]
	v_mfma_f32_16x16x32_bf16 v[16:19], v[172:175], v[198:201], v[16:19]
	v_mfma_f32_16x16x32_bf16 v[4:7], v[164:167], v[206:209], v[4:7]
	v_mfma_f32_16x16x32_bf16 v[0:3], v[172:175], v[206:209], v[0:3]
	s_setprio 0
	s_barrier
	ds_read_b128 v[144:147], v141
	ds_read_b128 v[148:151], v141 offset:1024
	ds_read_b128 v[152:155], v141 offset:2048
	ds_read_b128 v[156:159], v141 offset:3072
	ds_read_b128 v[160:163], v142
	ds_read_b128 v[164:167], v142 offset:1024
	ds_read_b128 v[168:171], v142 offset:2048
	ds_read_b128 v[172:175], v142 offset:3072
	ds_read_b128 v[178:181], v140 offset:32768
	ds_read_b128 v[182:185], v140 offset:33792
	ds_read_b128 v[186:189], v140 offset:34816
	ds_read_b128 v[190:193], v140 offset:35840
	ds_read_b128 v[194:197], v140 offset:36864
	ds_read_b128 v[198:201], v140 offset:37888
	ds_read_b128 v[202:205], v140 offset:38912
	ds_read_b128 v[206:209], v140 offset:39936
	s_add_u32 s62, s26, 0x40000
	s_mov_b32 m0, s45
	s_addc_u32 s63, s27, 0
	global_load_lds_dwordx4 v134, s[62:63]
	s_add_u32 s62, s26, 0x60000
	s_mov_b32 m0, s46
	s_addc_u32 s63, s27, 0
	global_load_lds_dwordx4 v134, s[62:63]
	s_waitcnt vmcnt(8)
	s_waitcnt lgkmcnt(0)
	s_barrier
; #define PG8_STAGE(bufoff, gbase, voff, p64) do { _Pragma("unroll") for (int _i = 0; _i < 2; ++_i) { \
;         const char* _gb = (const char*)(gbase) + (size_t)_i * (p64); const unsigned _la = ldsbase + (unsigned)(bufoff) + (unsigned)_i * 8192u; \
;         asm volatile("s_mov_b32 m0, %0\n\ts_nop 0\n\tglobal_load_lds_dwordx4 %1, %2" :: "s"(_la), "v"(voff), "s"(_gb) : "memory"); } } while (0)
; #define PG8_LDA(dst, b, h) do { _Pragma("unroll") for (int m = 0; m < 4; ++m) _Pragma("unroll") for (int k = 0; k < 2; ++k) dst[m][k] = *(const LAS bf16x8*)(lds + PG8_SA(b, h) + aoff + m * 2048 + k * 1024); } while (0)
; #define PG8_MMA(ai, bj, At, Bt) do { __builtin_amdgcn_s_setprio(1); _Pragma("unroll") for (int m = 0; m < 4; ++m) _Pragma("unroll") for (int n = 0; n < 2; ++n) _Pragma("unroll") for (int k = 0; k < 2; ++k) \
;         acc[ai][bj][m][n] = __builtin_amdgcn_mfma_f32_16x16x32_bf16(Bt[n][k], At[m][k], acc[ai][bj][m][n], 0, 0, 0); __builtin_amdgcn_s_setprio(0); } while (0)
; #define PG8_WAIT_V(n) asm volatile("s_waitcnt vmcnt(" #n ")" ::: "memory")
; #define PG8_WAIT_L(n) asm volatile("s_waitcnt lgkmcnt(" #n ")" ::: "memory")
; #define PG8_BAR __builtin_amdgcn_s_barrier()
; #define PG8_SCHED __builtin_amdgcn_sched_barrier(0)
; template <class Epi, class Sched>
; __device__ __forceinline__ void gemm_phase(LAS unsigned char* lds, const Sched& S, const Epi& E) {
;     ...
;             PG8_WAIT_V(8); PG8_WAIT_L(0); PG8_BAR; PG8_MMA(0, 0, At, B0); PG8_MMA(0, 1, At, B1); PG8_BAR; PG8_SCHED;
;             PG8_LDA(At, 1, 1); PG8_STAGE(PG8_SB(1, 0), b3, vB2, hB2 / 2); PG8_STAGE(PG8_SB(1, 1), b3 + hB2, vB2, hB2 / 2); PG8_STAGE(PG8_SA(1, 0), a3, vA2, hA2 / 2);
;             PG8_WAIT_V(8); PG8_WAIT_L(0); PG8_BAR; PG8_MMA(1, 0, At, B0); PG8_MMA(1, 1, At, B1); PG8_BAR; PG8_SCHED;
;         }
;         if (wr == 0) PG8_BAR;
	s_setprio 1
	v_mfma_f32_16x16x32_bf16 v[124:127], v[144:147], v[178:181], v[124:127]
	v_mfma_f32_16x16x32_bf16 v[120:123], v[152:155], v[178:181], v[120:123]
	v_mfma_f32_16x16x32_bf16 v[108:111], v[144:147], v[186:189], v[108:111]
	v_mfma_f32_16x16x32_bf16 v[104:107], v[152:155], v[186:189], v[104:107]
	v_mfma_f32_16x16x32_bf16 v[92:95], v[144:147], v[194:197], v[92:95]
	v_mfma_f32_16x16x32_bf16 v[88:91], v[152:155], v[194:197], v[88:91]
	v_mfma_f32_16x16x32_bf16 v[76:79], v[144:147], v[202:205], v[76:79]
	v_mfma_f32_16x16x32_bf16 v[72:75], v[152:155], v[202:205], v[72:75]
	v_mfma_f32_16x16x32_bf16 v[124:127], v[148:151], v[182:185], v[124:127]
	v_mfma_f32_16x16x32_bf16 v[120:123], v[156:159], v[182:185], v[120:123]
	v_mfma_f32_16x16x32_bf16 v[108:111], v[148:151], v[190:193], v[108:111]
	v_mfma_f32_16x16x32_bf16 v[104:107], v[156:159], v[190:193], v[104:107]
	v_mfma_f32_16x16x32_bf16 v[92:95], v[148:151], v[198:201], v[92:95]
	v_mfma_f32_16x16x32_bf16 v[88:91], v[156:159], v[198:201], v[88:91]
	v_mfma_f32_16x16x32_bf16 v[76:79], v[148:151], v[206:209], v[76:79]
	v_mfma_f32_16x16x32_bf16 v[72:75], v[156:159], v[206:209], v[72:75]
	v_mfma_f32_16x16x32_bf16 v[116:119], v[160:163], v[178:181], v[116:119]
	v_mfma_f32_16x16x32_bf16 v[112:115], v[168:171], v[178:181], v[112:115]
	v_mfma_f32_16x16x32_bf16 v[100:103], v[160:163], v[186:189], v[100:103]
	v_mfma_f32_16x16x32_bf16 v[96:99], v[168:171], v[186:189], v[96:99]
	v_mfma_f32_16x16x32_bf16 v[84:87], v[160:163], v[194:197], v[84:87]
	v_mfma_f32_16x16x32_bf16 v[80:83], v[168:171], v[194:197], v[80:83]
	v_mfma_f32_16x16x32_bf16 v[68:71], v[160:163], v[202:205], v[68:71]
	v_mfma_f32_16x16x32_bf16 v[64:67], v[168:171], v[202:205], v[64:67]
	v_mfma_f32_16x16x32_bf16 v[116:119], v[164:167], v[182:185], v[116:119]
	v_mfma_f32_16x16x32_bf16 v[112:115], v[172:175], v[182:185], v[112:115]
	v_mfma_f32_16x16x32_bf16 v[100:103], v[164:167], v[190:193], v[100:103]
	v_mfma_f32_16x16x32_bf16 v[96:99], v[172:175], v[190:193], v[96:99]
	v_mfma_f32_16x16x32_bf16 v[84:87], v[164:167], v[198:201], v[84:87]
	v_mfma_f32_16x16x32_bf16 v[80:83], v[172:175], v[198:201], v[80:83]
	v_mfma_f32_16x16x32_bf16 v[68:71], v[164:167], v[206:209], v[68:71]
	v_mfma_f32_16x16x32_bf16 v[64:67], v[172:175], v[206:209], v[64:67]
	s_setprio 0
	s_barrier
	s_add_u32 s62, s40, 0x80
	s_addc_u32 s63, s41, 0
	ds_read_b128 v[178:181], v140 offset:49152
	ds_read_b128 v[182:185], v140 offset:50176
	ds_read_b128 v[186:189], v140 offset:51200
	ds_read_b128 v[190:193], v140 offset:52224
	ds_read_b128 v[194:197], v140 offset:53248
	ds_read_b128 v[198:201], v140 offset:54272
	ds_read_b128 v[202:205], v140 offset:55296
	ds_read_b128 v[206:209], v140 offset:56320
	s_mov_b32 m0, s48
	s_nop 0
	global_load_lds_dwordx4 v135, s[62:63]
	s_add_u32 s62, s40, 0x20080
	s_mov_b32 m0, s49
	s_addc_u32 s63, s41, 0
	global_load_lds_dwordx4 v135, s[62:63]
	s_add_u32 s62, s40, 0x40080
	s_mov_b32 m0, s52
	s_addc_u32 s63, s41, 0
	global_load_lds_dwordx4 v135, s[62:63]
	s_add_u32 s40, s40, 0x60080
	s_mov_b32 m0, s53
	s_addc_u32 s41, s41, 0
	global_load_lds_dwordx4 v135, s[40:41]
	s_mov_b32 m0, s50
	s_nop 0
	global_load_lds_dwordx4 v134, s[38:39]
	s_add_u32 s26, s26, 0x20080
	s_mov_b32 m0, s51
	s_addc_u32 s27, s27, 0
	global_load_lds_dwordx4 v134, s[26:27]
	s_waitcnt vmcnt(8)
	s_waitcnt lgkmcnt(0)
	s_barrier
	s_setprio 1
	v_mfma_f32_16x16x32_bf16 v[60:63], v[144:147], v[178:181], v[60:63]
	v_mfma_f32_16x16x32_bf16 v[56:59], v[152:155], v[178:181], v[56:59]
	v_mfma_f32_16x16x32_bf16 v[44:47], v[144:147], v[186:189], v[44:47]
	v_mfma_f32_16x16x32_bf16 v[40:43], v[152:155], v[186:189], v[40:43]
	v_mfma_f32_16x16x32_bf16 v[28:31], v[144:147], v[194:197], v[28:31]
	v_mfma_f32_16x16x32_bf16 v[24:27], v[152:155], v[194:197], v[24:27]
	v_mfma_f32_16x16x32_bf16 v[12:15], v[144:147], v[202:205], v[12:15]
	v_mfma_f32_16x16x32_bf16 v[8:11], v[152:155], v[202:205], v[8:11]
	v_mfma_f32_16x16x32_bf16 v[60:63], v[148:151], v[182:185], v[60:63]
	v_mfma_f32_16x16x32_bf16 v[56:59], v[156:159], v[182:185], v[56:59]
	v_mfma_f32_16x16x32_bf16 v[44:47], v[148:151], v[190:193], v[44:47]
	v_mfma_f32_16x16x32_bf16 v[40:43], v[156:159], v[190:193], v[40:43]
	v_mfma_f32_16x16x32_bf16 v[28:31], v[148:151], v[198:201], v[28:31]
	v_mfma_f32_16x16x32_bf16 v[24:27], v[156:159], v[198:201], v[24:27]
	v_mfma_f32_16x16x32_bf16 v[12:15], v[148:151], v[206:209], v[12:15]
	v_mfma_f32_16x16x32_bf16 v[8:11], v[156:159], v[206:209], v[8:11]
	v_mfma_f32_16x16x32_bf16 v[52:55], v[160:163], v[178:181], v[52:55]
	v_mfma_f32_16x16x32_bf16 v[48:51], v[168:171], v[178:181], v[48:51]
	v_mfma_f32_16x16x32_bf16 v[36:39], v[160:163], v[186:189], v[36:39]
	v_mfma_f32_16x16x32_bf16 v[32:35], v[168:171], v[186:189], v[32:35]
	v_mfma_f32_16x16x32_bf16 v[20:23], v[160:163], v[194:197], v[20:23]
	v_mfma_f32_16x16x32_bf16 v[16:19], v[168:171], v[194:197], v[16:19]
	v_mfma_f32_16x16x32_bf16 v[4:7], v[160:163], v[202:205], v[4:7]
	v_mfma_f32_16x16x32_bf16 v[0:3], v[168:171], v[202:205], v[0:3]
	v_mfma_f32_16x16x32_bf16 v[52:55], v[164:167], v[182:185], v[52:55]
	v_mfma_f32_16x16x32_bf16 v[48:51], v[172:175], v[182:185], v[48:51]
	v_mfma_f32_16x16x32_bf16 v[36:39], v[164:167], v[190:193], v[36:39]
	v_mfma_f32_16x16x32_bf16 v[32:35], v[172:175], v[190:193], v[32:35]
	v_mfma_f32_16x16x32_bf16 v[20:23], v[164:167], v[198:201], v[20:23]
	v_mfma_f32_16x16x32_bf16 v[16:19], v[172:175], v[198:201], v[16:19]
	v_mfma_f32_16x16x32_bf16 v[4:7], v[164:167], v[206:209], v[4:7]
	v_mfma_f32_16x16x32_bf16 v[0:3], v[172:175], v[206:209], v[0:3]
	s_setprio 0
	s_barrier
	s_add_i32 s61, s61, 2
	s_add_u32 s24, s24, 0x100
	s_addc_u32 s25, s25, 0
	s_add_u32 s59, s59, 0x100
	s_addc_u32 s60, s60, 0
	s_cmp_gt_u32 s61, 13
	s_cbranch_scc0 .LBB0_1485
	s_and_b64 vcc, exec, s[14:15]
	s_cbranch_vccz .LBB0_1488
	s_barrier

; #define PG8_WAIT_V(n) asm volatile("s_waitcnt vmcnt(" #n ")" ::: "memory")
; __device__ __forceinline__ bool tile_of(long Lidx, int nM, int nN, int& pm, int& pn) {
;     const int nwg = nM * nN; if (Lidx >= nwg) return false;
;     int wgid = (int)Lidx; { const int q = nwg / NXCD, r = nwg % NXCD, xcd = wgid % NXCD, off = wgid / NXCD; wgid = (xcd < r ? xcd * (q + 1) : r * (q + 1) + (xcd - r) * q) + off; }
;     const int nig = WGM * nN, gid = wgid / nig, fm = gid * WGM, gsz = (nM - fm) < WGM ? (nM - fm) : WGM;
;     pm = fm + ((wgid % nig) % gsz); pn = (wgid % nig) / gsz; return true;
; template <class Epi, class Sched>
; __device__ __forceinline__ void gemm_phase(LAS unsigned char* lds, const Sched& S, const Epi& E) {
;     int tid = threadIdx.x; asm volatile("" : "+v"(tid));
;     const int wid = __builtin_amdgcn_readfirstlane(tid >> 6), lane = tid & 63, wr = wid >> 2, wc = wid & 3, fr = lane & 15, fq = lane >> 4;
;     int sR, sRb, sC2;
;     { int R, C; stage_rc(tid * 16, R, C); sR = R; sRb = (R & ~31) + perm32(R & 31); sC2 = C * 2; }
;     const size_t kstep = (size_t)(BK * 2);
;     const unsigned ldsbase = (unsigned)(size_t)lds + (unsigned)wid * 1024u;
;     const int aoff = lds_byte(wr * 64 + fr, fq * 8), boff = lds_byte(wc * 32 + fr, fq * 8);
;     ...
;     int ui = 0;
;     const char* cA; const char* cB; unsigned hA, hB; int nt; unsigned voffA, voffB;
;     { Unit u0; if (!S.next(0, u0)) return;
;       cA = u0.A; cB = u0.B; hA = (unsigned)HALF * u0.lda2; hB = (unsigned)HALF * u0.ldb2; nt = u0.nt;
;       voffA = (unsigned)(sR * u0.lda2 + sC2); voffB = (unsigned)(sRb * u0.ldb2 + sC2); }
;     f32x4 acc[2][2][4][2];
; #pragma unroll
;     for (int a = 0; a < 2; ++a)
; #pragma unroll
;         for (int b = 0; b < 2; ++b)
; #pragma unroll
;             for (int m = 0; m < 4; ++m)
; #pragma unroll
;                 for (int n = 0; n < 2; ++n) acc[a][b][m][n] = (f32x4){0.f, 0.f, 0.f, 0.f};
;     bf16x8 At[4][2], B0[2][2], B1[2][2];
;     PG8_STAGE(PG8_SB(0, 0), cB, voffB, hB / 2); PG8_STAGE(PG8_SB(0, 1), cB + hB, voffB, hB / 2); PG8_STAGE(PG8_SA(0, 0), cA, voffA, hA / 2); PG8_STAGE(PG8_SA(0, 1), cA + hA, voffA, hA / 2);
;     if (wr == 1) PG8_BAR;
;     PG8_WAIT_V(2); PG8_BAR;
;     PG8_STAGE(PG8_SB(1, 0), cB + kstep, voffB, hB / 2); PG8_STAGE(PG8_SA(1, 0), cA + kstep, voffA, hA / 2); PG8_STAGE(PG8_SB(1, 1), cB + hB + kstep, voffB, hB / 2);
.LBB0_1546:
	s_or_b64 exec, exec, s[6:7]
	s_mov_b64 s[6:7], s[0:1]
	s_waitcnt lgkmcnt(0)
	v_mov_b32_e32 v0, v176
	s_barrier
	v_readlane_b32 s4, v255, 7
	v_mov_b32_e32 v0, v176
	v_readlane_b32 s5, v255, 8
	s_and_b64 vcc, exec, s[4:5]
	v_readfirstlane_b32 s12, v0
	s_cbranch_vccnz .LBB0_1572
	s_load_dwordx2 s[8:9], s[6:7], 0xd0
	v_bfe_i32 v2, v0, 27, 1
	v_lshlrev_b32_e32 v1, 4, v0
	v_lshrrev_b32_e32 v2, 22, v2
	v_add_u32_e32 v2, v1, v2
	s_waitcnt lgkmcnt(0)
	s_add_u32 s4, s8, 0x8900000
	s_addc_u32 s5, s9, 0
	s_add_u32 s31, s8, 0x3780000
	s_addc_u32 s33, s9, 0
	s_ashr_i32 s6, s12, 6
	s_lshl_b32 s10, s6, 10
	s_add_i32 s34, s10, 0
	s_lshr_b32 s10, s73, 27
	s_add_i32 s10, s72, s10
	s_ashr_i32 s11, s10, 5
	s_and_b32 s10, s10, 0xffe0
	s_sub_i32 s10, s72, s10
	v_and_b32_e32 v2, 0xfffffc00, v2
	s_bfe_i32 s13, s10, 0x80000
	v_sub_u32_e32 v1, v1, v2
	s_bfe_u32 s13, s13, 0x3000c
	v_lshrrev_b32_e32 v2, 4, v1
	v_ashrrev_i32_e32 v4, 31, v0
	s_add_i32 s13, s10, s13
	v_bitop3_b32 v1, v2, v1, 32 bitop3:0x6c
	v_lshrrev_b32_e32 v4, 26, v4
	s_bfe_i32 s14, s13, 0x80000
	s_and_b32 s13, s13, 0xf8
	v_ashrrev_i32_e32 v2, 31, v1
	v_add_u32_e32 v4, v0, v4
	s_sub_i32 s10, s10, s13
	v_lshrrev_b32_e32 v2, 26, v2
	v_ashrrev_i32_e32 v4, 6, v4
	s_lshl_b32 s11, s11, 3
	s_sext_i32_i8 s10, s10
	v_add_u32_e32 v2, v1, v2
	v_lshlrev_b32_e32 v5, 3, v4
	s_add_i32 s10, s11, s10
	s_ashr_i32 s7, s12, 8
	v_ashrrev_i32_e32 v3, 6, v2
	v_and_b32_e32 v5, -16, v5
	v_and_b32_e32 v2, 0xc0, v2
	s_mul_hi_i32 s11, s10, 0x160000
	s_mul_i32 s10, s10, 0x160000
	v_add_u32_e32 v5, v3, v5
	v_sub_u32_e32 v1, v1, v2
	v_mov_b32_e32 v2, 1
	s_sext_i32_i16 s14, s14
	s_add_u32 s22, s4, s10
	v_lshrrev_b32_e32 v7, 2, v5
	v_lshlrev_b32_e32 v4, 5, v4
	v_ashrrev_i16_sdwa v1, v2, sext(v1) dst_sel:DWORD dst_unused:UNUSED_PAD src0_sel:DWORD src1_sel:BYTE_0
	s_addc_u32 s23, s5, s11
	s_ashr_i32 s10, s14, 3
	v_and_b32_e32 v7, 4, v7
	v_and_b32_e32 v4, 32, v4
	v_bfe_i32 v1, v1, 0, 16
	s_mul_hi_i32 s11, s10, 0x160000
	s_mul_i32 s10, s10, 0x160000
	v_lshlrev_b32_e32 v6, 1, v5
	v_and_or_b32 v3, v3, 3, v7
	s_add_u32 s24, s31, s10
	v_add_lshl_u32 v2, v4, v1, 1
	s_movk_i32 s13, 0x1600
	v_and_b32_e32 v6, 24, v6
	s_addc_u32 s25, s33, s11
	v_and_b32_e32 v1, 0x7fffe0, v5
	v_mad_u64_u32 v[144:145], s[10:11], v5, s13, v[2:3]
	s_add_i32 s35, s34, 0x10000
	v_or3_b32 v1, v6, v3, v1
	s_add_u32 s10, s24, 0x58000
	v_mad_u32_u24 v145, v1, s13, v2
	s_mov_b32 m0, s35
	s_nop 0
	global_load_lds_dwordx4 v145, s[24:25]
	s_addc_u32 s11, s25, 0
	s_add_i32 s36, s34, 0x12000
	s_mov_b32 m0, s36
	s_nop 0
	global_load_lds_dwordx4 v145, s[10:11]
	s_add_u32 s10, s24, 0xb0000
	s_addc_u32 s11, s25, 0
	s_add_i32 s37, s34, 0x14000
	s_mov_b32 m0, s37
	s_nop 0
	global_load_lds_dwordx4 v145, s[10:11]
	s_add_u32 s10, s24, 0x108000
	s_addc_u32 s11, s25, 0
	s_add_i32 s40, s34, 0x16000
	s_mov_b32 m0, s40
	s_nop 0
	global_load_lds_dwordx4 v145, s[10:11]
	s_mov_b32 m0, s34
	s_add_u32 s10, s22, 0x58000
	global_load_lds_dwordx4 v144, s[22:23]
	s_addc_u32 s11, s23, 0
	s_add_i32 s41, s34, 0x2000
	s_mov_b32 m0, s41
	s_nop 0
	global_load_lds_dwordx4 v144, s[10:11]
	s_add_u32 s10, s22, 0xb0000
	s_addc_u32 s11, s23, 0
	s_add_i32 s42, s34, 0x4000
	s_mov_b32 m0, s42
	s_nop 0
	global_load_lds_dwordx4 v144, s[10:11]
	s_add_u32 s14, s22, 0x108000
	s_addc_u32 s15, s23, 0
	s_add_i32 s43, s34, 0x6000
	s_mov_b32 m0, s43
	s_nop 0
	global_load_lds_dwordx4 v144, s[14:15]
	s_cmp_eq_u32 s7, 1
	s_mov_b32 s17, 0
	s_cselect_b64 s[10:11], -1, 0
	s_cmp_lg_u32 s7, 1
	s_cbranch_scc1 .LBB0_1549
	s_barrier

; #define PG8_STAGE(bufoff, gbase, voff, p64) do { _Pragma("unroll") for (int _i = 0; _i < 2; ++_i) { \
;         const char* _gb = (const char*)(gbase) + (size_t)_i * (p64); const unsigned _la = ldsbase + (unsigned)(bufoff) + (unsigned)_i * 8192u; \
;         asm volatile("s_mov_b32 m0, %0\n\ts_nop 0\n\tglobal_load_lds_dwordx4 %1, %2" :: "s"(_la), "v"(voff), "s"(_gb) : "memory"); } } while (0)
; #define PG8_LDA(dst, b, h) do { _Pragma("unroll") for (int m = 0; m < 4; ++m) _Pragma("unroll") for (int k = 0; k < 2; ++k) dst[m][k] = *(const LAS bf16x8*)(lds + PG8_SA(b, h) + aoff + m * 2048 + k * 1024); } while (0)
; #define PG8_LDB(dst, b, h) do { _Pragma("unroll") for (int n = 0; n < 2; ++n) _Pragma("unroll") for (int k = 0; k < 2; ++k) dst[n][k] = *(const LAS bf16x8*)(lds + PG8_SB(b, h) + boff + n * 2048 + k * 1024); } while (0)
; #define PG8_WAIT_V(n) asm volatile("s_waitcnt vmcnt(" #n ")" ::: "memory")
; #define PG8_WAIT_L(n) asm volatile("s_waitcnt lgkmcnt(" #n ")" ::: "memory")
; #define PG8_BAR __builtin_amdgcn_s_barrier()
; #define PG8_SCHED __builtin_amdgcn_sched_barrier(0)
; template <class Epi, class Sched>
; __device__ __forceinline__ void gemm_phase(LAS unsigned char* lds, const Sched& S, const Epi& E) {
;     ...
;         for (int t = 0; t < nt; t += 2) {
;             const bool last = (t == nt - 2);
;             const char* a1 = cA + (size_t)(t + 1) * kstep;
;             const char* a2 = last ? nA : cA + (size_t)(t + 2) * kstep; const char* b2 = last ? nB : cB + (size_t)(t + 2) * kstep;
;             const char* a3 = a2 + kstep; const char* b3 = b2 + kstep;
;             const unsigned vA2 = voffA, vB2 = voffB, hA2 = hA, hB2 = hB;
;             PG8_LDB(B0, 0, 0); PG8_LDB(B1, 0, 1); PG8_SCHED; PG8_LDA(At, 0, 0); PG8_STAGE(PG8_SA(1, 1), a1 + hA, voffA, hA / 2);
;             PG8_WAIT_V(8); PG8_WAIT_L(0); PG8_BAR; PG8_MMA(0, 0, At, B0); PG8_MMA(0, 1, At, B1); PG8_BAR; PG8_SCHED;
;     ...
;         if (!keep) {
; #pragma unroll
;             for (int a = 0; a < 2; ++a)
; #pragma unroll
;                 for (int b = 0; b < 2; ++b)
; #pragma unroll
;                     for (int m = 0; m < 4; ++m)
; #pragma unroll
;                         for (int n = 0; n < 2; ++n) acc[a][b][m][n] = (f32x4){0.f, 0.f, 0.f, 0.f};
;         }
;         cA = nA; cB = nB; nt = nnt; ++ui;
;         if (wr == 1) PG8_BAR;
.LBB0_1558:
	s_add_u32 s22, s22, 0xb0080
	s_addc_u32 s23, s23, 0
	s_add_u32 s59, s24, 0x100
	s_addc_u32 s60, s25, 0
	s_mov_b32 s61, -2
	v_mov_b64_e32 v[0:1], 0
	v_mov_b64_e32 v[2:3], 0
	v_mov_b64_e32 v[4:5], 0
	v_mov_b64_e32 v[6:7], 0
	s_waitcnt vmcnt(7)
	v_mov_b64_e32 v[8:9], 0
	v_mov_b64_e32 v[10:11], 0
	s_waitcnt vmcnt(6)
	v_mov_b64_e32 v[12:13], 0
	v_mov_b64_e32 v[14:15], 0
	s_waitcnt vmcnt(3)
	v_mov_b64_e32 v[16:17], 0
	v_mov_b64_e32 v[18:19], 0
	s_waitcnt vmcnt(2)
	v_mov_b64_e32 v[20:21], 0
	v_mov_b64_e32 v[22:23], 0
	s_waitcnt vmcnt(1)
	v_mov_b64_e32 v[24:25], 0
	v_mov_b64_e32 v[26:27], 0
	s_waitcnt vmcnt(0)
	v_mov_b64_e32 v[28:29], 0
	v_mov_b64_e32 v[30:31], 0
	v_mov_b64_e32 v[64:65], 0
	v_mov_b64_e32 v[66:67], 0
	v_mov_b64_e32 v[68:69], 0
	v_mov_b64_e32 v[70:71], 0
	v_mov_b64_e32 v[72:73], 0
	v_mov_b64_e32 v[74:75], 0
	v_mov_b64_e32 v[76:77], 0
	v_mov_b64_e32 v[78:79], 0
	v_mov_b64_e32 v[80:81], 0
	v_mov_b64_e32 v[82:83], 0
	v_mov_b64_e32 v[84:85], 0
	v_mov_b64_e32 v[86:87], 0
	v_mov_b64_e32 v[88:89], 0
	v_mov_b64_e32 v[90:91], 0
	v_mov_b64_e32 v[92:93], 0
	v_mov_b64_e32 v[94:95], 0
	v_mov_b64_e32 v[32:33], 0
	v_mov_b64_e32 v[34:35], 0
	v_mov_b64_e32 v[36:37], 0
	v_mov_b64_e32 v[38:39], 0
	v_mov_b64_e32 v[40:41], 0
	v_mov_b64_e32 v[42:43], 0
	v_mov_b64_e32 v[44:45], 0
	v_mov_b64_e32 v[46:47], 0
	v_mov_b64_e32 v[48:49], 0
	v_mov_b64_e32 v[50:51], 0
	v_mov_b64_e32 v[52:53], 0
	v_mov_b64_e32 v[54:55], 0
	v_mov_b64_e32 v[56:57], 0
	v_mov_b64_e32 v[58:59], 0
	v_mov_b64_e32 v[60:61], 0
	v_mov_b64_e32 v[62:63], 0
	v_mov_b64_e32 v[96:97], 0
	v_mov_b64_e32 v[98:99], 0
	v_mov_b64_e32 v[100:101], 0
	v_mov_b64_e32 v[102:103], 0
	v_mov_b64_e32 v[104:105], 0
	v_mov_b64_e32 v[106:107], 0
	v_mov_b64_e32 v[108:109], 0
	v_mov_b64_e32 v[110:111], 0
	v_mov_b64_e32 v[112:113], 0
	v_mov_b64_e32 v[114:115], 0
	v_mov_b64_e32 v[116:117], 0
	v_mov_b64_e32 v[118:119], 0
	v_mov_b64_e32 v[120:121], 0
	v_mov_b64_e32 v[122:123], 0
	v_mov_b64_e32 v[124:125], 0
	v_mov_b64_e32 v[126:127], 0
.LBB0_1559:
	ds_read_b128 v[128:131], v179
	ds_read_b128 v[132:135], v179 offset:1024
	ds_read_b128 v[136:139], v179 offset:2048
	ds_read_b128 v[140:143], v179 offset:3072
	ds_read_b128 v[150:153], v180
	ds_read_b128 v[154:157], v180 offset:1024
	ds_read_b128 v[158:161], v180 offset:2048
	ds_read_b128 v[162:165], v180 offset:3072
	s_add_u32 s24, s22, 0xfff50080
	s_addc_u32 s25, s23, -1
	s_cmp_eq_u32 s61, 40
	s_cselect_b32 s24, s18, s24
	s_cselect_b32 s25, s19, s25
	s_cselect_b32 s38, s20, s59
	s_cselect_b32 s39, s21, s60
	s_add_u32 s26, s24, 0x80
	s_addc_u32 s27, s25, 0
	ds_read_b128 v[166:169], v181
	ds_read_b128 v[170:173], v181 offset:1024
	ds_read_b128 v[184:187], v181 offset:2048
	ds_read_b128 v[188:191], v181 offset:3072
	ds_read_b128 v[192:195], v181 offset:4096
	ds_read_b128 v[196:199], v181 offset:5120
	ds_read_b128 v[200:203], v181 offset:6144
	ds_read_b128 v[204:207], v181 offset:7168
	s_mov_b32 m0, s54
	s_nop 0
	global_load_lds_dwordx4 v144, s[22:23]
	s_add_u32 s62, s22, 0x58000
	s_mov_b32 m0, s55
	s_addc_u32 s63, s23, 0
	global_load_lds_dwordx4 v144, s[62:63]
	s_waitcnt vmcnt(8)
	s_waitcnt lgkmcnt(0)
	s_barrier
	s_setprio 1
	v_mfma_f32_16x16x32_bf16 v[124:127], v[128:131], v[166:169], v[124:127]
	v_mfma_f32_16x16x32_bf16 v[120:123], v[136:139], v[166:169], v[120:123]
	v_mfma_f32_16x16x32_bf16 v[116:119], v[128:131], v[184:187], v[116:119]
	v_mfma_f32_16x16x32_bf16 v[112:115], v[136:139], v[184:187], v[112:115]
	v_mfma_f32_16x16x32_bf16 v[108:111], v[128:131], v[192:195], v[108:111]
	v_mfma_f32_16x16x32_bf16 v[104:107], v[136:139], v[192:195], v[104:107]
	v_mfma_f32_16x16x32_bf16 v[100:103], v[128:131], v[200:203], v[100:103]
	v_mfma_f32_16x16x32_bf16 v[96:99], v[136:139], v[200:203], v[96:99]
	v_mfma_f32_16x16x32_bf16 v[124:127], v[132:135], v[170:173], v[124:127]
	v_mfma_f32_16x16x32_bf16 v[120:123], v[140:143], v[170:173], v[120:123]
	v_mfma_f32_16x16x32_bf16 v[116:119], v[132:135], v[188:191], v[116:119]
	v_mfma_f32_16x16x32_bf16 v[112:115], v[140:143], v[188:191], v[112:115]
	v_mfma_f32_16x16x32_bf16 v[108:111], v[132:135], v[196:199], v[108:111]
	v_mfma_f32_16x16x32_bf16 v[104:107], v[140:143], v[196:199], v[104:107]
	v_mfma_f32_16x16x32_bf16 v[100:103], v[132:135], v[204:207], v[100:103]
	v_mfma_f32_16x16x32_bf16 v[96:99], v[140:143], v[204:207], v[96:99]
	v_mfma_f32_16x16x32_bf16 v[60:63], v[150:153], v[166:169], v[60:63]
	v_mfma_f32_16x16x32_bf16 v[56:59], v[158:161], v[166:169], v[56:59]
	v_mfma_f32_16x16x32_bf16 v[52:55], v[150:153], v[184:187], v[52:55]
	v_mfma_f32_16x16x32_bf16 v[48:51], v[158:161], v[184:187], v[48:51]
	v_mfma_f32_16x16x32_bf16 v[44:47], v[150:153], v[192:195], v[44:47]
	v_mfma_f32_16x16x32_bf16 v[40:43], v[158:161], v[192:195], v[40:43]
	v_mfma_f32_16x16x32_bf16 v[36:39], v[150:153], v[200:203], v[36:39]
	v_mfma_f32_16x16x32_bf16 v[32:35], v[158:161], v[200:203], v[32:35]
	v_mfma_f32_16x16x32_bf16 v[60:63], v[154:157], v[170:173], v[60:63]
	v_mfma_f32_16x16x32_bf16 v[56:59], v[162:165], v[170:173], v[56:59]
	v_mfma_f32_16x16x32_bf16 v[52:55], v[154:157], v[188:191], v[52:55]
	v_mfma_f32_16x16x32_bf16 v[48:51], v[162:165], v[188:191], v[48:51]
	v_mfma_f32_16x16x32_bf16 v[44:47], v[154:157], v[196:199], v[44:47]
	v_mfma_f32_16x16x32_bf16 v[40:43], v[162:165], v[196:199], v[40:43]
	v_mfma_f32_16x16x32_bf16 v[36:39], v[154:157], v[204:207], v[36:39]
	v_mfma_f32_16x16x32_bf16 v[32:35], v[162:165], v[204:207], v[32:35]
	s_setprio 0
	s_barrier
; #define PG8_STAGE(bufoff, gbase, voff, p64) do { _Pragma("unroll") for (int _i = 0; _i < 2; ++_i) { \
;         const char* _gb = (const char*)(gbase) + (size_t)_i * (p64); const unsigned _la = ldsbase + (unsigned)(bufoff) + (unsigned)_i * 8192u; \
;         asm volatile("s_mov_b32 m0, %0\n\ts_nop 0\n\tglobal_load_lds_dwordx4 %1, %2" :: "s"(_la), "v"(voff), "s"(_gb) : "memory"); } } while (0)
; #define PG8_LDA(dst, b, h) do { _Pragma("unroll") for (int m = 0; m < 4; ++m) _Pragma("unroll") for (int k = 0; k < 2; ++k) dst[m][k] = *(const LAS bf16x8*)(lds + PG8_SA(b, h) + aoff + m * 2048 + k * 1024); } while (0)
; #define PG8_LDB(dst, b, h) do { _Pragma("unroll") for (int n = 0; n < 2; ++n) _Pragma("unroll") for (int k = 0; k < 2; ++k) dst[n][k] = *(const LAS bf16x8*)(lds + PG8_SB(b, h) + boff + n * 2048 + k * 1024); } while (0)
; #define PG8_MMA(ai, bj, At, Bt) do { __builtin_amdgcn_s_setprio(1); _Pragma("unroll") for (int m = 0; m < 4; ++m) _Pragma("unroll") for (int n = 0; n < 2; ++n) _Pragma("unroll") for (int k = 0; k < 2; ++k) \
;         acc[ai][bj][m][n] = __builtin_amdgcn_mfma_f32_16x16x32_bf16(Bt[n][k], At[m][k], acc[ai][bj][m][n], 0, 0, 0); __builtin_amdgcn_s_setprio(0); } while (0)
; #define PG8_WAIT_V(n) asm volatile("s_waitcnt vmcnt(" #n ")" ::: "memory")
; #define PG8_WAIT_L(n) asm volatile("s_waitcnt lgkmcnt(" #n ")" ::: "memory")
; #define PG8_BAR __builtin_amdgcn_s_barrier()
; #define PG8_SCHED __builtin_amdgcn_sched_barrier(0)
; template <class Epi, class Sched>
; __device__ __forceinline__ void gemm_phase(LAS unsigned char* lds, const Sched& S, const Epi& E) {
;     ...
;             PG8_LDA(At, 0, 1); PG8_STAGE(PG8_SB(0, 0), b2, vB2, hB2 / 2); PG8_STAGE(PG8_SB(0, 1), b2 + hB2, vB2, hB2 / 2); PG8_STAGE(PG8_SA(0, 0), a2, vA2, hA2 / 2);
;             PG8_WAIT_V(8); PG8_WAIT_L(0); PG8_BAR; PG8_MMA(1, 0, At, B0); PG8_MMA(1, 1, At, B1); PG8_BAR; PG8_SCHED;
;             PG8_LDB(B0, 1, 0); PG8_LDB(B1, 1, 1); PG8_SCHED; PG8_LDA(At, 1, 0); PG8_STAGE(PG8_SA(0, 1), a2 + hA2, vA2, hA2 / 2);
;             PG8_WAIT_V(8); PG8_WAIT_L(0); PG8_BAR; PG8_MMA(0, 0, At, B0); PG8_MMA(0, 1, At, B1); PG8_BAR; PG8_SCHED;
	s_add_u32 s62, s38, 0x58000
	ds_read_b128 v[166:169], v181 offset:16384
	ds_read_b128 v[170:173], v181 offset:17408
	ds_read_b128 v[184:187], v181 offset:18432
	ds_read_b128 v[188:191], v181 offset:19456
	ds_read_b128 v[192:195], v181 offset:20480
	ds_read_b128 v[196:199], v181 offset:21504
	ds_read_b128 v[200:203], v181 offset:22528
	ds_read_b128 v[204:207], v181 offset:23552
	s_mov_b32 m0, s35
	s_nop 0
	global_load_lds_dwordx4 v145, s[38:39]
	s_mov_b32 m0, s36
	s_addc_u32 s63, s39, 0
	global_load_lds_dwordx4 v145, s[62:63]
	s_add_u32 s62, s38, 0xb0000
	s_mov_b32 m0, s37
	s_addc_u32 s63, s39, 0
	global_load_lds_dwordx4 v145, s[62:63]
	s_add_u32 s62, s38, 0x108000
	s_mov_b32 m0, s40
	s_addc_u32 s63, s39, 0
	global_load_lds_dwordx4 v145, s[62:63]
	s_mov_b32 m0, s34
	s_nop 0
	global_load_lds_dwordx4 v144, s[24:25]
	s_add_u32 s62, s24, 0x58000
	s_mov_b32 m0, s41
	s_addc_u32 s63, s25, 0
	global_load_lds_dwordx4 v144, s[62:63]
	s_waitcnt vmcnt(8)
	s_waitcnt lgkmcnt(0)
	s_barrier
	s_setprio 1
	v_mfma_f32_16x16x32_bf16 v[92:95], v[128:131], v[166:169], v[92:95]
	v_mfma_f32_16x16x32_bf16 v[88:91], v[136:139], v[166:169], v[88:91]
	v_mfma_f32_16x16x32_bf16 v[84:87], v[128:131], v[184:187], v[84:87]
	v_mfma_f32_16x16x32_bf16 v[80:83], v[136:139], v[184:187], v[80:83]
	v_mfma_f32_16x16x32_bf16 v[76:79], v[128:131], v[192:195], v[76:79]
	v_mfma_f32_16x16x32_bf16 v[72:75], v[136:139], v[192:195], v[72:75]
	v_mfma_f32_16x16x32_bf16 v[68:71], v[128:131], v[200:203], v[68:71]
	v_mfma_f32_16x16x32_bf16 v[64:67], v[136:139], v[200:203], v[64:67]
	v_mfma_f32_16x16x32_bf16 v[92:95], v[132:135], v[170:173], v[92:95]
	v_mfma_f32_16x16x32_bf16 v[88:91], v[140:143], v[170:173], v[88:91]
	v_mfma_f32_16x16x32_bf16 v[84:87], v[132:135], v[188:191], v[84:87]
	v_mfma_f32_16x16x32_bf16 v[80:83], v[140:143], v[188:191], v[80:83]
	v_mfma_f32_16x16x32_bf16 v[76:79], v[132:135], v[196:199], v[76:79]
	v_mfma_f32_16x16x32_bf16 v[72:75], v[140:143], v[196:199], v[72:75]
	v_mfma_f32_16x16x32_bf16 v[68:71], v[132:135], v[204:207], v[68:71]
	v_mfma_f32_16x16x32_bf16 v[64:67], v[140:143], v[204:207], v[64:67]
	v_mfma_f32_16x16x32_bf16 v[28:31], v[150:153], v[166:169], v[28:31]
	v_mfma_f32_16x16x32_bf16 v[24:27], v[158:161], v[166:169], v[24:27]
	v_mfma_f32_16x16x32_bf16 v[20:23], v[150:153], v[184:187], v[20:23]
	v_mfma_f32_16x16x32_bf16 v[16:19], v[158:161], v[184:187], v[16:19]
	v_mfma_f32_16x16x32_bf16 v[12:15], v[150:153], v[192:195], v[12:15]
	v_mfma_f32_16x16x32_bf16 v[8:11], v[158:161], v[192:195], v[8:11]
	v_mfma_f32_16x16x32_bf16 v[4:7], v[150:153], v[200:203], v[4:7]
	v_mfma_f32_16x16x32_bf16 v[0:3], v[158:161], v[200:203], v[0:3]
	v_mfma_f32_16x16x32_bf16 v[28:31], v[154:157], v[170:173], v[28:31]
	v_mfma_f32_16x16x32_bf16 v[24:27], v[162:165], v[170:173], v[24:27]
	v_mfma_f32_16x16x32_bf16 v[20:23], v[154:157], v[188:191], v[20:23]
	v_mfma_f32_16x16x32_bf16 v[16:19], v[162:165], v[188:191], v[16:19]
	v_mfma_f32_16x16x32_bf16 v[12:15], v[154:157], v[196:199], v[12:15]
	v_mfma_f32_16x16x32_bf16 v[8:11], v[162:165], v[196:199], v[8:11]
	v_mfma_f32_16x16x32_bf16 v[4:7], v[154:157], v[204:207], v[4:7]
	v_mfma_f32_16x16x32_bf16 v[0:3], v[162:165], v[204:207], v[0:3]
	s_setprio 0
	s_barrier
	ds_read_b128 v[128:131], v182
	ds_read_b128 v[132:135], v182 offset:1024
	ds_read_b128 v[136:139], v182 offset:2048
	ds_read_b128 v[140:143], v182 offset:3072
	ds_read_b128 v[150:153], v183
	ds_read_b128 v[154:157], v183 offset:1024
	ds_read_b128 v[158:161], v183 offset:2048
	ds_read_b128 v[162:165], v183 offset:3072
	ds_read_b128 v[166:169], v181 offset:32768
	ds_read_b128 v[170:173], v181 offset:33792
	ds_read_b128 v[184:187], v181 offset:34816
	ds_read_b128 v[188:191], v181 offset:35840
	ds_read_b128 v[192:195], v181 offset:36864
	ds_read_b128 v[196:199], v181 offset:37888
	ds_read_b128 v[200:203], v181 offset:38912
	ds_read_b128 v[204:207], v181 offset:39936
	s_add_u32 s62, s24, 0xb0000
	s_mov_b32 m0, s42
	s_addc_u32 s63, s25, 0
	global_load_lds_dwordx4 v144, s[62:63]
	s_add_u32 s62, s24, 0x108000
	s_mov_b32 m0, s43
	s_addc_u32 s63, s25, 0
	global_load_lds_dwordx4 v144, s[62:63]
	s_waitcnt vmcnt(8)
	s_waitcnt lgkmcnt(0)
	s_barrier
; #define PG8_STAGE(bufoff, gbase, voff, p64) do { _Pragma("unroll") for (int _i = 0; _i < 2; ++_i) { \
;         const char* _gb = (const char*)(gbase) + (size_t)_i * (p64); const unsigned _la = ldsbase + (unsigned)(bufoff) + (unsigned)_i * 8192u; \
;         asm volatile("s_mov_b32 m0, %0\n\ts_nop 0\n\tglobal_load_lds_dwordx4 %1, %2" :: "s"(_la), "v"(voff), "s"(_gb) : "memory"); } } while (0)
; #define PG8_LDA(dst, b, h) do { _Pragma("unroll") for (int m = 0; m < 4; ++m) _Pragma("unroll") for (int k = 0; k < 2; ++k) dst[m][k] = *(const LAS bf16x8*)(lds + PG8_SA(b, h) + aoff + m * 2048 + k * 1024); } while (0)
; #define PG8_MMA(ai, bj, At, Bt) do { __builtin_amdgcn_s_setprio(1); _Pragma("unroll") for (int m = 0; m < 4; ++m) _Pragma("unroll") for (int n = 0; n < 2; ++n) _Pragma("unroll") for (int k = 0; k < 2; ++k) \
;         acc[ai][bj][m][n] = __builtin_amdgcn_mfma_f32_16x16x32_bf16(Bt[n][k], At[m][k], acc[ai][bj][m][n], 0, 0, 0); __builtin_amdgcn_s_setprio(0); } while (0)
; #define PG8_WAIT_V(n) asm volatile("s_waitcnt vmcnt(" #n ")" ::: "memory")
; #define PG8_WAIT_L(n) asm volatile("s_waitcnt lgkmcnt(" #n ")" ::: "memory")
; #define PG8_BAR __builtin_amdgcn_s_barrier()
; #define PG8_SCHED __builtin_amdgcn_sched_barrier(0)
; template <class Epi, class Sched>
; __device__ __forceinline__ void gemm_phase(LAS unsigned char* lds, const Sched& S, const Epi& E) {
;     ...
;             PG8_WAIT_V(8); PG8_WAIT_L(0); PG8_BAR; PG8_MMA(0, 0, At, B0); PG8_MMA(0, 1, At, B1); PG8_BAR; PG8_SCHED;
;             PG8_LDA(At, 1, 1); PG8_STAGE(PG8_SB(1, 0), b3, vB2, hB2 / 2); PG8_STAGE(PG8_SB(1, 1), b3 + hB2, vB2, hB2 / 2); PG8_STAGE(PG8_SA(1, 0), a3, vA2, hA2 / 2);
;             PG8_WAIT_V(8); PG8_WAIT_L(0); PG8_BAR; PG8_MMA(1, 0, At, B0); PG8_MMA(1, 1, At, B1); PG8_BAR; PG8_SCHED;
;         }
;         if (wr == 0) PG8_BAR;
	s_setprio 1
	v_mfma_f32_16x16x32_bf16 v[124:127], v[128:131], v[166:169], v[124:127]
	v_mfma_f32_16x16x32_bf16 v[120:123], v[136:139], v[166:169], v[120:123]
	v_mfma_f32_16x16x32_bf16 v[116:119], v[128:131], v[184:187], v[116:119]
	v_mfma_f32_16x16x32_bf16 v[112:115], v[136:139], v[184:187], v[112:115]
	v_mfma_f32_16x16x32_bf16 v[108:111], v[128:131], v[192:195], v[108:111]
	v_mfma_f32_16x16x32_bf16 v[104:107], v[136:139], v[192:195], v[104:107]
	v_mfma_f32_16x16x32_bf16 v[100:103], v[128:131], v[200:203], v[100:103]
	v_mfma_f32_16x16x32_bf16 v[96:99], v[136:139], v[200:203], v[96:99]
	v_mfma_f32_16x16x32_bf16 v[124:127], v[132:135], v[170:173], v[124:127]
	v_mfma_f32_16x16x32_bf16 v[120:123], v[140:143], v[170:173], v[120:123]
	v_mfma_f32_16x16x32_bf16 v[116:119], v[132:135], v[188:191], v[116:119]
	v_mfma_f32_16x16x32_bf16 v[112:115], v[140:143], v[188:191], v[112:115]
	v_mfma_f32_16x16x32_bf16 v[108:111], v[132:135], v[196:199], v[108:111]
	v_mfma_f32_16x16x32_bf16 v[104:107], v[140:143], v[196:199], v[104:107]
	v_mfma_f32_16x16x32_bf16 v[100:103], v[132:135], v[204:207], v[100:103]
	v_mfma_f32_16x16x32_bf16 v[96:99], v[140:143], v[204:207], v[96:99]
	v_mfma_f32_16x16x32_bf16 v[60:63], v[150:153], v[166:169], v[60:63]
	v_mfma_f32_16x16x32_bf16 v[56:59], v[158:161], v[166:169], v[56:59]
	v_mfma_f32_16x16x32_bf16 v[52:55], v[150:153], v[184:187], v[52:55]
	v_mfma_f32_16x16x32_bf16 v[48:51], v[158:161], v[184:187], v[48:51]
	v_mfma_f32_16x16x32_bf16 v[44:47], v[150:153], v[192:195], v[44:47]
	v_mfma_f32_16x16x32_bf16 v[40:43], v[158:161], v[192:195], v[40:43]
	v_mfma_f32_16x16x32_bf16 v[36:39], v[150:153], v[200:203], v[36:39]
	v_mfma_f32_16x16x32_bf16 v[32:35], v[158:161], v[200:203], v[32:35]
	v_mfma_f32_16x16x32_bf16 v[60:63], v[154:157], v[170:173], v[60:63]
	v_mfma_f32_16x16x32_bf16 v[56:59], v[162:165], v[170:173], v[56:59]
	v_mfma_f32_16x16x32_bf16 v[52:55], v[154:157], v[188:191], v[52:55]
	v_mfma_f32_16x16x32_bf16 v[48:51], v[162:165], v[188:191], v[48:51]
	v_mfma_f32_16x16x32_bf16 v[44:47], v[154:157], v[196:199], v[44:47]
	v_mfma_f32_16x16x32_bf16 v[40:43], v[162:165], v[196:199], v[40:43]
	v_mfma_f32_16x16x32_bf16 v[36:39], v[154:157], v[204:207], v[36:39]
	v_mfma_f32_16x16x32_bf16 v[32:35], v[162:165], v[204:207], v[32:35]
	s_setprio 0
	s_barrier
	s_add_u32 s62, s38, 0x80
	s_addc_u32 s63, s39, 0
	ds_read_b128 v[166:169], v181 offset:49152
	ds_read_b128 v[170:173], v181 offset:50176
	ds_read_b128 v[184:187], v181 offset:51200
	ds_read_b128 v[188:191], v181 offset:52224
	ds_read_b128 v[192:195], v181 offset:53248
	ds_read_b128 v[196:199], v181 offset:54272
	ds_read_b128 v[200:203], v181 offset:55296
	ds_read_b128 v[204:207], v181 offset:56320
	s_mov_b32 m0, s48
	s_nop 0
	global_load_lds_dwordx4 v145, s[62:63]
	s_add_u32 s62, s38, 0x58080
	s_mov_b32 m0, s49
	s_addc_u32 s63, s39, 0
	global_load_lds_dwordx4 v145, s[62:63]
	s_add_u32 s62, s38, 0xb0080
	s_mov_b32 m0, s52
	s_addc_u32 s63, s39, 0
	global_load_lds_dwordx4 v145, s[62:63]
	s_add_u32 s38, s38, 0x108080
	s_mov_b32 m0, s53
	s_addc_u32 s39, s39, 0
	global_load_lds_dwordx4 v145, s[38:39]
	s_mov_b32 m0, s50
	s_nop 0
	global_load_lds_dwordx4 v144, s[26:27]
	s_add_u32 s24, s24, 0x58080
	s_mov_b32 m0, s51
	s_addc_u32 s25, s25, 0
	global_load_lds_dwordx4 v144, s[24:25]
	s_waitcnt vmcnt(8)
	s_waitcnt lgkmcnt(0)
	s_barrier
	s_setprio 1
	v_mfma_f32_16x16x32_bf16 v[92:95], v[128:131], v[166:169], v[92:95]
	v_mfma_f32_16x16x32_bf16 v[88:91], v[136:139], v[166:169], v[88:91]
	v_mfma_f32_16x16x32_bf16 v[84:87], v[128:131], v[184:187], v[84:87]
	v_mfma_f32_16x16x32_bf16 v[80:83], v[136:139], v[184:187], v[80:83]
	v_mfma_f32_16x16x32_bf16 v[76:79], v[128:131], v[192:195], v[76:79]
	v_mfma_f32_16x16x32_bf16 v[72:75], v[136:139], v[192:195], v[72:75]
	v_mfma_f32_16x16x32_bf16 v[68:71], v[128:131], v[200:203], v[68:71]
	v_mfma_f32_16x16x32_bf16 v[64:67], v[136:139], v[200:203], v[64:67]
	v_mfma_f32_16x16x32_bf16 v[92:95], v[132:135], v[170:173], v[92:95]
	v_mfma_f32_16x16x32_bf16 v[88:91], v[140:143], v[170:173], v[88:91]
	v_mfma_f32_16x16x32_bf16 v[84:87], v[132:135], v[188:191], v[84:87]
	v_mfma_f32_16x16x32_bf16 v[80:83], v[140:143], v[188:191], v[80:83]
	v_mfma_f32_16x16x32_bf16 v[76:79], v[132:135], v[196:199], v[76:79]
	v_mfma_f32_16x16x32_bf16 v[72:75], v[140:143], v[196:199], v[72:75]
	v_mfma_f32_16x16x32_bf16 v[68:71], v[132:135], v[204:207], v[68:71]
	v_mfma_f32_16x16x32_bf16 v[64:67], v[140:143], v[204:207], v[64:67]
	v_mfma_f32_16x16x32_bf16 v[28:31], v[150:153], v[166:169], v[28:31]
	v_mfma_f32_16x16x32_bf16 v[24:27], v[158:161], v[166:169], v[24:27]
	v_mfma_f32_16x16x32_bf16 v[20:23], v[150:153], v[184:187], v[20:23]
	v_mfma_f32_16x16x32_bf16 v[16:19], v[158:161], v[184:187], v[16:19]
	v_mfma_f32_16x16x32_bf16 v[12:15], v[150:153], v[192:195], v[12:15]
	v_mfma_f32_16x16x32_bf16 v[8:11], v[158:161], v[192:195], v[8:11]
	v_mfma_f32_16x16x32_bf16 v[4:7], v[150:153], v[200:203], v[4:7]
	v_mfma_f32_16x16x32_bf16 v[0:3], v[158:161], v[200:203], v[0:3]
	v_mfma_f32_16x16x32_bf16 v[28:31], v[154:157], v[170:173], v[28:31]
	v_mfma_f32_16x16x32_bf16 v[24:27], v[162:165], v[170:173], v[24:27]
	v_mfma_f32_16x16x32_bf16 v[20:23], v[154:157], v[188:191], v[20:23]
	v_mfma_f32_16x16x32_bf16 v[16:19], v[162:165], v[188:191], v[16:19]
	v_mfma_f32_16x16x32_bf16 v[12:15], v[154:157], v[196:199], v[12:15]
	v_mfma_f32_16x16x32_bf16 v[8:11], v[162:165], v[196:199], v[8:11]
	v_mfma_f32_16x16x32_bf16 v[4:7], v[154:157], v[204:207], v[4:7]
	v_mfma_f32_16x16x32_bf16 v[0:3], v[162:165], v[204:207], v[0:3]
	s_setprio 0
	s_barrier
	s_add_i32 s61, s61, 2
	s_add_u32 s22, s22, 0x100
	s_addc_u32 s23, s23, 0
	s_add_u32 s59, s59, 0x100
	s_addc_u32 s60, s60, 0
	s_cmp_gt_u32 s61, 41
	s_cbranch_scc0 .LBB0_1559
	s_and_b64 vcc, exec, s[12:13]
	s_cbranch_vccz .LBB0_1562
	s_barrier
